# v1 + sc1 (write-through) on all non-nt global_store_dwordx4 (186 sites)
# baseline (speedup 1.0000x reference)
.LBB0_73:
	s_or_b64 exec, exec, s[10:11]
	s_waitcnt vmcnt(0)
	v_mul_f32_e32 v0, v19, v0
	v_mul_f32_e32 v1, v4, v0
	v_cvt_pk_bf16_f32 v1, v1, s0
	ds_write_b16 v30, v1 offset:192
	v_mul_f32_e32 v1, v5, v0
	v_cvt_pk_bf16_f32 v1, v1, s0
	ds_write_b16 v30, v1 offset:464
	v_mul_f32_e32 v1, v6, v0
	v_mul_f32_e32 v0, v7, v0
	s_sub_i32 s10, 0, s21
	v_cvt_pk_bf16_f32 v1, v1, s0
	v_cvt_pk_bf16_f32 v0, v0, s0
	v_or_b32_e32 v4, s20, v226
	s_add_i32 s10, s34, s10
	ds_write_b16 v30, v1 offset:736
	ds_write_b16 v30, v0 offset:1008
	s_waitcnt lgkmcnt(0)
	s_barrier
	ds_read_b128 v[0:3], v27
	v_ashrrev_i32_e32 v5, 31, v4
	s_ashr_i32 s11, s10, 31
	v_lshlrev_b64 v[4:5], 12, v[4:5]
	v_lshl_add_u64 v[4:5], s[6:7], 0, v[4:5]
	s_lshl_b64 s[10:11], s[10:11], 1
	v_lshl_add_u64 v[4:5], v[4:5], 0, s[10:11]
	v_mov_b32_e32 v19, v17
	v_lshl_add_u64 v[8:9], v[4:5], 0, v[18:19]
	ds_read_b128 v[4:7], v28
	s_waitcnt lgkmcnt(1)
	global_store_dwordx4 v[8:9], v[0:3], off sc1
	s_add_i32 s25, s25, s24
	s_add_i32 s34, s34, s35
	v_add_u32_e32 v0, s20, v26
	v_ashrrev_i32_e32 v1, 31, v0
	v_lshlrev_b64 v[0:1], 12, v[0:1]
	v_lshl_add_u64 v[0:1], s[6:7], 0, v[0:1]
	v_lshl_add_u64 v[0:1], v[0:1], 0, s[10:11]
	v_lshl_add_u64 v[0:1], v[0:1], 0, v[18:19]
	s_cmp_ge_i32 s25, s30
	s_waitcnt lgkmcnt(0)
	global_store_dwordx4 v[0:1], v[4:7], off sc1
	s_barrier
	s_cbranch_scc1 .LBB0_19

.LBB0_243:
	s_or_b64 exec, exec, s[6:7]
	s_bitcmp0_b32 s27, 1
	s_cselect_b64 s[8:9], -1, 0
	v_ashrrev_i32_e32 v158, 6, v160
	s_and_b32 s29, s27, 32
	v_ashrrev_i32_e32 v159, 31, v158
	v_cvt_pk_bf16_f32 v124, v124, v125
	v_cvt_pk_bf16_f32 v125, v126, v127
	v_cvt_pk_bf16_f32 v126, v120, v121
	s_bitcmp1_b32 s27, 5
	v_ashrrev_i32_e32 v120, 5, v152
	v_cvt_pk_bf16_f32 v127, v122, v123
	s_mov_b64 s[6:7], -1
	s_cselect_b64 s[80:81], -1, 0
	s_cmp_eq_u32 s29, 0
	v_lshlrev_b64 v[158:159], 12, v[158:159]
	v_ashrrev_i32_e32 v121, 31, v120
	s_cbranch_scc1 .LBB0_245
	v_lshlrev_b64 v[122:123], 20, v[120:121]
	v_lshl_add_u64 v[122:123], s[12:13], 0, v[122:123]
	v_lshl_add_u64 v[122:123], v[122:123], 0, v[158:159]
	v_lshl_add_u64 v[122:123], v[122:123], 0, v[134:135]
	s_mov_b64 s[6:7], 0
	global_store_dwordx4 v[122:123], v[124:127], off sc1
.LBB0_245:
	s_mul_i32 s27, s74, 0x180
	v_or_b32_e32 v122, s27, v169
	v_cndmask_b32_e64 v160, v122, v160, s[8:9]
	s_andn2_b64 vcc, exec, s[6:7]
	v_ashrrev_i32_e32 v161, 31, v160
	s_cbranch_vccnz .LBB0_247
	v_mad_i64_i32 v[122:123], s[6:7], s84, v152, 0
	v_lshl_add_u64 v[122:123], v[122:123], 1, s[12:13]
	v_lshl_add_u64 v[122:123], v[160:161], 1, v[122:123]
	global_store_dwordx4 v[122:123], v[124:127], off sc1

.LBB0_277:
	v_lshlrev_b64 v[112:113], 20, v[120:121]
	v_lshl_add_u64 v[112:113], s[12:13], 0, v[112:113]
	v_lshl_add_u64 v[112:113], v[112:113], 0, v[158:159]
	v_lshl_add_u64 v[112:113], v[112:113], 0, v[134:135]
	global_store_dwordx4 v[112:113], v[116:119], off offset:256 sc1
	s_cbranch_execnz .LBB0_251
.LBB0_278:
	v_mad_i64_i32 v[112:113], s[74:75], s84, v122, 0
	v_lshl_add_u64 v[112:113], v[112:113], 1, s[12:13]
	v_lshl_add_u64 v[112:113], v[160:161], 1, v[112:113]
	global_store_dwordx4 v[112:113], v[116:119], off sc1
	v_or_b32_e32 v112, 32, v152
	v_ashrrev_i32_e32 v113, 31, v112
	s_and_saveexec_b64 s[74:75], s[78:79]
	s_cbranch_execnz .LBB0_252
	s_branch .LBB0_253
.LBB0_279:
	v_lshlrev_b64 v[104:105], 20, v[106:107]
	v_lshl_add_u64 v[104:105], s[12:13], 0, v[104:105]
	v_lshl_add_u64 v[104:105], v[104:105], 0, v[158:159]
	v_lshl_add_u64 v[104:105], v[104:105], 0, v[134:135]
	global_store_dwordx4 v[104:105], v[108:111], off sc1
	s_cbranch_execnz .LBB0_255
.LBB0_280:
	v_mad_i64_i32 v[104:105], s[74:75], s84, v112, 0
	v_lshl_add_u64 v[104:105], v[104:105], 1, s[12:13]
	v_lshl_add_u64 v[104:105], v[160:161], 1, v[104:105]
	global_store_dwordx4 v[104:105], v[108:111], off sc1
	v_or_b32_e32 v104, 48, v152
	v_ashrrev_i32_e32 v105, 31, v104
	s_and_saveexec_b64 s[74:75], s[78:79]
	s_cbranch_execnz .LBB0_256
	s_branch .LBB0_257
.LBB0_281:
	v_lshlrev_b64 v[96:97], 20, v[98:99]
	v_lshl_add_u64 v[96:97], s[12:13], 0, v[96:97]
	v_lshl_add_u64 v[96:97], v[96:97], 0, v[158:159]
	v_lshl_add_u64 v[96:97], v[96:97], 0, v[134:135]
	global_store_dwordx4 v[96:97], v[100:103], off offset:256 sc1
	s_cbranch_execnz .LBB0_259
.LBB0_282:
	v_mad_i64_i32 v[96:97], s[74:75], s84, v104, 0
	v_lshl_add_u64 v[96:97], v[96:97], 1, s[12:13]
	v_lshl_add_u64 v[96:97], v[160:161], 1, v[96:97]
	global_store_dwordx4 v[96:97], v[100:103], off sc1
	v_add_u32_e32 v96, 0x80, v152
	v_ashrrev_i32_e32 v97, 31, v96
	s_and_saveexec_b64 s[74:75], s[78:79]
	s_cbranch_execnz .LBB0_260
	s_branch .LBB0_261
.LBB0_283:
	v_lshlrev_b64 v[88:89], 20, v[90:91]
	v_lshl_add_u64 v[88:89], s[12:13], 0, v[88:89]
	v_lshl_add_u64 v[88:89], v[88:89], 0, v[158:159]
	v_lshl_add_u64 v[88:89], v[88:89], 0, v[134:135]
	global_store_dwordx4 v[88:89], v[92:95], off sc1
	s_cbranch_execnz .LBB0_263
.LBB0_284:
	v_mad_i64_i32 v[88:89], s[74:75], s84, v96, 0
	v_lshl_add_u64 v[88:89], v[88:89], 1, s[12:13]
	v_lshl_add_u64 v[88:89], v[160:161], 1, v[88:89]
	global_store_dwordx4 v[88:89], v[92:95], off sc1
	v_add_u32_e32 v88, 0x90, v152
	v_ashrrev_i32_e32 v89, 31, v88
	s_and_saveexec_b64 s[74:75], s[78:79]
	s_cbranch_execnz .LBB0_264
	s_branch .LBB0_265
.LBB0_285:
	v_lshlrev_b64 v[80:81], 20, v[82:83]
	v_lshl_add_u64 v[80:81], s[12:13], 0, v[80:81]
	v_lshl_add_u64 v[80:81], v[80:81], 0, v[158:159]
	v_lshl_add_u64 v[80:81], v[80:81], 0, v[134:135]
	global_store_dwordx4 v[80:81], v[84:87], off offset:256 sc1
	s_cbranch_execnz .LBB0_267
.LBB0_286:
	v_mad_i64_i32 v[80:81], s[74:75], s84, v88, 0
	v_lshl_add_u64 v[80:81], v[80:81], 1, s[12:13]
	v_lshl_add_u64 v[80:81], v[160:161], 1, v[80:81]
	global_store_dwordx4 v[80:81], v[84:87], off sc1
	v_add_u32_e32 v80, 0xa0, v152
	v_ashrrev_i32_e32 v81, 31, v80
	s_and_saveexec_b64 s[74:75], s[78:79]
	s_cbranch_execnz .LBB0_268
	s_branch .LBB0_269
.LBB0_287:
	v_lshlrev_b64 v[72:73], 20, v[74:75]
	v_lshl_add_u64 v[72:73], s[12:13], 0, v[72:73]
	v_lshl_add_u64 v[72:73], v[72:73], 0, v[158:159]
	v_lshl_add_u64 v[72:73], v[72:73], 0, v[134:135]
	global_store_dwordx4 v[72:73], v[76:79], off sc1
	s_cbranch_execnz .LBB0_271
.LBB0_288:
	v_mad_i64_i32 v[72:73], s[74:75], s84, v80, 0
	v_lshl_add_u64 v[72:73], v[72:73], 1, s[12:13]
	v_lshl_add_u64 v[72:73], v[160:161], 1, v[72:73]
	global_store_dwordx4 v[72:73], v[76:79], off sc1
	v_add_u32_e32 v72, 0xb0, v152
	v_ashrrev_i32_e32 v73, 31, v72
	s_and_saveexec_b64 s[74:75], s[78:79]
	s_cbranch_execnz .LBB0_272
	s_branch .LBB0_273
.LBB0_289:
	v_lshlrev_b64 v[66:67], 20, v[64:65]
	v_lshl_add_u64 v[66:67], s[12:13], 0, v[66:67]
	v_lshl_add_u64 v[66:67], v[66:67], 0, v[158:159]
	v_lshl_add_u64 v[66:67], v[66:67], 0, v[134:135]
	global_store_dwordx4 v[66:67], v[68:71], off offset:256 sc1
	s_cbranch_execnz .LBB0_275
.LBB0_290:
	v_mad_i64_i32 v[66:67], s[74:75], s84, v72, 0
	v_lshl_add_u64 v[66:67], v[66:67], 1, s[12:13]
	v_lshl_add_u64 v[66:67], v[160:161], 1, v[66:67]
	global_store_dwordx4 v[66:67], v[68:71], off sc1
	s_bitset1_b32 s28, 7
	s_andn2_b64 vcc, exec, s[76:77]
	v_or_b32_e32 v70, s28, v169
	s_cbranch_vccz .LBB0_276

.LBB0_294:
	s_or_b64 exec, exec, s[76:77]
	v_ashrrev_i32_e32 v76, 6, v70
	v_ashrrev_i32_e32 v77, 31, v76
	v_cvt_pk_bf16_f32 v60, v60, v61
	v_cvt_pk_bf16_f32 v61, v62, v63
	v_cvt_pk_bf16_f32 v62, v56, v57
	v_cvt_pk_bf16_f32 v63, v58, v59
	s_mov_b64 s[76:77], -1
	s_and_b64 vcc, exec, s[6:7]
	v_lshlrev_b64 v[56:57], 12, v[76:77]
	s_cbranch_vccnz .LBB0_296
	v_lshlrev_b64 v[58:59], 20, v[120:121]
	v_lshl_add_u64 v[58:59], s[12:13], 0, v[58:59]
	v_lshl_add_u64 v[58:59], v[58:59], 0, v[56:57]
	v_lshl_add_u64 v[58:59], v[58:59], 0, v[134:135]
	s_mov_b64 s[76:77], 0
	global_store_dwordx4 v[58:59], v[60:63], off sc1
.LBB0_296:
	s_ashr_i32 s27, s28, 7
	s_mulk_i32 s27, 0xc0
	v_add_u32_e32 v58, s27, v169
	v_cndmask_b32_e64 v58, v58, v70, s[8:9]
	s_andn2_b64 vcc, exec, s[76:77]
	v_ashrrev_i32_e32 v59, 31, v58
	s_cbranch_vccnz .LBB0_298
	v_mad_i64_i32 v[70:71], s[8:9], s84, v152, 0
	v_lshl_add_u64 v[70:71], v[70:71], 1, s[12:13]
	v_lshl_add_u64 v[70:71], v[58:59], 1, v[70:71]
	global_store_dwordx4 v[70:71], v[60:63], off sc1

.LBB0_324:
	s_or_b64 exec, exec, s[8:9]
	v_cvt_pk_bf16_f32 v4, v4, v5
	v_cvt_pk_bf16_f32 v5, v6, v7
	v_cvt_pk_bf16_f32 v6, v0, v1
	v_cvt_pk_bf16_f32 v7, v2, v3
	s_and_b64 vcc, exec, s[6:7]
	s_mov_b64 s[6:7], -1
	s_cbranch_vccnz .LBB0_326
	v_lshlrev_b64 v[0:1], 20, v[64:65]
	v_lshl_add_u64 v[0:1], s[12:13], 0, v[0:1]
	v_lshl_add_u64 v[0:1], v[0:1], 0, v[56:57]
	v_lshl_add_u64 v[0:1], v[0:1], 0, v[134:135]
	s_mov_b64 s[6:7], 0
	global_store_dwordx4 v[0:1], v[4:7], off offset:256 sc1
.LBB0_326:
	s_andn2_b64 vcc, exec, s[6:7]
	s_cbranch_vccnz .LBB0_213
	v_mad_i64_i32 v[0:1], s[6:7], s84, v72, 0
	v_lshl_add_u64 v[0:1], v[0:1], 1, s[12:13]
	v_lshl_add_u64 v[0:1], v[58:59], 1, v[0:1]
	global_store_dwordx4 v[0:1], v[4:7], off sc1
	s_branch .LBB0_213
.LBB0_328:
	v_lshlrev_b64 v[48:49], 20, v[120:121]
	v_lshl_add_u64 v[48:49], s[12:13], 0, v[48:49]
	v_lshl_add_u64 v[48:49], v[48:49], 0, v[56:57]
	v_lshl_add_u64 v[48:49], v[48:49], 0, v[134:135]
	global_store_dwordx4 v[48:49], v[52:55], off offset:256 sc1
	s_cbranch_execnz .LBB0_302
.LBB0_329:
	v_mad_i64_i32 v[48:49], s[8:9], s84, v122, 0
	v_lshl_add_u64 v[48:49], v[48:49], 1, s[12:13]
	v_lshl_add_u64 v[48:49], v[58:59], 1, v[48:49]
	global_store_dwordx4 v[48:49], v[52:55], off sc1
	s_and_saveexec_b64 s[8:9], s[74:75]
	s_cbranch_execnz .LBB0_303
	s_branch .LBB0_304
.LBB0_330:
	v_lshlrev_b64 v[40:41], 20, v[106:107]
	v_lshl_add_u64 v[40:41], s[12:13], 0, v[40:41]
	v_lshl_add_u64 v[40:41], v[40:41], 0, v[56:57]
	v_lshl_add_u64 v[40:41], v[40:41], 0, v[134:135]
	global_store_dwordx4 v[40:41], v[44:47], off sc1
	s_cbranch_execnz .LBB0_306
.LBB0_331:
	v_mad_i64_i32 v[40:41], s[8:9], s84, v112, 0
	v_lshl_add_u64 v[40:41], v[40:41], 1, s[12:13]
	v_lshl_add_u64 v[40:41], v[58:59], 1, v[40:41]
	global_store_dwordx4 v[40:41], v[44:47], off sc1
	s_and_saveexec_b64 s[8:9], s[74:75]
	s_cbranch_execnz .LBB0_307
	s_branch .LBB0_308
.LBB0_332:
	v_lshlrev_b64 v[32:33], 20, v[98:99]
	v_lshl_add_u64 v[32:33], s[12:13], 0, v[32:33]
	v_lshl_add_u64 v[32:33], v[32:33], 0, v[56:57]
	v_lshl_add_u64 v[32:33], v[32:33], 0, v[134:135]
	global_store_dwordx4 v[32:33], v[36:39], off offset:256 sc1
	s_cbranch_execnz .LBB0_310
.LBB0_333:
	v_mad_i64_i32 v[32:33], s[8:9], s84, v104, 0
	v_lshl_add_u64 v[32:33], v[32:33], 1, s[12:13]
	v_lshl_add_u64 v[32:33], v[58:59], 1, v[32:33]
	global_store_dwordx4 v[32:33], v[36:39], off sc1
	s_and_saveexec_b64 s[8:9], s[74:75]
	s_cbranch_execnz .LBB0_311
	s_branch .LBB0_312
.LBB0_334:
	v_lshlrev_b64 v[24:25], 20, v[90:91]
	v_lshl_add_u64 v[24:25], s[12:13], 0, v[24:25]
	v_lshl_add_u64 v[24:25], v[24:25], 0, v[56:57]
	v_lshl_add_u64 v[24:25], v[24:25], 0, v[134:135]
	global_store_dwordx4 v[24:25], v[28:31], off sc1
	s_cbranch_execnz .LBB0_314
.LBB0_335:
	v_mad_i64_i32 v[24:25], s[8:9], s84, v96, 0
	v_lshl_add_u64 v[24:25], v[24:25], 1, s[12:13]
	v_lshl_add_u64 v[24:25], v[58:59], 1, v[24:25]
	global_store_dwordx4 v[24:25], v[28:31], off sc1
	s_and_saveexec_b64 s[8:9], s[74:75]
	s_cbranch_execnz .LBB0_315
	s_branch .LBB0_316
.LBB0_336:
	v_lshlrev_b64 v[16:17], 20, v[82:83]
	v_lshl_add_u64 v[16:17], s[12:13], 0, v[16:17]
	v_lshl_add_u64 v[16:17], v[16:17], 0, v[56:57]
	v_lshl_add_u64 v[16:17], v[16:17], 0, v[134:135]
	global_store_dwordx4 v[16:17], v[20:23], off offset:256 sc1
	s_cbranch_execnz .LBB0_318
.LBB0_337:
	v_mad_i64_i32 v[16:17], s[8:9], s84, v88, 0
	v_lshl_add_u64 v[16:17], v[16:17], 1, s[12:13]
	v_lshl_add_u64 v[16:17], v[58:59], 1, v[16:17]
	global_store_dwordx4 v[16:17], v[20:23], off sc1
	s_and_saveexec_b64 s[8:9], s[74:75]
	s_cbranch_execnz .LBB0_319
	s_branch .LBB0_320
.LBB0_338:
	v_lshlrev_b64 v[8:9], 20, v[74:75]
	v_lshl_add_u64 v[8:9], s[12:13], 0, v[8:9]
	v_lshl_add_u64 v[8:9], v[8:9], 0, v[56:57]
	v_lshl_add_u64 v[8:9], v[8:9], 0, v[134:135]
	global_store_dwordx4 v[8:9], v[12:15], off sc1
	s_cbranch_execnz .LBB0_322
.LBB0_339:
	v_mad_i64_i32 v[8:9], s[8:9], s84, v80, 0
	v_lshl_add_u64 v[8:9], v[8:9], 1, s[12:13]
	v_lshl_add_u64 v[8:9], v[58:59], 1, v[8:9]
	global_store_dwordx4 v[8:9], v[12:15], off sc1
	s_and_saveexec_b64 s[8:9], s[74:75]
	s_cbranch_execnz .LBB0_323
	s_branch .LBB0_324

.LBB0_346:
	s_waitcnt vmcnt(0)
	v_cvt_pk_bf16_f32 v0, v0, s0
	ds_write_b16 v26, v0
	v_cvt_pk_bf16_f32 v0, v1, s0
	ds_write_b16 v26, v0 offset:272
	v_cvt_pk_bf16_f32 v0, v2, s0
	ds_write_b16 v26, v0 offset:544
	v_cvt_pk_bf16_f32 v0, v3, s0
	ds_write_b16 v26, v0 offset:816
	v_cvt_pk_bf16_f32 v0, v8, s0
	ds_write_b16 v26, v0 offset:64
	v_cvt_pk_bf16_f32 v0, v9, s0
	ds_write_b16 v26, v0 offset:336
	v_cvt_pk_bf16_f32 v0, v10, s0
	ds_write_b16 v26, v0 offset:608
	v_cvt_pk_bf16_f32 v0, v11, s0
	ds_write_b16 v26, v0 offset:880
	v_cvt_pk_bf16_f32 v0, v4, s0
	ds_write_b16 v26, v0 offset:128
	v_cvt_pk_bf16_f32 v0, v5, s0
	ds_write_b16 v26, v0 offset:400
	v_cvt_pk_bf16_f32 v0, v6, s0
	ds_write_b16 v26, v0 offset:672
	v_cvt_pk_bf16_f32 v0, v7, s0
	ds_write_b16 v26, v0 offset:944
	v_cvt_pk_bf16_f32 v0, v12, s0
	ds_write_b16 v26, v0 offset:192
	v_cvt_pk_bf16_f32 v0, v13, s0
	ds_write_b16 v26, v0 offset:464
	v_cvt_pk_bf16_f32 v0, v14, s0
	s_sub_i32 s6, 0, s20
	ds_write_b16 v26, v0 offset:736
	v_cvt_pk_bf16_f32 v0, v15, s0
	v_or_b32_e32 v4, s19, v226
	s_add_i32 s6, s17, s6
	ds_write_b16 v26, v0 offset:1008
	s_waitcnt lgkmcnt(0)
	s_barrier
	ds_read_b128 v[0:3], v27
	v_ashrrev_i32_e32 v5, 31, v4
	s_ashr_i32 s7, s6, 31
	v_lshlrev_b64 v[4:5], 12, v[4:5]
	v_lshl_add_u64 v[4:5], s[8:9], 0, v[4:5]
	s_lshl_b64 s[6:7], s[6:7], 1
	v_lshl_add_u64 v[4:5], v[4:5], 0, s[6:7]
	v_mov_b32_e32 v19, v17
	v_lshl_add_u64 v[8:9], v[4:5], 0, v[18:19]
	ds_read_b128 v[4:7], v28
	s_waitcnt lgkmcnt(1)
	global_store_dwordx4 v[8:9], v[0:3], off sc1
	s_add_i32 s3, s3, s16
	s_add_i32 s17, s17, s18
	v_add_u32_e32 v0, s19, v25
	v_ashrrev_i32_e32 v1, 31, v0
	v_lshlrev_b64 v[0:1], 12, v[0:1]
	v_lshl_add_u64 v[0:1], s[8:9], 0, v[0:1]
	v_lshl_add_u64 v[0:1], v[0:1], 0, s[6:7]
	v_lshl_add_u64 v[0:1], v[0:1], 0, v[18:19]
	s_cmpk_lt_i32 s3, 0x200
	s_waitcnt lgkmcnt(0)
	global_store_dwordx4 v[0:1], v[4:7], off sc1
	s_barrier
	s_cbranch_scc0 .LBB0_355

.LBB0_417:
	v_pk_add_f32 v[64:65], v[80:81], 0 op_sel_hi:[1,0]
	s_lshl_b64 s[8:9], s[22:23], 12
	v_pk_add_f32 v[64:65], v[82:83], v[64:65]
	s_add_u32 s8, s42, s8
	v_pk_add_f32 v[64:65], v[84:85], v[64:65]
	s_addc_u32 s9, s43, s9
	v_pk_add_f32 v[64:65], v[86:87], v[64:65]
	s_add_u32 s8, s8, s91
	v_pk_add_f32 v[64:65], v[88:89], v[64:65]
	s_addc_u32 s9, s9, 0
	v_pk_add_f32 v[64:65], v[90:91], v[64:65]
	v_mov_b32_e32 v189, v181
	v_pk_add_f32 v[64:65], v[92:93], v[64:65]
	v_or_b32_e32 v180, s82, v197
	v_pk_add_f32 v[64:65], v[94:95], v[64:65]
	s_nop 0
	v_pk_add_f32 v[64:65], v[96:97], v[64:65]
	s_barrier
	v_pk_add_f32 v[64:65], v[98:99], v[64:65]
	s_nop 0
	v_pk_add_f32 v[64:65], v[100:101], v[64:65]
	s_nop 0
	v_pk_add_f32 v[64:65], v[102:103], v[64:65]
	s_nop 0
	v_pk_add_f32 v[64:65], v[104:105], v[64:65]
	s_nop 0
	v_pk_add_f32 v[64:65], v[106:107], v[64:65]
	s_nop 0
	v_pk_add_f32 v[64:65], v[108:109], v[64:65]
	s_nop 0
	v_pk_add_f32 v[64:65], v[110:111], v[64:65]
	s_nop 0
	v_add_f32_e32 v64, v64, v65
	v_add_f32_e32 v64, v154, v64
	ds_bpermute_b32 v65, v171, v64
	s_waitcnt lgkmcnt(0)
	v_add_f32_e32 v70, v64, v65
	v_div_scale_f32 v64, s[10:11], v70, v70, 1.0
	v_rcp_f32_e32 v71, v64
	s_add_u32 s10, s89, s91
	s_addc_u32 s11, s90, 0
	s_add_i32 s88, s88, s46
	v_fma_f32 v65, -v64, v71, 1.0
	v_fmac_f32_e32 v71, v65, v71
	v_div_scale_f32 v65, vcc, 1.0, v70, 1.0
	v_mul_f32_e32 v72, v65, v71
	v_fma_f32 v66, -v64, v72, v65
	v_fmac_f32_e32 v72, v66, v71
	v_fma_f32 v73, -v64, v72, v65
	v_lshl_add_u64 v[64:65], s[10:11], 0, v[188:189]
	s_mov_b64 s[10:11], 0x1c00
	v_lshl_add_u64 v[68:69], v[64:65], 0, s[10:11]
	v_mad_u64_u32 v[64:65], s[10:11], v180, s73, v[68:69]
	global_load_dwordx4 v[64:67], v[64:65], off
	v_div_fmas_f32 v71, v73, v71, v72
	v_div_fixup_f32 v70, v71, v70, 1.0
	v_pk_mul_f32 v[16:17], v[16:17], v[70:71] op_sel_hi:[1,0]
	v_pk_mul_f32 v[18:19], v[18:19], v[70:71] op_sel_hi:[1,0]
	v_pk_mul_f32 v[0:1], v[0:1], v[70:71] op_sel_hi:[1,0]
	v_pk_mul_f32 v[2:3], v[2:3], v[70:71] op_sel_hi:[1,0]
	v_cvt_pk_bf16_f32 v16, v16, v17
	v_cvt_pk_bf16_f32 v17, v18, v19
	v_pk_mul_f32 v[18:19], v[20:21], v[70:71] op_sel_hi:[1,0]
	v_pk_mul_f32 v[20:21], v[22:23], v[70:71] op_sel_hi:[1,0]
	v_cvt_pk_bf16_f32 v0, v0, v1
	v_cvt_pk_bf16_f32 v1, v2, v3
	v_pk_mul_f32 v[2:3], v[4:5], v[70:71] op_sel_hi:[1,0]
	v_pk_mul_f32 v[4:5], v[6:7], v[70:71] op_sel_hi:[1,0]
	v_mad_u64_u32 v[72:73], s[10:11], v170, s65, v[182:183]
	v_cvt_pk_bf16_f32 v18, v18, v19
	v_cvt_pk_bf16_f32 v19, v20, v21
	v_cvt_pk_bf16_f32 v2, v2, v3
	v_cvt_pk_bf16_f32 v3, v4, v5
	ds_write2_b64 v72, v[16:17], v[18:19] offset0:16 offset1:18
	v_pk_mul_f32 v[16:17], v[24:25], v[70:71] op_sel_hi:[1,0]
	v_pk_mul_f32 v[18:19], v[26:27], v[70:71] op_sel_hi:[1,0]
	ds_write2_b64 v72, v[0:1], v[2:3] offset0:24 offset1:26
	v_pk_mul_f32 v[0:1], v[8:9], v[70:71] op_sel_hi:[1,0]
	v_pk_mul_f32 v[2:3], v[10:11], v[70:71] op_sel_hi:[1,0]
	v_cvt_pk_bf16_f32 v16, v16, v17
	v_cvt_pk_bf16_f32 v17, v18, v19
	v_pk_mul_f32 v[18:19], v[28:29], v[70:71] op_sel_hi:[1,0]
	v_pk_mul_f32 v[20:21], v[30:31], v[70:71] op_sel_hi:[1,0]
	v_cvt_pk_bf16_f32 v0, v0, v1
	v_cvt_pk_bf16_f32 v1, v2, v3
	v_pk_mul_f32 v[2:3], v[12:13], v[70:71] op_sel_hi:[1,0]
	v_pk_mul_f32 v[4:5], v[14:15], v[70:71] op_sel_hi:[1,0]
	v_cvt_pk_bf16_f32 v18, v18, v19
	v_cvt_pk_bf16_f32 v19, v20, v21
	v_cvt_pk_bf16_f32 v2, v2, v3
	v_cvt_pk_bf16_f32 v3, v4, v5
	v_pk_mul_f32 v[48:49], v[48:49], v[70:71] op_sel_hi:[1,0]
	v_pk_mul_f32 v[50:51], v[50:51], v[70:71] op_sel_hi:[1,0]
	v_pk_mul_f32 v[32:33], v[32:33], v[70:71] op_sel_hi:[1,0]
	v_pk_mul_f32 v[34:35], v[34:35], v[70:71] op_sel_hi:[1,0]
	ds_write2_b64 v72, v[16:17], v[18:19] offset0:20 offset1:22
	ds_write2_b64 v72, v[0:1], v[2:3] offset0:28 offset1:30
	v_lshl_add_u64 v[0:1], s[8:9], 0, v[188:189]
	s_mov_b64 s[8:9], 0x5004c00
	v_cvt_pk_bf16_f32 v48, v48, v49
	v_cvt_pk_bf16_f32 v49, v50, v51
	v_pk_mul_f32 v[50:51], v[52:53], v[70:71] op_sel_hi:[1,0]
	v_pk_mul_f32 v[52:53], v[54:55], v[70:71] op_sel_hi:[1,0]
	v_cvt_pk_bf16_f32 v32, v32, v33
	v_cvt_pk_bf16_f32 v33, v34, v35
	v_pk_mul_f32 v[34:35], v[36:37], v[70:71] op_sel_hi:[1,0]
	v_pk_mul_f32 v[36:37], v[38:39], v[70:71] op_sel_hi:[1,0]
	v_lshl_add_u64 v[12:13], v[0:1], 0, s[8:9]
	v_cvt_pk_bf16_f32 v50, v50, v51
	v_cvt_pk_bf16_f32 v51, v52, v53
	v_cvt_pk_bf16_f32 v34, v34, v35
	v_cvt_pk_bf16_f32 v35, v36, v37
	ds_write2_b64 v72, v[48:49], v[50:51] offset1:2
	v_pk_mul_f32 v[48:49], v[56:57], v[70:71] op_sel_hi:[1,0]
	v_pk_mul_f32 v[50:51], v[58:59], v[70:71] op_sel_hi:[1,0]
	ds_write2_b64 v72, v[32:33], v[34:35] offset0:8 offset1:10
	v_pk_mul_f32 v[32:33], v[40:41], v[70:71] op_sel_hi:[1,0]
	v_pk_mul_f32 v[34:35], v[42:43], v[70:71] op_sel_hi:[1,0]
	v_cvt_pk_bf16_f32 v48, v48, v49
	v_cvt_pk_bf16_f32 v49, v50, v51
	v_pk_mul_f32 v[50:51], v[60:61], v[70:71] op_sel_hi:[1,0]
	v_pk_mul_f32 v[52:53], v[62:63], v[70:71] op_sel_hi:[1,0]
	v_cvt_pk_bf16_f32 v32, v32, v33
	v_cvt_pk_bf16_f32 v33, v34, v35
	v_pk_mul_f32 v[34:35], v[44:45], v[70:71] op_sel_hi:[1,0]
	v_pk_mul_f32 v[36:37], v[46:47], v[70:71] op_sel_hi:[1,0]
	v_cvt_pk_bf16_f32 v50, v50, v51
	v_cvt_pk_bf16_f32 v51, v52, v53
	v_cvt_pk_bf16_f32 v34, v34, v35
	v_cvt_pk_bf16_f32 v35, v36, v37
	ds_write2_b64 v72, v[48:49], v[50:51] offset0:4 offset1:6
	ds_write2_b64 v72, v[32:33], v[34:35] offset0:12 offset1:14
	s_waitcnt vmcnt(0)
	v_lshlrev_b32_e32 v18, 16, v64
	v_and_b32_e32 v16, 0xffff0000, v64
	v_mul_f32_e32 v0, 0xbfb8aa3b, v18
	v_mul_f32_e32 v1, 0xbfb8aa3b, v16
	v_exp_f32_e32 v0, v0
	v_exp_f32_e32 v1, v1
	v_mad_u64_u32 v[14:15], s[8:9], v180, s65, v[184:185]
	ds_read_b128 v[4:7], v14
	v_pk_add_f32 v[8:9], v[0:1], 1.0 op_sel_hi:[1,0]
	ds_read_b128 v[0:3], v14 offset:1088
	v_div_scale_f32 v15, s[8:9], v9, v9, v16
	v_rcp_f32_e32 v17, v15
	s_waitcnt lgkmcnt(1)
	v_lshlrev_b32_e32 v10, 16, v4
	v_and_b32_e32 v11, 0xffff0000, v4
	v_and_b32_e32 v21, 0xffff0000, v65
	v_fma_f32 v4, -v15, v17, 1.0
	v_fmac_f32_e32 v17, v4, v17
	v_div_scale_f32 v4, vcc, v16, v9, v16
	v_mul_f32_e32 v19, v4, v17
	v_fma_f32 v20, -v15, v19, v4
	v_fmac_f32_e32 v19, v20, v17
	v_fma_f32 v4, -v15, v19, v4
	v_div_scale_f32 v15, s[8:9], v8, v8, v18
	v_rcp_f32_e32 v20, v15
	v_div_fmas_f32 v4, v4, v17, v19
	v_div_fixup_f32 v9, v4, v9, v16
	v_mul_f32_e32 v17, 0xbfb8aa3b, v21
	v_fma_f32 v4, -v15, v20, 1.0
	v_fmac_f32_e32 v20, v4, v20
	v_div_scale_f32 v4, vcc, v18, v8, v18
	v_mul_f32_e32 v19, v4, v20
	v_fma_f32 v16, -v15, v19, v4
	v_fmac_f32_e32 v19, v16, v20
	v_fma_f32 v4, -v15, v19, v4
	v_lshlrev_b32_e32 v15, 16, v65
	v_mul_f32_e32 v16, 0xbfb8aa3b, v15
	v_exp_f32_e32 v16, v16
	v_exp_f32_e32 v17, v17
	v_div_fmas_f32 v4, v4, v20, v19
	v_div_fixup_f32 v8, v4, v8, v18
	v_pk_mul_f32 v[8:9], v[8:9], v[10:11]
	v_pk_add_f32 v[10:11], v[16:17], 1.0 op_sel_hi:[1,0]
	v_cvt_pk_bf16_f32 v4, v8, v9
	v_div_scale_f32 v16, s[8:9], v11, v11, v21
	v_rcp_f32_e32 v17, v16
	v_lshlrev_b32_e32 v8, 16, v5
	v_and_b32_e32 v9, 0xffff0000, v5
	v_lshlrev_b32_e32 v20, 16, v66
	v_fma_f32 v5, -v16, v17, 1.0
	v_fmac_f32_e32 v17, v5, v17
	v_div_scale_f32 v5, vcc, v21, v11, v21
	v_mul_f32_e32 v18, v5, v17
	v_fma_f32 v19, -v16, v18, v5
	v_fmac_f32_e32 v18, v19, v17
	v_fma_f32 v5, -v16, v18, v5
	v_div_scale_f32 v16, s[8:9], v10, v10, v15
	v_rcp_f32_e32 v19, v16
	v_div_fmas_f32 v5, v5, v17, v18
	v_div_fixup_f32 v11, v5, v11, v21
	v_and_b32_e32 v21, 0xffff0000, v66
	v_fma_f32 v5, -v16, v19, 1.0
	v_fmac_f32_e32 v19, v5, v19
	v_div_scale_f32 v5, vcc, v15, v10, v15
	v_mul_f32_e32 v18, v5, v19
	v_fma_f32 v17, -v16, v18, v5
	v_fmac_f32_e32 v18, v17, v19
	v_fma_f32 v5, -v16, v18, v5
	v_mul_f32_e32 v16, 0xbfb8aa3b, v20
	v_mul_f32_e32 v17, 0xbfb8aa3b, v21
	v_exp_f32_e32 v16, v16
	v_exp_f32_e32 v17, v17
	v_div_fmas_f32 v5, v5, v19, v18
	v_div_fixup_f32 v10, v5, v10, v15
	v_pk_mul_f32 v[8:9], v[10:11], v[8:9]
	v_pk_add_f32 v[10:11], v[16:17], 1.0 op_sel_hi:[1,0]
	v_cvt_pk_bf16_f32 v5, v8, v9
	v_div_scale_f32 v15, s[8:9], v11, v11, v21
	v_rcp_f32_e32 v16, v15
	v_lshlrev_b32_e32 v8, 16, v6
	v_and_b32_e32 v9, 0xffff0000, v6
	s_cmpk_lt_i32 s88, 0x100
	v_fma_f32 v6, -v15, v16, 1.0
	v_fmac_f32_e32 v16, v6, v16
	v_div_scale_f32 v6, vcc, v21, v11, v21
	v_mul_f32_e32 v17, v6, v16
	v_fma_f32 v18, -v15, v17, v6
	v_fmac_f32_e32 v17, v18, v16
	v_fma_f32 v6, -v15, v17, v6
	v_div_scale_f32 v15, s[8:9], v10, v10, v20
	v_rcp_f32_e32 v18, v15
	v_div_fmas_f32 v6, v6, v16, v17
	v_div_fixup_f32 v11, v6, v11, v21
	v_and_b32_e32 v21, 0xffff0000, v67
	v_fma_f32 v6, -v15, v18, 1.0
	v_fmac_f32_e32 v18, v6, v18
	v_div_scale_f32 v6, vcc, v20, v10, v20
	v_mul_f32_e32 v19, v6, v18
	v_fma_f32 v16, -v15, v19, v6
	v_fmac_f32_e32 v19, v16, v18
	v_fma_f32 v6, -v15, v19, v6
	v_lshlrev_b32_e32 v15, 16, v67
	v_mul_f32_e32 v16, 0xbfb8aa3b, v15
	v_mul_f32_e32 v17, 0xbfb8aa3b, v21
	v_exp_f32_e32 v16, v16
	v_exp_f32_e32 v17, v17
	v_div_fmas_f32 v6, v6, v18, v19
	v_div_fixup_f32 v10, v6, v10, v20
	v_pk_mul_f32 v[8:9], v[10:11], v[8:9]
	v_pk_add_f32 v[10:11], v[16:17], 1.0 op_sel_hi:[1,0]
	v_cvt_pk_bf16_f32 v6, v8, v9
	v_div_scale_f32 v16, s[8:9], v11, v11, v21
	v_rcp_f32_e32 v17, v16
	v_lshlrev_b32_e32 v8, 16, v7
	v_and_b32_e32 v9, 0xffff0000, v7
	v_fma_f32 v7, -v16, v17, 1.0
	v_fmac_f32_e32 v17, v7, v17
	v_div_scale_f32 v7, vcc, v21, v11, v21
	v_mul_f32_e32 v18, v7, v17
	v_fma_f32 v19, -v16, v18, v7
	v_fmac_f32_e32 v18, v19, v17
	v_fma_f32 v7, -v16, v18, v7
	v_div_scale_f32 v16, s[8:9], v10, v10, v15
	v_rcp_f32_e32 v19, v16
	v_div_fmas_f32 v7, v7, v17, v18
	v_div_fixup_f32 v11, v7, v11, v21
	v_fma_f32 v7, -v16, v19, 1.0
	v_fmac_f32_e32 v19, v7, v19
	v_div_scale_f32 v7, vcc, v15, v10, v15
	v_mul_f32_e32 v17, v7, v19
	v_fma_f32 v18, -v16, v17, v7
	v_fmac_f32_e32 v17, v18, v19
	v_fma_f32 v7, -v16, v17, v7
	v_div_fmas_f32 v7, v7, v19, v17
	v_div_fixup_f32 v10, v7, v10, v15
	v_pk_mul_f32 v[8:9], v[10:11], v[8:9]
	s_waitcnt lgkmcnt(0)
	v_lshlrev_b32_e32 v16, 16, v0
	v_cvt_pk_bf16_f32 v7, v8, v9
	v_lshlrev_b64 v[8:9], 12, v[180:181]
	v_lshl_add_u64 v[8:9], v[12:13], 0, v[8:9]
	global_store_dwordx4 v[8:9], v[4:7], off sc1
	v_or_b32_e32 v8, 4, v180
	v_and_b32_e32 v17, 0xffff0000, v0
	v_mad_u64_u32 v[4:5], s[8:9], v8, s73, v[68:69]
	global_load_dwordx4 v[4:7], v[4:5], off
	s_waitcnt vmcnt(0)
	v_lshlrev_b32_e32 v15, 16, v4
	v_and_b32_e32 v4, 0xffff0000, v4
	v_mul_f32_e32 v9, 0xbfb8aa3b, v15
	v_exp_f32_e32 v10, v9
	v_mul_f32_e32 v9, 0xbfb8aa3b, v4
	v_exp_f32_e32 v11, v9
	v_mov_b32_e32 v9, v181
	v_pk_add_f32 v[10:11], v[10:11], 1.0 op_sel_hi:[1,0]
	s_nop 0
	v_div_scale_f32 v18, s[8:9], v11, v11, v4
	v_rcp_f32_e32 v19, v18
	s_nop 0
	v_fma_f32 v0, -v18, v19, 1.0
	v_fmac_f32_e32 v19, v0, v19
	v_div_scale_f32 v0, vcc, v4, v11, v4
	v_mul_f32_e32 v20, v0, v19
	v_fma_f32 v21, -v18, v20, v0
	v_fmac_f32_e32 v20, v21, v19
	v_fma_f32 v0, -v18, v20, v0
	v_div_scale_f32 v18, s[8:9], v10, v10, v15
	v_rcp_f32_e32 v21, v18
	v_div_fmas_f32 v0, v0, v19, v20
	v_div_fixup_f32 v11, v0, v11, v4
	v_and_b32_e32 v20, 0xffff0000, v5
	v_fma_f32 v0, -v18, v21, 1.0
	v_fmac_f32_e32 v21, v0, v21
	v_div_scale_f32 v0, vcc, v15, v10, v15
	v_mul_f32_e32 v19, v0, v21
	v_fma_f32 v4, -v18, v19, v0
	v_fmac_f32_e32 v19, v4, v21
	v_fma_f32 v0, -v18, v19, v0
	v_lshlrev_b32_e32 v18, 16, v5
	v_mul_f32_e32 v4, 0xbfb8aa3b, v18
	v_mul_f32_e32 v5, 0xbfb8aa3b, v20
	v_exp_f32_e32 v4, v4
	v_exp_f32_e32 v5, v5
	v_div_fmas_f32 v0, v0, v21, v19
	v_div_fixup_f32 v10, v0, v10, v15
	v_pk_mul_f32 v[10:11], v[10:11], v[16:17]
	v_pk_add_f32 v[4:5], v[4:5], 1.0 op_sel_hi:[1,0]
	v_cvt_pk_bf16_f32 v0, v10, v11
	v_div_scale_f32 v15, s[8:9], v5, v5, v20
	v_rcp_f32_e32 v16, v15
	v_lshlrev_b32_e32 v10, 16, v1
	v_and_b32_e32 v11, 0xffff0000, v1
	v_fma_f32 v1, -v15, v16, 1.0
	v_fmac_f32_e32 v16, v1, v16
	v_div_scale_f32 v1, vcc, v20, v5, v20
	v_mul_f32_e32 v17, v1, v16
	v_fma_f32 v19, -v15, v17, v1
	v_fmac_f32_e32 v17, v19, v16
	v_fma_f32 v1, -v15, v17, v1
	v_div_scale_f32 v15, s[8:9], v4, v4, v18
	v_rcp_f32_e32 v19, v15
	v_div_fmas_f32 v1, v1, v16, v17
	v_div_fixup_f32 v5, v1, v5, v20
	v_fma_f32 v1, -v15, v19, 1.0
	v_fmac_f32_e32 v19, v1, v19
	v_div_scale_f32 v1, vcc, v18, v4, v18
	v_mul_f32_e32 v20, v1, v19
	v_fma_f32 v16, -v15, v20, v1
	v_fmac_f32_e32 v20, v16, v19
	v_fma_f32 v1, -v15, v20, v1
	v_lshlrev_b32_e32 v15, 16, v6
	v_and_b32_e32 v6, 0xffff0000, v6
	v_mul_f32_e32 v16, 0xbfb8aa3b, v15
	v_mul_f32_e32 v17, 0xbfb8aa3b, v6
	v_exp_f32_e32 v16, v16
	v_exp_f32_e32 v17, v17
	v_div_fmas_f32 v1, v1, v19, v20
	v_div_fixup_f32 v4, v1, v4, v18
	v_pk_mul_f32 v[4:5], v[4:5], v[10:11]
	v_pk_add_f32 v[10:11], v[16:17], 1.0 op_sel_hi:[1,0]
	v_cvt_pk_bf16_f32 v1, v4, v5
	v_div_scale_f32 v16, s[8:9], v11, v11, v6
	v_rcp_f32_e32 v17, v16
	v_lshlrev_b32_e32 v4, 16, v2
	v_and_b32_e32 v5, 0xffff0000, v2
	v_fma_f32 v2, -v16, v17, 1.0
	v_fmac_f32_e32 v17, v2, v17
	v_div_scale_f32 v2, vcc, v6, v11, v6
	v_mul_f32_e32 v18, v2, v17
	v_fma_f32 v19, -v16, v18, v2
	v_fmac_f32_e32 v18, v19, v17
	v_fma_f32 v2, -v16, v18, v2
	v_div_scale_f32 v16, s[8:9], v10, v10, v15
	v_rcp_f32_e32 v19, v16
	v_div_fmas_f32 v2, v2, v17, v18
	v_div_fixup_f32 v11, v2, v11, v6
	v_and_b32_e32 v18, 0xffff0000, v7
	v_fma_f32 v2, -v16, v19, 1.0
	v_fmac_f32_e32 v19, v2, v19
	v_div_scale_f32 v2, vcc, v15, v10, v15
	v_mul_f32_e32 v17, v2, v19
	v_fma_f32 v6, -v16, v17, v2
	v_fmac_f32_e32 v17, v6, v19
	v_fma_f32 v2, -v16, v17, v2
	v_lshlrev_b32_e32 v16, 16, v7
	v_mul_f32_e32 v6, 0xbfb8aa3b, v16
	v_mul_f32_e32 v7, 0xbfb8aa3b, v18
	v_exp_f32_e32 v6, v6
	v_exp_f32_e32 v7, v7
	v_div_fmas_f32 v2, v2, v19, v17
	v_div_fixup_f32 v10, v2, v10, v15
	v_pk_mul_f32 v[4:5], v[10:11], v[4:5]
	v_pk_add_f32 v[6:7], v[6:7], 1.0 op_sel_hi:[1,0]
	v_cvt_pk_bf16_f32 v2, v4, v5
	v_div_scale_f32 v10, s[8:9], v7, v7, v18
	v_rcp_f32_e32 v11, v10
	v_lshlrev_b32_e32 v4, 16, v3
	v_and_b32_e32 v5, 0xffff0000, v3
	v_fma_f32 v3, -v10, v11, 1.0
	v_fmac_f32_e32 v11, v3, v11
	v_div_scale_f32 v3, vcc, v18, v7, v18
	v_mul_f32_e32 v15, v3, v11
	v_fma_f32 v17, -v10, v15, v3
	v_fmac_f32_e32 v15, v17, v11
	v_fma_f32 v3, -v10, v15, v3
	v_div_scale_f32 v10, s[8:9], v6, v6, v16
	v_rcp_f32_e32 v17, v10
	v_div_fmas_f32 v3, v3, v11, v15
	v_div_fixup_f32 v7, v3, v7, v18
	v_fma_f32 v3, -v10, v17, 1.0
	v_fmac_f32_e32 v17, v3, v17
	v_div_scale_f32 v3, vcc, v16, v6, v16
	v_mul_f32_e32 v11, v3, v17
	v_fma_f32 v15, -v10, v11, v3
	v_fmac_f32_e32 v11, v15, v17
	v_fma_f32 v3, -v10, v11, v3
	v_div_fmas_f32 v3, v3, v17, v11
	v_div_fixup_f32 v6, v3, v6, v16
	v_pk_mul_f32 v[4:5], v[6:7], v[4:5]
	v_or_b32_e32 v16, 8, v180
	v_cvt_pk_bf16_f32 v3, v4, v5
	v_lshlrev_b64 v[4:5], 12, v[8:9]
	v_lshl_add_u64 v[4:5], v[12:13], 0, v[4:5]
	global_store_dwordx4 v[4:5], v[0:3], off sc1
	ds_read_b128 v[4:7], v14 offset:2176
	v_mov_b32_e32 v17, v181
	v_mad_u64_u32 v[0:1], s[8:9], v16, s73, v[68:69]
	global_load_dwordx4 v[8:11], v[0:1], off
	s_waitcnt vmcnt(0)
	v_lshlrev_b32_e32 v15, 16, v8
	v_and_b32_e32 v8, 0xffff0000, v8
	v_mul_f32_e32 v0, 0xbfb8aa3b, v15
	v_mul_f32_e32 v1, 0xbfb8aa3b, v8
	v_exp_f32_e32 v0, v0
	v_exp_f32_e32 v1, v1
	s_nop 0
	v_pk_add_f32 v[18:19], v[0:1], 1.0 op_sel_hi:[1,0]
	s_nop 0
	v_div_scale_f32 v22, s[8:9], v19, v19, v8
	v_rcp_f32_e32 v23, v22
	ds_read_b128 v[0:3], v14 offset:3264
	s_waitcnt lgkmcnt(1)
	v_lshlrev_b32_e32 v20, 16, v4
	v_and_b32_e32 v21, 0xffff0000, v4
	v_fma_f32 v4, -v22, v23, 1.0
	v_fmac_f32_e32 v23, v4, v23
	v_div_scale_f32 v4, vcc, v8, v19, v8
	v_mul_f32_e32 v24, v4, v23
	v_fma_f32 v25, -v22, v24, v4
	v_fmac_f32_e32 v24, v25, v23
	v_fma_f32 v4, -v22, v24, v4
	v_div_scale_f32 v22, s[8:9], v18, v18, v15
	v_rcp_f32_e32 v25, v22
	v_div_fmas_f32 v4, v4, v23, v24
	v_div_fixup_f32 v19, v4, v19, v8
	v_and_b32_e32 v24, 0xffff0000, v9
	v_fma_f32 v4, -v22, v25, 1.0
	v_fmac_f32_e32 v25, v4, v25
	v_div_scale_f32 v4, vcc, v15, v18, v15
	v_mul_f32_e32 v23, v4, v25
	v_fma_f32 v8, -v22, v23, v4
	v_fmac_f32_e32 v23, v8, v25
	v_fma_f32 v4, -v22, v23, v4
	v_lshlrev_b32_e32 v22, 16, v9
	v_mul_f32_e32 v8, 0xbfb8aa3b, v22
	v_mul_f32_e32 v9, 0xbfb8aa3b, v24
	v_exp_f32_e32 v8, v8
	v_exp_f32_e32 v9, v9
	v_div_fmas_f32 v4, v4, v25, v23
	v_div_fixup_f32 v18, v4, v18, v15
	v_pk_mul_f32 v[18:19], v[18:19], v[20:21]
	v_pk_add_f32 v[8:9], v[8:9], 1.0 op_sel_hi:[1,0]
	v_cvt_pk_bf16_f32 v4, v18, v19
	v_div_scale_f32 v15, s[8:9], v9, v9, v24
	v_rcp_f32_e32 v20, v15
	v_lshlrev_b32_e32 v18, 16, v5
	v_and_b32_e32 v19, 0xffff0000, v5
	v_fma_f32 v5, -v15, v20, 1.0
	v_fmac_f32_e32 v20, v5, v20
	v_div_scale_f32 v5, vcc, v24, v9, v24
	v_mul_f32_e32 v21, v5, v20
	v_fma_f32 v23, -v15, v21, v5
	v_fmac_f32_e32 v21, v23, v20
	v_fma_f32 v5, -v15, v21, v5
	v_div_scale_f32 v15, s[8:9], v8, v8, v22
	v_rcp_f32_e32 v23, v15
	v_div_fmas_f32 v5, v5, v20, v21
	v_div_fixup_f32 v9, v5, v9, v24
	v_fma_f32 v5, -v15, v23, 1.0
	v_fmac_f32_e32 v23, v5, v23
	v_div_scale_f32 v5, vcc, v22, v8, v22
	v_mul_f32_e32 v24, v5, v23
	v_fma_f32 v20, -v15, v24, v5
	v_fmac_f32_e32 v24, v20, v23
	v_fma_f32 v5, -v15, v24, v5
	v_lshlrev_b32_e32 v15, 16, v10
	v_and_b32_e32 v10, 0xffff0000, v10
	v_mul_f32_e32 v20, 0xbfb8aa3b, v15
	v_mul_f32_e32 v21, 0xbfb8aa3b, v10
	v_exp_f32_e32 v20, v20
	v_exp_f32_e32 v21, v21
	v_div_fmas_f32 v5, v5, v23, v24
	v_div_fixup_f32 v8, v5, v8, v22
	v_pk_mul_f32 v[8:9], v[8:9], v[18:19]
	v_pk_add_f32 v[18:19], v[20:21], 1.0 op_sel_hi:[1,0]
	v_cvt_pk_bf16_f32 v5, v8, v9
	v_div_scale_f32 v20, s[8:9], v19, v19, v10
	v_rcp_f32_e32 v21, v20
	v_lshlrev_b32_e32 v8, 16, v6
	v_and_b32_e32 v9, 0xffff0000, v6
	v_fma_f32 v6, -v20, v21, 1.0
	v_fmac_f32_e32 v21, v6, v21
	v_div_scale_f32 v6, vcc, v10, v19, v10
	v_mul_f32_e32 v22, v6, v21
	v_fma_f32 v23, -v20, v22, v6
	v_fmac_f32_e32 v22, v23, v21
	v_fma_f32 v6, -v20, v22, v6
	v_div_scale_f32 v20, s[8:9], v18, v18, v15
	v_rcp_f32_e32 v23, v20
	v_div_fmas_f32 v6, v6, v21, v22
	v_div_fixup_f32 v19, v6, v19, v10
	v_and_b32_e32 v22, 0xffff0000, v11
	v_fma_f32 v6, -v20, v23, 1.0
	v_fmac_f32_e32 v23, v6, v23
	v_div_scale_f32 v6, vcc, v15, v18, v15
	v_mul_f32_e32 v21, v6, v23
	v_fma_f32 v10, -v20, v21, v6
	v_fmac_f32_e32 v21, v10, v23
	v_fma_f32 v6, -v20, v21, v6
	v_lshlrev_b32_e32 v20, 16, v11
	v_mul_f32_e32 v10, 0xbfb8aa3b, v20
	v_mul_f32_e32 v11, 0xbfb8aa3b, v22
	v_exp_f32_e32 v10, v10
	v_exp_f32_e32 v11, v11
	v_div_fmas_f32 v6, v6, v23, v21
	v_div_fixup_f32 v18, v6, v18, v15
	v_pk_mul_f32 v[8:9], v[18:19], v[8:9]
	v_pk_add_f32 v[10:11], v[10:11], 1.0 op_sel_hi:[1,0]
	v_cvt_pk_bf16_f32 v6, v8, v9
	v_div_scale_f32 v15, s[8:9], v11, v11, v22
	v_rcp_f32_e32 v18, v15
	v_lshlrev_b32_e32 v8, 16, v7
	v_and_b32_e32 v9, 0xffff0000, v7
	v_fma_f32 v7, -v15, v18, 1.0
	v_fmac_f32_e32 v18, v7, v18
	v_div_scale_f32 v7, vcc, v22, v11, v22
	v_mul_f32_e32 v19, v7, v18
	v_fma_f32 v21, -v15, v19, v7
	v_fmac_f32_e32 v19, v21, v18
	v_fma_f32 v7, -v15, v19, v7
	v_div_scale_f32 v15, s[8:9], v10, v10, v20
	v_rcp_f32_e32 v21, v15
	v_div_fmas_f32 v7, v7, v18, v19
	v_div_fixup_f32 v11, v7, v11, v22
	v_fma_f32 v7, -v15, v21, 1.0
	v_fmac_f32_e32 v21, v7, v21
	v_div_scale_f32 v7, vcc, v20, v10, v20
	v_mul_f32_e32 v18, v7, v21
	v_fma_f32 v19, -v15, v18, v7
	v_fmac_f32_e32 v18, v19, v21
	v_fma_f32 v7, -v15, v18, v7
	v_div_fmas_f32 v7, v7, v21, v18
	v_div_fixup_f32 v10, v7, v10, v20
	v_pk_mul_f32 v[8:9], v[10:11], v[8:9]
	s_nop 0
	v_cvt_pk_bf16_f32 v7, v8, v9
	v_lshlrev_b64 v[8:9], 12, v[16:17]
	v_lshl_add_u64 v[8:9], v[12:13], 0, v[8:9]
	global_store_dwordx4 v[8:9], v[4:7], off sc1
	v_or_b32_e32 v8, 12, v180
	s_waitcnt lgkmcnt(0)
	v_lshlrev_b32_e32 v16, 16, v0
	v_mad_u64_u32 v[4:5], s[8:9], v8, s73, v[68:69]
	global_load_dwordx4 v[4:7], v[4:5], off
	v_and_b32_e32 v17, 0xffff0000, v0
	s_waitcnt vmcnt(0)
	v_lshlrev_b32_e32 v15, 16, v4
	v_and_b32_e32 v4, 0xffff0000, v4
	v_mul_f32_e32 v9, 0xbfb8aa3b, v15
	v_exp_f32_e32 v10, v9
	v_mul_f32_e32 v9, 0xbfb8aa3b, v4
	v_exp_f32_e32 v11, v9
	v_mov_b32_e32 v9, v181
	v_pk_add_f32 v[10:11], v[10:11], 1.0 op_sel_hi:[1,0]
	s_nop 0
	v_div_scale_f32 v18, s[8:9], v11, v11, v4
	v_rcp_f32_e32 v19, v18
	s_nop 0
	v_fma_f32 v0, -v18, v19, 1.0
	v_fmac_f32_e32 v19, v0, v19
	v_div_scale_f32 v0, vcc, v4, v11, v4
	v_mul_f32_e32 v20, v0, v19
	v_fma_f32 v21, -v18, v20, v0
	v_fmac_f32_e32 v20, v21, v19
	v_fma_f32 v0, -v18, v20, v0
	v_div_scale_f32 v18, s[8:9], v10, v10, v15
	v_rcp_f32_e32 v21, v18
	v_div_fmas_f32 v0, v0, v19, v20
	v_div_fixup_f32 v11, v0, v11, v4
	v_and_b32_e32 v20, 0xffff0000, v5
	v_fma_f32 v0, -v18, v21, 1.0
	v_fmac_f32_e32 v21, v0, v21
	v_div_scale_f32 v0, vcc, v15, v10, v15
	v_mul_f32_e32 v19, v0, v21
	v_fma_f32 v4, -v18, v19, v0
	v_fmac_f32_e32 v19, v4, v21
	v_fma_f32 v0, -v18, v19, v0
	v_lshlrev_b32_e32 v18, 16, v5
	v_mul_f32_e32 v4, 0xbfb8aa3b, v18
	v_mul_f32_e32 v5, 0xbfb8aa3b, v20
	v_exp_f32_e32 v4, v4
	v_exp_f32_e32 v5, v5
	v_div_fmas_f32 v0, v0, v21, v19
	v_div_fixup_f32 v10, v0, v10, v15
	v_pk_mul_f32 v[10:11], v[10:11], v[16:17]
	v_pk_add_f32 v[4:5], v[4:5], 1.0 op_sel_hi:[1,0]
	v_cvt_pk_bf16_f32 v0, v10, v11
	v_div_scale_f32 v15, s[8:9], v5, v5, v20
	v_rcp_f32_e32 v16, v15
	v_lshlrev_b32_e32 v10, 16, v1
	v_and_b32_e32 v11, 0xffff0000, v1
	v_fma_f32 v1, -v15, v16, 1.0
	v_fmac_f32_e32 v16, v1, v16
	v_div_scale_f32 v1, vcc, v20, v5, v20
	v_mul_f32_e32 v17, v1, v16
	v_fma_f32 v19, -v15, v17, v1
	v_fmac_f32_e32 v17, v19, v16
	v_fma_f32 v1, -v15, v17, v1
	v_div_scale_f32 v15, s[8:9], v4, v4, v18
	v_rcp_f32_e32 v19, v15
	v_div_fmas_f32 v1, v1, v16, v17
	v_div_fixup_f32 v5, v1, v5, v20
	v_fma_f32 v1, -v15, v19, 1.0
	v_fmac_f32_e32 v19, v1, v19
	v_div_scale_f32 v1, vcc, v18, v4, v18
	v_mul_f32_e32 v20, v1, v19
	v_fma_f32 v16, -v15, v20, v1
	v_fmac_f32_e32 v20, v16, v19
	v_fma_f32 v1, -v15, v20, v1
	v_lshlrev_b32_e32 v15, 16, v6
	v_and_b32_e32 v6, 0xffff0000, v6
	v_mul_f32_e32 v16, 0xbfb8aa3b, v15
	v_mul_f32_e32 v17, 0xbfb8aa3b, v6
	v_exp_f32_e32 v16, v16
	v_exp_f32_e32 v17, v17
	v_div_fmas_f32 v1, v1, v19, v20
	v_div_fixup_f32 v4, v1, v4, v18
	v_pk_mul_f32 v[4:5], v[4:5], v[10:11]
	v_pk_add_f32 v[10:11], v[16:17], 1.0 op_sel_hi:[1,0]
	v_cvt_pk_bf16_f32 v1, v4, v5
	v_div_scale_f32 v16, s[8:9], v11, v11, v6
	v_rcp_f32_e32 v17, v16
	v_lshlrev_b32_e32 v4, 16, v2
	v_and_b32_e32 v5, 0xffff0000, v2
	v_fma_f32 v2, -v16, v17, 1.0
	v_fmac_f32_e32 v17, v2, v17
	v_div_scale_f32 v2, vcc, v6, v11, v6
	v_mul_f32_e32 v18, v2, v17
	v_fma_f32 v19, -v16, v18, v2
	v_fmac_f32_e32 v18, v19, v17
	v_fma_f32 v2, -v16, v18, v2
	v_div_scale_f32 v16, s[8:9], v10, v10, v15
	v_rcp_f32_e32 v19, v16
	v_div_fmas_f32 v2, v2, v17, v18
	v_div_fixup_f32 v11, v2, v11, v6
	v_and_b32_e32 v18, 0xffff0000, v7
	v_fma_f32 v2, -v16, v19, 1.0
	v_fmac_f32_e32 v19, v2, v19
	v_div_scale_f32 v2, vcc, v15, v10, v15
	v_mul_f32_e32 v17, v2, v19
	v_fma_f32 v6, -v16, v17, v2
	v_fmac_f32_e32 v17, v6, v19
	v_fma_f32 v2, -v16, v17, v2
	v_lshlrev_b32_e32 v16, 16, v7
	v_mul_f32_e32 v6, 0xbfb8aa3b, v16
	v_mul_f32_e32 v7, 0xbfb8aa3b, v18
	v_exp_f32_e32 v6, v6
	v_exp_f32_e32 v7, v7
	v_div_fmas_f32 v2, v2, v19, v17
	v_div_fixup_f32 v10, v2, v10, v15
	v_pk_mul_f32 v[4:5], v[10:11], v[4:5]
	v_pk_add_f32 v[6:7], v[6:7], 1.0 op_sel_hi:[1,0]
	v_cvt_pk_bf16_f32 v2, v4, v5
	v_div_scale_f32 v10, s[8:9], v7, v7, v18
	v_rcp_f32_e32 v11, v10
	v_lshlrev_b32_e32 v4, 16, v3
	v_and_b32_e32 v5, 0xffff0000, v3
	v_fma_f32 v3, -v10, v11, 1.0
	v_fmac_f32_e32 v11, v3, v11
	v_div_scale_f32 v3, vcc, v18, v7, v18
	v_mul_f32_e32 v15, v3, v11
	v_fma_f32 v17, -v10, v15, v3
	v_fmac_f32_e32 v15, v17, v11
	v_fma_f32 v3, -v10, v15, v3
	v_div_scale_f32 v10, s[8:9], v6, v6, v16
	v_rcp_f32_e32 v17, v10
	v_div_fmas_f32 v3, v3, v11, v15
	v_div_fixup_f32 v7, v3, v7, v18
	v_fma_f32 v3, -v10, v17, 1.0
	v_fmac_f32_e32 v17, v3, v17
	v_div_scale_f32 v3, vcc, v16, v6, v16
	v_mul_f32_e32 v11, v3, v17
	v_fma_f32 v15, -v10, v11, v3
	v_fmac_f32_e32 v11, v15, v17
	v_fma_f32 v3, -v10, v11, v3
	v_div_fmas_f32 v3, v3, v17, v11
	v_div_fixup_f32 v6, v3, v6, v16
	v_pk_mul_f32 v[4:5], v[6:7], v[4:5]
	v_or_b32_e32 v16, 16, v180
	v_cvt_pk_bf16_f32 v3, v4, v5
	v_lshlrev_b64 v[4:5], 12, v[8:9]
	v_lshl_add_u64 v[4:5], v[12:13], 0, v[4:5]
	global_store_dwordx4 v[4:5], v[0:3], off sc1
	ds_read_b128 v[4:7], v14 offset:4352
	v_mov_b32_e32 v17, v181
	v_mad_u64_u32 v[0:1], s[8:9], v16, s73, v[68:69]
	global_load_dwordx4 v[8:11], v[0:1], off
	s_waitcnt vmcnt(0)
	v_lshlrev_b32_e32 v15, 16, v8
	v_and_b32_e32 v8, 0xffff0000, v8
	v_mul_f32_e32 v0, 0xbfb8aa3b, v15
	v_mul_f32_e32 v1, 0xbfb8aa3b, v8
	v_exp_f32_e32 v0, v0
	v_exp_f32_e32 v1, v1
	s_nop 0
	v_pk_add_f32 v[18:19], v[0:1], 1.0 op_sel_hi:[1,0]
	s_nop 0
	v_div_scale_f32 v22, s[8:9], v19, v19, v8
	v_rcp_f32_e32 v23, v22
	ds_read_b128 v[0:3], v14 offset:5440
	s_waitcnt lgkmcnt(1)
	v_lshlrev_b32_e32 v20, 16, v4
	v_and_b32_e32 v21, 0xffff0000, v4
	v_fma_f32 v4, -v22, v23, 1.0
	v_fmac_f32_e32 v23, v4, v23
	v_div_scale_f32 v4, vcc, v8, v19, v8
	v_mul_f32_e32 v24, v4, v23
	v_fma_f32 v25, -v22, v24, v4
	v_fmac_f32_e32 v24, v25, v23
	v_fma_f32 v4, -v22, v24, v4
	v_div_scale_f32 v22, s[8:9], v18, v18, v15
	v_rcp_f32_e32 v25, v22
	v_div_fmas_f32 v4, v4, v23, v24
	v_div_fixup_f32 v19, v4, v19, v8
	v_and_b32_e32 v24, 0xffff0000, v9
	v_fma_f32 v4, -v22, v25, 1.0
	v_fmac_f32_e32 v25, v4, v25
	v_div_scale_f32 v4, vcc, v15, v18, v15
	v_mul_f32_e32 v23, v4, v25
	v_fma_f32 v8, -v22, v23, v4
	v_fmac_f32_e32 v23, v8, v25
	v_fma_f32 v4, -v22, v23, v4
	v_lshlrev_b32_e32 v22, 16, v9
	v_mul_f32_e32 v8, 0xbfb8aa3b, v22
	v_mul_f32_e32 v9, 0xbfb8aa3b, v24
	v_exp_f32_e32 v8, v8
	v_exp_f32_e32 v9, v9
	v_div_fmas_f32 v4, v4, v25, v23
	v_div_fixup_f32 v18, v4, v18, v15
	v_pk_mul_f32 v[18:19], v[18:19], v[20:21]
	v_pk_add_f32 v[8:9], v[8:9], 1.0 op_sel_hi:[1,0]
	v_cvt_pk_bf16_f32 v4, v18, v19
	v_div_scale_f32 v15, s[8:9], v9, v9, v24
	v_rcp_f32_e32 v20, v15
	v_lshlrev_b32_e32 v18, 16, v5
	v_and_b32_e32 v19, 0xffff0000, v5
	v_fma_f32 v5, -v15, v20, 1.0
	v_fmac_f32_e32 v20, v5, v20
	v_div_scale_f32 v5, vcc, v24, v9, v24
	v_mul_f32_e32 v21, v5, v20
	v_fma_f32 v23, -v15, v21, v5
	v_fmac_f32_e32 v21, v23, v20
	v_fma_f32 v5, -v15, v21, v5
	v_div_scale_f32 v15, s[8:9], v8, v8, v22
	v_rcp_f32_e32 v23, v15
	v_div_fmas_f32 v5, v5, v20, v21
	v_div_fixup_f32 v9, v5, v9, v24
	v_fma_f32 v5, -v15, v23, 1.0
	v_fmac_f32_e32 v23, v5, v23
	v_div_scale_f32 v5, vcc, v22, v8, v22
	v_mul_f32_e32 v24, v5, v23
	v_fma_f32 v20, -v15, v24, v5
	v_fmac_f32_e32 v24, v20, v23
	v_fma_f32 v5, -v15, v24, v5
	v_lshlrev_b32_e32 v15, 16, v10
	v_and_b32_e32 v10, 0xffff0000, v10
	v_mul_f32_e32 v20, 0xbfb8aa3b, v15
	v_mul_f32_e32 v21, 0xbfb8aa3b, v10
	v_exp_f32_e32 v20, v20
	v_exp_f32_e32 v21, v21
	v_div_fmas_f32 v5, v5, v23, v24
	v_div_fixup_f32 v8, v5, v8, v22
	v_pk_mul_f32 v[8:9], v[8:9], v[18:19]
	v_pk_add_f32 v[18:19], v[20:21], 1.0 op_sel_hi:[1,0]
	v_cvt_pk_bf16_f32 v5, v8, v9
	v_div_scale_f32 v20, s[8:9], v19, v19, v10
	v_rcp_f32_e32 v21, v20
	v_lshlrev_b32_e32 v8, 16, v6
	v_and_b32_e32 v9, 0xffff0000, v6
	v_fma_f32 v6, -v20, v21, 1.0
	v_fmac_f32_e32 v21, v6, v21
	v_div_scale_f32 v6, vcc, v10, v19, v10
	v_mul_f32_e32 v22, v6, v21
	v_fma_f32 v23, -v20, v22, v6
	v_fmac_f32_e32 v22, v23, v21
	v_fma_f32 v6, -v20, v22, v6
	v_div_scale_f32 v20, s[8:9], v18, v18, v15
	v_rcp_f32_e32 v23, v20
	v_div_fmas_f32 v6, v6, v21, v22
	v_div_fixup_f32 v19, v6, v19, v10
	v_and_b32_e32 v22, 0xffff0000, v11
	v_fma_f32 v6, -v20, v23, 1.0
	v_fmac_f32_e32 v23, v6, v23
	v_div_scale_f32 v6, vcc, v15, v18, v15
	v_mul_f32_e32 v21, v6, v23
	v_fma_f32 v10, -v20, v21, v6
	v_fmac_f32_e32 v21, v10, v23
	v_fma_f32 v6, -v20, v21, v6
	v_lshlrev_b32_e32 v20, 16, v11
	v_mul_f32_e32 v10, 0xbfb8aa3b, v20
	v_mul_f32_e32 v11, 0xbfb8aa3b, v22
	v_exp_f32_e32 v10, v10
	v_exp_f32_e32 v11, v11
	v_div_fmas_f32 v6, v6, v23, v21
	v_div_fixup_f32 v18, v6, v18, v15
	v_pk_mul_f32 v[8:9], v[18:19], v[8:9]
	v_pk_add_f32 v[10:11], v[10:11], 1.0 op_sel_hi:[1,0]
	v_cvt_pk_bf16_f32 v6, v8, v9
	v_div_scale_f32 v15, s[8:9], v11, v11, v22
	v_rcp_f32_e32 v18, v15
	v_lshlrev_b32_e32 v8, 16, v7
	v_and_b32_e32 v9, 0xffff0000, v7
	v_fma_f32 v7, -v15, v18, 1.0
	v_fmac_f32_e32 v18, v7, v18
	v_div_scale_f32 v7, vcc, v22, v11, v22
	v_mul_f32_e32 v19, v7, v18
	v_fma_f32 v21, -v15, v19, v7
	v_fmac_f32_e32 v19, v21, v18
	v_fma_f32 v7, -v15, v19, v7
	v_div_scale_f32 v15, s[8:9], v10, v10, v20
	v_rcp_f32_e32 v21, v15
	v_div_fmas_f32 v7, v7, v18, v19
	v_div_fixup_f32 v11, v7, v11, v22
	v_fma_f32 v7, -v15, v21, 1.0
	v_fmac_f32_e32 v21, v7, v21
	v_div_scale_f32 v7, vcc, v20, v10, v20
	v_mul_f32_e32 v18, v7, v21
	v_fma_f32 v19, -v15, v18, v7
	v_fmac_f32_e32 v18, v19, v21
	v_fma_f32 v7, -v15, v18, v7
	v_div_fmas_f32 v7, v7, v21, v18
	v_div_fixup_f32 v10, v7, v10, v20
	v_pk_mul_f32 v[8:9], v[10:11], v[8:9]
	s_nop 0
	v_cvt_pk_bf16_f32 v7, v8, v9
	v_lshlrev_b64 v[8:9], 12, v[16:17]
	v_lshl_add_u64 v[8:9], v[12:13], 0, v[8:9]
	global_store_dwordx4 v[8:9], v[4:7], off sc1
	v_or_b32_e32 v8, 20, v180
	s_waitcnt lgkmcnt(0)
	v_lshlrev_b32_e32 v16, 16, v0
	v_mad_u64_u32 v[4:5], s[8:9], v8, s73, v[68:69]
	global_load_dwordx4 v[4:7], v[4:5], off
	v_and_b32_e32 v17, 0xffff0000, v0
	s_waitcnt vmcnt(0)
	v_lshlrev_b32_e32 v15, 16, v4
	v_and_b32_e32 v4, 0xffff0000, v4
	v_mul_f32_e32 v9, 0xbfb8aa3b, v15
	v_exp_f32_e32 v10, v9
	v_mul_f32_e32 v9, 0xbfb8aa3b, v4
	v_exp_f32_e32 v11, v9
	v_mov_b32_e32 v9, v181
	v_pk_add_f32 v[10:11], v[10:11], 1.0 op_sel_hi:[1,0]
	s_nop 0
	v_div_scale_f32 v18, s[8:9], v11, v11, v4
	v_rcp_f32_e32 v19, v18
	s_nop 0
	v_fma_f32 v0, -v18, v19, 1.0
	v_fmac_f32_e32 v19, v0, v19
	v_div_scale_f32 v0, vcc, v4, v11, v4
	v_mul_f32_e32 v20, v0, v19
	v_fma_f32 v21, -v18, v20, v0
	v_fmac_f32_e32 v20, v21, v19
	v_fma_f32 v0, -v18, v20, v0
	v_div_scale_f32 v18, s[8:9], v10, v10, v15
	v_rcp_f32_e32 v21, v18
	v_div_fmas_f32 v0, v0, v19, v20
	v_div_fixup_f32 v11, v0, v11, v4
	v_and_b32_e32 v20, 0xffff0000, v5
	v_fma_f32 v0, -v18, v21, 1.0
	v_fmac_f32_e32 v21, v0, v21
	v_div_scale_f32 v0, vcc, v15, v10, v15
	v_mul_f32_e32 v19, v0, v21
	v_fma_f32 v4, -v18, v19, v0
	v_fmac_f32_e32 v19, v4, v21
	v_fma_f32 v0, -v18, v19, v0
	v_lshlrev_b32_e32 v18, 16, v5
	v_mul_f32_e32 v4, 0xbfb8aa3b, v18
	v_mul_f32_e32 v5, 0xbfb8aa3b, v20
	v_exp_f32_e32 v4, v4
	v_exp_f32_e32 v5, v5
	v_div_fmas_f32 v0, v0, v21, v19
	v_div_fixup_f32 v10, v0, v10, v15
	v_pk_mul_f32 v[10:11], v[10:11], v[16:17]
	v_pk_add_f32 v[4:5], v[4:5], 1.0 op_sel_hi:[1,0]
	v_cvt_pk_bf16_f32 v0, v10, v11
	v_div_scale_f32 v15, s[8:9], v5, v5, v20
	v_rcp_f32_e32 v16, v15
	v_lshlrev_b32_e32 v10, 16, v1
	v_and_b32_e32 v11, 0xffff0000, v1
	v_fma_f32 v1, -v15, v16, 1.0
	v_fmac_f32_e32 v16, v1, v16
	v_div_scale_f32 v1, vcc, v20, v5, v20
	v_mul_f32_e32 v17, v1, v16
	v_fma_f32 v19, -v15, v17, v1
	v_fmac_f32_e32 v17, v19, v16
	v_fma_f32 v1, -v15, v17, v1
	v_div_scale_f32 v15, s[8:9], v4, v4, v18
	v_rcp_f32_e32 v19, v15
	v_div_fmas_f32 v1, v1, v16, v17
	v_div_fixup_f32 v5, v1, v5, v20
	v_fma_f32 v1, -v15, v19, 1.0
	v_fmac_f32_e32 v19, v1, v19
	v_div_scale_f32 v1, vcc, v18, v4, v18
	v_mul_f32_e32 v20, v1, v19
	v_fma_f32 v16, -v15, v20, v1
	v_fmac_f32_e32 v20, v16, v19
	v_fma_f32 v1, -v15, v20, v1
	v_lshlrev_b32_e32 v15, 16, v6
	v_and_b32_e32 v6, 0xffff0000, v6
	v_mul_f32_e32 v16, 0xbfb8aa3b, v15
	v_mul_f32_e32 v17, 0xbfb8aa3b, v6
	v_exp_f32_e32 v16, v16
	v_exp_f32_e32 v17, v17
	v_div_fmas_f32 v1, v1, v19, v20
	v_div_fixup_f32 v4, v1, v4, v18
	v_pk_mul_f32 v[4:5], v[4:5], v[10:11]
	v_pk_add_f32 v[10:11], v[16:17], 1.0 op_sel_hi:[1,0]
	v_cvt_pk_bf16_f32 v1, v4, v5
	v_div_scale_f32 v16, s[8:9], v11, v11, v6
	v_rcp_f32_e32 v17, v16
	v_lshlrev_b32_e32 v4, 16, v2
	v_and_b32_e32 v5, 0xffff0000, v2
	v_fma_f32 v2, -v16, v17, 1.0
	v_fmac_f32_e32 v17, v2, v17
	v_div_scale_f32 v2, vcc, v6, v11, v6
	v_mul_f32_e32 v18, v2, v17
	v_fma_f32 v19, -v16, v18, v2
	v_fmac_f32_e32 v18, v19, v17
	v_fma_f32 v2, -v16, v18, v2
	v_div_scale_f32 v16, s[8:9], v10, v10, v15
	v_rcp_f32_e32 v19, v16
	v_div_fmas_f32 v2, v2, v17, v18
	v_div_fixup_f32 v11, v2, v11, v6
	v_and_b32_e32 v18, 0xffff0000, v7
	v_fma_f32 v2, -v16, v19, 1.0
	v_fmac_f32_e32 v19, v2, v19
	v_div_scale_f32 v2, vcc, v15, v10, v15
	v_mul_f32_e32 v17, v2, v19
	v_fma_f32 v6, -v16, v17, v2
	v_fmac_f32_e32 v17, v6, v19
	v_fma_f32 v2, -v16, v17, v2
	v_lshlrev_b32_e32 v16, 16, v7
	v_mul_f32_e32 v6, 0xbfb8aa3b, v16
	v_mul_f32_e32 v7, 0xbfb8aa3b, v18
	v_exp_f32_e32 v6, v6
	v_exp_f32_e32 v7, v7
	v_div_fmas_f32 v2, v2, v19, v17
	v_div_fixup_f32 v10, v2, v10, v15
	v_pk_mul_f32 v[4:5], v[10:11], v[4:5]
	v_pk_add_f32 v[6:7], v[6:7], 1.0 op_sel_hi:[1,0]
	v_cvt_pk_bf16_f32 v2, v4, v5
	v_div_scale_f32 v10, s[8:9], v7, v7, v18
	v_rcp_f32_e32 v11, v10
	v_lshlrev_b32_e32 v4, 16, v3
	v_and_b32_e32 v5, 0xffff0000, v3
	v_fma_f32 v3, -v10, v11, 1.0
	v_fmac_f32_e32 v11, v3, v11
	v_div_scale_f32 v3, vcc, v18, v7, v18
	v_mul_f32_e32 v15, v3, v11
	v_fma_f32 v17, -v10, v15, v3
	v_fmac_f32_e32 v15, v17, v11
	v_fma_f32 v3, -v10, v15, v3
	v_div_scale_f32 v10, s[8:9], v6, v6, v16
	v_rcp_f32_e32 v17, v10
	v_div_fmas_f32 v3, v3, v11, v15
	v_div_fixup_f32 v7, v3, v7, v18
	v_fma_f32 v3, -v10, v17, 1.0
	v_fmac_f32_e32 v17, v3, v17
	v_div_scale_f32 v3, vcc, v16, v6, v16
	v_mul_f32_e32 v11, v3, v17
	v_fma_f32 v15, -v10, v11, v3
	v_fmac_f32_e32 v11, v15, v17
	v_fma_f32 v3, -v10, v11, v3
	v_div_fmas_f32 v3, v3, v17, v11
	v_div_fixup_f32 v6, v3, v6, v16
	v_pk_mul_f32 v[4:5], v[6:7], v[4:5]
	v_or_b32_e32 v16, 24, v180
	v_cvt_pk_bf16_f32 v3, v4, v5
	v_lshlrev_b64 v[4:5], 12, v[8:9]
	v_lshl_add_u64 v[4:5], v[12:13], 0, v[4:5]
	global_store_dwordx4 v[4:5], v[0:3], off sc1
	ds_read_b128 v[4:7], v14 offset:6528
	v_mov_b32_e32 v17, v181
	v_mad_u64_u32 v[0:1], s[8:9], v16, s73, v[68:69]
	global_load_dwordx4 v[8:11], v[0:1], off
	v_or_b32_e32 v180, 28, v180
	s_waitcnt vmcnt(0)
	v_lshlrev_b32_e32 v20, 16, v8
	v_and_b32_e32 v8, 0xffff0000, v8
	v_mul_f32_e32 v0, 0xbfb8aa3b, v20
	v_mul_f32_e32 v1, 0xbfb8aa3b, v8
	v_exp_f32_e32 v0, v0
	v_exp_f32_e32 v1, v1
	s_nop 0
	v_pk_add_f32 v[18:19], v[0:1], 1.0 op_sel_hi:[1,0]
	s_nop 0
	v_div_scale_f32 v21, s[8:9], v19, v19, v8
	v_rcp_f32_e32 v22, v21
	ds_read_b128 v[0:3], v14 offset:7616
	s_waitcnt lgkmcnt(1)
	v_lshlrev_b32_e32 v14, 16, v4
	v_and_b32_e32 v15, 0xffff0000, v4
	v_fma_f32 v4, -v21, v22, 1.0
	v_fmac_f32_e32 v22, v4, v22
	v_div_scale_f32 v4, vcc, v8, v19, v8
	v_mul_f32_e32 v23, v4, v22
	v_fma_f32 v24, -v21, v23, v4
	v_fmac_f32_e32 v23, v24, v22
	v_fma_f32 v4, -v21, v23, v4
	v_div_scale_f32 v21, s[8:9], v18, v18, v20
	v_rcp_f32_e32 v24, v21
	v_div_fmas_f32 v4, v4, v22, v23
	v_div_fixup_f32 v19, v4, v19, v8
	v_and_b32_e32 v23, 0xffff0000, v9
	v_fma_f32 v4, -v21, v24, 1.0
	v_fmac_f32_e32 v24, v4, v24
	v_div_scale_f32 v4, vcc, v20, v18, v20
	v_mul_f32_e32 v22, v4, v24
	v_fma_f32 v8, -v21, v22, v4
	v_fmac_f32_e32 v22, v8, v24
	v_fma_f32 v4, -v21, v22, v4
	v_lshlrev_b32_e32 v21, 16, v9
	v_mul_f32_e32 v8, 0xbfb8aa3b, v21
	v_mul_f32_e32 v9, 0xbfb8aa3b, v23
	v_exp_f32_e32 v8, v8
	v_exp_f32_e32 v9, v9
	v_div_fmas_f32 v4, v4, v24, v22
	v_div_fixup_f32 v18, v4, v18, v20
	v_pk_mul_f32 v[14:15], v[18:19], v[14:15]
	v_pk_add_f32 v[8:9], v[8:9], 1.0 op_sel_hi:[1,0]
	v_cvt_pk_bf16_f32 v4, v14, v15
	v_div_scale_f32 v18, s[8:9], v9, v9, v23
	v_rcp_f32_e32 v19, v18
	v_lshlrev_b32_e32 v14, 16, v5
	v_and_b32_e32 v15, 0xffff0000, v5
	v_fma_f32 v5, -v18, v19, 1.0
	v_fmac_f32_e32 v19, v5, v19
	v_div_scale_f32 v5, vcc, v23, v9, v23
	v_mul_f32_e32 v20, v5, v19
	v_fma_f32 v22, -v18, v20, v5
	v_fmac_f32_e32 v20, v22, v19
	v_fma_f32 v5, -v18, v20, v5
	v_div_scale_f32 v18, s[8:9], v8, v8, v21
	v_rcp_f32_e32 v22, v18
	v_div_fmas_f32 v5, v5, v19, v20
	v_div_fixup_f32 v9, v5, v9, v23
	v_lshlrev_b32_e32 v23, 16, v10
	v_fma_f32 v5, -v18, v22, 1.0
	v_fmac_f32_e32 v22, v5, v22
	v_div_scale_f32 v5, vcc, v21, v8, v21
	v_mul_f32_e32 v20, v5, v22
	v_fma_f32 v19, -v18, v20, v5
	v_fmac_f32_e32 v20, v19, v22
	v_and_b32_e32 v10, 0xffff0000, v10
	v_fma_f32 v5, -v18, v20, v5
	v_mul_f32_e32 v18, 0xbfb8aa3b, v23
	v_mul_f32_e32 v19, 0xbfb8aa3b, v10
	v_exp_f32_e32 v18, v18
	v_exp_f32_e32 v19, v19
	v_div_fmas_f32 v5, v5, v22, v20
	v_div_fixup_f32 v8, v5, v8, v21
	v_pk_mul_f32 v[8:9], v[8:9], v[14:15]
	v_pk_add_f32 v[14:15], v[18:19], 1.0 op_sel_hi:[1,0]
	v_cvt_pk_bf16_f32 v5, v8, v9
	v_div_scale_f32 v18, s[8:9], v15, v15, v10
	v_rcp_f32_e32 v19, v18
	v_lshlrev_b32_e32 v8, 16, v6
	v_and_b32_e32 v9, 0xffff0000, v6
	v_fma_f32 v6, -v18, v19, 1.0
	v_fmac_f32_e32 v19, v6, v19
	v_div_scale_f32 v6, vcc, v10, v15, v10
	v_mul_f32_e32 v20, v6, v19
	v_fma_f32 v21, -v18, v20, v6
	v_fmac_f32_e32 v20, v21, v19
	v_fma_f32 v6, -v18, v20, v6
	v_div_scale_f32 v18, s[8:9], v14, v14, v23
	v_rcp_f32_e32 v21, v18
	v_div_fmas_f32 v6, v6, v19, v20
	v_div_fixup_f32 v15, v6, v15, v10
	v_and_b32_e32 v20, 0xffff0000, v11
	v_fma_f32 v6, -v18, v21, 1.0
	v_fmac_f32_e32 v21, v6, v21
	v_div_scale_f32 v6, vcc, v23, v14, v23
	v_mul_f32_e32 v19, v6, v21
	v_fma_f32 v10, -v18, v19, v6
	v_fmac_f32_e32 v19, v10, v21
	v_fma_f32 v6, -v18, v19, v6
	v_lshlrev_b32_e32 v18, 16, v11
	v_mul_f32_e32 v10, 0xbfb8aa3b, v18
	v_mul_f32_e32 v11, 0xbfb8aa3b, v20
	v_exp_f32_e32 v10, v10
	v_exp_f32_e32 v11, v11
	v_div_fmas_f32 v6, v6, v21, v19
	v_div_fixup_f32 v14, v6, v14, v23
	v_pk_mul_f32 v[8:9], v[14:15], v[8:9]
	v_pk_add_f32 v[10:11], v[10:11], 1.0 op_sel_hi:[1,0]
	v_cvt_pk_bf16_f32 v6, v8, v9
	v_div_scale_f32 v14, s[8:9], v11, v11, v20
	v_rcp_f32_e32 v15, v14
	v_lshlrev_b32_e32 v8, 16, v7
	v_and_b32_e32 v9, 0xffff0000, v7
	v_fma_f32 v7, -v14, v15, 1.0
	v_fmac_f32_e32 v15, v7, v15
	v_div_scale_f32 v7, vcc, v20, v11, v20
	v_mul_f32_e32 v19, v7, v15
	v_fma_f32 v21, -v14, v19, v7
	v_fmac_f32_e32 v19, v21, v15
	v_fma_f32 v7, -v14, v19, v7
	v_div_scale_f32 v14, s[8:9], v10, v10, v18
	v_rcp_f32_e32 v21, v14
	v_div_fmas_f32 v7, v7, v15, v19
	v_div_fixup_f32 v11, v7, v11, v20
	v_fma_f32 v7, -v14, v21, 1.0
	v_fmac_f32_e32 v21, v7, v21
	v_div_scale_f32 v7, vcc, v18, v10, v18
	v_mul_f32_e32 v15, v7, v21
	v_fma_f32 v19, -v14, v15, v7
	v_fmac_f32_e32 v15, v19, v21
	v_fma_f32 v7, -v14, v15, v7
	v_div_fmas_f32 v7, v7, v21, v15
	v_div_fixup_f32 v10, v7, v10, v18
	v_pk_mul_f32 v[8:9], v[10:11], v[8:9]
	s_waitcnt lgkmcnt(0)
	v_lshlrev_b32_e32 v10, 16, v0
	v_cvt_pk_bf16_f32 v7, v8, v9
	v_lshlrev_b64 v[8:9], 12, v[16:17]
	v_lshl_add_u64 v[8:9], v[12:13], 0, v[8:9]
	global_store_dwordx4 v[8:9], v[4:7], off sc1
	v_and_b32_e32 v11, 0xffff0000, v0
	s_nop 0
	v_mad_u64_u32 v[4:5], s[8:9], v180, s73, v[68:69]
	global_load_dwordx4 v[4:7], v[4:5], off
	s_waitcnt vmcnt(0)
	v_lshlrev_b32_e32 v14, 16, v4
	v_and_b32_e32 v4, 0xffff0000, v4
	v_mul_f32_e32 v8, 0xbfb8aa3b, v14
	v_mul_f32_e32 v9, 0xbfb8aa3b, v4
	v_exp_f32_e32 v8, v8
	v_exp_f32_e32 v9, v9
	s_nop 0
	v_pk_add_f32 v[8:9], v[8:9], 1.0 op_sel_hi:[1,0]
	s_nop 0
	v_div_scale_f32 v15, s[8:9], v9, v9, v4
	v_rcp_f32_e32 v16, v15
	s_nop 0
	v_fma_f32 v0, -v15, v16, 1.0
	v_fmac_f32_e32 v16, v0, v16
	v_div_scale_f32 v0, vcc, v4, v9, v4
	v_mul_f32_e32 v17, v0, v16
	v_fma_f32 v18, -v15, v17, v0
	v_fmac_f32_e32 v17, v18, v16
	v_fma_f32 v0, -v15, v17, v0
	v_div_scale_f32 v15, s[8:9], v8, v8, v14
	v_rcp_f32_e32 v18, v15
	v_div_fmas_f32 v0, v0, v16, v17
	v_div_fixup_f32 v9, v0, v9, v4
	v_and_b32_e32 v17, 0xffff0000, v5
	v_fma_f32 v0, -v15, v18, 1.0
	v_fmac_f32_e32 v18, v0, v18
	v_div_scale_f32 v0, vcc, v14, v8, v14
	v_mul_f32_e32 v16, v0, v18
	v_fma_f32 v4, -v15, v16, v0
	v_fmac_f32_e32 v16, v4, v18
	v_fma_f32 v0, -v15, v16, v0
	v_lshlrev_b32_e32 v15, 16, v5
	v_mul_f32_e32 v4, 0xbfb8aa3b, v15
	v_mul_f32_e32 v5, 0xbfb8aa3b, v17
	v_exp_f32_e32 v4, v4
	v_exp_f32_e32 v5, v5
	v_div_fmas_f32 v0, v0, v18, v16
	v_div_fixup_f32 v8, v0, v8, v14
	v_pk_mul_f32 v[8:9], v[8:9], v[10:11]
	v_pk_add_f32 v[4:5], v[4:5], 1.0 op_sel_hi:[1,0]
	v_cvt_pk_bf16_f32 v0, v8, v9
	v_div_scale_f32 v10, s[8:9], v5, v5, v17
	v_rcp_f32_e32 v11, v10
	v_lshlrev_b32_e32 v8, 16, v1
	v_and_b32_e32 v9, 0xffff0000, v1
	v_fma_f32 v1, -v10, v11, 1.0
	v_fmac_f32_e32 v11, v1, v11
	v_div_scale_f32 v1, vcc, v17, v5, v17
	v_mul_f32_e32 v14, v1, v11
	v_fma_f32 v16, -v10, v14, v1
	v_fmac_f32_e32 v14, v16, v11
	v_fma_f32 v1, -v10, v14, v1
	v_div_scale_f32 v10, s[8:9], v4, v4, v15
	v_rcp_f32_e32 v16, v10
	v_div_fmas_f32 v1, v1, v11, v14
	v_div_fixup_f32 v5, v1, v5, v17
	v_lshlrev_b32_e32 v17, 16, v6
	v_fma_f32 v1, -v10, v16, 1.0
	v_fmac_f32_e32 v16, v1, v16
	v_div_scale_f32 v1, vcc, v15, v4, v15
	v_mul_f32_e32 v14, v1, v16
	v_fma_f32 v11, -v10, v14, v1
	v_fmac_f32_e32 v14, v11, v16
	v_and_b32_e32 v6, 0xffff0000, v6
	v_fma_f32 v1, -v10, v14, v1
	v_mul_f32_e32 v10, 0xbfb8aa3b, v17
	v_mul_f32_e32 v11, 0xbfb8aa3b, v6
	v_exp_f32_e32 v10, v10
	v_exp_f32_e32 v11, v11
	v_div_fmas_f32 v1, v1, v16, v14
	v_div_fixup_f32 v4, v1, v4, v15
	v_pk_mul_f32 v[4:5], v[4:5], v[8:9]
	v_pk_add_f32 v[8:9], v[10:11], 1.0 op_sel_hi:[1,0]
	v_cvt_pk_bf16_f32 v1, v4, v5
	v_div_scale_f32 v10, s[8:9], v9, v9, v6
	v_rcp_f32_e32 v11, v10
	v_lshlrev_b32_e32 v4, 16, v2
	v_and_b32_e32 v5, 0xffff0000, v2
	v_fma_f32 v2, -v10, v11, 1.0
	v_fmac_f32_e32 v11, v2, v11
	v_div_scale_f32 v2, vcc, v6, v9, v6
	v_mul_f32_e32 v14, v2, v11
	v_fma_f32 v15, -v10, v14, v2
	v_fmac_f32_e32 v14, v15, v11
	v_fma_f32 v2, -v10, v14, v2
	v_div_scale_f32 v10, s[8:9], v8, v8, v17
	v_rcp_f32_e32 v15, v10
	v_div_fmas_f32 v2, v2, v11, v14
	v_div_fixup_f32 v9, v2, v9, v6
	v_and_b32_e32 v14, 0xffff0000, v7
	v_fma_f32 v2, -v10, v15, 1.0
	v_fmac_f32_e32 v15, v2, v15
	v_div_scale_f32 v2, vcc, v17, v8, v17
	v_mul_f32_e32 v11, v2, v15
	v_fma_f32 v6, -v10, v11, v2
	v_fmac_f32_e32 v11, v6, v15
	v_fma_f32 v2, -v10, v11, v2
	v_lshlrev_b32_e32 v10, 16, v7
	v_mul_f32_e32 v6, 0xbfb8aa3b, v10
	v_mul_f32_e32 v7, 0xbfb8aa3b, v14
	v_exp_f32_e32 v6, v6
	v_exp_f32_e32 v7, v7
	v_div_fmas_f32 v2, v2, v15, v11
	v_div_fixup_f32 v8, v2, v8, v17
	v_pk_mul_f32 v[4:5], v[8:9], v[4:5]
	v_pk_add_f32 v[6:7], v[6:7], 1.0 op_sel_hi:[1,0]
	v_cvt_pk_bf16_f32 v2, v4, v5
	v_div_scale_f32 v8, s[8:9], v7, v7, v14
	v_rcp_f32_e32 v9, v8
	v_lshlrev_b32_e32 v4, 16, v3
	v_and_b32_e32 v5, 0xffff0000, v3
	v_fma_f32 v3, -v8, v9, 1.0
	v_fmac_f32_e32 v9, v3, v9
	v_div_scale_f32 v3, vcc, v14, v7, v14
	v_mul_f32_e32 v11, v3, v9
	v_fma_f32 v15, -v8, v11, v3
	v_fmac_f32_e32 v11, v15, v9
	v_fma_f32 v3, -v8, v11, v3
	v_div_scale_f32 v8, s[8:9], v6, v6, v10
	v_rcp_f32_e32 v15, v8
	v_div_fmas_f32 v3, v3, v9, v11
	v_div_fixup_f32 v7, v3, v7, v14
	v_fma_f32 v3, -v8, v15, 1.0
	v_fmac_f32_e32 v15, v3, v15
	v_div_scale_f32 v3, vcc, v10, v6, v10
	v_mul_f32_e32 v9, v3, v15
	v_fma_f32 v11, -v8, v9, v3
	v_fmac_f32_e32 v9, v11, v15
	v_fma_f32 v3, -v8, v9, v3
	v_div_fmas_f32 v3, v3, v15, v9
	v_div_fixup_f32 v6, v3, v6, v10
	v_pk_mul_f32 v[4:5], v[6:7], v[4:5]
	s_nop 0
	v_cvt_pk_bf16_f32 v3, v4, v5
	v_lshlrev_b64 v[4:5], 12, v[180:181]
	v_lshl_add_u64 v[4:5], v[12:13], 0, v[4:5]
	global_store_dwordx4 v[4:5], v[0:3], off sc1
	s_barrier
	s_cbranch_scc0 .LBB0_414

.LBB0_473:
	s_or_b64 exec, exec, s[54:55]
	v_cndmask_b32_e64 v14, 0, v14, s[8:9]
	v_add_f32_e32 v15, v15, v14
	v_cndmask_b32_e64 v14, v14, v15, s[10:11]
	v_add_f32_e32 v15, v16, v14
	v_cndmask_b32_e64 v14, v14, v15, s[12:13]
	v_add_f32_e32 v15, v17, v14
	v_cndmask_b32_e64 v14, v14, v15, s[14:15]
	v_add_f32_e32 v15, v18, v14
	v_cndmask_b32_e64 v14, v14, v15, s[16:17]
	v_add_f32_e32 v15, v19, v14
	v_cndmask_b32_e64 v14, v14, v15, s[18:19]
	v_add_f32_e32 v12, v12, v14
	v_cndmask_b32_e64 v12, v14, v12, s[20:21]
	v_add_f32_e32 v13, v13, v12
	v_or_b32_e32 v20, 0x80, v23
	v_cndmask_b32_e64 v17, v12, v13, s[22:23]
	v_lshlrev_b32_e32 v12, 1, v20
	v_add_f32_e32 v13, v26, v17
	v_add3_u32 v16, 0, v12, v40
	v_mul_f32_e32 v12, 0x3fb8aa3b, v13
	v_exp_f32_e32 v12, v12
	v_and_b32_e32 v202, 31, v22
	v_lshrrev_b32_e32 v180, 5, v23
	ds_read_u16 v14, v16 offset:12288
	ds_read_u16 v15, v16 offset:12688
	ds_read_u16 v18, v16 offset:13088
	ds_read_u16 v19, v16 offset:13488
	ds_read_u16 v22, v16 offset:13888
	ds_read_u16 v23, v16 offset:14288
	ds_read_u16 v26, v16 offset:14688
	ds_read_u16 v35, v16 offset:15088
	s_waitcnt lgkmcnt(7)
	v_lshlrev_b32_e32 v14, 16, v14
	v_mul_f32_e32 v12, v12, v14
	v_cvt_pk_bf16_f32 v12, v12, s0
	ds_write_b16 v16, v12 offset:12288
	v_mul_f32_e32 v12, 0xbfb8aa3b, v13
	v_exp_f32_e32 v36, v12
	v_sub_f32_e32 v12, v21, v13
	v_add_f32_e32 v13, v24, v17
	v_mul_f32_e32 v14, 0x3fb8aa3b, v13
	v_exp_f32_e32 v14, v14
	s_waitcnt lgkmcnt(7)
	v_lshlrev_b32_e32 v15, 16, v15
	v_mul_f32_e32 v12, 0x3fb8aa3b, v12
	v_exp_f32_e32 v12, v12
	v_mul_f32_e32 v14, v14, v15
	v_cvt_pk_bf16_f32 v14, v14, s0
	ds_write_b16 v16, v14 offset:12688
	v_mul_f32_e32 v14, 0xbfb8aa3b, v13
	v_exp_f32_e32 v24, v14
	ds_read_u16 v14, v16 offset:38288
	ds_read_u16 v37, v16 offset:39088
	ds_read_u16 v38, v16 offset:39488
	ds_read_u16 v39, v16 offset:39888
	ds_read_u16 v40, v16 offset:40288
	ds_read_u16 v41, v16 offset:40688
	ds_read_u16 v42, v16 offset:38688
	ds_read_u16 v43, v16 offset:37888
	v_sub_f32_e32 v13, v21, v13
	v_mul_f32_e32 v13, 0x3fb8aa3b, v13
	v_exp_f32_e32 v13, v13
	s_waitcnt lgkmcnt(7)
	v_lshlrev_b32_e32 v15, 16, v14
	s_waitcnt lgkmcnt(0)
	v_lshlrev_b32_e32 v14, 16, v43
	v_mul_f32_e32 v36, v36, v14
	v_cvt_pk_bf16_f32 v36, v36, s0
	v_add_f32_e32 v25, v25, v17
	ds_write_b16 v16, v36 offset:37888
	v_mul_f32_e32 v36, 0x3fb8aa3b, v25
	v_mul_f32_e32 v24, v24, v15
	v_exp_f32_e32 v36, v36
	v_pk_mul_f32 v[12:13], v[12:13], v[14:15]
	v_add_f32_e32 v15, v27, v17
	v_lshlrev_b32_e32 v14, 16, v18
	v_mul_f32_e32 v18, 0x3fb8aa3b, v15
	v_exp_f32_e32 v18, v18
	v_mul_f32_e32 v14, v36, v14
	v_cvt_pk_bf16_f32 v14, v14, s0
	v_lshlrev_b32_e32 v19, 16, v19
	v_cvt_pk_bf16_f32 v24, v24, s0
	ds_write_b16 v16, v14 offset:13088
	v_mul_f32_e32 v14, 0xbfb8aa3b, v25
	v_mul_f32_e32 v18, v18, v19
	ds_write_b16 v16, v24 offset:38288
	v_exp_f32_e32 v24, v14
	v_cvt_pk_bf16_f32 v18, v18, s0
	ds_write_b16 v16, v18 offset:13488
	v_mul_f32_e32 v18, 0xbfb8aa3b, v15
	v_sub_f32_e32 v14, v21, v25
	v_exp_f32_e32 v25, v18
	v_sub_f32_e32 v15, v21, v15
	v_mul_f32_e32 v14, 0x3fb8aa3b, v14
	v_mul_f32_e32 v15, 0x3fb8aa3b, v15
	v_lshlrev_b32_e32 v18, 16, v42
	v_exp_f32_e32 v14, v14
	v_exp_f32_e32 v15, v15
	v_mul_f32_e32 v24, v24, v18
	v_lshlrev_b32_e32 v19, 16, v37
	v_cvt_pk_bf16_f32 v24, v24, s0
	ds_write_b16 v16, v24 offset:38688
	v_mul_f32_e32 v24, v25, v19
	v_add_f32_e32 v25, v28, v17
	v_mul_f32_e32 v27, 0x3fb8aa3b, v25
	v_exp_f32_e32 v27, v27
	v_pk_mul_f32 v[14:15], v[14:15], v[18:19]
	v_add_f32_e32 v19, v29, v17
	v_lshlrev_b32_e32 v18, 16, v22
	v_mul_f32_e32 v22, 0x3fb8aa3b, v19
	v_exp_f32_e32 v22, v22
	v_mul_f32_e32 v18, v27, v18
	v_cvt_pk_bf16_f32 v18, v18, s0
	v_lshlrev_b32_e32 v23, 16, v23
	v_cvt_pk_bf16_f32 v24, v24, s0
	ds_write_b16 v16, v18 offset:13888
	v_mul_f32_e32 v18, 0xbfb8aa3b, v25
	v_mul_f32_e32 v22, v22, v23
	ds_write_b16 v16, v24 offset:39088
	v_exp_f32_e32 v24, v18
	v_cvt_pk_bf16_f32 v22, v22, s0
	ds_write_b16 v16, v22 offset:14288
	v_mul_f32_e32 v22, 0xbfb8aa3b, v19
	v_sub_f32_e32 v18, v21, v25
	v_exp_f32_e32 v25, v22
	v_sub_f32_e32 v19, v21, v19
	v_lshlrev_b32_e32 v22, 16, v38
	v_mul_f32_e32 v18, 0x3fb8aa3b, v18
	v_mul_f32_e32 v19, 0x3fb8aa3b, v19
	v_mul_f32_e32 v24, v24, v22
	v_exp_f32_e32 v18, v18
	v_exp_f32_e32 v19, v19
	v_lshlrev_b32_e32 v23, 16, v39
	v_cvt_pk_bf16_f32 v24, v24, s0
	ds_write_b16 v16, v24 offset:39488
	v_mul_f32_e32 v24, v25, v23
	v_add_f32_e32 v25, v33, v17
	v_mul_f32_e32 v27, 0x3fb8aa3b, v25
	v_exp_f32_e32 v27, v27
	v_add_f32_e32 v17, v34, v17
	v_pk_mul_f32 v[18:19], v[18:19], v[22:23]
	v_mul_f32_e32 v23, 0x3fb8aa3b, v17
	v_exp_f32_e32 v23, v23
	v_lshlrev_b32_e32 v22, 16, v26
	v_cvt_pk_bf16_f32 v24, v24, s0
	v_mul_f32_e32 v22, v27, v22
	ds_write_b16 v16, v24 offset:39888
	v_cvt_pk_bf16_f32 v22, v22, s0
	v_lshlrev_b32_e32 v24, 16, v35
	ds_write_b16 v16, v22 offset:14688
	v_mul_f32_e32 v22, 0xbfb8aa3b, v25
	v_mul_f32_e32 v23, v23, v24
	v_exp_f32_e32 v26, v22
	v_cvt_pk_bf16_f32 v23, v23, s0
	ds_write_b16 v16, v23 offset:15088
	v_mul_f32_e32 v23, 0xbfb8aa3b, v17
	v_sub_f32_e32 v22, v21, v25
	v_exp_f32_e32 v27, v23
	v_sub_f32_e32 v17, v21, v17
	v_mul_f32_e32 v22, 0x3fb8aa3b, v22
	v_mul_f32_e32 v17, 0x3fb8aa3b, v17
	v_lshlrev_b32_e32 v24, 16, v40
	v_exp_f32_e32 v22, v22
	v_exp_f32_e32 v23, v17
	v_mul_f32_e32 v17, v26, v24
	v_lshlrev_b32_e32 v25, 16, v41
	v_cvt_pk_bf16_f32 v17, v17, s0
	ds_write_b16 v16, v17 offset:40288
	v_mul_f32_e32 v17, v27, v25
	v_cvt_pk_bf16_f32 v17, v17, s0
	s_mul_i32 s25, s57, 0x24000
	ds_write_b16 v16, v17 offset:40688
	v_pk_mul_f32 v[16:17], v[22:23], v[24:25]
	s_mul_hi_i32 s24, s57, 0x24000
	s_add_u32 s8, s69, s25
	v_cvt_pk_bf16_f32 v12, v12, v13
	v_cvt_pk_bf16_f32 v13, v14, v15
	v_cvt_pk_bf16_f32 v15, v16, v17
	v_mad_u32_u24 v16, v20, s66, 0
	s_addc_u32 s9, s70, s24
	v_add3_u32 v17, v16, v30, v31
	s_bfe_i32 s10, s59, 0x10006
	v_cvt_pk_bf16_f32 v14, v18, v19
	ds_write_b64 v17, v[12:13] offset:63488
	v_add_u32_e32 v12, v16, v32
	s_and_b32 s12, s10, 3
	ds_write_b64 v12, v[14:15] offset:63488
	v_lshl_add_u32 v16, v180, 4, 0
	v_lshl_or_b32 v12, s12, 5, v202
	v_mad_u32_u24 v203, v12, s66, v16
	s_waitcnt lgkmcnt(0)
	s_barrier
	ds_read_b128 v[12:15], v203 offset:63488
	ds_read_b128 v[204:207], v203 offset:63520
	s_add_i32 s11, s12, 1
	s_waitcnt lgkmcnt(1)
	v_mfma_f32_32x32x16_bf16 v[128:143], v[12:15], v[0:3], 0
	s_add_i32 s10, s12, 2
	v_lshlrev_b32_e32 v180, 3, v180
	s_lshl_b32 s13, s12, 1
	s_add_i32 s57, s57, s46
	s_add_i32 s56, s56, s72
	v_mfma_f32_32x32x16_bf16 v[112:127], v[12:15], v[4:7], 0
	v_mfma_f32_32x32x16_bf16 v[96:111], v[12:15], v[8:11], 0
	v_lshl_or_b32 v12, s11, 5, v202
	v_mad_u32_u24 v220, v12, s66, v16
	ds_read_b128 v[12:15], v220 offset:63488
	ds_read_b128 v[208:211], v220 offset:63520
	s_lshl_b32 s11, s11, 1
	s_waitcnt lgkmcnt(1)
	v_mfma_f32_32x32x16_bf16 v[80:95], v[12:15], v[0:3], 0
	v_mfma_f32_32x32x16_bf16 v[64:79], v[12:15], v[4:7], 0
	v_mfma_f32_32x32x16_bf16 v[48:63], v[12:15], v[8:11], 0
	v_lshl_or_b32 v12, s10, 5, v202
	v_mad_u32_u24 v221, v12, s66, v16
	ds_read_b128 v[12:15], v221 offset:63488
	ds_read_b128 v[216:219], v221 offset:63520
	s_lshl_b32 s10, s10, 1
	s_waitcnt lgkmcnt(1)
	v_mfma_f32_32x32x16_bf16 v[32:47], v[12:15], v[0:3], 0
	v_mfma_f32_32x32x16_bf16 v[16:31], v[12:15], v[4:7], 0
	v_mfma_f32_32x32x16_bf16 v[0:15], v[12:15], v[8:11], 0
	v_mfma_f32_32x32x16_bf16 v[128:143], v[204:207], v[168:171], v[128:143]
	v_mfma_f32_32x32x16_bf16 v[112:127], v[204:207], v[172:175], v[112:127]
	v_mfma_f32_32x32x16_bf16 v[96:111], v[204:207], v[176:179], v[96:111]
	v_mfma_f32_32x32x16_bf16 v[80:95], v[208:211], v[168:171], v[80:95]
	v_mfma_f32_32x32x16_bf16 v[64:79], v[208:211], v[172:175], v[64:79]
	v_mfma_f32_32x32x16_bf16 v[48:63], v[208:211], v[176:179], v[48:63]
	s_waitcnt lgkmcnt(0)
	v_mfma_f32_32x32x16_bf16 v[32:47], v[216:219], v[168:171], v[32:47]
	v_mfma_f32_32x32x16_bf16 v[16:31], v[216:219], v[172:175], v[16:31]
	ds_read_b128 v[168:171], v203 offset:63552
	ds_read_b128 v[172:175], v203 offset:63584
	v_mfma_f32_32x32x16_bf16 v[0:15], v[216:219], v[176:179], v[0:15]
	s_waitcnt lgkmcnt(1)
	v_mfma_f32_32x32x16_bf16 v[128:143], v[168:171], v[156:159], v[128:143]
	v_mfma_f32_32x32x16_bf16 v[112:127], v[168:171], v[160:163], v[112:127]
	v_mfma_f32_32x32x16_bf16 v[96:111], v[168:171], v[164:167], v[96:111]
	ds_read_b128 v[168:171], v220 offset:63552
	ds_read_b128 v[176:179], v220 offset:63584
	s_waitcnt lgkmcnt(1)
	v_mfma_f32_32x32x16_bf16 v[80:95], v[168:171], v[156:159], v[80:95]
	v_mfma_f32_32x32x16_bf16 v[64:79], v[168:171], v[160:163], v[64:79]
	v_mfma_f32_32x32x16_bf16 v[48:63], v[168:171], v[164:167], v[48:63]
	ds_read_b128 v[168:171], v221 offset:63552
	ds_read_b128 v[204:207], v221 offset:63584
	s_waitcnt lgkmcnt(1)
	v_mfma_f32_32x32x16_bf16 v[32:47], v[168:171], v[156:159], v[32:47]
	v_mfma_f32_32x32x16_bf16 v[16:31], v[168:171], v[160:163], v[16:31]
	ds_read_b128 v[156:159], v187 offset:37888
	ds_read_b128 v[160:163], v187 offset:12288
	s_waitcnt lgkmcnt(1)
	global_store_dwordx4 v[190:191], v[156:159], off offset:1536 sc1
	v_mfma_f32_32x32x16_bf16 v[128:143], v[172:175], v[148:151], v[128:143]
	v_mfma_f32_32x32x16_bf16 v[0:15], v[168:171], v[164:167], v[0:15]
	ds_read_b128 v[156:159], v189 offset:37888
	ds_read_b128 v[164:167], v189 offset:12288
	s_waitcnt lgkmcnt(2)
	global_store_dwordx4 v[190:191], v[160:163], off sc1
	ds_read_b128 v[160:163], v201 offset:37888
	ds_read_b128 v[168:171], v201 offset:12288
	s_nop 4
	v_cvt_pk_bf16_f32 v128, v128, v129
	s_waitcnt lgkmcnt(3)
	global_store_dwordx4 v[192:193], v[156:159], off offset:1536 sc1
	v_cvt_pk_bf16_f32 v129, v130, v131
	s_waitcnt lgkmcnt(2)
	global_store_dwordx4 v[192:193], v[164:167], off sc1
	s_waitcnt lgkmcnt(1)
	global_store_dwordx4 v[194:195], v[160:163], off offset:1536 sc1
	s_waitcnt lgkmcnt(0)
	global_store_dwordx4 v[194:195], v[168:171], off sc1
	v_lshl_add_u64 v[156:157], s[8:9], 0, v[180:181]
	s_mul_i32 s8, s58, 36
	s_add_i32 s9, s13, s8
	v_mfma_f32_32x32x16_bf16 v[112:127], v[172:175], v[152:155], v[112:127]
	v_lshl_or_b32 v130, s9, 6, v202
	v_ashrrev_i32_e32 v131, 31, v130
	v_lshl_add_u64 v[158:159], v[130:131], 4, v[156:157]
	global_store_dwordx2 v[158:159], v[128:129], off
	v_cvt_pk_bf16_f32 v128, v132, v133
	v_or_b32_e32 v132, 32, v130
	v_ashrrev_i32_e32 v133, 31, v132
	v_cvt_pk_bf16_f32 v129, v134, v135
	v_lshl_add_u64 v[132:133], v[132:133], 4, v[156:157]
	global_store_dwordx2 v[132:133], v[128:129], off
	v_or_b32_e32 v132, 64, v130
	s_add_i32 s9, s8, 12
	v_ashrrev_i32_e32 v133, 31, v132
	v_or_b32_e32 v130, 0x60, v130
	s_add_i32 s12, s13, s9
	v_mfma_f32_32x32x16_bf16 v[96:111], v[172:175], v[144:147], v[96:111]
	v_cvt_pk_bf16_f32 v128, v136, v137
	v_cvt_pk_bf16_f32 v129, v138, v139
	v_lshl_add_u64 v[132:133], v[132:133], 4, v[156:157]
	v_ashrrev_i32_e32 v131, 31, v130
	v_cvt_pk_bf16_f32 v112, v112, v113
	v_cvt_pk_bf16_f32 v113, v114, v115
	v_lshl_or_b32 v114, s12, 6, v202
	global_store_dwordx2 v[132:133], v[128:129], off
	v_cvt_pk_bf16_f32 v128, v140, v141
	v_cvt_pk_bf16_f32 v129, v142, v143
	v_lshl_add_u64 v[130:131], v[130:131], 4, v[156:157]
	v_ashrrev_i32_e32 v115, 31, v114
	global_store_dwordx2 v[130:131], v[128:129], off
	v_lshl_add_u64 v[128:129], v[114:115], 4, v[156:157]
	global_store_dwordx2 v[128:129], v[112:113], off
	v_cvt_pk_bf16_f32 v112, v116, v117
	v_or_b32_e32 v116, 32, v114
	v_ashrrev_i32_e32 v117, 31, v116
	v_cvt_pk_bf16_f32 v113, v118, v119
	v_lshl_add_u64 v[116:117], v[116:117], 4, v[156:157]
	global_store_dwordx2 v[116:117], v[112:113], off
	v_or_b32_e32 v116, 64, v114
	s_add_i32 s12, s8, 24
	v_ashrrev_i32_e32 v117, 31, v116
	v_or_b32_e32 v114, 0x60, v114
	s_add_i32 s13, s13, s12
	v_mfma_f32_32x32x16_bf16 v[80:95], v[176:179], v[148:151], v[80:95]
	v_cvt_pk_bf16_f32 v112, v120, v121
	v_cvt_pk_bf16_f32 v113, v122, v123
	v_lshl_add_u64 v[116:117], v[116:117], 4, v[156:157]
	v_ashrrev_i32_e32 v115, 31, v114
	v_cvt_pk_bf16_f32 v96, v96, v97
	v_cvt_pk_bf16_f32 v97, v98, v99
	v_lshl_or_b32 v98, s13, 6, v202
	global_store_dwordx2 v[116:117], v[112:113], off
	v_cvt_pk_bf16_f32 v112, v124, v125
	v_cvt_pk_bf16_f32 v113, v126, v127
	v_lshl_add_u64 v[114:115], v[114:115], 4, v[156:157]
	v_ashrrev_i32_e32 v99, 31, v98
	global_store_dwordx2 v[114:115], v[112:113], off
	v_lshl_add_u64 v[112:113], v[98:99], 4, v[156:157]
	global_store_dwordx2 v[112:113], v[96:97], off
	v_cvt_pk_bf16_f32 v96, v100, v101
	v_or_b32_e32 v100, 32, v98
	v_ashrrev_i32_e32 v101, 31, v100
	v_cvt_pk_bf16_f32 v97, v102, v103
	v_lshl_add_u64 v[100:101], v[100:101], 4, v[156:157]
	global_store_dwordx2 v[100:101], v[96:97], off
	v_or_b32_e32 v100, 64, v98
	v_ashrrev_i32_e32 v101, 31, v100
	v_or_b32_e32 v98, 0x60, v98
	s_add_i32 s13, s11, s8
	v_mfma_f32_32x32x16_bf16 v[64:79], v[176:179], v[152:155], v[64:79]
	v_cvt_pk_bf16_f32 v96, v104, v105
	v_cvt_pk_bf16_f32 v97, v106, v107
	v_lshl_add_u64 v[100:101], v[100:101], 4, v[156:157]
	v_ashrrev_i32_e32 v99, 31, v98
	v_cvt_pk_bf16_f32 v80, v80, v81
	v_cvt_pk_bf16_f32 v81, v82, v83
	v_lshl_or_b32 v82, s13, 6, v202
	global_store_dwordx2 v[100:101], v[96:97], off
	v_cvt_pk_bf16_f32 v96, v108, v109
	v_cvt_pk_bf16_f32 v97, v110, v111
	v_lshl_add_u64 v[98:99], v[98:99], 4, v[156:157]
	v_ashrrev_i32_e32 v83, 31, v82
	global_store_dwordx2 v[98:99], v[96:97], off
	v_lshl_add_u64 v[96:97], v[82:83], 4, v[156:157]
	global_store_dwordx2 v[96:97], v[80:81], off
	v_cvt_pk_bf16_f32 v80, v84, v85
	v_or_b32_e32 v84, 32, v82
	v_ashrrev_i32_e32 v85, 31, v84
	v_cvt_pk_bf16_f32 v81, v86, v87
	v_lshl_add_u64 v[84:85], v[84:85], 4, v[156:157]
	global_store_dwordx2 v[84:85], v[80:81], off
	v_or_b32_e32 v84, 64, v82
	v_ashrrev_i32_e32 v85, 31, v84
	v_or_b32_e32 v82, 0x60, v82
	s_add_i32 s13, s11, s9
	v_mfma_f32_32x32x16_bf16 v[48:63], v[176:179], v[144:147], v[48:63]
	v_cvt_pk_bf16_f32 v80, v88, v89
	v_cvt_pk_bf16_f32 v81, v90, v91
	v_lshl_add_u64 v[84:85], v[84:85], 4, v[156:157]
	v_ashrrev_i32_e32 v83, 31, v82
	v_cvt_pk_bf16_f32 v64, v64, v65
	v_cvt_pk_bf16_f32 v65, v66, v67
	v_lshl_or_b32 v66, s13, 6, v202
	global_store_dwordx2 v[84:85], v[80:81], off
	v_cvt_pk_bf16_f32 v80, v92, v93
	v_cvt_pk_bf16_f32 v81, v94, v95
	v_lshl_add_u64 v[82:83], v[82:83], 4, v[156:157]
	v_ashrrev_i32_e32 v67, 31, v66
	global_store_dwordx2 v[82:83], v[80:81], off
	v_lshl_add_u64 v[80:81], v[66:67], 4, v[156:157]
	global_store_dwordx2 v[80:81], v[64:65], off
	v_cvt_pk_bf16_f32 v64, v68, v69
	v_or_b32_e32 v68, 32, v66
	v_ashrrev_i32_e32 v69, 31, v68
	v_cvt_pk_bf16_f32 v65, v70, v71
	v_lshl_add_u64 v[68:69], v[68:69], 4, v[156:157]
	global_store_dwordx2 v[68:69], v[64:65], off
	v_or_b32_e32 v68, 64, v66
	v_ashrrev_i32_e32 v69, 31, v68
	v_or_b32_e32 v66, 0x60, v66
	s_add_i32 s11, s11, s12
	v_mfma_f32_32x32x16_bf16 v[32:47], v[204:207], v[148:151], v[32:47]
	v_cvt_pk_bf16_f32 v64, v72, v73
	v_cvt_pk_bf16_f32 v65, v74, v75
	v_lshl_add_u64 v[68:69], v[68:69], 4, v[156:157]
	v_ashrrev_i32_e32 v67, 31, v66
	v_cvt_pk_bf16_f32 v48, v48, v49
	v_cvt_pk_bf16_f32 v49, v50, v51
	v_lshl_or_b32 v50, s11, 6, v202
	global_store_dwordx2 v[68:69], v[64:65], off
	v_cvt_pk_bf16_f32 v64, v76, v77
	v_cvt_pk_bf16_f32 v65, v78, v79
	v_lshl_add_u64 v[66:67], v[66:67], 4, v[156:157]
	v_ashrrev_i32_e32 v51, 31, v50
	global_store_dwordx2 v[66:67], v[64:65], off
	v_lshl_add_u64 v[64:65], v[50:51], 4, v[156:157]
	global_store_dwordx2 v[64:65], v[48:49], off
	v_cvt_pk_bf16_f32 v48, v52, v53
	v_or_b32_e32 v52, 32, v50
	v_ashrrev_i32_e32 v53, 31, v52
	v_cvt_pk_bf16_f32 v49, v54, v55
	v_lshl_add_u64 v[52:53], v[52:53], 4, v[156:157]
	global_store_dwordx2 v[52:53], v[48:49], off
	v_or_b32_e32 v52, 64, v50
	v_ashrrev_i32_e32 v53, 31, v52
	v_or_b32_e32 v50, 0x60, v50
	s_add_i32 s8, s10, s8
	v_mfma_f32_32x32x16_bf16 v[16:31], v[204:207], v[152:155], v[16:31]
	v_cvt_pk_bf16_f32 v48, v56, v57
	v_cvt_pk_bf16_f32 v49, v58, v59
	v_lshl_add_u64 v[52:53], v[52:53], 4, v[156:157]
	v_ashrrev_i32_e32 v51, 31, v50
	v_cvt_pk_bf16_f32 v32, v32, v33
	v_cvt_pk_bf16_f32 v33, v34, v35
	v_lshl_or_b32 v34, s8, 6, v202
	global_store_dwordx2 v[52:53], v[48:49], off
	v_cvt_pk_bf16_f32 v48, v60, v61
	v_cvt_pk_bf16_f32 v49, v62, v63
	v_lshl_add_u64 v[50:51], v[50:51], 4, v[156:157]
	v_ashrrev_i32_e32 v35, 31, v34
	global_store_dwordx2 v[50:51], v[48:49], off
	v_lshl_add_u64 v[48:49], v[34:35], 4, v[156:157]
	global_store_dwordx2 v[48:49], v[32:33], off
	v_cvt_pk_bf16_f32 v32, v36, v37
	v_or_b32_e32 v36, 32, v34
	v_ashrrev_i32_e32 v37, 31, v36
	v_cvt_pk_bf16_f32 v33, v38, v39
	v_lshl_add_u64 v[36:37], v[36:37], 4, v[156:157]
	global_store_dwordx2 v[36:37], v[32:33], off
	v_or_b32_e32 v36, 64, v34
	v_ashrrev_i32_e32 v37, 31, v36
	v_or_b32_e32 v34, 0x60, v34
	s_add_i32 s8, s10, s9
	v_mfma_f32_32x32x16_bf16 v[0:15], v[204:207], v[144:147], v[0:15]
	v_cvt_pk_bf16_f32 v32, v40, v41
	v_cvt_pk_bf16_f32 v33, v42, v43
	v_lshl_add_u64 v[36:37], v[36:37], 4, v[156:157]
	v_ashrrev_i32_e32 v35, 31, v34
	v_cvt_pk_bf16_f32 v16, v16, v17
	v_cvt_pk_bf16_f32 v17, v18, v19
	v_lshl_or_b32 v18, s8, 6, v202
	global_store_dwordx2 v[36:37], v[32:33], off
	v_cvt_pk_bf16_f32 v32, v44, v45
	v_cvt_pk_bf16_f32 v33, v46, v47
	v_lshl_add_u64 v[34:35], v[34:35], 4, v[156:157]
	v_ashrrev_i32_e32 v19, 31, v18
	global_store_dwordx2 v[34:35], v[32:33], off
	v_lshl_add_u64 v[32:33], v[18:19], 4, v[156:157]
	global_store_dwordx2 v[32:33], v[16:17], off
	v_cvt_pk_bf16_f32 v16, v20, v21
	v_or_b32_e32 v20, 32, v18
	v_ashrrev_i32_e32 v21, 31, v20
	v_cvt_pk_bf16_f32 v17, v22, v23
	v_lshl_add_u64 v[20:21], v[20:21], 4, v[156:157]
	global_store_dwordx2 v[20:21], v[16:17], off
	v_or_b32_e32 v20, 64, v18
	v_ashrrev_i32_e32 v21, 31, v20
	v_or_b32_e32 v18, 0x60, v18
	s_add_i32 s10, s10, s12
	v_cvt_pk_bf16_f32 v16, v24, v25
	v_cvt_pk_bf16_f32 v17, v26, v27
	v_lshl_add_u64 v[20:21], v[20:21], 4, v[156:157]
	v_ashrrev_i32_e32 v19, 31, v18
	v_cvt_pk_bf16_f32 v0, v0, v1
	v_cvt_pk_bf16_f32 v1, v2, v3
	v_lshl_or_b32 v2, s10, 6, v202
	global_store_dwordx2 v[20:21], v[16:17], off
	v_cvt_pk_bf16_f32 v16, v28, v29
	v_cvt_pk_bf16_f32 v17, v30, v31
	v_lshl_add_u64 v[18:19], v[18:19], 4, v[156:157]
	v_ashrrev_i32_e32 v3, 31, v2
	global_store_dwordx2 v[18:19], v[16:17], off
	v_lshl_add_u64 v[16:17], v[2:3], 4, v[156:157]
	global_store_dwordx2 v[16:17], v[0:1], off
	v_cvt_pk_bf16_f32 v0, v4, v5
	v_or_b32_e32 v4, 32, v2
	v_ashrrev_i32_e32 v5, 31, v4
	v_cvt_pk_bf16_f32 v1, v6, v7
	v_lshl_add_u64 v[4:5], v[4:5], 4, v[156:157]
	global_store_dwordx2 v[4:5], v[0:1], off
	v_or_b32_e32 v4, 64, v2
	v_ashrrev_i32_e32 v5, 31, v4
	v_or_b32_e32 v2, 0x60, v2
	v_cvt_pk_bf16_f32 v0, v8, v9
	v_cvt_pk_bf16_f32 v1, v10, v11
	v_lshl_add_u64 v[4:5], v[4:5], 4, v[156:157]
	v_ashrrev_i32_e32 v3, 31, v2
	global_store_dwordx2 v[4:5], v[0:1], off
	v_cvt_pk_bf16_f32 v0, v12, v13
	v_cvt_pk_bf16_f32 v1, v14, v15
	v_lshl_add_u64 v[2:3], v[2:3], 4, v[156:157]
	s_cmpk_gt_i32 s57, 0x3ff
	global_store_dwordx2 v[2:3], v[0:1], off
	s_barrier
	s_cbranch_scc1 .LBB0_411

.LBB0_542:
	v_lshlrev_b32_e32 v136, 16, v60
	v_and_b32_e32 v137, 0xffff0000, v60
	v_lshlrev_b32_e32 v60, 16, v61
	v_and_b32_e32 v61, 0xffff0000, v61
	v_lshlrev_b32_e32 v138, 16, v62
	v_and_b32_e32 v139, 0xffff0000, v62
	v_lshlrev_b32_e32 v62, 16, v63
	v_and_b32_e32 v63, 0xffff0000, v63
	v_pk_fma_f32 v[64:65], v[64:65], v[126:127], v[136:137]
	v_pk_fma_f32 v[66:67], v[66:67], v[122:123], v[60:61]
	s_waitcnt vmcnt(0)
	v_lshlrev_b32_e32 v60, 16, v72
	v_and_b32_e32 v61, 0xffff0000, v72
	v_pk_fma_f32 v[126:127], v[52:53], v[128:129], v[138:139]
	v_pk_fma_f32 v[128:129], v[54:55], v[124:125], v[62:63]
	v_cvt_pk_bf16_f32 v52, v64, v65
	v_lshlrev_b32_e32 v62, 16, v80
	v_and_b32_e32 v63, 0xffff0000, v80
	v_pk_fma_f32 v[64:65], v[64:65], v[96:97], v[60:61]
	v_lshlrev_b32_e32 v122, 16, v84
	v_and_b32_e32 v123, 0xffff0000, v84
	v_pk_fma_f32 v[62:63], v[64:65], v[92:93], v[62:63]
	v_lshlrev_b32_e32 v124, 16, v88
	v_and_b32_e32 v125, 0xffff0000, v88
	v_cvt_pk_bf16_f32 v60, v64, v65
	v_cvt_pk_bf16_f32 v64, v62, v63
	v_pk_fma_f32 v[62:63], v[62:63], v[100:101], v[122:123]
	v_lshlrev_b32_e32 v80, 16, v81
	v_cvt_pk_bf16_f32 v72, v62, v63
	v_pk_fma_f32 v[122:123], v[62:63], v[104:105], v[124:125]
	v_lshlrev_b32_e32 v62, 16, v73
	v_and_b32_e32 v63, 0xffff0000, v73
	v_and_b32_e32 v81, 0xffff0000, v81
	v_pk_fma_f32 v[62:63], v[66:67], v[98:99], v[62:63]
	v_lshlrev_b32_e32 v84, 16, v85
	v_and_b32_e32 v85, 0xffff0000, v85
	v_cvt_pk_bf16_f32 v61, v62, v63
	v_pk_fma_f32 v[62:63], v[62:63], v[94:95], v[80:81]
	v_lshlrev_b32_e32 v88, 16, v89
	v_and_b32_e32 v89, 0xffff0000, v89
	v_cvt_pk_bf16_f32 v65, v62, v63
	v_pk_fma_f32 v[62:63], v[62:63], v[102:103], v[84:85]
	v_cvt_pk_bf16_f32 v53, v66, v67
	v_cvt_pk_bf16_f32 v73, v62, v63
	v_pk_fma_f32 v[124:125], v[62:63], v[106:107], v[88:89]
	v_lshlrev_b32_e32 v62, 16, v74
	v_and_b32_e32 v63, 0xffff0000, v74
	v_lshlrev_b32_e32 v66, 16, v82
	v_and_b32_e32 v67, 0xffff0000, v82
	v_pk_fma_f32 v[48:49], v[48:49], v[126:127], v[62:63]
	v_lshlrev_b32_e32 v80, 16, v86
	v_and_b32_e32 v81, 0xffff0000, v86
	v_cvt_pk_bf16_f32 v62, v48, v49
	v_pk_fma_f32 v[48:49], v[56:57], v[48:49], v[66:67]
	v_lshlrev_b32_e32 v84, 16, v90
	v_and_b32_e32 v85, 0xffff0000, v90
	v_cvt_pk_bf16_f32 v66, v48, v49
	v_pk_fma_f32 v[48:49], v[76:77], v[48:49], v[80:81]
	v_cvt_pk_bf16_f32 v54, v126, v127
	v_cvt_pk_bf16_f32 v74, v48, v49
	v_pk_fma_f32 v[126:127], v[48:49], v[68:69], v[84:85]
	v_lshlrev_b32_e32 v48, 16, v75
	v_and_b32_e32 v49, 0xffff0000, v75
	v_lshlrev_b32_e32 v56, 16, v83
	v_and_b32_e32 v57, 0xffff0000, v83
	v_pk_fma_f32 v[48:49], v[50:51], v[128:129], v[48:49]
	v_lshlrev_b32_e32 v68, 16, v87
	v_and_b32_e32 v69, 0xffff0000, v87
	v_cvt_pk_bf16_f32 v63, v48, v49
	v_pk_fma_f32 v[48:49], v[58:59], v[48:49], v[56:57]
	v_lshl_add_u64 v[130:131], v[120:121], 0, s[12:13]
	v_cvt_pk_bf16_f32 v55, v128, v129
	v_cvt_pk_bf16_f32 v67, v48, v49
	v_pk_fma_f32 v[48:49], v[78:79], v[48:49], v[68:69]
	v_lshl_add_u64 v[132:133], v[120:121], 0, s[16:17]
	v_lshl_add_u64 v[134:135], v[120:121], 0, s[20:21]
	v_lshl_add_u64 v[120:121], v[120:121], 0, s[24:25]
	v_lshlrev_b32_e32 v76, 16, v91
	v_and_b32_e32 v77, 0xffff0000, v91
	v_cvt_pk_bf16_f32 v75, v48, v49
	global_store_dwordx4 v[130:131], v[52:55], off sc1
	global_store_dwordx4 v[132:133], v[60:63], off sc1
	global_store_dwordx4 v[134:135], v[64:67], off sc1
	global_store_dwordx4 v[120:121], v[72:75], off sc1
	v_mov_b64_e32 v[62:63], v[38:39]
	v_mov_b64_e32 v[66:67], v[46:47]
	v_mov_b64_e32 v[54:55], v[42:43]
	s_add_i32 s79, s79, 8
	v_pk_fma_f32 v[128:129], v[48:49], v[70:71], v[76:77]
	v_lshl_add_u64 v[116:117], v[116:117], 0, s[28:29]
	v_lshl_add_u64 v[118:119], v[118:119], 0, s[30:31]
	s_andn2_b64 vcc, exec, s[60:61]
	v_mov_b64_e32 v[60:61], v[36:37]
	v_mov_b64_e32 v[64:65], v[44:45]
	v_mov_b64_e32 v[52:53], v[40:41]
	s_cbranch_vccz .LBB0_545
.LBB0_543:
	v_lshl_add_u64 v[120:121], s[42:43], 0, v[116:117]
	v_add_co_u32_e32 v48, vcc, s68, v120
	v_lshl_add_u64 v[68:69], s[42:43], 0, v[118:119]
	s_nop 0
	v_addc_co_u32_e32 v49, vcc, 0, v121, vcc
	v_add_co_u32_e32 v56, vcc, s69, v68
	v_lshl_add_u64 v[50:51], v[68:69], 0, s[14:15]
	s_nop 0
	v_addc_co_u32_e32 v57, vcc, 0, v69, vcc
	v_add_co_u32_e32 v58, vcc, s70, v120
	v_lshl_add_u64 v[70:71], v[68:69], 0, s[18:19]
	s_nop 0
	v_addc_co_u32_e32 v59, vcc, 0, v121, vcc
	global_load_dwordx4 v[72:75], v[48:49], off nt
	s_nop 0
	global_load_dwordx4 v[48:51], v[50:51], off offset:16
	s_nop 0
	global_load_dwordx4 v[96:99], v[56:57], off
	global_load_dwordx4 v[92:95], v[56:57], off offset:3072
	global_load_dwordx4 v[80:83], v[58:59], off nt
	s_nop 0
	global_load_dwordx4 v[56:59], v[70:71], off offset:16
	v_add_co_u32_e32 v70, vcc, s71, v120
	v_lshl_add_u64 v[76:77], v[68:69], 0, s[22:23]
	s_nop 0
	v_addc_co_u32_e32 v71, vcc, 0, v121, vcc
	v_add_co_u32_e32 v88, vcc, s72, v68
	global_load_dwordx4 v[84:87], v[70:71], off nt
	s_nop 0
	global_load_dwordx4 v[76:79], v[76:77], off offset:16
	v_addc_co_u32_e32 v89, vcc, 0, v69, vcc
	v_add_co_u32_e32 v70, vcc, s73, v120
	v_lshlrev_b32_e32 v134, 16, v0
	s_nop 0
	v_addc_co_u32_e32 v71, vcc, 0, v121, vcc
	global_load_dwordx4 v[100:103], v[88:89], off offset:2048
	s_nop 0
	global_load_dwordx4 v[88:91], v[70:71], off nt
	v_lshl_add_u64 v[70:71], v[68:69], 0, s[26:27]
	v_add_co_u32_e32 v68, vcc, s74, v68
	v_and_b32_e32 v135, 0xffff0000, v0
	s_nop 0
	v_addc_co_u32_e32 v69, vcc, 0, v69, vcc
	global_load_dwordx4 v[104:107], v[68:69], off offset:1024
	s_nop 0
	global_load_dwordx4 v[68:71], v[70:71], off offset:16
	v_cvt_pk_bf16_f32 v130, v122, v123
	v_lshlrev_b32_e32 v136, 16, v12
	v_and_b32_e32 v137, 0xffff0000, v12
	v_pk_fma_f32 v[122:123], v[122:123], v[8:9], v[134:135]
	v_cvt_pk_bf16_f32 v131, v124, v125
	v_cvt_pk_bf16_f32 v134, v122, v123
	v_pk_fma_f32 v[122:123], v[20:21], v[122:123], v[136:137]
	v_lshlrev_b32_e32 v136, 16, v1
	v_and_b32_e32 v137, 0xffff0000, v1
	v_lshlrev_b32_e32 v140, 16, v13
	v_and_b32_e32 v141, 0xffff0000, v13
	v_pk_fma_f32 v[124:125], v[124:125], v[10:11], v[136:137]
	v_lshlrev_b32_e32 v136, 16, v2
	v_and_b32_e32 v137, 0xffff0000, v2
	v_cvt_pk_bf16_f32 v132, v126, v127
	v_cvt_pk_bf16_f32 v135, v124, v125
	v_pk_fma_f32 v[124:125], v[22:23], v[124:125], v[140:141]
	v_lshlrev_b32_e32 v140, 16, v14
	v_and_b32_e32 v141, 0xffff0000, v14
	v_pk_fma_f32 v[126:127], v[126:127], v[4:5], v[136:137]
	v_lshlrev_b32_e32 v146, 16, v26
	v_and_b32_e32 v147, 0xffff0000, v26
	v_cvt_pk_bf16_f32 v136, v126, v127
	v_pk_fma_f32 v[150:151], v[16:17], v[126:127], v[140:141]
	v_lshlrev_b32_e32 v126, 16, v3
	v_and_b32_e32 v127, 0xffff0000, v3
	v_cvt_pk_bf16_f32 v133, v128, v129
	v_pk_fma_f32 v[126:127], v[128:129], v[6:7], v[126:127]
	v_pk_fma_f32 v[128:129], v[28:29], v[150:151], v[146:147]
	v_add_co_u32_e32 v146, vcc, s75, v120
	v_lshlrev_b32_e32 v152, 16, v15
	s_nop 0
	v_addc_co_u32_e32 v147, vcc, 0, v121, vcc
	global_store_dwordx4 v[146:147], v[130:133], off sc1
	v_and_b32_e32 v153, 0xffff0000, v15
	v_cvt_pk_bf16_f32 v137, v126, v127
	v_add_co_u32_e32 v130, vcc, s76, v120
	v_pk_fma_f32 v[152:153], v[18:19], v[126:127], v[152:153]
	s_nop 0
	v_addc_co_u32_e32 v131, vcc, 0, v121, vcc
	global_store_dwordx4 v[130:131], v[134:137], off sc1
	v_add_co_u32_e32 v130, vcc, 0x14924000, v120
	v_cvt_pk_bf16_f32 v138, v122, v123
	v_cvt_pk_bf16_f32 v139, v124, v125
	v_cvt_pk_bf16_f32 v140, v150, v151
	v_cvt_pk_bf16_f32 v141, v152, v153
	v_addc_co_u32_e32 v131, vcc, 0, v121, vcc
	v_lshlrev_b32_e32 v142, 16, v24
	v_and_b32_e32 v143, 0xffff0000, v24
	v_lshlrev_b32_e32 v144, 16, v25
	v_and_b32_e32 v145, 0xffff0000, v25
	v_lshlrev_b32_e32 v148, 16, v27
	v_and_b32_e32 v149, 0xffff0000, v27
	global_store_dwordx4 v[130:131], v[138:141], off sc1
	v_add_co_u32_e32 v130, vcc, 0x149b4000, v120
	s_cmp_gt_u32 s79, 55
	v_pk_fma_f32 v[126:127], v[32:33], v[122:123], v[142:143]
	v_pk_fma_f32 v[122:123], v[34:35], v[124:125], v[144:145]
	v_pk_fma_f32 v[124:125], v[30:31], v[152:153], v[148:149]
	v_addc_co_u32_e32 v131, vcc, 0, v121, vcc
	s_cselect_b64 s[60:61], -1, 0
	v_cvt_pk_bf16_f32 v142, v126, v127
	v_cvt_pk_bf16_f32 v143, v122, v123
	v_cvt_pk_bf16_f32 v144, v128, v129
	v_cvt_pk_bf16_f32 v145, v124, v125
	s_and_b64 vcc, exec, s[60:61]
	global_store_dwordx4 v[130:131], v[142:145], off sc1
	s_cbranch_vccnz .LBB0_542
	v_add_u32_e32 v34, s79, v110
	v_add_u32_e32 v0, 8, v34
	v_add_u32_e32 v10, 9, v34
	v_add_u32_e32 v24, 10, v34
	v_add_u32_e32 v34, 11, v34
	v_ashrrev_i32_e32 v1, 31, v0
	v_ashrrev_i32_e32 v11, 31, v10
	v_ashrrev_i32_e32 v25, 31, v24
	v_ashrrev_i32_e32 v35, 31, v34
	v_lshlrev_b64 v[0:1], 2, v[0:1]
	v_lshlrev_b64 v[16:17], 2, v[10:11]
	v_lshlrev_b64 v[24:25], 2, v[24:25]
	v_lshlrev_b64 v[40:41], 2, v[34:35]
	v_or_b32_e32 v0, v0, v108
	v_or_b32_e32 v16, v16, v108
	v_or_b32_e32 v24, v24, v108
	v_or_b32_e32 v40, v40, v108
	v_mad_u64_u32 v[2:3], s[80:81], v0, s63, v[112:113]
	v_mad_u64_u32 v[8:9], s[80:81], v0, s65, v[114:115]
	v_mad_u64_u32 v[12:13], s[80:81], v16, s63, v[112:113]
	v_mad_u64_u32 v[20:21], s[80:81], v16, s65, v[114:115]
	v_mad_u64_u32 v[26:27], s[80:81], v24, s63, v[112:113]
	v_mad_u64_u32 v[32:33], s[80:81], v24, s65, v[114:115]
	v_mad_u64_u32 v[36:37], s[80:81], v40, s63, v[112:113]
	v_mad_u64_u32 v[44:45], s[80:81], v40, s65, v[114:115]
	v_mad_i32_i24 v3, v1, s63, v3
	v_mad_i32_i24 v9, v1, s65, v9
	v_mad_i32_i24 v13, v17, s63, v13
	v_mad_i32_i24 v21, v17, s65, v21
	v_mad_i32_i24 v27, v25, s63, v27
	v_mad_i32_i24 v33, v25, s65, v33
	v_mad_i32_i24 v37, v41, s63, v37
	v_mad_i32_i24 v45, v41, s65, v45
	global_load_dwordx4 v[0:3], v[2:3], off nt
	s_nop 0
	global_load_dwordx4 v[4:7], v[8:9], off offset:16
	s_nop 0
	global_load_dwordx4 v[8:11], v[8:9], off
	s_nop 0
	global_load_dwordx4 v[12:15], v[12:13], off nt
	s_nop 0
	global_load_dwordx4 v[16:19], v[20:21], off offset:16
	s_nop 0
	global_load_dwordx4 v[20:23], v[20:21], off
	s_nop 0
	global_load_dwordx4 v[24:27], v[26:27], off nt
	s_nop 0
	global_load_dwordx4 v[28:31], v[32:33], off offset:16
	s_nop 0
	global_load_dwordx4 v[32:35], v[32:33], off
	s_nop 0
	global_load_dwordx4 v[36:39], v[36:37], off nt
	s_nop 0
	global_load_dwordx4 v[40:43], v[44:45], off offset:16
	s_nop 0
	global_load_dwordx4 v[44:47], v[44:45], off
	s_branch .LBB0_542

.LBB0_548:
	v_lshlrev_b32_e32 v168, 16, v28
	v_and_b32_e32 v169, 0xffff0000, v28
	v_lshlrev_b32_e32 v28, 16, v29
	v_and_b32_e32 v29, 0xffff0000, v29
	v_pk_fma_f32 v[28:29], v[34:35], v[150:151], v[28:29]
	v_lshlrev_b32_e32 v34, 16, v30
	v_and_b32_e32 v35, 0xffff0000, v30
	v_pk_fma_f32 v[34:35], v[24:25], v[152:153], v[34:35]
	v_lshlrev_b32_e32 v24, 16, v31
	v_and_b32_e32 v25, 0xffff0000, v31
	v_pk_fma_f32 v[30:31], v[26:27], v[154:155], v[24:25]
	v_lshlrev_b32_e32 v24, 16, v48
	v_and_b32_e32 v25, 0xffff0000, v48
	v_pk_fma_f32 v[60:61], v[60:61], v[156:157], v[24:25]
	v_lshlrev_b32_e32 v24, 16, v49
	v_and_b32_e32 v25, 0xffff0000, v49
	v_pk_fma_f32 v[48:49], v[62:63], v[158:159], v[24:25]
	v_lshlrev_b32_e32 v24, 16, v50
	v_and_b32_e32 v25, 0xffff0000, v50
	v_pk_fma_f32 v[32:33], v[32:33], v[146:147], v[168:169]
	v_pk_fma_f32 v[52:53], v[52:53], v[160:161], v[24:25]
	v_lshlrev_b32_e32 v24, 16, v51
	v_and_b32_e32 v25, 0xffff0000, v51
	v_lshl_add_u64 v[164:165], v[144:145], 0, s[36:37]
	v_pk_fma_f32 v[50:51], v[54:55], v[162:163], v[24:25]
	v_cvt_pk_bf16_f32 v24, v32, v33
	v_cvt_pk_bf16_f32 v25, v28, v29
	v_cvt_pk_bf16_f32 v26, v34, v35
	v_cvt_pk_bf16_f32 v27, v30, v31
	global_store_dwordx4 v[164:165], v[24:27], off sc1
	v_lshl_add_u64 v[144:145], v[144:145], 0, s[38:39]
	v_lshl_add_u64 v[166:167], v[148:149], 0, s[36:37]
	s_waitcnt vmcnt(0)
	v_lshlrev_b32_e32 v24, 16, v108
	v_and_b32_e32 v25, 0xffff0000, v108
	v_pk_fma_f32 v[32:33], v[32:33], v[116:117], v[24:25]
	v_lshlrev_b32_e32 v24, 16, v109
	v_and_b32_e32 v25, 0xffff0000, v109
	v_pk_fma_f32 v[28:29], v[28:29], v[118:119], v[24:25]
	v_lshlrev_b32_e32 v24, 16, v110
	v_and_b32_e32 v25, 0xffff0000, v110
	v_pk_fma_f32 v[34:35], v[34:35], v[112:113], v[24:25]
	v_lshlrev_b32_e32 v24, 16, v111
	v_and_b32_e32 v25, 0xffff0000, v111
	v_pk_fma_f32 v[30:31], v[30:31], v[114:115], v[24:25]
	v_cvt_pk_bf16_f32 v24, v32, v33
	v_cvt_pk_bf16_f32 v25, v28, v29
	v_cvt_pk_bf16_f32 v26, v34, v35
	v_cvt_pk_bf16_f32 v27, v30, v31
	global_store_dwordx4 v[144:145], v[24:27], off sc1
	v_lshl_add_u64 v[148:149], v[148:149], 0, s[38:39]
	s_add_i32 s60, s60, 4
	v_lshlrev_b32_e32 v24, 16, v100
	v_and_b32_e32 v25, 0xffff0000, v100
	v_pk_fma_f32 v[146:147], v[32:33], v[104:105], v[24:25]
	v_lshlrev_b32_e32 v24, 16, v101
	v_and_b32_e32 v25, 0xffff0000, v101
	v_pk_fma_f32 v[150:151], v[28:29], v[106:107], v[24:25]
	v_lshlrev_b32_e32 v24, 16, v102
	v_and_b32_e32 v25, 0xffff0000, v102
	v_pk_fma_f32 v[152:153], v[34:35], v[96:97], v[24:25]
	v_lshlrev_b32_e32 v24, 16, v103
	v_and_b32_e32 v25, 0xffff0000, v103
	v_pk_fma_f32 v[154:155], v[30:31], v[98:99], v[24:25]
	v_cvt_pk_bf16_f32 v24, v60, v61
	v_cvt_pk_bf16_f32 v25, v48, v49
	v_cvt_pk_bf16_f32 v26, v52, v53
	v_cvt_pk_bf16_f32 v27, v50, v51
	global_store_dwordx4 v[166:167], v[24:27], off sc1
	v_lshl_add_u64 v[136:137], v[136:137], 0, s[52:53]
	v_lshl_add_u64 v[138:139], v[138:139], 0, s[54:55]
	v_lshlrev_b32_e32 v24, 16, v84
	v_and_b32_e32 v25, 0xffff0000, v84
	v_pk_fma_f32 v[28:29], v[60:61], v[92:93], v[24:25]
	v_lshlrev_b32_e32 v24, 16, v85
	v_and_b32_e32 v25, 0xffff0000, v85
	v_pk_fma_f32 v[30:31], v[48:49], v[94:95], v[24:25]
	v_lshlrev_b32_e32 v24, 16, v86
	v_and_b32_e32 v25, 0xffff0000, v86
	v_pk_fma_f32 v[32:33], v[52:53], v[88:89], v[24:25]
	v_lshlrev_b32_e32 v24, 16, v87
	v_and_b32_e32 v25, 0xffff0000, v87
	v_pk_fma_f32 v[34:35], v[50:51], v[90:91], v[24:25]
	v_cvt_pk_bf16_f32 v24, v28, v29
	v_cvt_pk_bf16_f32 v25, v30, v31
	v_cvt_pk_bf16_f32 v26, v32, v33
	v_cvt_pk_bf16_f32 v27, v34, v35
	global_store_dwordx4 v[148:149], v[24:27], off sc1
	v_mov_b64_e32 v[48:49], v[56:57]
	v_mov_b64_e32 v[60:61], v[64:65]
	v_lshlrev_b32_e32 v24, 16, v76
	v_and_b32_e32 v25, 0xffff0000, v76
	v_pk_fma_f32 v[156:157], v[28:29], v[80:81], v[24:25]
	v_lshlrev_b32_e32 v24, 16, v77
	v_and_b32_e32 v25, 0xffff0000, v77
	v_pk_fma_f32 v[158:159], v[30:31], v[82:83], v[24:25]
	v_lshlrev_b32_e32 v24, 16, v78
	v_and_b32_e32 v25, 0xffff0000, v78
	v_pk_fma_f32 v[160:161], v[32:33], v[72:73], v[24:25]
	v_lshlrev_b32_e32 v24, 16, v79
	v_and_b32_e32 v25, 0xffff0000, v79
	v_pk_fma_f32 v[162:163], v[34:35], v[74:75], v[24:25]
	v_mov_b64_e32 v[24:25], v[40:41]
	v_mov_b64_e32 v[32:33], v[44:45]
	v_mov_b64_e32 v[28:29], v[36:37]
	v_mov_b64_e32 v[52:53], v[68:69]
	v_lshl_add_u64 v[140:141], v[140:141], 0, s[52:53]
	v_lshl_add_u64 v[142:143], v[142:143], 0, s[54:55]
	s_and_b64 vcc, exec, s[58:59]
	v_mov_b64_e32 v[50:51], v[58:59]
	v_mov_b64_e32 v[26:27], v[42:43]
	v_mov_b64_e32 v[34:35], v[46:47]
	v_mov_b64_e32 v[30:31], v[38:39]
	v_mov_b64_e32 v[62:63], v[66:67]
	v_mov_b64_e32 v[54:55], v[70:71]
	s_cbranch_vccnz .LBB0_538
.LBB0_549:
	v_lshl_add_u64 v[144:145], s[42:43], 0, v[140:141]
	v_add_co_u32_e32 v72, vcc, s77, v144
	v_lshl_add_u64 v[74:75], s[42:43], 0, v[142:143]
	s_nop 0
	v_addc_co_u32_e32 v73, vcc, 0, v145, vcc
	global_load_dwordx4 v[108:111], v[72:73], off nt
	global_load_dwordx4 v[116:119], v[74:75], off offset:-3072
	v_add_co_u32_e32 v72, vcc, s78, v144
	v_lshl_add_u64 v[148:149], s[42:43], 0, v[136:137]
	s_nop 0
	v_addc_co_u32_e32 v73, vcc, 0, v145, vcc
	global_load_dwordx4 v[100:103], v[72:73], off nt
	global_load_dwordx4 v[96:99], v[74:75], off offset:16
	global_load_dwordx4 v[112:115], v[74:75], off offset:-3056
	global_load_dwordx4 v[104:107], v[74:75], off
	v_add_co_u32_e32 v72, vcc, s77, v148
	v_lshl_add_u64 v[80:81], s[42:43], 0, v[138:139]
	s_nop 0
	v_addc_co_u32_e32 v73, vcc, 0, v149, vcc
	global_load_dwordx4 v[84:87], v[72:73], off nt
	global_load_dwordx4 v[92:95], v[80:81], off offset:-3072
	v_add_co_u32_e32 v72, vcc, s78, v148
	v_cvt_pk_bf16_f32 v164, v146, v147
	s_nop 0
	v_addc_co_u32_e32 v73, vcc, 0, v149, vcc
	global_load_dwordx4 v[76:79], v[72:73], off nt
	s_nop 0
	global_load_dwordx4 v[72:75], v[80:81], off offset:16
	global_load_dwordx4 v[88:91], v[80:81], off offset:-3056
	s_nop 0
	global_load_dwordx4 v[80:83], v[80:81], off
	v_add_co_u32_e32 v168, vcc, s75, v144
	v_cvt_pk_bf16_f32 v165, v150, v151
	v_cvt_pk_bf16_f32 v166, v152, v153
	v_cvt_pk_bf16_f32 v167, v154, v155
	v_addc_co_u32_e32 v169, vcc, 0, v145, vcc
	global_store_dwordx4 v[168:169], v[164:167], off sc1
	v_lshlrev_b32_e32 v168, 16, v3
	v_and_b32_e32 v169, 0xffff0000, v3
	v_lshlrev_b32_e32 v166, 16, v1
	v_and_b32_e32 v167, 0xffff0000, v1
	v_lshlrev_b32_e32 v164, 16, v0
	v_and_b32_e32 v165, 0xffff0000, v0
	v_pk_fma_f32 v[150:151], v[10:11], v[150:151], v[166:167]
	v_lshlrev_b32_e32 v166, 16, v2
	v_and_b32_e32 v167, 0xffff0000, v2
	v_pk_fma_f32 v[146:147], v[8:9], v[146:147], v[164:165]
	v_pk_fma_f32 v[152:153], v[4:5], v[152:153], v[166:167]
	v_pk_fma_f32 v[154:155], v[6:7], v[154:155], v[168:169]
	v_add_co_u32_e32 v168, vcc, s76, v144
	v_cvt_pk_bf16_f32 v164, v146, v147
	v_cvt_pk_bf16_f32 v165, v150, v151
	v_cvt_pk_bf16_f32 v166, v152, v153
	v_cvt_pk_bf16_f32 v167, v154, v155
	v_addc_co_u32_e32 v169, vcc, 0, v145, vcc
	global_store_dwordx4 v[168:169], v[164:167], off sc1
	v_add_co_u32_e32 v168, vcc, s75, v148
	s_nop 0
	v_cvt_pk_bf16_f32 v164, v156, v157
	v_cvt_pk_bf16_f32 v165, v158, v159
	v_cvt_pk_bf16_f32 v166, v160, v161
	v_cvt_pk_bf16_f32 v167, v162, v163
	v_addc_co_u32_e32 v169, vcc, 0, v149, vcc
	global_store_dwordx4 v[168:169], v[164:167], off sc1
	v_lshlrev_b32_e32 v168, 16, v15
	v_and_b32_e32 v169, 0xffff0000, v15
	v_lshlrev_b32_e32 v166, 16, v13
	v_and_b32_e32 v167, 0xffff0000, v13
	v_lshlrev_b32_e32 v164, 16, v12
	v_and_b32_e32 v165, 0xffff0000, v12
	v_pk_fma_f32 v[158:159], v[22:23], v[158:159], v[166:167]
	v_lshlrev_b32_e32 v166, 16, v14
	v_and_b32_e32 v167, 0xffff0000, v14
	v_pk_fma_f32 v[162:163], v[18:19], v[162:163], v[168:169]
	v_add_co_u32_e32 v168, vcc, 0x14894000, v148
	s_cmp_gt_u32 s60, 59
	v_pk_fma_f32 v[156:157], v[20:21], v[156:157], v[164:165]
	v_pk_fma_f32 v[160:161], v[16:17], v[160:161], v[166:167]
	v_addc_co_u32_e32 v169, vcc, 0, v149, vcc
	s_cselect_b64 s[58:59], -1, 0
	v_cvt_pk_bf16_f32 v164, v156, v157
	v_cvt_pk_bf16_f32 v165, v158, v159
	v_cvt_pk_bf16_f32 v166, v160, v161
	v_cvt_pk_bf16_f32 v167, v162, v163
	s_and_b64 vcc, exec, s[58:59]
	global_store_dwordx4 v[168:169], v[164:167], off sc1
	s_cbranch_vccnz .LBB0_548
	v_add_u32_e32 v10, s60, v122
	v_add_u32_e32 v0, 4, v10
	v_add_u32_e32 v10, 5, v10
	v_ashrrev_i32_e32 v1, 31, v0
	v_ashrrev_i32_e32 v11, 31, v10
	v_lshlrev_b64 v[0:1], 2, v[0:1]
	v_lshlrev_b64 v[12:13], 2, v[10:11]
	v_or_b32_e32 v0, v0, v120
	v_or_b32_e32 v12, v12, v120
	v_mad_u64_u32 v[2:3], s[80:81], v0, s63, v[124:125]
	v_mad_u64_u32 v[8:9], s[80:81], v0, s65, v[126:127]
	v_mad_u64_u32 v[14:15], s[80:81], v12, s63, v[124:125]
	v_mad_i32_i24 v3, v1, s63, v3
	v_mad_i32_i24 v9, v1, s65, v9
	v_mad_i32_i24 v15, v13, s63, v15
	v_add_u32_e32 v22, s60, v130
	global_load_dwordx4 v[0:3], v[2:3], off nt
	s_nop 0
	global_load_dwordx4 v[4:7], v[8:9], off offset:16
	s_nop 0
	global_load_dwordx4 v[8:11], v[8:9], off
	s_nop 0
	global_load_dwordx4 v[36:39], v[14:15], off nt
	v_mad_u64_u32 v[14:15], s[80:81], v12, s65, v[126:127]
	v_add_u32_e32 v12, 4, v22
	v_add_u32_e32 v22, 5, v22
	v_mad_i32_i24 v15, v13, s65, v15
	v_ashrrev_i32_e32 v13, 31, v12
	v_ashrrev_i32_e32 v23, 31, v22
	v_lshlrev_b64 v[12:13], 2, v[12:13]
	v_lshlrev_b64 v[64:65], 2, v[22:23]
	v_or_b32_e32 v12, v12, v128
	v_or_b32_e32 v64, v64, v128
	global_load_dwordx4 v[40:43], v[14:15], off offset:16
	global_load_dwordx4 v[44:47], v[14:15], off
	v_mad_u64_u32 v[14:15], s[80:81], v12, s63, v[132:133]
	v_mad_u64_u32 v[20:21], s[80:81], v12, s65, v[134:135]
	v_mad_u64_u32 v[56:57], s[80:81], v64, s63, v[132:133]
	v_mad_u64_u32 v[66:67], s[80:81], v64, s65, v[134:135]
	v_mad_i32_i24 v15, v13, s63, v15
	v_mad_i32_i24 v21, v13, s65, v21
	v_mad_i32_i24 v57, v65, s63, v57
	v_mad_i32_i24 v67, v65, s65, v67
	global_load_dwordx4 v[12:15], v[14:15], off nt
	s_nop 0
	global_load_dwordx4 v[16:19], v[20:21], off offset:16
	s_nop 0
	global_load_dwordx4 v[20:23], v[20:21], off
	s_nop 0
	global_load_dwordx4 v[56:59], v[56:57], off nt
	s_nop 0
	global_load_dwordx4 v[68:71], v[66:67], off offset:16
	s_nop 0
	global_load_dwordx4 v[64:67], v[66:67], off
	s_branch .LBB0_548

.LBB0_607:
	s_or_b64 exec, exec, s[6:7]
	s_waitcnt lgkmcnt(0)
	v_ashrrev_i32_e32 v0, 3, v237
	v_add_u32_e32 v0, v0, v238
	v_mul_lo_u32 v1, v0, 48
	v_sub_u32_e32 v12, v230, v1
	v_ashrrev_i32_e32 v1, 31, v0
	v_lshl_add_u64 v[10:11], s[12:13], 0, v[0:1]
	v_mov_b64_e32 v[8:9], s[42:43]
	v_mad_u64_u32 v[4:5], s[6:7], v10, s70, v[8:9]
	v_mov_b32_e32 v6, v5
	v_lshlrev_b32_e32 v2, 3, v12
	v_mad_u64_u32 v[6:7], s[6:7], v11, s70, v[6:7]
	s_mul_i32 s56, s16, 0x300
	v_mov_b32_e32 v5, v6
	v_ashrrev_i32_e32 v3, 31, v2
	v_lshl_add_u64 v[4:5], v[4:5], 0, s[56:57]
	v_lshlrev_b64 v[16:17], 1, v[2:3]
	v_lshl_add_u64 v[4:5], v[4:5], 0, v[16:17]
	v_add_co_u32_e32 v4, vcc, s80, v4
	s_nop 1
	v_addc_co_u32_e32 v5, vcc, 0, v5, vcc
	s_barrier
	global_load_dwordx4 v[22:25], v[4:5], off offset:3072 nt
	v_lshl_add_u32 v1, v0, 2, 0
	v_mul_lo_u32 v0, v0, s79
	v_lshlrev_b32_e32 v4, 4, v12
	v_add3_u32 v0, v1, v0, v4
	s_load_dwordx2 s[18:19], s[0:1], 0x38
	ds_read_b128 v[26:29], v0 offset:63488
	ds_read2st64_b32 v[18:19], v1 offset0:16 offset1:17
	ds_read2st64_b32 v[14:15], v1 offset0:18 offset1:19
	s_add_u32 s16, s71, s56
	s_addc_u32 s17, s72, 0
	s_waitcnt lgkmcnt(0)
	v_lshlrev_b32_e32 v12, 16, v26
	v_and_b32_e32 v13, 0xffff0000, v26
	v_lshlrev_b32_e32 v20, 16, v27
	v_and_b32_e32 v21, 0xffff0000, v27
	v_lshl_add_u64 v[4:5], v[2:3], 2, s[18:19]
	global_load_dwordx4 v[0:3], v[4:5], off offset:16
	s_nop 0
	global_load_dwordx4 v[4:7], v[4:5], off
	v_lshlrev_b64 v[10:11], 12, v[10:11]
	v_lshl_add_u64 v[10:11], s[16:17], 0, v[10:11]
	v_lshl_add_u64 v[16:17], v[10:11], 0, v[16:17]
	s_add_i32 s3, s3, s73
	s_waitcnt vmcnt(2)
	v_lshlrev_b32_e32 v30, 16, v22
	v_and_b32_e32 v31, 0xffff0000, v22
	v_lshlrev_b32_e32 v32, 16, v23
	v_and_b32_e32 v33, 0xffff0000, v23
	v_mul_f32_e32 v22, 0xbfb8aa3b, v30
	v_mul_f32_e32 v23, 0xbfb8aa3b, v31
	v_exp_f32_e32 v22, v22
	v_exp_f32_e32 v23, v23
	v_mul_f32_e32 v26, 0xbfb8aa3b, v32
	v_mul_f32_e32 v27, 0xbfb8aa3b, v33
	v_exp_f32_e32 v26, v26
	v_exp_f32_e32 v27, v27
	v_pk_add_f32 v[22:23], v[22:23], 1.0 op_sel_hi:[1,0]
	v_lshlrev_b32_e32 v34, 16, v24
	v_div_scale_f32 v36, s[6:7], v23, v23, v31
	v_pk_add_f32 v[26:27], v[26:27], 1.0 op_sel_hi:[1,0]
	v_div_scale_f32 v38, s[6:7], v22, v22, v30
	v_rcp_f32_e32 v44, v36
	v_div_scale_f32 v40, s[8:9], v27, v27, v33
	v_rcp_f32_e32 v45, v38
	v_rcp_f32_e32 v46, v40
	v_fma_f32 v120, -v36, v44, 1.0
	v_div_scale_f32 v37, vcc, v31, v23, v31
	v_fma_f32 v121, -v38, v45, 1.0
	v_fmac_f32_e32 v44, v120, v44
	v_div_scale_f32 v39, s[6:7], v30, v22, v30
	v_fma_f32 v122, -v40, v46, 1.0
	v_fmac_f32_e32 v45, v121, v45
	v_mul_f32_e32 v120, v37, v44
	v_div_scale_f32 v41, s[8:9], v33, v27, v33
	v_fmac_f32_e32 v46, v122, v46
	v_mul_f32_e32 v121, v39, v45
	v_fma_f32 v124, -v36, v120, v37
	v_mul_f32_e32 v122, v41, v46
	v_fma_f32 v125, -v38, v121, v39
	v_fmac_f32_e32 v120, v124, v44
	v_fma_f32 v126, -v40, v122, v41
	v_fmac_f32_e32 v121, v125, v45
	v_fma_f32 v36, -v36, v120, v37
	v_fmac_f32_e32 v122, v126, v46
	v_fma_f32 v37, -v38, v121, v39
	v_div_fmas_f32 v36, v36, v44, v120
	s_mov_b64 vcc, s[6:7]
	v_and_b32_e32 v24, 0xffff0000, v24
	v_div_scale_f32 v42, s[10:11], v26, v26, v32
	v_fma_f32 v38, -v40, v122, v41
	v_div_fixup_f32 v23, v36, v23, v31
	v_div_fmas_f32 v31, v37, v45, v121
	s_mov_b64 vcc, s[8:9]
	v_mul_f32_e32 v35, 0xbfb8aa3b, v34
	v_rcp_f32_e32 v47, v42
	v_div_fixup_f32 v22, v31, v22, v30
	v_div_fmas_f32 v30, v38, v46, v122
	v_mul_f32_e32 v31, 0xbfb8aa3b, v24
	v_div_fixup_f32 v27, v30, v27, v33
	v_exp_f32_e32 v30, v35
	v_exp_f32_e32 v31, v31
	v_fma_f32 v123, -v42, v47, 1.0
	v_div_scale_f32 v43, s[10:11], v32, v26, v32
	v_fmac_f32_e32 v47, v123, v47
	v_pk_add_f32 v[30:31], v[30:31], 1.0 op_sel_hi:[1,0]
	v_mul_f32_e32 v123, v43, v47
	v_div_scale_f32 v35, s[6:7], v31, v31, v24
	v_fma_f32 v127, -v42, v123, v43
	v_rcp_f32_e32 v36, v35
	v_fmac_f32_e32 v123, v127, v47
	v_fma_f32 v33, -v42, v123, v43
	s_mov_b64 vcc, s[10:11]
	v_div_fmas_f32 v33, v33, v47, v123
	v_div_fixup_f32 v26, v33, v26, v32
	v_lshlrev_b32_e32 v32, 16, v28
	v_and_b32_e32 v33, 0xffff0000, v28
	v_fma_f32 v28, -v35, v36, 1.0
	v_fmac_f32_e32 v36, v28, v36
	v_div_scale_f32 v28, vcc, v24, v31, v24
	v_mul_f32_e32 v37, v28, v36
	v_fma_f32 v38, -v35, v37, v28
	v_fmac_f32_e32 v37, v38, v36
	v_fma_f32 v28, -v35, v37, v28
	v_div_scale_f32 v35, s[6:7], v30, v30, v34
	v_rcp_f32_e32 v38, v35
	v_div_fmas_f32 v28, v28, v36, v37
	v_div_fixup_f32 v31, v28, v31, v24
	v_div_scale_f32 v28, vcc, v34, v30, v34
	v_fma_f32 v24, -v35, v38, 1.0
	v_fmac_f32_e32 v38, v24, v38
	v_mul_f32_e32 v36, v28, v38
	v_fma_f32 v24, -v35, v36, v28
	v_lshlrev_b32_e32 v37, 16, v25
	v_and_b32_e32 v39, 0xffff0000, v25
	v_fmac_f32_e32 v36, v24, v38
	v_mul_f32_e32 v24, 0xbfb8aa3b, v37
	v_mul_f32_e32 v25, 0xbfb8aa3b, v39
	v_exp_f32_e32 v24, v24
	v_exp_f32_e32 v25, v25
	v_fma_f32 v28, -v35, v36, v28
	v_div_fmas_f32 v28, v28, v38, v36
	v_div_fixup_f32 v30, v28, v30, v34
	v_pk_add_f32 v[24:25], v[24:25], 1.0 op_sel_hi:[1,0]
	v_lshlrev_b32_e32 v28, 16, v29
	v_div_scale_f32 v35, s[6:7], v25, v25, v39
	v_rcp_f32_e32 v36, v35
	v_and_b32_e32 v29, 0xffff0000, v29
	v_fma_f32 v34, -v35, v36, 1.0
	v_fmac_f32_e32 v36, v34, v36
	v_div_scale_f32 v34, vcc, v39, v25, v39
	v_mul_f32_e32 v38, v34, v36
	v_fma_f32 v40, -v35, v38, v34
	v_fmac_f32_e32 v38, v40, v36
	v_fma_f32 v34, -v35, v38, v34
	v_div_scale_f32 v35, s[6:7], v24, v24, v37
	v_rcp_f32_e32 v40, v35
	v_div_fmas_f32 v34, v34, v36, v38
	v_div_fixup_f32 v25, v34, v25, v39
	v_mov_b32_e32 v39, v18
	v_fma_f32 v34, -v35, v40, 1.0
	v_fmac_f32_e32 v40, v34, v40
	v_div_scale_f32 v34, vcc, v37, v24, v37
	v_mul_f32_e32 v36, v34, v40
	v_fma_f32 v38, -v35, v36, v34
	v_fmac_f32_e32 v36, v38, v40
	v_fma_f32 v34, -v35, v36, v34
	v_div_fmas_f32 v34, v34, v40, v36
	v_div_fixup_f32 v24, v34, v24, v37
	v_ashrrev_i32_e32 v34, 3, v235
	v_add_u32_e32 v34, v34, v236
	v_lshl_add_u32 v40, v34, 2, 0
	ds_read2st64_b32 v[36:37], v40 offset0:16 offset1:17
	ds_read2st64_b32 v[10:11], v40 offset0:18 offset1:19
	v_mul_lo_u32 v35, v34, 48
	s_waitcnt lgkmcnt(1)
	v_mov_b32_e32 v38, v36
	v_mov_b32_e32 v18, v37
	v_pk_add_f32 v[18:19], v[38:39], v[18:19]
	s_waitcnt lgkmcnt(0)
	v_mov_b32_e32 v36, v10
	v_mov_b32_e32 v37, v14
	v_pk_add_f32 v[18:19], v[18:19], v[36:37]
	v_mov_b32_e32 v14, v11
	v_pk_add_f32 v[14:15], v[18:19], v[14:15]
	v_mov_b64_e32 v[10:11], s[66:67]
	v_pk_fma_f32 v[36:37], v[14:15], s[64:65], v[10:11] op_sel_hi:[1,0,0]
	s_nop 0
	v_mul_f32_e32 v14, 0x4b800000, v37
	v_cmp_gt_f32_e32 vcc, s81, v37
	s_nop 1
	v_cndmask_b32_e32 v14, v37, v14, vcc
	v_rsq_f32_e32 v15, v14
	v_sub_u32_e32 v37, v234, v35
	v_ashrrev_i32_e32 v35, 31, v34
	v_lshlrev_b32_e32 v14, 3, v37
	v_mul_f32_e32 v18, 0x45800000, v15
	v_cndmask_b32_e32 v18, v15, v18, vcc
	v_pk_mul_f32 v[12:13], v[18:19], v[12:13] op_sel_hi:[0,1]
	s_waitcnt vmcnt(0)
	v_pk_mul_f32 v[4:5], v[4:5], v[12:13]
	v_pk_mul_f32 v[12:13], v[18:19], v[20:21] op_sel_hi:[0,1]
	v_pk_mul_f32 v[6:7], v[6:7], v[12:13]
	v_pk_mul_f32 v[4:5], v[22:23], v[4:5]
	v_pk_mul_f32 v[6:7], v[26:27], v[6:7]
	v_cvt_pk_bf16_f32 v4, v4, v5
	v_cvt_pk_bf16_f32 v5, v6, v7
	v_pk_mul_f32 v[6:7], v[18:19], v[32:33] op_sel_hi:[0,1]
	v_pk_mul_f32 v[0:1], v[0:1], v[6:7]
	v_ashrrev_i32_e32 v15, 31, v14
	v_pk_mul_f32 v[0:1], v[30:31], v[0:1]
	v_mul_f32_e32 v20, 0x4b800000, v36
	v_cvt_pk_bf16_f32 v6, v0, v1
	v_pk_mul_f32 v[0:1], v[18:19], v[28:29] op_sel_hi:[0,1]
	v_pk_mul_f32 v[0:1], v[2:3], v[0:1]
	v_lshlrev_b32_e32 v21, 4, v37
	v_pk_mul_f32 v[0:1], v[24:25], v[0:1]
	s_nop 0
	v_cvt_pk_bf16_f32 v7, v0, v1
	v_lshl_add_u64 v[0:1], s[12:13], 0, v[34:35]
	v_mad_u64_u32 v[2:3], s[6:7], v0, s70, v[8:9]
	global_store_dwordx4 v[16:17], v[4:7], off sc1
	v_lshl_add_u64 v[16:17], v[14:15], 2, s[18:19]
	s_nop 0
	v_mov_b32_e32 v4, v3
	v_mad_u64_u32 v[4:5], s[6:7], v1, s70, v[4:5]
	v_mov_b32_e32 v3, v4
	v_lshl_add_u64 v[2:3], v[2:3], 0, s[56:57]
	v_lshlrev_b64 v[6:7], 1, v[14:15]
	v_lshl_add_u64 v[2:3], v[2:3], 0, v[6:7]
	v_add_co_u32_e32 v2, vcc, s80, v2
	v_lshlrev_b64 v[0:1], 12, v[0:1]
	s_nop 0
	v_addc_co_u32_e32 v3, vcc, 0, v3, vcc
	global_load_dwordx4 v[2:5], v[2:3], off offset:3072 nt
	s_nop 0
	global_load_dwordx4 v[12:15], v[16:17], off
	s_nop 0
	global_load_dwordx4 v[16:19], v[16:17], off offset:16
	v_cmp_gt_f32_e32 vcc, s81, v36
	v_lshl_add_u64 v[0:1], s[16:17], 0, v[0:1]
	v_lshl_add_u64 v[0:1], v[0:1], 0, v[6:7]
	v_cndmask_b32_e32 v20, v36, v20, vcc
	v_rsq_f32_e32 v26, v20
	v_mul_lo_u32 v20, v34, s79
	v_add3_u32 v20, v40, v20, v21
	ds_read_b128 v[20:23], v20 offset:63488
	v_mul_f32_e32 v28, 0x45800000, v26
	v_cndmask_b32_e32 v26, v26, v28, vcc
	s_waitcnt lgkmcnt(0)
	v_lshlrev_b32_e32 v28, 16, v20
	v_and_b32_e32 v29, 0xffff0000, v20
	s_waitcnt vmcnt(2)
	v_lshlrev_b32_e32 v27, 16, v2
	v_and_b32_e32 v2, 0xffff0000, v2
	v_mul_f32_e32 v24, 0xbfb8aa3b, v27
	v_mul_f32_e32 v25, 0xbfb8aa3b, v2
	v_exp_f32_e32 v24, v24
	v_exp_f32_e32 v25, v25
	v_pk_mul_f32 v[28:29], v[26:27], v[28:29] op_sel_hi:[0,1]
	s_waitcnt vmcnt(1)
	v_pk_mul_f32 v[12:13], v[12:13], v[28:29]
	v_pk_add_f32 v[24:25], v[24:25], 1.0 op_sel_hi:[1,0]
	s_nop 0
	v_div_scale_f32 v30, s[6:7], v25, v25, v2
	v_rcp_f32_e32 v31, v30
	s_nop 0
	v_fma_f32 v20, -v30, v31, 1.0
	v_fmac_f32_e32 v31, v20, v31
	v_div_scale_f32 v20, vcc, v2, v25, v2
	v_mul_f32_e32 v28, v20, v31
	v_fma_f32 v29, -v30, v28, v20
	v_fmac_f32_e32 v28, v29, v31
	v_div_scale_f32 v29, s[6:7], v24, v24, v27
	v_fma_f32 v20, -v30, v28, v20
	v_rcp_f32_e32 v30, v29
	v_div_fmas_f32 v20, v20, v31, v28
	v_div_fixup_f32 v25, v20, v25, v2
	v_fma_f32 v2, -v29, v30, 1.0
	v_fmac_f32_e32 v30, v2, v30
	v_div_scale_f32 v2, vcc, v27, v24, v27
	v_mul_f32_e32 v20, v2, v30
	v_fma_f32 v28, -v29, v20, v2
	v_fmac_f32_e32 v20, v28, v30
	v_fma_f32 v2, -v29, v20, v2
	v_div_fmas_f32 v2, v2, v30, v20
	v_lshlrev_b32_e32 v20, 16, v3
	v_div_fixup_f32 v24, v2, v24, v27
	v_and_b32_e32 v27, 0xffff0000, v3
	v_mul_f32_e32 v2, 0xbfb8aa3b, v20
	v_exp_f32_e32 v28, v2
	v_mul_f32_e32 v2, 0xbfb8aa3b, v27
	v_exp_f32_e32 v29, v2
	v_pk_mul_f32 v[2:3], v[24:25], v[12:13]
	v_lshlrev_b32_e32 v12, 16, v21
	v_cvt_pk_bf16_f32 v2, v2, v3
	v_pk_add_f32 v[24:25], v[28:29], 1.0 op_sel_hi:[1,0]
	v_and_b32_e32 v13, 0xffff0000, v21
	v_div_scale_f32 v3, s[6:7], v25, v25, v27
	v_rcp_f32_e32 v28, v3
	v_pk_mul_f32 v[12:13], v[26:27], v[12:13] op_sel_hi:[0,1]
	v_pk_mul_f32 v[12:13], v[14:15], v[12:13]
	v_fma_f32 v14, -v3, v28, 1.0
	v_fmac_f32_e32 v28, v14, v28
	v_div_scale_f32 v14, vcc, v27, v25, v27
	v_mul_f32_e32 v15, v14, v28
	v_fma_f32 v21, -v3, v15, v14
	v_fmac_f32_e32 v15, v21, v28
	v_fma_f32 v3, -v3, v15, v14
	v_div_scale_f32 v14, s[6:7], v24, v24, v20
	v_rcp_f32_e32 v21, v14
	v_div_fmas_f32 v3, v3, v28, v15
	v_div_fixup_f32 v15, v3, v25, v27
	v_fma_f32 v3, -v14, v21, 1.0
	v_fmac_f32_e32 v21, v3, v21
	v_div_scale_f32 v3, vcc, v20, v24, v20
	v_mul_f32_e32 v25, v3, v21
	v_fma_f32 v27, -v14, v25, v3
	v_fmac_f32_e32 v25, v27, v21
	v_fma_f32 v3, -v14, v25, v3
	v_div_fmas_f32 v3, v3, v21, v25
	v_div_fixup_f32 v14, v3, v24, v20
	v_lshlrev_b32_e32 v24, 16, v4
	v_and_b32_e32 v4, 0xffff0000, v4
	v_mul_f32_e32 v3, 0xbfb8aa3b, v24
	v_exp_f32_e32 v20, v3
	v_mul_f32_e32 v3, 0xbfb8aa3b, v4
	v_exp_f32_e32 v21, v3
	v_pk_mul_f32 v[12:13], v[14:15], v[12:13]
	v_pk_add_f32 v[14:15], v[20:21], 1.0 op_sel_hi:[1,0]
	s_nop 0
	v_div_scale_f32 v20, s[6:7], v15, v15, v4
	v_rcp_f32_e32 v21, v20
	v_cvt_pk_bf16_f32 v3, v12, v13
	v_lshlrev_b32_e32 v12, 16, v22
	v_and_b32_e32 v13, 0xffff0000, v22
	v_pk_mul_f32 v[12:13], v[26:27], v[12:13] op_sel_hi:[0,1]
	s_waitcnt vmcnt(0)
	v_pk_mul_f32 v[12:13], v[16:17], v[12:13]
	v_fma_f32 v16, -v20, v21, 1.0
	v_fmac_f32_e32 v21, v16, v21
	v_div_scale_f32 v16, vcc, v4, v15, v4
	v_mul_f32_e32 v17, v16, v21
	v_fma_f32 v22, -v20, v17, v16
	v_fmac_f32_e32 v17, v22, v21
	v_fma_f32 v16, -v20, v17, v16
	v_div_scale_f32 v20, s[6:7], v14, v14, v24
	v_rcp_f32_e32 v22, v20
	v_div_fmas_f32 v16, v16, v21, v17
	v_div_fixup_f32 v15, v16, v15, v4
	v_and_b32_e32 v21, 0xffff0000, v5
	v_fma_f32 v4, -v20, v22, 1.0
	v_fmac_f32_e32 v22, v4, v22
	v_div_scale_f32 v4, vcc, v24, v14, v24
	v_mul_f32_e32 v16, v4, v22
	v_fma_f32 v17, -v20, v16, v4
	v_fmac_f32_e32 v16, v17, v22
	v_fma_f32 v4, -v20, v16, v4
	v_div_fmas_f32 v4, v4, v22, v16
	v_lshlrev_b32_e32 v20, 16, v5
	v_div_fixup_f32 v14, v4, v14, v24
	v_mul_f32_e32 v4, 0xbfb8aa3b, v20
	v_exp_f32_e32 v16, v4
	v_mul_f32_e32 v4, 0xbfb8aa3b, v21
	v_exp_f32_e32 v17, v4
	v_pk_mul_f32 v[4:5], v[14:15], v[12:13]
	v_lshlrev_b32_e32 v12, 16, v23
	v_cvt_pk_bf16_f32 v4, v4, v5
	v_pk_add_f32 v[14:15], v[16:17], 1.0 op_sel_hi:[1,0]
	v_and_b32_e32 v13, 0xffff0000, v23
	v_div_scale_f32 v5, s[6:7], v15, v15, v21
	v_rcp_f32_e32 v16, v5
	v_pk_mul_f32 v[12:13], v[26:27], v[12:13] op_sel_hi:[0,1]
	v_pk_mul_f32 v[12:13], v[18:19], v[12:13]
	v_fma_f32 v17, -v5, v16, 1.0
	v_fmac_f32_e32 v16, v17, v16
	v_div_scale_f32 v17, vcc, v21, v15, v21
	v_mul_f32_e32 v18, v17, v16
	v_fma_f32 v19, -v5, v18, v17
	v_fmac_f32_e32 v18, v19, v16
	v_fma_f32 v5, -v5, v18, v17
	v_div_scale_f32 v17, s[6:7], v14, v14, v20
	v_rcp_f32_e32 v19, v17
	v_div_fmas_f32 v5, v5, v16, v18
	v_div_fixup_f32 v15, v5, v15, v21
	v_fma_f32 v5, -v17, v19, 1.0
	v_fmac_f32_e32 v19, v5, v19
	v_div_scale_f32 v5, vcc, v20, v14, v20
	v_mul_f32_e32 v16, v5, v19
	v_fma_f32 v18, -v17, v16, v5
	v_fmac_f32_e32 v16, v18, v19
	v_fma_f32 v5, -v17, v16, v5
	v_div_fmas_f32 v5, v5, v19, v16
	v_div_fixup_f32 v14, v5, v14, v20
	v_pk_mul_f32 v[12:13], v[14:15], v[12:13]
	s_nop 0
	v_cvt_pk_bf16_f32 v5, v12, v13
	global_store_dwordx4 v[0:1], v[2:5], off sc1
	v_ashrrev_i32_e32 v0, 3, v232
	v_add_u32_e32 v0, v0, v233
	v_mul_lo_u32 v1, v0, 48
	v_sub_u32_e32 v12, v231, v1
	v_ashrrev_i32_e32 v1, 31, v0
	v_lshl_add_u64 v[20:21], s[12:13], 0, v[0:1]
	v_mad_u64_u32 v[4:5], s[6:7], v20, s70, v[8:9]
	v_mov_b32_e32 v6, v5
	v_lshlrev_b32_e32 v2, 3, v12
	v_mad_u64_u32 v[6:7], s[6:7], v21, s70, v[6:7]
	v_mov_b32_e32 v5, v6
	v_ashrrev_i32_e32 v3, 31, v2
	v_lshl_add_u64 v[4:5], v[4:5], 0, s[56:57]
	v_lshlrev_b64 v[22:23], 1, v[2:3]
	v_lshl_add_u64 v[4:5], v[4:5], 0, v[22:23]
	v_add_co_u32_e32 v4, vcc, s80, v4
	v_lshl_add_u32 v13, v0, 2, 0
	s_nop 0
	v_addc_co_u32_e32 v5, vcc, 0, v5, vcc
	global_load_dwordx4 v[4:7], v[4:5], off offset:3072 nt
	v_mul_lo_u32 v14, v0, s79
	v_lshlrev_b32_e32 v12, 4, v12
	v_add3_u32 v12, v13, v14, v12
	ds_read2st64_b32 v[24:25], v13 offset0:16 offset1:17
	ds_read2st64_b32 v[26:27], v13 offset0:18 offset1:19
	ds_read_b128 v[12:15], v12 offset:63488
	v_lshl_add_u64 v[16:17], v[2:3], 2, s[18:19]
	s_waitcnt lgkmcnt(0)
	v_lshlrev_b32_e32 v30, 16, v12
	v_and_b32_e32 v31, 0xffff0000, v12
	s_waitcnt vmcnt(0)
	v_lshlrev_b32_e32 v32, 16, v4
	v_and_b32_e32 v4, 0xffff0000, v4
	v_mul_f32_e32 v0, 0xbfb8aa3b, v32
	v_mul_f32_e32 v1, 0xbfb8aa3b, v4
	v_exp_f32_e32 v0, v0
	v_exp_f32_e32 v1, v1
	v_lshlrev_b32_e32 v37, 16, v5
	v_lshlrev_b32_e32 v40, 16, v6
	v_and_b32_e32 v6, 0xffff0000, v6
	v_pk_add_f32 v[28:29], v[0:1], 1.0 op_sel_hi:[1,0]
	global_load_dwordx4 v[0:3], v[16:17], off offset:16
	s_nop 0
	global_load_dwordx4 v[16:19], v[16:17], off
	v_div_scale_f32 v33, s[6:7], v29, v29, v4
	v_rcp_f32_e32 v34, v33
	v_lshlrev_b32_e32 v41, 16, v7
	v_and_b32_e32 v7, 0xffff0000, v7
	v_fma_f32 v12, -v33, v34, 1.0
	v_fmac_f32_e32 v34, v12, v34
	v_div_scale_f32 v12, vcc, v4, v29, v4
	v_mul_f32_e32 v35, v12, v34
	v_fma_f32 v36, -v33, v35, v12
	v_fmac_f32_e32 v35, v36, v34
	v_fma_f32 v12, -v33, v35, v12
	v_div_scale_f32 v33, s[6:7], v28, v28, v32
	v_rcp_f32_e32 v36, v33
	v_div_fmas_f32 v12, v12, v34, v35
	v_div_fixup_f32 v29, v12, v29, v4
	v_div_scale_f32 v12, vcc, v32, v28, v32
	v_fma_f32 v4, -v33, v36, 1.0
	v_fmac_f32_e32 v36, v4, v36
	v_mul_f32_e32 v34, v12, v36
	v_fma_f32 v4, -v33, v34, v12
	v_and_b32_e32 v35, 0xffff0000, v5
	v_fmac_f32_e32 v34, v4, v36
	v_mul_f32_e32 v4, 0xbfb8aa3b, v37
	v_mul_f32_e32 v5, 0xbfb8aa3b, v35
	v_exp_f32_e32 v4, v4
	v_exp_f32_e32 v5, v5
	v_fma_f32 v12, -v33, v34, v12
	v_div_fmas_f32 v12, v12, v36, v34
	v_div_fixup_f32 v28, v12, v28, v32
	v_pk_add_f32 v[4:5], v[4:5], 1.0 op_sel_hi:[1,0]
	v_lshlrev_b32_e32 v12, 16, v13
	v_div_scale_f32 v33, s[6:7], v5, v5, v35
	v_rcp_f32_e32 v34, v33
	v_and_b32_e32 v13, 0xffff0000, v13
	v_fma_f32 v32, -v33, v34, 1.0
	v_fmac_f32_e32 v34, v32, v34
	v_div_scale_f32 v32, vcc, v35, v5, v35
	v_mul_f32_e32 v36, v32, v34
	v_fma_f32 v38, -v33, v36, v32
	v_fmac_f32_e32 v36, v38, v34
	v_div_scale_f32 v38, s[6:7], v4, v4, v37
	v_rcp_f32_e32 v39, v38
	v_fma_f32 v32, -v33, v36, v32
	v_div_fmas_f32 v32, v32, v34, v36
	v_div_fixup_f32 v33, v32, v5, v35
	v_fma_f32 v5, -v38, v39, 1.0
	v_fmac_f32_e32 v39, v5, v39
	v_div_scale_f32 v5, vcc, v37, v4, v37
	v_mul_f32_e32 v32, v5, v39
	v_fma_f32 v34, -v38, v32, v5
	v_fmac_f32_e32 v32, v34, v39
	v_mul_f32_e32 v34, 0xbfb8aa3b, v40
	v_mul_f32_e32 v35, 0xbfb8aa3b, v6
	v_exp_f32_e32 v34, v34
	v_exp_f32_e32 v35, v35
	v_fma_f32 v5, -v38, v32, v5
	v_div_fmas_f32 v5, v5, v39, v32
	v_div_fixup_f32 v32, v5, v4, v37
	v_pk_add_f32 v[34:35], v[34:35], 1.0 op_sel_hi:[1,0]
	v_lshlrev_b32_e32 v36, 16, v14
	v_div_scale_f32 v38, s[6:7], v35, v35, v6
	v_rcp_f32_e32 v39, v38
	v_and_b32_e32 v37, 0xffff0000, v14
	v_fma_f32 v4, -v38, v39, 1.0
	v_fmac_f32_e32 v39, v4, v39
	v_div_scale_f32 v4, vcc, v6, v35, v6
	v_mul_f32_e32 v5, v4, v39
	v_fma_f32 v14, -v38, v5, v4
	v_fmac_f32_e32 v5, v14, v39
	v_div_scale_f32 v14, s[6:7], v34, v34, v40
	v_fma_f32 v4, -v38, v5, v4
	v_rcp_f32_e32 v38, v14
	v_div_fmas_f32 v4, v4, v39, v5
	v_div_fixup_f32 v35, v4, v35, v6
	v_div_scale_f32 v6, vcc, v40, v34, v40
	v_fma_f32 v4, -v14, v38, 1.0
	v_fmac_f32_e32 v38, v4, v38
	v_mul_f32_e32 v39, v6, v38
	v_fma_f32 v4, -v14, v39, v6
	v_fmac_f32_e32 v39, v4, v38
	v_mul_f32_e32 v4, 0xbfb8aa3b, v41
	v_mul_f32_e32 v5, 0xbfb8aa3b, v7
	v_exp_f32_e32 v4, v4
	v_exp_f32_e32 v5, v5
	v_fma_f32 v6, -v14, v39, v6
	v_div_fmas_f32 v6, v6, v38, v39
	v_div_fixup_f32 v34, v6, v34, v40
	v_pk_add_f32 v[4:5], v[4:5], 1.0 op_sel_hi:[1,0]
	v_lshlrev_b32_e32 v14, 16, v15
	v_div_scale_f32 v38, s[6:7], v5, v5, v7
	v_rcp_f32_e32 v39, v38
	v_and_b32_e32 v15, 0xffff0000, v15
	v_fma_f32 v6, -v38, v39, 1.0
	v_fmac_f32_e32 v39, v6, v39
	v_div_scale_f32 v6, vcc, v7, v5, v7
	v_mul_f32_e32 v40, v6, v39
	v_fma_f32 v42, -v38, v40, v6
	v_fmac_f32_e32 v40, v42, v39
	v_fma_f32 v6, -v38, v40, v6
	v_div_scale_f32 v38, s[6:7], v4, v4, v41
	v_rcp_f32_e32 v42, v38
	v_div_fmas_f32 v6, v6, v39, v40
	v_div_fixup_f32 v39, v6, v5, v7
	v_fma_f32 v5, -v38, v42, 1.0
	v_fmac_f32_e32 v42, v5, v42
	v_div_scale_f32 v5, vcc, v41, v4, v41
	v_mul_f32_e32 v6, v5, v42
	v_fma_f32 v7, -v38, v6, v5
	v_fmac_f32_e32 v6, v7, v42
	v_fma_f32 v5, -v38, v6, v5
	v_div_fmas_f32 v5, v5, v42, v6
	v_div_fixup_f32 v38, v5, v4, v41
	v_lshlrev_b64 v[4:5], 12, v[20:21]
	v_add_u32_e32 v21, 0x600, v230
	v_mul_hi_i32 v6, v21, s74
	v_lshrrev_b32_e32 v7, 31, v6
	v_ashrrev_i32_e32 v6, 3, v6
	v_add_u32_e32 v20, v6, v7
	v_lshl_add_u32 v42, v20, 2, 0
	ds_read2st64_b32 v[6:7], v42 offset0:16 offset1:17
	v_lshl_add_u64 v[4:5], s[16:17], 0, v[4:5]
	v_lshl_add_u64 v[22:23], v[4:5], 0, v[22:23]
	ds_read2st64_b32 v[4:5], v42 offset0:18 offset1:19
	v_mov_b32_e32 v41, v24
	s_waitcnt lgkmcnt(1)
	v_mov_b32_e32 v40, v6
	v_mov_b32_e32 v24, v7
	v_pk_add_f32 v[6:7], v[40:41], v[24:25]
	s_waitcnt lgkmcnt(0)
	v_mov_b32_e32 v24, v4
	v_mov_b32_e32 v25, v26
	v_pk_add_f32 v[6:7], v[6:7], v[24:25]
	v_mov_b32_e32 v26, v5
	v_pk_add_f32 v[4:5], v[6:7], v[26:27]
	v_mul_lo_u32 v43, v20, 48
	v_pk_fma_f32 v[24:25], v[4:5], s[64:65], v[10:11] op_sel_hi:[1,0,0]
	s_nop 0
	v_mul_f32_e32 v4, 0x4b800000, v25
	v_cmp_gt_f32_e32 vcc, s81, v25
	s_nop 1
	v_cndmask_b32_e32 v4, v25, v4, vcc
	v_rsq_f32_e32 v4, v4
	v_sub_u32_e32 v25, v21, v43
	v_ashrrev_i32_e32 v21, 31, v20
	v_lshlrev_b32_e32 v26, 3, v25
	v_mul_f32_e32 v5, 0x45800000, v4
	v_cndmask_b32_e32 v40, v4, v5, vcc
	v_pk_mul_f32 v[4:5], v[40:41], v[30:31] op_sel_hi:[0,1]
	v_pk_mul_f32 v[6:7], v[40:41], v[12:13] op_sel_hi:[0,1]
	s_waitcnt vmcnt(0)
	v_pk_mul_f32 v[4:5], v[16:17], v[4:5]
	v_pk_mul_f32 v[6:7], v[18:19], v[6:7]
	v_pk_mul_f32 v[4:5], v[28:29], v[4:5]
	v_pk_mul_f32 v[6:7], v[32:33], v[6:7]
	v_cvt_pk_bf16_f32 v4, v4, v5
	v_cvt_pk_bf16_f32 v5, v6, v7
	v_pk_mul_f32 v[6:7], v[40:41], v[36:37] op_sel_hi:[0,1]
	v_pk_mul_f32 v[0:1], v[0:1], v[6:7]
	v_ashrrev_i32_e32 v27, 31, v26
	v_pk_mul_f32 v[0:1], v[34:35], v[0:1]
	v_lshl_add_u64 v[16:17], v[26:27], 2, s[18:19]
	v_cvt_pk_bf16_f32 v6, v0, v1
	v_pk_mul_f32 v[0:1], v[40:41], v[14:15] op_sel_hi:[0,1]
	v_pk_mul_f32 v[0:1], v[2:3], v[0:1]
	s_nop 0
	v_pk_mul_f32 v[0:1], v[38:39], v[0:1]
	s_nop 0
	v_cvt_pk_bf16_f32 v7, v0, v1
	v_lshl_add_u64 v[0:1], s[12:13], 0, v[20:21]
	v_mad_u64_u32 v[2:3], s[6:7], v0, s70, v[8:9]
	global_store_dwordx4 v[22:23], v[4:7], off sc1
	v_mul_f32_e32 v21, 0x4b800000, v24
	v_mul_lo_u32 v20, v20, s79
	v_mov_b32_e32 v4, v3
	v_mad_u64_u32 v[4:5], s[6:7], v1, s70, v[4:5]
	v_mov_b32_e32 v3, v4
	v_lshl_add_u64 v[2:3], v[2:3], 0, s[56:57]
	v_lshlrev_b64 v[6:7], 1, v[26:27]
	v_lshl_add_u64 v[2:3], v[2:3], 0, v[6:7]
	v_add_co_u32_e32 v2, vcc, s80, v2
	v_lshlrev_b64 v[0:1], 12, v[0:1]
	s_nop 0
	v_addc_co_u32_e32 v3, vcc, 0, v3, vcc
	global_load_dwordx4 v[2:5], v[2:3], off offset:3072 nt
	s_nop 0
	global_load_dwordx4 v[12:15], v[16:17], off
	s_nop 0
	global_load_dwordx4 v[16:19], v[16:17], off offset:16
	v_cmp_gt_f32_e32 vcc, s81, v24
	v_lshl_add_u64 v[0:1], s[16:17], 0, v[0:1]
	v_lshl_add_u64 v[0:1], v[0:1], 0, v[6:7]
	v_cndmask_b32_e32 v21, v24, v21, vcc
	v_rsq_f32_e32 v26, v21
	v_lshlrev_b32_e32 v21, 4, v25
	v_add3_u32 v20, v42, v20, v21
	ds_read_b128 v[20:23], v20 offset:63488
	v_mul_f32_e32 v28, 0x45800000, v26
	v_cndmask_b32_e32 v26, v26, v28, vcc
	s_waitcnt lgkmcnt(0)
	v_lshlrev_b32_e32 v28, 16, v20
	v_and_b32_e32 v29, 0xffff0000, v20
	s_waitcnt vmcnt(2)
	v_lshlrev_b32_e32 v27, 16, v2
	v_and_b32_e32 v2, 0xffff0000, v2
	v_mul_f32_e32 v24, 0xbfb8aa3b, v27
	v_mul_f32_e32 v25, 0xbfb8aa3b, v2
	v_exp_f32_e32 v24, v24
	v_exp_f32_e32 v25, v25
	v_pk_mul_f32 v[28:29], v[26:27], v[28:29] op_sel_hi:[0,1]
	s_waitcnt vmcnt(1)
	v_pk_mul_f32 v[12:13], v[12:13], v[28:29]
	v_pk_add_f32 v[24:25], v[24:25], 1.0 op_sel_hi:[1,0]
	s_nop 0
	v_div_scale_f32 v30, s[6:7], v25, v25, v2
	v_rcp_f32_e32 v31, v30
	s_nop 0
	v_fma_f32 v20, -v30, v31, 1.0
	v_fmac_f32_e32 v31, v20, v31
	v_div_scale_f32 v20, vcc, v2, v25, v2
	v_mul_f32_e32 v28, v20, v31
	v_fma_f32 v29, -v30, v28, v20
	v_fmac_f32_e32 v28, v29, v31
	v_div_scale_f32 v29, s[6:7], v24, v24, v27
	v_fma_f32 v20, -v30, v28, v20
	v_rcp_f32_e32 v30, v29
	v_div_fmas_f32 v20, v20, v31, v28
	v_div_fixup_f32 v25, v20, v25, v2
	v_fma_f32 v2, -v29, v30, 1.0
	v_fmac_f32_e32 v30, v2, v30
	v_div_scale_f32 v2, vcc, v27, v24, v27
	v_mul_f32_e32 v20, v2, v30
	v_fma_f32 v28, -v29, v20, v2
	v_fmac_f32_e32 v20, v28, v30
	v_fma_f32 v2, -v29, v20, v2
	v_div_fmas_f32 v2, v2, v30, v20
	v_lshlrev_b32_e32 v20, 16, v3
	v_div_fixup_f32 v24, v2, v24, v27
	v_and_b32_e32 v27, 0xffff0000, v3
	v_mul_f32_e32 v2, 0xbfb8aa3b, v20
	v_exp_f32_e32 v28, v2
	v_mul_f32_e32 v2, 0xbfb8aa3b, v27
	v_exp_f32_e32 v29, v2
	v_pk_mul_f32 v[2:3], v[24:25], v[12:13]
	v_lshlrev_b32_e32 v12, 16, v21
	v_cvt_pk_bf16_f32 v2, v2, v3
	v_pk_add_f32 v[24:25], v[28:29], 1.0 op_sel_hi:[1,0]
	v_and_b32_e32 v13, 0xffff0000, v21
	v_div_scale_f32 v3, s[6:7], v25, v25, v27
	v_rcp_f32_e32 v28, v3
	v_pk_mul_f32 v[12:13], v[26:27], v[12:13] op_sel_hi:[0,1]
	v_pk_mul_f32 v[12:13], v[14:15], v[12:13]
	v_fma_f32 v14, -v3, v28, 1.0
	v_fmac_f32_e32 v28, v14, v28
	v_div_scale_f32 v14, vcc, v27, v25, v27
	v_mul_f32_e32 v15, v14, v28
	v_fma_f32 v21, -v3, v15, v14
	v_fmac_f32_e32 v15, v21, v28
	v_fma_f32 v3, -v3, v15, v14
	v_div_scale_f32 v14, s[6:7], v24, v24, v20
	v_rcp_f32_e32 v21, v14
	v_div_fmas_f32 v3, v3, v28, v15
	v_div_fixup_f32 v15, v3, v25, v27
	v_fma_f32 v3, -v14, v21, 1.0
	v_fmac_f32_e32 v21, v3, v21
	v_div_scale_f32 v3, vcc, v20, v24, v20
	v_mul_f32_e32 v25, v3, v21
	v_fma_f32 v27, -v14, v25, v3
	v_fmac_f32_e32 v25, v27, v21
	v_fma_f32 v3, -v14, v25, v3
	v_div_fmas_f32 v3, v3, v21, v25
	v_div_fixup_f32 v14, v3, v24, v20
	v_lshlrev_b32_e32 v24, 16, v4
	v_and_b32_e32 v4, 0xffff0000, v4
	v_mul_f32_e32 v3, 0xbfb8aa3b, v24
	v_exp_f32_e32 v20, v3
	v_mul_f32_e32 v3, 0xbfb8aa3b, v4
	v_exp_f32_e32 v21, v3
	v_pk_mul_f32 v[12:13], v[14:15], v[12:13]
	v_pk_add_f32 v[14:15], v[20:21], 1.0 op_sel_hi:[1,0]
	s_nop 0
	v_div_scale_f32 v20, s[6:7], v15, v15, v4
	v_rcp_f32_e32 v21, v20
	v_cvt_pk_bf16_f32 v3, v12, v13
	v_lshlrev_b32_e32 v12, 16, v22
	v_and_b32_e32 v13, 0xffff0000, v22
	v_pk_mul_f32 v[12:13], v[26:27], v[12:13] op_sel_hi:[0,1]
	s_waitcnt vmcnt(0)
	v_pk_mul_f32 v[12:13], v[16:17], v[12:13]
	v_fma_f32 v16, -v20, v21, 1.0
	v_fmac_f32_e32 v21, v16, v21
	v_div_scale_f32 v16, vcc, v4, v15, v4
	v_mul_f32_e32 v17, v16, v21
	v_fma_f32 v22, -v20, v17, v16
	v_fmac_f32_e32 v17, v22, v21
	v_fma_f32 v16, -v20, v17, v16
	v_div_scale_f32 v20, s[6:7], v14, v14, v24
	v_rcp_f32_e32 v22, v20
	v_div_fmas_f32 v16, v16, v21, v17
	v_div_fixup_f32 v15, v16, v15, v4
	v_and_b32_e32 v21, 0xffff0000, v5
	v_fma_f32 v4, -v20, v22, 1.0
	v_fmac_f32_e32 v22, v4, v22
	v_div_scale_f32 v4, vcc, v24, v14, v24
	v_mul_f32_e32 v16, v4, v22
	v_fma_f32 v17, -v20, v16, v4
	v_fmac_f32_e32 v16, v17, v22
	v_fma_f32 v4, -v20, v16, v4
	v_div_fmas_f32 v4, v4, v22, v16
	v_lshlrev_b32_e32 v20, 16, v5
	v_div_fixup_f32 v14, v4, v14, v24
	v_mul_f32_e32 v4, 0xbfb8aa3b, v20
	v_exp_f32_e32 v16, v4
	v_mul_f32_e32 v4, 0xbfb8aa3b, v21
	v_exp_f32_e32 v17, v4
	v_pk_mul_f32 v[4:5], v[14:15], v[12:13]
	v_lshlrev_b32_e32 v12, 16, v23
	v_cvt_pk_bf16_f32 v4, v4, v5
	v_pk_add_f32 v[14:15], v[16:17], 1.0 op_sel_hi:[1,0]
	v_and_b32_e32 v13, 0xffff0000, v23
	v_div_scale_f32 v5, s[6:7], v15, v15, v21
	v_rcp_f32_e32 v16, v5
	v_pk_mul_f32 v[12:13], v[26:27], v[12:13] op_sel_hi:[0,1]
	v_pk_mul_f32 v[12:13], v[18:19], v[12:13]
	v_fma_f32 v17, -v5, v16, 1.0
	v_fmac_f32_e32 v16, v17, v16
	v_div_scale_f32 v17, vcc, v21, v15, v21
	v_mul_f32_e32 v18, v17, v16
	v_fma_f32 v19, -v5, v18, v17
	v_fmac_f32_e32 v18, v19, v16
	v_fma_f32 v5, -v5, v18, v17
	v_div_scale_f32 v17, s[6:7], v14, v14, v20
	v_rcp_f32_e32 v19, v17
	v_div_fmas_f32 v5, v5, v16, v18
	v_div_fixup_f32 v15, v5, v15, v21
	v_fma_f32 v5, -v17, v19, 1.0
	v_fmac_f32_e32 v19, v5, v19
	v_div_scale_f32 v5, vcc, v20, v14, v20
	v_mul_f32_e32 v16, v5, v19
	v_fma_f32 v18, -v17, v16, v5
	v_fmac_f32_e32 v16, v18, v19
	v_fma_f32 v5, -v17, v16, v5
	v_div_fmas_f32 v5, v5, v19, v16
	v_div_fixup_f32 v14, v5, v14, v20
	v_pk_mul_f32 v[12:13], v[14:15], v[12:13]
	s_nop 0
	v_cvt_pk_bf16_f32 v5, v12, v13
	global_store_dwordx4 v[0:1], v[2:5], off sc1
	v_add_u32_e32 v1, 0x800, v230
	v_mul_hi_i32 v0, v1, s74
	v_lshrrev_b32_e32 v2, 31, v0
	v_ashrrev_i32_e32 v0, 3, v0
	v_add_u32_e32 v0, v0, v2
	v_mul_lo_u32 v2, v0, 48
	v_sub_u32_e32 v12, v1, v2
	v_ashrrev_i32_e32 v1, 31, v0
	v_lshl_add_u64 v[20:21], s[12:13], 0, v[0:1]
	v_mad_u64_u32 v[4:5], s[6:7], v20, s70, v[8:9]
	v_mov_b32_e32 v6, v5
	v_lshlrev_b32_e32 v2, 3, v12
	v_mad_u64_u32 v[6:7], s[6:7], v21, s70, v[6:7]
	v_mov_b32_e32 v5, v6
	v_ashrrev_i32_e32 v3, 31, v2
	v_lshl_add_u64 v[4:5], v[4:5], 0, s[56:57]
	v_lshlrev_b64 v[22:23], 1, v[2:3]
	v_lshl_add_u64 v[4:5], v[4:5], 0, v[22:23]
	v_add_co_u32_e32 v4, vcc, s80, v4
	v_lshl_add_u32 v13, v0, 2, 0
	s_nop 0
	v_addc_co_u32_e32 v5, vcc, 0, v5, vcc
	global_load_dwordx4 v[4:7], v[4:5], off offset:3072 nt
	v_mul_lo_u32 v14, v0, s79
	v_lshlrev_b32_e32 v12, 4, v12
	v_add3_u32 v12, v13, v14, v12
	ds_read2st64_b32 v[24:25], v13 offset0:16 offset1:17
	ds_read2st64_b32 v[26:27], v13 offset0:18 offset1:19
	ds_read_b128 v[12:15], v12 offset:63488
	v_lshl_add_u64 v[16:17], v[2:3], 2, s[18:19]
	s_waitcnt lgkmcnt(0)
	v_lshlrev_b32_e32 v30, 16, v12
	v_and_b32_e32 v31, 0xffff0000, v12
	s_waitcnt vmcnt(0)
	v_lshlrev_b32_e32 v32, 16, v4
	v_and_b32_e32 v4, 0xffff0000, v4
	v_mul_f32_e32 v0, 0xbfb8aa3b, v32
	v_mul_f32_e32 v1, 0xbfb8aa3b, v4
	v_exp_f32_e32 v0, v0
	v_exp_f32_e32 v1, v1
	v_lshlrev_b32_e32 v37, 16, v5
	v_lshlrev_b32_e32 v40, 16, v6
	v_and_b32_e32 v6, 0xffff0000, v6
	v_pk_add_f32 v[28:29], v[0:1], 1.0 op_sel_hi:[1,0]
	global_load_dwordx4 v[0:3], v[16:17], off offset:16
	s_nop 0
	global_load_dwordx4 v[16:19], v[16:17], off
	v_div_scale_f32 v33, s[6:7], v29, v29, v4
	v_rcp_f32_e32 v34, v33
	v_lshlrev_b32_e32 v41, 16, v7
	v_and_b32_e32 v7, 0xffff0000, v7
	v_fma_f32 v12, -v33, v34, 1.0
	v_fmac_f32_e32 v34, v12, v34
	v_div_scale_f32 v12, vcc, v4, v29, v4
	v_mul_f32_e32 v35, v12, v34
	v_fma_f32 v36, -v33, v35, v12
	v_fmac_f32_e32 v35, v36, v34
	v_fma_f32 v12, -v33, v35, v12
	v_div_scale_f32 v33, s[6:7], v28, v28, v32
	v_rcp_f32_e32 v36, v33
	v_div_fmas_f32 v12, v12, v34, v35
	v_div_fixup_f32 v29, v12, v29, v4
	v_div_scale_f32 v12, vcc, v32, v28, v32
	v_fma_f32 v4, -v33, v36, 1.0
	v_fmac_f32_e32 v36, v4, v36
	v_mul_f32_e32 v34, v12, v36
	v_fma_f32 v4, -v33, v34, v12
	v_and_b32_e32 v35, 0xffff0000, v5
	v_fmac_f32_e32 v34, v4, v36
	v_mul_f32_e32 v4, 0xbfb8aa3b, v37
	v_mul_f32_e32 v5, 0xbfb8aa3b, v35
	v_exp_f32_e32 v4, v4
	v_exp_f32_e32 v5, v5
	v_fma_f32 v12, -v33, v34, v12
	v_div_fmas_f32 v12, v12, v36, v34
	v_div_fixup_f32 v28, v12, v28, v32
	v_pk_add_f32 v[4:5], v[4:5], 1.0 op_sel_hi:[1,0]
	v_lshlrev_b32_e32 v12, 16, v13
	v_div_scale_f32 v33, s[6:7], v5, v5, v35
	v_rcp_f32_e32 v34, v33
	v_and_b32_e32 v13, 0xffff0000, v13
	v_fma_f32 v32, -v33, v34, 1.0
	v_fmac_f32_e32 v34, v32, v34
	v_div_scale_f32 v32, vcc, v35, v5, v35
	v_mul_f32_e32 v36, v32, v34
	v_fma_f32 v38, -v33, v36, v32
	v_fmac_f32_e32 v36, v38, v34
	v_div_scale_f32 v38, s[6:7], v4, v4, v37
	v_rcp_f32_e32 v39, v38
	v_fma_f32 v32, -v33, v36, v32
	v_div_fmas_f32 v32, v32, v34, v36
	v_div_fixup_f32 v33, v32, v5, v35
	v_fma_f32 v5, -v38, v39, 1.0
	v_fmac_f32_e32 v39, v5, v39
	v_div_scale_f32 v5, vcc, v37, v4, v37
	v_mul_f32_e32 v32, v5, v39
	v_fma_f32 v34, -v38, v32, v5
	v_fmac_f32_e32 v32, v34, v39
	v_mul_f32_e32 v34, 0xbfb8aa3b, v40
	v_mul_f32_e32 v35, 0xbfb8aa3b, v6
	v_exp_f32_e32 v34, v34
	v_exp_f32_e32 v35, v35
	v_fma_f32 v5, -v38, v32, v5
	v_div_fmas_f32 v5, v5, v39, v32
	v_div_fixup_f32 v32, v5, v4, v37
	v_pk_add_f32 v[34:35], v[34:35], 1.0 op_sel_hi:[1,0]
	v_lshlrev_b32_e32 v36, 16, v14
	v_div_scale_f32 v38, s[6:7], v35, v35, v6
	v_rcp_f32_e32 v39, v38
	v_and_b32_e32 v37, 0xffff0000, v14
	v_fma_f32 v4, -v38, v39, 1.0
	v_fmac_f32_e32 v39, v4, v39
	v_div_scale_f32 v4, vcc, v6, v35, v6
	v_mul_f32_e32 v5, v4, v39
	v_fma_f32 v14, -v38, v5, v4
	v_fmac_f32_e32 v5, v14, v39
	v_div_scale_f32 v14, s[6:7], v34, v34, v40
	v_fma_f32 v4, -v38, v5, v4
	v_rcp_f32_e32 v38, v14
	v_div_fmas_f32 v4, v4, v39, v5
	v_div_fixup_f32 v35, v4, v35, v6
	v_div_scale_f32 v6, vcc, v40, v34, v40
	v_fma_f32 v4, -v14, v38, 1.0
	v_fmac_f32_e32 v38, v4, v38
	v_mul_f32_e32 v39, v6, v38
	v_fma_f32 v4, -v14, v39, v6
	v_fmac_f32_e32 v39, v4, v38
	v_mul_f32_e32 v4, 0xbfb8aa3b, v41
	v_mul_f32_e32 v5, 0xbfb8aa3b, v7
	v_exp_f32_e32 v4, v4
	v_exp_f32_e32 v5, v5
	v_fma_f32 v6, -v14, v39, v6
	v_div_fmas_f32 v6, v6, v38, v39
	v_div_fixup_f32 v34, v6, v34, v40
	v_pk_add_f32 v[4:5], v[4:5], 1.0 op_sel_hi:[1,0]
	v_lshlrev_b32_e32 v14, 16, v15
	v_div_scale_f32 v38, s[6:7], v5, v5, v7
	v_rcp_f32_e32 v39, v38
	v_and_b32_e32 v15, 0xffff0000, v15
	v_fma_f32 v6, -v38, v39, 1.0
	v_fmac_f32_e32 v39, v6, v39
	v_div_scale_f32 v6, vcc, v7, v5, v7
	v_mul_f32_e32 v40, v6, v39
	v_fma_f32 v42, -v38, v40, v6
	v_fmac_f32_e32 v40, v42, v39
	v_fma_f32 v6, -v38, v40, v6
	v_div_scale_f32 v38, s[6:7], v4, v4, v41
	v_rcp_f32_e32 v42, v38
	v_div_fmas_f32 v6, v6, v39, v40
	v_div_fixup_f32 v39, v6, v5, v7
	v_fma_f32 v5, -v38, v42, 1.0
	v_fmac_f32_e32 v42, v5, v42
	v_div_scale_f32 v5, vcc, v41, v4, v41
	v_mul_f32_e32 v6, v5, v42
	v_fma_f32 v7, -v38, v6, v5
	v_fmac_f32_e32 v6, v7, v42
	v_fma_f32 v5, -v38, v6, v5
	v_div_fmas_f32 v5, v5, v42, v6
	v_div_fixup_f32 v38, v5, v4, v41
	v_lshlrev_b64 v[4:5], 12, v[20:21]
	v_add_u32_e32 v21, 0xa00, v230
	v_mul_hi_i32 v6, v21, s74
	v_lshrrev_b32_e32 v7, 31, v6
	v_ashrrev_i32_e32 v6, 3, v6
	v_add_u32_e32 v20, v6, v7
	v_lshl_add_u32 v42, v20, 2, 0
	ds_read2st64_b32 v[6:7], v42 offset0:16 offset1:17
	v_lshl_add_u64 v[4:5], s[16:17], 0, v[4:5]
	v_lshl_add_u64 v[22:23], v[4:5], 0, v[22:23]
	ds_read2st64_b32 v[4:5], v42 offset0:18 offset1:19
	v_mov_b32_e32 v41, v24
	s_waitcnt lgkmcnt(1)
	v_mov_b32_e32 v40, v6
	v_mov_b32_e32 v24, v7
	v_pk_add_f32 v[6:7], v[40:41], v[24:25]
	s_waitcnt lgkmcnt(0)
	v_mov_b32_e32 v24, v4
	v_mov_b32_e32 v25, v26
	v_pk_add_f32 v[6:7], v[6:7], v[24:25]
	v_mov_b32_e32 v26, v5
	v_pk_add_f32 v[4:5], v[6:7], v[26:27]
	v_mul_lo_u32 v43, v20, 48
	v_pk_fma_f32 v[24:25], v[4:5], s[64:65], v[10:11] op_sel_hi:[1,0,0]
	s_nop 0
	v_mul_f32_e32 v4, 0x4b800000, v25
	v_cmp_gt_f32_e32 vcc, s81, v25
	s_nop 1
	v_cndmask_b32_e32 v4, v25, v4, vcc
	v_rsq_f32_e32 v4, v4
	v_sub_u32_e32 v25, v21, v43
	v_ashrrev_i32_e32 v21, 31, v20
	v_lshlrev_b32_e32 v10, 3, v25
	v_mul_f32_e32 v5, 0x45800000, v4
	v_cndmask_b32_e32 v26, v4, v5, vcc
	v_pk_mul_f32 v[4:5], v[26:27], v[30:31] op_sel_hi:[0,1]
	v_pk_mul_f32 v[6:7], v[26:27], v[12:13] op_sel_hi:[0,1]
	s_waitcnt vmcnt(0)
	v_pk_mul_f32 v[4:5], v[16:17], v[4:5]
	v_pk_mul_f32 v[6:7], v[18:19], v[6:7]
	v_pk_mul_f32 v[4:5], v[28:29], v[4:5]
	v_pk_mul_f32 v[6:7], v[32:33], v[6:7]
	v_cvt_pk_bf16_f32 v4, v4, v5
	v_cvt_pk_bf16_f32 v5, v6, v7
	v_pk_mul_f32 v[6:7], v[26:27], v[36:37] op_sel_hi:[0,1]
	v_pk_mul_f32 v[0:1], v[0:1], v[6:7]
	v_ashrrev_i32_e32 v11, 31, v10
	v_pk_mul_f32 v[0:1], v[34:35], v[0:1]
	v_lshlrev_b64 v[18:19], 1, v[10:11]
	v_cvt_pk_bf16_f32 v6, v0, v1
	v_pk_mul_f32 v[0:1], v[26:27], v[14:15] op_sel_hi:[0,1]
	v_pk_mul_f32 v[0:1], v[2:3], v[0:1]
	v_lshl_add_u64 v[10:11], v[10:11], 2, s[18:19]
	v_pk_mul_f32 v[0:1], v[38:39], v[0:1]
	v_mul_f32_e32 v14, 0x4b800000, v24
	v_cvt_pk_bf16_f32 v7, v0, v1
	v_lshl_add_u64 v[0:1], s[12:13], 0, v[20:21]
	v_mad_u64_u32 v[2:3], s[6:7], v0, s70, v[8:9]
	global_store_dwordx4 v[22:23], v[4:7], off sc1
	v_lshlrev_b32_e32 v15, 4, v25
	s_nop 0
	v_mov_b32_e32 v4, v3
	v_mad_u64_u32 v[4:5], s[6:7], v1, s70, v[4:5]
	v_mov_b32_e32 v3, v4
	v_lshl_add_u64 v[2:3], v[2:3], 0, s[56:57]
	v_lshl_add_u64 v[2:3], v[2:3], 0, v[18:19]
	v_add_co_u32_e32 v2, vcc, s80, v2
	v_lshlrev_b64 v[0:1], 12, v[0:1]
	s_nop 0
	v_addc_co_u32_e32 v3, vcc, 0, v3, vcc
	global_load_dwordx4 v[2:5], v[2:3], off offset:3072 nt
	s_nop 0
	global_load_dwordx4 v[6:9], v[10:11], off
	s_nop 0
	global_load_dwordx4 v[10:13], v[10:11], off offset:16
	v_cmp_gt_f32_e32 vcc, s81, v24
	v_lshl_add_u64 v[0:1], s[16:17], 0, v[0:1]
	v_lshl_add_u64 v[0:1], v[0:1], 0, v[18:19]
	v_cndmask_b32_e32 v14, v24, v14, vcc
	v_rsq_f32_e32 v22, v14
	v_mul_lo_u32 v14, v20, s79
	v_add3_u32 v14, v42, v14, v15
	ds_read_b128 v[14:17], v14 offset:63488
	v_mul_f32_e32 v24, 0x45800000, v22
	v_cndmask_b32_e32 v22, v22, v24, vcc
	s_waitcnt lgkmcnt(0)
	v_lshlrev_b32_e32 v24, 16, v14
	v_and_b32_e32 v25, 0xffff0000, v14
	s_waitcnt vmcnt(2)
	v_lshlrev_b32_e32 v23, 16, v2
	v_and_b32_e32 v2, 0xffff0000, v2
	v_mul_f32_e32 v20, 0xbfb8aa3b, v23
	v_mul_f32_e32 v21, 0xbfb8aa3b, v2
	v_exp_f32_e32 v20, v20
	v_exp_f32_e32 v21, v21
	v_pk_mul_f32 v[24:25], v[22:23], v[24:25] op_sel_hi:[0,1]
	s_waitcnt vmcnt(1)
	v_pk_mul_f32 v[6:7], v[6:7], v[24:25]
	v_pk_add_f32 v[20:21], v[20:21], 1.0 op_sel_hi:[1,0]
	s_nop 0
	v_div_scale_f32 v26, s[6:7], v21, v21, v2
	v_rcp_f32_e32 v27, v26
	s_nop 0
	v_fma_f32 v14, -v26, v27, 1.0
	v_fmac_f32_e32 v27, v14, v27
	v_div_scale_f32 v14, vcc, v2, v21, v2
	v_mul_f32_e32 v24, v14, v27
	v_fma_f32 v25, -v26, v24, v14
	v_fmac_f32_e32 v24, v25, v27
	v_div_scale_f32 v25, s[6:7], v20, v20, v23
	v_fma_f32 v14, -v26, v24, v14
	v_rcp_f32_e32 v26, v25
	v_div_fmas_f32 v14, v14, v27, v24
	v_div_fixup_f32 v21, v14, v21, v2
	v_fma_f32 v2, -v25, v26, 1.0
	v_fmac_f32_e32 v26, v2, v26
	v_div_scale_f32 v2, vcc, v23, v20, v23
	v_mul_f32_e32 v14, v2, v26
	v_fma_f32 v24, -v25, v14, v2
	v_fmac_f32_e32 v14, v24, v26
	v_fma_f32 v2, -v25, v14, v2
	v_div_fmas_f32 v2, v2, v26, v14
	v_lshlrev_b32_e32 v14, 16, v3
	v_div_fixup_f32 v20, v2, v20, v23
	v_and_b32_e32 v23, 0xffff0000, v3
	v_mul_f32_e32 v2, 0xbfb8aa3b, v14
	v_exp_f32_e32 v24, v2
	v_mul_f32_e32 v2, 0xbfb8aa3b, v23
	v_exp_f32_e32 v25, v2
	v_pk_mul_f32 v[2:3], v[20:21], v[6:7]
	v_lshlrev_b32_e32 v6, 16, v15
	v_cvt_pk_bf16_f32 v2, v2, v3
	v_pk_add_f32 v[20:21], v[24:25], 1.0 op_sel_hi:[1,0]
	v_and_b32_e32 v7, 0xffff0000, v15
	v_div_scale_f32 v3, s[6:7], v21, v21, v23
	v_rcp_f32_e32 v24, v3
	v_pk_mul_f32 v[6:7], v[22:23], v[6:7] op_sel_hi:[0,1]
	v_pk_mul_f32 v[6:7], v[8:9], v[6:7]
	v_fma_f32 v8, -v3, v24, 1.0
	v_fmac_f32_e32 v24, v8, v24
	v_div_scale_f32 v8, vcc, v23, v21, v23
	v_mul_f32_e32 v9, v8, v24
	v_fma_f32 v15, -v3, v9, v8
	v_fmac_f32_e32 v9, v15, v24
	v_fma_f32 v3, -v3, v9, v8
	v_div_scale_f32 v8, s[6:7], v20, v20, v14
	v_rcp_f32_e32 v15, v8
	v_div_fmas_f32 v3, v3, v24, v9
	v_div_fixup_f32 v9, v3, v21, v23
	v_fma_f32 v3, -v8, v15, 1.0
	v_fmac_f32_e32 v15, v3, v15
	v_div_scale_f32 v3, vcc, v14, v20, v14
	v_mul_f32_e32 v21, v3, v15
	v_fma_f32 v23, -v8, v21, v3
	v_fmac_f32_e32 v21, v23, v15
	v_fma_f32 v3, -v8, v21, v3
	v_div_fmas_f32 v3, v3, v15, v21
	v_div_fixup_f32 v8, v3, v20, v14
	v_lshlrev_b32_e32 v20, 16, v4
	v_and_b32_e32 v4, 0xffff0000, v4
	v_mul_f32_e32 v3, 0xbfb8aa3b, v20
	v_exp_f32_e32 v14, v3
	v_mul_f32_e32 v3, 0xbfb8aa3b, v4
	v_exp_f32_e32 v15, v3
	v_pk_mul_f32 v[6:7], v[8:9], v[6:7]
	v_pk_add_f32 v[8:9], v[14:15], 1.0 op_sel_hi:[1,0]
	s_nop 0
	v_div_scale_f32 v14, s[6:7], v9, v9, v4
	v_rcp_f32_e32 v15, v14
	v_cvt_pk_bf16_f32 v3, v6, v7
	v_lshlrev_b32_e32 v6, 16, v16
	v_and_b32_e32 v7, 0xffff0000, v16
	v_pk_mul_f32 v[6:7], v[22:23], v[6:7] op_sel_hi:[0,1]
	s_waitcnt vmcnt(0)
	v_pk_mul_f32 v[6:7], v[10:11], v[6:7]
	v_fma_f32 v10, -v14, v15, 1.0
	v_fmac_f32_e32 v15, v10, v15
	v_div_scale_f32 v10, vcc, v4, v9, v4
	v_mul_f32_e32 v11, v10, v15
	v_fma_f32 v16, -v14, v11, v10
	v_fmac_f32_e32 v11, v16, v15
	v_fma_f32 v10, -v14, v11, v10
	v_div_scale_f32 v14, s[6:7], v8, v8, v20
	v_rcp_f32_e32 v16, v14
	v_div_fmas_f32 v10, v10, v15, v11
	v_div_fixup_f32 v9, v10, v9, v4
	v_and_b32_e32 v15, 0xffff0000, v5
	v_fma_f32 v4, -v14, v16, 1.0
	v_fmac_f32_e32 v16, v4, v16
	v_div_scale_f32 v4, vcc, v20, v8, v20
	v_mul_f32_e32 v10, v4, v16
	v_fma_f32 v11, -v14, v10, v4
	v_fmac_f32_e32 v10, v11, v16
	v_fma_f32 v4, -v14, v10, v4
	v_div_fmas_f32 v4, v4, v16, v10
	v_lshlrev_b32_e32 v14, 16, v5
	v_div_fixup_f32 v8, v4, v8, v20
	v_mul_f32_e32 v4, 0xbfb8aa3b, v14
	v_exp_f32_e32 v10, v4
	v_mul_f32_e32 v4, 0xbfb8aa3b, v15
	v_exp_f32_e32 v11, v4
	v_pk_mul_f32 v[4:5], v[8:9], v[6:7]
	v_lshlrev_b32_e32 v6, 16, v17
	v_cvt_pk_bf16_f32 v4, v4, v5
	v_pk_add_f32 v[8:9], v[10:11], 1.0 op_sel_hi:[1,0]
	v_and_b32_e32 v7, 0xffff0000, v17
	v_div_scale_f32 v5, s[6:7], v9, v9, v15
	v_rcp_f32_e32 v10, v5
	v_pk_mul_f32 v[6:7], v[22:23], v[6:7] op_sel_hi:[0,1]
	v_pk_mul_f32 v[6:7], v[12:13], v[6:7]
	v_fma_f32 v11, -v5, v10, 1.0
	v_fmac_f32_e32 v10, v11, v10
	v_div_scale_f32 v11, vcc, v15, v9, v15
	v_mul_f32_e32 v12, v11, v10
	v_fma_f32 v13, -v5, v12, v11
	v_fmac_f32_e32 v12, v13, v10
	v_fma_f32 v5, -v5, v12, v11
	v_div_scale_f32 v11, s[6:7], v8, v8, v14
	v_rcp_f32_e32 v13, v11
	v_div_fmas_f32 v5, v5, v10, v12
	v_div_fixup_f32 v9, v5, v9, v15
	v_fma_f32 v5, -v11, v13, 1.0
	v_fmac_f32_e32 v13, v5, v13
	v_div_scale_f32 v5, vcc, v14, v8, v14
	v_mul_f32_e32 v10, v5, v13
	v_fma_f32 v12, -v11, v10, v5
	v_fmac_f32_e32 v10, v12, v13
	v_fma_f32 v5, -v11, v10, v5
	v_div_fmas_f32 v5, v5, v13, v10
	v_div_fixup_f32 v8, v5, v8, v14
	v_pk_mul_f32 v[6:7], v[8:9], v[6:7]
	s_andn2_b64 vcc, exec, s[14:15]
	v_cvt_pk_bf16_f32 v5, v6, v7
	global_store_dwordx4 v[0:1], v[2:5], off sc1
	s_barrier
	s_cbranch_vccz .LBB0_628

.LBB0_694:
	ds_read_b128 v[150:153], v147
	ds_read_b128 v[154:157], v147 offset:1024
	ds_read_b128 v[158:161], v147 offset:2048
	ds_read_b128 v[162:165], v147 offset:3072
	s_add_u32 s33, s34, 0xfff80080
	s_addc_u32 s36, s35, -1
	s_cmp_eq_u32 s77, 28
	s_cselect_b32 s39, s27, s36
	s_cselect_b32 s38, s73, s33
	s_cselect_b32 s37, s25, s76
	s_cselect_b32 s36, s74, s75
	v_lshl_add_u64 v[198:199], s[34:35], 0, v[136:137]
	s_add_i32 m0, s23, 0xc000
	ds_read_b128 v[166:169], v148
	ds_read_b128 v[170:173], v148 offset:1024
	ds_read_b128 v[174:177], v148 offset:2048
	ds_read_b128 v[178:181], v148 offset:3072
	ds_read_b128 v[182:185], v148 offset:4096
	ds_read_b128 v[186:189], v148 offset:5120
	ds_read_b128 v[190:193], v148 offset:6144
	ds_read_b128 v[194:197], v148 offset:7168
	global_load_lds_dwordx4 v[198:199], off
	v_lshl_add_u64 v[198:199], s[34:35], 0, v[138:139]
	s_add_i32 m0, s23, 0xe000
	s_nop 0
	global_load_lds_dwordx4 v[198:199], off
	s_waitcnt lgkmcnt(8)
	s_barrier
	s_waitcnt lgkmcnt(0)
	s_setprio 1
	s_waitcnt lgkmcnt(0)
	v_mfma_f32_16x16x32_bf16 v[124:127], v[150:153], v[166:169], v[124:127]
	v_mfma_f32_16x16x32_bf16 v[120:123], v[158:161], v[166:169], v[120:123]
	v_mfma_f32_16x16x32_bf16 v[116:119], v[150:153], v[174:177], v[116:119]
	v_mfma_f32_16x16x32_bf16 v[112:115], v[158:161], v[174:177], v[112:115]
	v_mfma_f32_16x16x32_bf16 v[108:111], v[150:153], v[182:185], v[108:111]
	v_mfma_f32_16x16x32_bf16 v[104:107], v[158:161], v[182:185], v[104:107]
	v_mfma_f32_16x16x32_bf16 v[100:103], v[150:153], v[190:193], v[100:103]
	v_mfma_f32_16x16x32_bf16 v[96:99], v[158:161], v[190:193], v[96:99]
	v_mfma_f32_16x16x32_bf16 v[124:127], v[154:157], v[170:173], v[124:127]
	v_mfma_f32_16x16x32_bf16 v[120:123], v[162:165], v[170:173], v[120:123]
	v_mfma_f32_16x16x32_bf16 v[116:119], v[154:157], v[178:181], v[116:119]
	v_mfma_f32_16x16x32_bf16 v[112:115], v[162:165], v[178:181], v[112:115]
	v_mfma_f32_16x16x32_bf16 v[108:111], v[154:157], v[186:189], v[108:111]
	v_mfma_f32_16x16x32_bf16 v[104:107], v[162:165], v[186:189], v[104:107]
	v_mfma_f32_16x16x32_bf16 v[100:103], v[154:157], v[194:197], v[100:103]
	v_mfma_f32_16x16x32_bf16 v[96:99], v[162:165], v[194:197], v[96:99]
	s_setprio 0
	s_barrier
	s_add_i32 s33, s66, s56
	v_lshl_add_u64 v[210:211], s[36:37], 0, v[130:131]
	s_mov_b32 m0, s33
	ds_read_b128 v[198:201], v149
	ds_read_b128 v[202:205], v149 offset:1024
	ds_read_b128 v[206:209], v149 offset:2048
	ds_read_b128 v[216:219], v149 offset:3072
	global_load_lds_dwordx4 v[210:211], off
	v_lshl_add_u64 v[220:221], s[36:37], 0, v[134:135]
	s_add_i32 m0, s33, 0x2000
	s_nop 0
	global_load_lds_dwordx4 v[220:221], off
	s_barrier
	s_waitcnt lgkmcnt(0)
	s_setprio 1
	s_waitcnt lgkmcnt(0)
	v_mfma_f32_16x16x32_bf16 v[80:83], v[198:201], v[166:169], v[80:83]
	v_mfma_f32_16x16x32_bf16 v[72:75], v[206:209], v[166:169], v[72:75]
	v_mfma_f32_16x16x32_bf16 v[68:71], v[198:201], v[174:177], v[68:71]
	v_mfma_f32_16x16x32_bf16 v[60:63], v[206:209], v[174:177], v[60:63]
	v_mfma_f32_16x16x32_bf16 v[52:55], v[198:201], v[182:185], v[52:55]
	v_mfma_f32_16x16x32_bf16 v[48:51], v[206:209], v[182:185], v[48:51]
	v_mfma_f32_16x16x32_bf16 v[36:39], v[198:201], v[190:193], v[36:39]
	v_mfma_f32_16x16x32_bf16 v[32:35], v[206:209], v[190:193], v[32:35]
	v_mfma_f32_16x16x32_bf16 v[80:83], v[202:205], v[170:173], v[80:83]
	v_mfma_f32_16x16x32_bf16 v[72:75], v[216:219], v[170:173], v[72:75]
	v_mfma_f32_16x16x32_bf16 v[68:71], v[202:205], v[178:181], v[68:71]
	v_mfma_f32_16x16x32_bf16 v[60:63], v[216:219], v[178:181], v[60:63]
	v_mfma_f32_16x16x32_bf16 v[52:55], v[202:205], v[186:189], v[52:55]
	v_mfma_f32_16x16x32_bf16 v[48:51], v[216:219], v[186:189], v[48:51]
	v_mfma_f32_16x16x32_bf16 v[36:39], v[202:205], v[194:197], v[36:39]
	v_mfma_f32_16x16x32_bf16 v[32:35], v[216:219], v[194:197], v[32:35]
	s_setprio 0
	s_mov_b32 m0, s23
	v_lshl_add_u64 v[222:223], s[38:39], 0, v[128:129]
	s_barrier
	ds_read_b128 v[166:169], v148 offset:16384
	ds_read_b128 v[170:173], v148 offset:17408
	ds_read_b128 v[174:177], v148 offset:18432
	ds_read_b128 v[178:181], v148 offset:19456
	ds_read_b128 v[182:185], v148 offset:20480
	ds_read_b128 v[186:189], v148 offset:21504
	ds_read_b128 v[190:193], v148 offset:22528
	ds_read_b128 v[194:197], v148 offset:23552
	global_load_lds_dwordx4 v[222:223], off
	v_lshl_add_u64 v[224:225], s[38:39], 0, v[132:133]
	s_mov_b32 m0, s58
	s_nop 0
	global_load_lds_dwordx4 v[224:225], off
	s_barrier
	s_waitcnt lgkmcnt(0)
	s_setprio 1
	s_waitcnt lgkmcnt(0)
	v_mfma_f32_16x16x32_bf16 v[92:95], v[150:153], v[166:169], v[92:95]
	v_mfma_f32_16x16x32_bf16 v[88:91], v[158:161], v[166:169], v[88:91]
	v_mfma_f32_16x16x32_bf16 v[84:87], v[150:153], v[174:177], v[84:87]
	v_mfma_f32_16x16x32_bf16 v[76:79], v[158:161], v[174:177], v[76:79]
	v_mfma_f32_16x16x32_bf16 v[64:67], v[150:153], v[182:185], v[64:67]
	v_mfma_f32_16x16x32_bf16 v[56:59], v[158:161], v[182:185], v[56:59]
	v_mfma_f32_16x16x32_bf16 v[44:47], v[150:153], v[190:193], v[44:47]
	v_mfma_f32_16x16x32_bf16 v[40:43], v[158:161], v[190:193], v[40:43]
	v_mfma_f32_16x16x32_bf16 v[92:95], v[154:157], v[170:173], v[92:95]
	v_mfma_f32_16x16x32_bf16 v[88:91], v[162:165], v[170:173], v[88:91]
	v_mfma_f32_16x16x32_bf16 v[84:87], v[154:157], v[178:181], v[84:87]
	v_mfma_f32_16x16x32_bf16 v[76:79], v[162:165], v[178:181], v[76:79]
	v_mfma_f32_16x16x32_bf16 v[64:67], v[154:157], v[186:189], v[64:67]
	v_mfma_f32_16x16x32_bf16 v[56:59], v[162:165], v[186:189], v[56:59]
	v_mfma_f32_16x16x32_bf16 v[44:47], v[154:157], v[194:197], v[44:47]
	v_mfma_f32_16x16x32_bf16 v[40:43], v[162:165], v[194:197], v[40:43]
	s_setprio 0
	s_barrier
	s_add_u32 s78, s36, 0x80000
	s_addc_u32 s79, s37, 0
	s_add_i32 s33, s67, s56
	v_lshl_add_u64 v[150:151], s[78:79], 0, v[130:131]
	s_mov_b32 m0, s33
	s_nop 0
	global_load_lds_dwordx4 v[150:151], off
	v_lshl_add_u64 v[150:151], s[78:79], 0, v[134:135]
	s_add_i32 m0, s33, 0x2000
	s_nop 0
	global_load_lds_dwordx4 v[150:151], off
	s_waitcnt vmcnt(6)
	s_barrier
	s_setprio 1
	v_mfma_f32_16x16x32_bf16 v[28:31], v[198:201], v[166:169], v[28:31]
	v_mfma_f32_16x16x32_bf16 v[24:27], v[206:209], v[166:169], v[24:27]
	v_mfma_f32_16x16x32_bf16 v[20:23], v[198:201], v[174:177], v[20:23]
	v_mfma_f32_16x16x32_bf16 v[16:19], v[206:209], v[174:177], v[16:19]
	v_mfma_f32_16x16x32_bf16 v[12:15], v[198:201], v[182:185], v[12:15]
	v_mfma_f32_16x16x32_bf16 v[8:11], v[206:209], v[182:185], v[8:11]
	v_mfma_f32_16x16x32_bf16 v[4:7], v[198:201], v[190:193], v[4:7]
	v_mfma_f32_16x16x32_bf16 v[0:3], v[206:209], v[190:193], v[0:3]
	v_mfma_f32_16x16x32_bf16 v[28:31], v[202:205], v[170:173], v[28:31]
	v_mfma_f32_16x16x32_bf16 v[24:27], v[216:219], v[170:173], v[24:27]
	v_mfma_f32_16x16x32_bf16 v[20:23], v[202:205], v[178:181], v[20:23]
	v_mfma_f32_16x16x32_bf16 v[16:19], v[216:219], v[178:181], v[16:19]
	v_mfma_f32_16x16x32_bf16 v[12:15], v[202:205], v[186:189], v[12:15]
	v_mfma_f32_16x16x32_bf16 v[8:11], v[216:219], v[186:189], v[8:11]
	v_mfma_f32_16x16x32_bf16 v[4:7], v[202:205], v[194:197], v[4:7]
	v_mfma_f32_16x16x32_bf16 v[0:3], v[216:219], v[194:197], v[0:3]
	s_setprio 0
	s_add_i32 s33, 0, 0x18000
	v_add_u32_e32 v162, s33, v145
	s_barrier
	ds_read_b128 v[150:153], v162
	ds_read_b128 v[154:157], v162 offset:1024
	ds_read_b128 v[158:161], v162 offset:2048
	ds_read_b128 v[162:165], v162 offset:3072
	s_add_u32 s38, s38, 0x80000
	s_addc_u32 s39, s39, 0
	s_mov_b32 m0, s59
	v_lshl_add_u64 v[198:199], s[38:39], 0, v[128:129]
	ds_read_b128 v[166:169], v148 offset:32768
	ds_read_b128 v[170:173], v148 offset:33792
	ds_read_b128 v[174:177], v148 offset:34816
	ds_read_b128 v[178:181], v148 offset:35840
	ds_read_b128 v[182:185], v148 offset:36864
	ds_read_b128 v[186:189], v148 offset:37888
	ds_read_b128 v[190:193], v148 offset:38912
	ds_read_b128 v[194:197], v148 offset:39936
	global_load_lds_dwordx4 v[198:199], off
	v_lshl_add_u64 v[198:199], s[38:39], 0, v[132:133]
	s_mov_b32 m0, s60
	s_nop 0
	global_load_lds_dwordx4 v[198:199], off
	s_waitcnt lgkmcnt(8)
	s_barrier
	s_waitcnt lgkmcnt(0)
	s_setprio 1
	s_waitcnt lgkmcnt(0)
	v_mfma_f32_16x16x32_bf16 v[124:127], v[150:153], v[166:169], v[124:127]
	v_mfma_f32_16x16x32_bf16 v[120:123], v[158:161], v[166:169], v[120:123]
	v_mfma_f32_16x16x32_bf16 v[116:119], v[150:153], v[174:177], v[116:119]
	v_mfma_f32_16x16x32_bf16 v[112:115], v[158:161], v[174:177], v[112:115]
	v_mfma_f32_16x16x32_bf16 v[108:111], v[150:153], v[182:185], v[108:111]
	v_mfma_f32_16x16x32_bf16 v[104:107], v[158:161], v[182:185], v[104:107]
	v_mfma_f32_16x16x32_bf16 v[100:103], v[150:153], v[190:193], v[100:103]
	v_mfma_f32_16x16x32_bf16 v[96:99], v[158:161], v[190:193], v[96:99]
	v_mfma_f32_16x16x32_bf16 v[124:127], v[154:157], v[170:173], v[124:127]
	v_mfma_f32_16x16x32_bf16 v[120:123], v[162:165], v[170:173], v[120:123]
	v_mfma_f32_16x16x32_bf16 v[116:119], v[154:157], v[178:181], v[116:119]
	v_mfma_f32_16x16x32_bf16 v[112:115], v[162:165], v[178:181], v[112:115]
	v_mfma_f32_16x16x32_bf16 v[108:111], v[154:157], v[186:189], v[108:111]
	v_mfma_f32_16x16x32_bf16 v[104:107], v[162:165], v[186:189], v[104:107]
	v_mfma_f32_16x16x32_bf16 v[100:103], v[154:157], v[194:197], v[100:103]
	v_mfma_f32_16x16x32_bf16 v[96:99], v[162:165], v[194:197], v[96:99]
	s_setprio 0
	s_barrier
	s_add_i32 s38, 0, 0x1c000
	s_add_i32 s33, s33, s56
	v_add_u32_e32 v216, s38, v145
	v_lshl_add_u64 v[210:211], v[210:211], 0, s[14:15]
	s_mov_b32 m0, s33
	ds_read_b128 v[198:201], v216
	ds_read_b128 v[202:205], v216 offset:1024
	ds_read_b128 v[206:209], v216 offset:2048
	ds_read_b128 v[216:219], v216 offset:3072
	global_load_lds_dwordx4 v[210:211], off
	v_lshl_add_u64 v[210:211], v[220:221], 0, s[14:15]
	s_add_i32 m0, s33, 0x2000
	s_nop 0
	global_load_lds_dwordx4 v[210:211], off
	s_barrier
	s_waitcnt lgkmcnt(0)
	s_setprio 1
	s_waitcnt lgkmcnt(0)
	v_mfma_f32_16x16x32_bf16 v[80:83], v[198:201], v[166:169], v[80:83]
	v_mfma_f32_16x16x32_bf16 v[72:75], v[206:209], v[166:169], v[72:75]
	v_mfma_f32_16x16x32_bf16 v[68:71], v[198:201], v[174:177], v[68:71]
	v_mfma_f32_16x16x32_bf16 v[60:63], v[206:209], v[174:177], v[60:63]
	v_mfma_f32_16x16x32_bf16 v[52:55], v[198:201], v[182:185], v[52:55]
	v_mfma_f32_16x16x32_bf16 v[48:51], v[206:209], v[182:185], v[48:51]
	v_mfma_f32_16x16x32_bf16 v[36:39], v[198:201], v[190:193], v[36:39]
	v_mfma_f32_16x16x32_bf16 v[32:35], v[206:209], v[190:193], v[32:35]
	v_mfma_f32_16x16x32_bf16 v[80:83], v[202:205], v[170:173], v[80:83]
	v_mfma_f32_16x16x32_bf16 v[72:75], v[216:219], v[170:173], v[72:75]
	v_mfma_f32_16x16x32_bf16 v[68:71], v[202:205], v[178:181], v[68:71]
	v_mfma_f32_16x16x32_bf16 v[60:63], v[216:219], v[178:181], v[60:63]
	v_mfma_f32_16x16x32_bf16 v[52:55], v[202:205], v[186:189], v[52:55]
	v_mfma_f32_16x16x32_bf16 v[48:51], v[216:219], v[186:189], v[48:51]
	v_mfma_f32_16x16x32_bf16 v[36:39], v[202:205], v[194:197], v[36:39]
	v_mfma_f32_16x16x32_bf16 v[32:35], v[216:219], v[194:197], v[32:35]
	s_setprio 0
	s_mov_b32 m0, s63
	v_lshl_add_u64 v[210:211], v[222:223], 0, s[14:15]
	s_barrier
	ds_read_b128 v[166:169], v148 offset:49152
	ds_read_b128 v[170:173], v148 offset:50176
	ds_read_b128 v[174:177], v148 offset:51200
	ds_read_b128 v[178:181], v148 offset:52224
	ds_read_b128 v[182:185], v148 offset:53248
	ds_read_b128 v[186:189], v148 offset:54272
	ds_read_b128 v[190:193], v148 offset:55296
	ds_read_b128 v[194:197], v148 offset:56320
	global_load_lds_dwordx4 v[210:211], off
	v_lshl_add_u64 v[210:211], v[224:225], 0, s[14:15]
	s_mov_b32 m0, s64
	s_nop 0
	global_load_lds_dwordx4 v[210:211], off
	s_barrier
	s_waitcnt lgkmcnt(0)
	s_setprio 1
	s_waitcnt lgkmcnt(0)
	v_mfma_f32_16x16x32_bf16 v[92:95], v[150:153], v[166:169], v[92:95]
	v_mfma_f32_16x16x32_bf16 v[88:91], v[158:161], v[166:169], v[88:91]
	v_mfma_f32_16x16x32_bf16 v[84:87], v[150:153], v[174:177], v[84:87]
	v_mfma_f32_16x16x32_bf16 v[76:79], v[158:161], v[174:177], v[76:79]
	v_mfma_f32_16x16x32_bf16 v[64:67], v[150:153], v[182:185], v[64:67]
	v_mfma_f32_16x16x32_bf16 v[56:59], v[158:161], v[182:185], v[56:59]
	v_mfma_f32_16x16x32_bf16 v[44:47], v[150:153], v[190:193], v[44:47]
	v_mfma_f32_16x16x32_bf16 v[40:43], v[158:161], v[190:193], v[40:43]
	v_mfma_f32_16x16x32_bf16 v[92:95], v[154:157], v[170:173], v[92:95]
	v_mfma_f32_16x16x32_bf16 v[88:91], v[162:165], v[170:173], v[88:91]
	v_mfma_f32_16x16x32_bf16 v[84:87], v[154:157], v[178:181], v[84:87]
	v_mfma_f32_16x16x32_bf16 v[76:79], v[162:165], v[178:181], v[76:79]
	v_mfma_f32_16x16x32_bf16 v[64:67], v[154:157], v[186:189], v[64:67]
	v_mfma_f32_16x16x32_bf16 v[56:59], v[162:165], v[186:189], v[56:59]
	v_mfma_f32_16x16x32_bf16 v[44:47], v[154:157], v[194:197], v[44:47]
	v_mfma_f32_16x16x32_bf16 v[40:43], v[162:165], v[194:197], v[40:43]
	s_setprio 0
	s_barrier
	s_add_u32 s36, s36, 0x80080
	s_addc_u32 s37, s37, 0
	s_add_i32 s33, s38, s56
	v_lshl_add_u64 v[150:151], s[36:37], 0, v[130:131]
	s_mov_b32 m0, s33
	s_nop 0
	global_load_lds_dwordx4 v[150:151], off
	v_lshl_add_u64 v[150:151], s[36:37], 0, v[134:135]
	s_add_i32 m0, s33, 0x2000
	s_nop 0
	global_load_lds_dwordx4 v[150:151], off
	s_waitcnt vmcnt(6)
	s_barrier
	s_setprio 1
	v_mfma_f32_16x16x32_bf16 v[28:31], v[198:201], v[166:169], v[28:31]
	v_mfma_f32_16x16x32_bf16 v[24:27], v[206:209], v[166:169], v[24:27]
	v_mfma_f32_16x16x32_bf16 v[20:23], v[198:201], v[174:177], v[20:23]
	v_mfma_f32_16x16x32_bf16 v[16:19], v[206:209], v[174:177], v[16:19]
	v_mfma_f32_16x16x32_bf16 v[12:15], v[198:201], v[182:185], v[12:15]
	v_mfma_f32_16x16x32_bf16 v[8:11], v[206:209], v[182:185], v[8:11]
	v_mfma_f32_16x16x32_bf16 v[4:7], v[198:201], v[190:193], v[4:7]
	v_mfma_f32_16x16x32_bf16 v[0:3], v[206:209], v[190:193], v[0:3]
	v_mfma_f32_16x16x32_bf16 v[28:31], v[202:205], v[170:173], v[28:31]
	v_mfma_f32_16x16x32_bf16 v[24:27], v[216:219], v[170:173], v[24:27]
	v_mfma_f32_16x16x32_bf16 v[20:23], v[202:205], v[178:181], v[20:23]
	v_mfma_f32_16x16x32_bf16 v[16:19], v[216:219], v[178:181], v[16:19]
	v_mfma_f32_16x16x32_bf16 v[12:15], v[202:205], v[186:189], v[12:15]
	v_mfma_f32_16x16x32_bf16 v[8:11], v[216:219], v[186:189], v[8:11]
	v_mfma_f32_16x16x32_bf16 v[4:7], v[202:205], v[194:197], v[4:7]
	v_mfma_f32_16x16x32_bf16 v[0:3], v[216:219], v[194:197], v[0:3]
	s_setprio 0
	s_add_i32 s77, s77, 2
	s_add_u32 s34, s34, 0x100
	s_addc_u32 s35, s35, 0
	s_add_u32 s75, s75, 0x100
	s_addc_u32 s76, s76, 0
	s_cmp_gt_u32 s77, 29
	s_barrier
	s_cbranch_scc0 .LBB0_694
	v_lshl_add_u32 v150, s22, 8, v144
	v_lshl_or_b32 v152, s72, 8, v146
	v_ashrrev_i32_e32 v151, 31, v150
	v_ashrrev_i32_e32 v153, 31, v152
	v_cvt_pk_bf16_f32 v124, v124, v125
	v_cvt_pk_bf16_f32 v125, v126, v127
	v_cvt_pk_bf16_f32 v126, v120, v121
	v_lshlrev_b64 v[120:121], 12, v[150:151]
	v_cvt_pk_bf16_f32 v127, v122, v123
	v_lshl_add_u64 v[120:121], s[12:13], 0, v[120:121]
	v_lshlrev_b64 v[122:123], 1, v[152:153]
	v_lshl_add_u64 v[120:121], v[120:121], 0, v[122:123]
	v_cvt_pk_bf16_f32 v92, v92, v93
	v_cvt_pk_bf16_f32 v93, v94, v95
	v_cvt_pk_bf16_f32 v95, v90, v91
	v_add_co_u32_e32 v90, vcc, s68, v120
	v_cvt_pk_bf16_f32 v84, v84, v85
	s_nop 0
	v_addc_co_u32_e32 v91, vcc, 0, v121, vcc
	v_cvt_pk_bf16_f32 v85, v86, v87
	v_cvt_pk_bf16_f32 v87, v78, v79
	v_add_co_u32_e32 v78, vcc, s69, v120
	v_cvt_pk_bf16_f32 v64, v64, v65
	s_nop 0
	v_addc_co_u32_e32 v79, vcc, 0, v121, vcc
	v_cvt_pk_bf16_f32 v65, v66, v67
	v_cvt_pk_bf16_f32 v67, v58, v59
	v_add_co_u32_e32 v58, vcc, s70, v120
	global_store_dwordx4 v[120:121], v[124:127], off sc1
	s_nop 0
	v_addc_co_u32_e32 v59, vcc, 0, v121, vcc
	v_or_b32_e32 v124, 16, v150
	v_cvt_pk_bf16_f32 v116, v116, v117
	v_cvt_pk_bf16_f32 v117, v118, v119
	v_cvt_pk_bf16_f32 v119, v114, v115
	v_ashrrev_i32_e32 v125, 31, v124
	v_or_b32_e32 v114, 32, v150
	v_cvt_pk_bf16_f32 v108, v108, v109
	v_cvt_pk_bf16_f32 v109, v110, v111
	v_cvt_pk_bf16_f32 v111, v106, v107
	v_or_b32_e32 v106, 48, v150
	v_cvt_pk_bf16_f32 v44, v44, v45
	v_cvt_pk_bf16_f32 v45, v46, v47
	v_cvt_pk_bf16_f32 v46, v40, v41
	v_add_co_u32_e32 v40, vcc, s71, v120
	v_cvt_pk_bf16_f32 v118, v112, v113
	v_lshlrev_b64 v[112:113], 12, v[124:125]
	v_ashrrev_i32_e32 v115, 31, v114
	v_ashrrev_i32_e32 v107, 31, v106
	v_cvt_pk_bf16_f32 v47, v42, v43
	v_addc_co_u32_e32 v41, vcc, 0, v121, vcc
	v_lshl_add_u64 v[112:113], s[12:13], 0, v[112:113]
	v_cvt_pk_bf16_f32 v110, v104, v105
	v_lshlrev_b64 v[104:105], 12, v[114:115]
	v_cvt_pk_bf16_f32 v100, v100, v101
	v_cvt_pk_bf16_f32 v101, v102, v103
	v_cvt_pk_bf16_f32 v102, v96, v97
	v_lshlrev_b64 v[96:97], 12, v[106:107]
	global_store_dwordx4 v[40:41], v[44:47], off sc1
	v_cvt_pk_bf16_f32 v40, v80, v81
	v_cvt_pk_bf16_f32 v41, v82, v83
	v_cvt_pk_bf16_f32 v42, v72, v73
	v_cvt_pk_bf16_f32 v43, v74, v75
	v_lshl_add_u64 v[112:113], v[112:113], 0, v[122:123]
	v_lshl_add_u64 v[104:105], s[12:13], 0, v[104:105]
	v_lshl_add_u64 v[96:97], s[12:13], 0, v[96:97]
	v_cvt_pk_bf16_f32 v66, v56, v57
	global_store_dwordx4 v[120:121], v[40:43], off offset:256 sc1
	v_lshl_add_u64 v[104:105], v[104:105], 0, v[122:123]
	v_cvt_pk_bf16_f32 v103, v98, v99
	v_cvt_pk_bf16_f32 v40, v68, v69
	v_cvt_pk_bf16_f32 v41, v70, v71
	v_cvt_pk_bf16_f32 v42, v60, v61
	v_cvt_pk_bf16_f32 v43, v62, v63
	v_lshl_add_u64 v[96:97], v[96:97], 0, v[122:123]
	v_cvt_pk_bf16_f32 v94, v88, v89
	v_lshl_add_u64 v[88:89], v[120:121], 0, s[10:11]
	v_cvt_pk_bf16_f32 v86, v76, v77
	v_lshl_add_u64 v[76:77], v[120:121], 0, s[16:17]
	v_lshl_add_u64 v[56:57], v[120:121], 0, s[18:19]
	global_store_dwordx4 v[58:59], v[64:67], off sc1
	v_lshl_add_u64 v[58:59], v[120:121], 0, s[20:21]
	global_store_dwordx4 v[112:113], v[40:43], off offset:256 sc1
	v_cvt_pk_bf16_f32 v36, v36, v37
	v_cvt_pk_bf16_f32 v37, v38, v39
	v_cvt_pk_bf16_f32 v40, v52, v53
	v_cvt_pk_bf16_f32 v41, v54, v55
	v_cvt_pk_bf16_f32 v42, v48, v49
	v_cvt_pk_bf16_f32 v43, v50, v51
	v_cvt_pk_bf16_f32 v38, v32, v33
	v_cvt_pk_bf16_f32 v39, v34, v35
	v_cvt_pk_bf16_f32 v28, v28, v29
	v_cvt_pk_bf16_f32 v29, v30, v31
	v_cvt_pk_bf16_f32 v30, v24, v25
	v_cvt_pk_bf16_f32 v31, v26, v27
	v_cvt_pk_bf16_f32 v20, v20, v21
	v_cvt_pk_bf16_f32 v21, v22, v23
	v_cvt_pk_bf16_f32 v22, v16, v17
	v_cvt_pk_bf16_f32 v23, v18, v19
	v_cvt_pk_bf16_f32 v12, v12, v13
	v_cvt_pk_bf16_f32 v13, v14, v15
	v_cvt_pk_bf16_f32 v14, v8, v9
	v_cvt_pk_bf16_f32 v15, v10, v11
	v_cvt_pk_bf16_f32 v4, v4, v5
	v_cvt_pk_bf16_f32 v5, v6, v7
	v_cvt_pk_bf16_f32 v6, v0, v1
	v_cvt_pk_bf16_f32 v7, v2, v3
	s_and_b64 vcc, exec, s[6:7]
	s_mov_b32 s22, s26
	s_mov_b32 s72, s24
	s_mov_b64 s[36:37], s[30:31]
	s_mov_b64 s[34:35], s[28:29]
	global_store_dwordx4 v[112:113], v[116:119], off sc1
	global_store_dwordx4 v[104:105], v[108:111], off sc1
	global_store_dwordx4 v[96:97], v[100:103], off sc1
	global_store_dwordx4 v[90:91], v[92:95], off sc1
	global_store_dwordx4 v[78:79], v[84:87], off sc1
	global_store_dwordx4 v[104:105], v[40:43], off offset:256 sc1
	global_store_dwordx4 v[96:97], v[36:39], off offset:256 sc1
	global_store_dwordx4 v[88:89], v[28:31], off offset:256 sc1
	global_store_dwordx4 v[76:77], v[20:23], off offset:256 sc1
	global_store_dwordx4 v[56:57], v[12:15], off offset:256 sc1
	global_store_dwordx4 v[58:59], v[4:7], off offset:256 sc1
	s_cbranch_vccz .LBB0_687
	s_waitcnt vmcnt(0)
	s_cmpk_gt_u32 s3, 0xff
	s_cbranch_scc1 .LBB0_698
	s_barrier

.LBB0_820:
	ds_read_b128 v[152:155], v148
	ds_read_b128 v[156:159], v148 offset:1024
	ds_read_b128 v[160:163], v148 offset:2048
	ds_read_b128 v[164:167], v148 offset:3072
	s_add_u32 s26, s24, 0xfff80080
	s_addc_u32 s27, s25, -1
	s_cmp_eq_u32 s67, 28
	s_cselect_b32 s29, s19, s27
	s_cselect_b32 s28, s63, s26
	s_cselect_b32 s27, s15, s66
	s_cselect_b32 s26, s64, s65
	v_lshl_add_u64 v[196:197], s[24:25], 0, v[136:137]
	s_add_i32 m0, s13, 0xc000
	ds_read_b128 v[168:171], v149
	ds_read_b128 v[172:175], v149 offset:1024
	ds_read_b128 v[176:179], v149 offset:2048
	ds_read_b128 v[180:183], v149 offset:3072
	ds_read_b128 v[184:187], v149 offset:4096
	ds_read_b128 v[188:191], v149 offset:5120
	ds_read_b128 v[192:195], v149 offset:6144
	ds_read_b128 v[200:203], v149 offset:7168
	global_load_lds_dwordx4 v[196:197], off
	v_lshl_add_u64 v[196:197], s[24:25], 0, v[138:139]
	s_add_i32 m0, s13, 0xe000
	s_nop 0
	global_load_lds_dwordx4 v[196:197], off
	s_waitcnt lgkmcnt(8)
	s_barrier
	s_waitcnt lgkmcnt(0)
	s_setprio 1
	s_waitcnt lgkmcnt(0)
	v_mfma_f32_16x16x32_bf16 v[124:127], v[152:155], v[168:171], v[124:127]
	v_mfma_f32_16x16x32_bf16 v[120:123], v[160:163], v[168:171], v[120:123]
	v_mfma_f32_16x16x32_bf16 v[116:119], v[152:155], v[176:179], v[116:119]
	v_mfma_f32_16x16x32_bf16 v[112:115], v[160:163], v[176:179], v[112:115]
	v_mfma_f32_16x16x32_bf16 v[108:111], v[152:155], v[184:187], v[108:111]
	v_mfma_f32_16x16x32_bf16 v[104:107], v[160:163], v[184:187], v[104:107]
	v_mfma_f32_16x16x32_bf16 v[100:103], v[152:155], v[192:195], v[100:103]
	v_mfma_f32_16x16x32_bf16 v[96:99], v[160:163], v[192:195], v[96:99]
	v_mfma_f32_16x16x32_bf16 v[124:127], v[156:159], v[172:175], v[124:127]
	v_mfma_f32_16x16x32_bf16 v[120:123], v[164:167], v[172:175], v[120:123]
	v_mfma_f32_16x16x32_bf16 v[116:119], v[156:159], v[180:183], v[116:119]
	v_mfma_f32_16x16x32_bf16 v[112:115], v[164:167], v[180:183], v[112:115]
	v_mfma_f32_16x16x32_bf16 v[108:111], v[156:159], v[188:191], v[108:111]
	v_mfma_f32_16x16x32_bf16 v[104:107], v[164:167], v[188:191], v[104:107]
	v_mfma_f32_16x16x32_bf16 v[100:103], v[156:159], v[200:203], v[100:103]
	v_mfma_f32_16x16x32_bf16 v[96:99], v[164:167], v[200:203], v[96:99]
	s_setprio 0
	s_barrier
	s_add_i32 s33, s59, s30
	v_lshl_add_u64 v[196:197], s[26:27], 0, v[130:131]
	s_mov_b32 m0, s33
	ds_read_b128 v[204:207], v150
	ds_read_b128 v[208:211], v150 offset:1024
	ds_read_b128 v[216:219], v150 offset:2048
	ds_read_b128 v[220:223], v150 offset:3072
	global_load_lds_dwordx4 v[196:197], off
	v_lshl_add_u64 v[224:225], s[26:27], 0, v[128:129]
	s_add_i32 m0, s33, 0x2000
	s_nop 0
	global_load_lds_dwordx4 v[224:225], off
	s_barrier
	s_waitcnt lgkmcnt(0)
	s_setprio 1
	s_waitcnt lgkmcnt(0)
	v_mfma_f32_16x16x32_bf16 v[84:87], v[204:207], v[168:171], v[84:87]
	v_mfma_f32_16x16x32_bf16 v[76:79], v[216:219], v[168:171], v[76:79]
	v_mfma_f32_16x16x32_bf16 v[68:71], v[204:207], v[176:179], v[68:71]
	v_mfma_f32_16x16x32_bf16 v[64:67], v[216:219], v[176:179], v[64:67]
	v_mfma_f32_16x16x32_bf16 v[52:55], v[204:207], v[184:187], v[52:55]
	v_mfma_f32_16x16x32_bf16 v[48:51], v[216:219], v[184:187], v[48:51]
	v_mfma_f32_16x16x32_bf16 v[40:43], v[204:207], v[192:195], v[40:43]
	v_mfma_f32_16x16x32_bf16 v[32:35], v[216:219], v[192:195], v[32:35]
	v_mfma_f32_16x16x32_bf16 v[84:87], v[208:211], v[172:175], v[84:87]
	v_mfma_f32_16x16x32_bf16 v[76:79], v[220:223], v[172:175], v[76:79]
	v_mfma_f32_16x16x32_bf16 v[68:71], v[208:211], v[180:183], v[68:71]
	v_mfma_f32_16x16x32_bf16 v[64:67], v[220:223], v[180:183], v[64:67]
	v_mfma_f32_16x16x32_bf16 v[52:55], v[208:211], v[188:191], v[52:55]
	v_mfma_f32_16x16x32_bf16 v[48:51], v[220:223], v[188:191], v[48:51]
	v_mfma_f32_16x16x32_bf16 v[40:43], v[208:211], v[200:203], v[40:43]
	v_mfma_f32_16x16x32_bf16 v[32:35], v[220:223], v[200:203], v[32:35]
	s_setprio 0
	s_mov_b32 m0, s13
	v_lshl_add_u64 v[230:231], s[28:29], 0, v[134:135]
	s_barrier
	ds_read_b128 v[168:171], v149 offset:16384
	ds_read_b128 v[172:175], v149 offset:17408
	ds_read_b128 v[176:179], v149 offset:18432
	ds_read_b128 v[180:183], v149 offset:19456
	ds_read_b128 v[184:187], v149 offset:20480
	ds_read_b128 v[188:191], v149 offset:21504
	ds_read_b128 v[192:195], v149 offset:22528
	ds_read_b128 v[200:203], v149 offset:23552
	global_load_lds_dwordx4 v[230:231], off
	v_lshl_add_u64 v[232:233], s[28:29], 0, v[132:133]
	s_mov_b32 m0, s39
	s_nop 0
	global_load_lds_dwordx4 v[232:233], off
	s_barrier
	s_waitcnt lgkmcnt(0)
	s_setprio 1
	s_waitcnt lgkmcnt(0)
	v_mfma_f32_16x16x32_bf16 v[92:95], v[152:155], v[168:171], v[92:95]
	v_mfma_f32_16x16x32_bf16 v[88:91], v[160:163], v[168:171], v[88:91]
	v_mfma_f32_16x16x32_bf16 v[80:83], v[152:155], v[176:179], v[80:83]
	v_mfma_f32_16x16x32_bf16 v[72:75], v[160:163], v[176:179], v[72:75]
	v_mfma_f32_16x16x32_bf16 v[60:63], v[152:155], v[184:187], v[60:63]
	v_mfma_f32_16x16x32_bf16 v[56:59], v[160:163], v[184:187], v[56:59]
	v_mfma_f32_16x16x32_bf16 v[44:47], v[152:155], v[192:195], v[44:47]
	v_mfma_f32_16x16x32_bf16 v[36:39], v[160:163], v[192:195], v[36:39]
	v_mfma_f32_16x16x32_bf16 v[92:95], v[156:159], v[172:175], v[92:95]
	v_mfma_f32_16x16x32_bf16 v[88:91], v[164:167], v[172:175], v[88:91]
	v_mfma_f32_16x16x32_bf16 v[80:83], v[156:159], v[180:183], v[80:83]
	v_mfma_f32_16x16x32_bf16 v[72:75], v[164:167], v[180:183], v[72:75]
	v_mfma_f32_16x16x32_bf16 v[60:63], v[156:159], v[188:191], v[60:63]
	v_mfma_f32_16x16x32_bf16 v[56:59], v[164:167], v[188:191], v[56:59]
	v_mfma_f32_16x16x32_bf16 v[44:47], v[156:159], v[200:203], v[44:47]
	v_mfma_f32_16x16x32_bf16 v[36:39], v[164:167], v[200:203], v[36:39]
	s_setprio 0
	s_barrier
	s_add_u32 s68, s26, 0x80000
	s_addc_u32 s69, s27, 0
	s_add_i32 s33, s60, s30
	v_lshl_add_u64 v[152:153], s[68:69], 0, v[130:131]
	s_mov_b32 m0, s33
	s_nop 0
	global_load_lds_dwordx4 v[152:153], off
	v_lshl_add_u64 v[152:153], s[68:69], 0, v[128:129]
	s_add_i32 m0, s33, 0x2000
	s_nop 0
	global_load_lds_dwordx4 v[152:153], off
	s_waitcnt vmcnt(6)
	s_barrier
	s_setprio 1
	v_mfma_f32_16x16x32_bf16 v[28:31], v[204:207], v[168:171], v[28:31]
	v_mfma_f32_16x16x32_bf16 v[24:27], v[216:219], v[168:171], v[24:27]
	v_mfma_f32_16x16x32_bf16 v[20:23], v[204:207], v[176:179], v[20:23]
	v_mfma_f32_16x16x32_bf16 v[16:19], v[216:219], v[176:179], v[16:19]
	v_mfma_f32_16x16x32_bf16 v[12:15], v[204:207], v[184:187], v[12:15]
	v_mfma_f32_16x16x32_bf16 v[8:11], v[216:219], v[184:187], v[8:11]
	v_mfma_f32_16x16x32_bf16 v[4:7], v[204:207], v[192:195], v[4:7]
	v_mfma_f32_16x16x32_bf16 v[0:3], v[216:219], v[192:195], v[0:3]
	v_mfma_f32_16x16x32_bf16 v[28:31], v[208:211], v[172:175], v[28:31]
	v_mfma_f32_16x16x32_bf16 v[24:27], v[220:223], v[172:175], v[24:27]
	v_mfma_f32_16x16x32_bf16 v[20:23], v[208:211], v[180:183], v[20:23]
	v_mfma_f32_16x16x32_bf16 v[16:19], v[220:223], v[180:183], v[16:19]
	v_mfma_f32_16x16x32_bf16 v[12:15], v[208:211], v[188:191], v[12:15]
	v_mfma_f32_16x16x32_bf16 v[8:11], v[220:223], v[188:191], v[8:11]
	v_mfma_f32_16x16x32_bf16 v[4:7], v[208:211], v[200:203], v[4:7]
	v_mfma_f32_16x16x32_bf16 v[0:3], v[220:223], v[200:203], v[0:3]
	s_setprio 0
	s_add_i32 s33, 0, 0x18000
	v_add_u32_e32 v151, s33, v146
	s_barrier
	ds_read_b128 v[152:155], v151
	ds_read_b128 v[156:159], v151 offset:1024
	ds_read_b128 v[160:163], v151 offset:2048
	ds_read_b128 v[164:167], v151 offset:3072
	s_add_u32 s28, s28, 0x80000
	s_addc_u32 s29, s29, 0
	s_mov_b32 m0, s52
	v_lshl_add_u64 v[204:205], s[28:29], 0, v[134:135]
	ds_read_b128 v[168:171], v149 offset:32768
	ds_read_b128 v[172:175], v149 offset:33792
	ds_read_b128 v[176:179], v149 offset:34816
	ds_read_b128 v[180:183], v149 offset:35840
	ds_read_b128 v[184:187], v149 offset:36864
	ds_read_b128 v[188:191], v149 offset:37888
	ds_read_b128 v[192:195], v149 offset:38912
	ds_read_b128 v[200:203], v149 offset:39936
	global_load_lds_dwordx4 v[204:205], off
	v_lshl_add_u64 v[204:205], s[28:29], 0, v[132:133]
	s_mov_b32 m0, s53
	s_nop 0
	global_load_lds_dwordx4 v[204:205], off
	s_waitcnt lgkmcnt(8)
	s_barrier
	s_waitcnt lgkmcnt(0)
	s_setprio 1
	s_waitcnt lgkmcnt(0)
	v_mfma_f32_16x16x32_bf16 v[124:127], v[152:155], v[168:171], v[124:127]
	v_mfma_f32_16x16x32_bf16 v[120:123], v[160:163], v[168:171], v[120:123]
	v_mfma_f32_16x16x32_bf16 v[116:119], v[152:155], v[176:179], v[116:119]
	v_mfma_f32_16x16x32_bf16 v[112:115], v[160:163], v[176:179], v[112:115]
	v_mfma_f32_16x16x32_bf16 v[108:111], v[152:155], v[184:187], v[108:111]
	v_mfma_f32_16x16x32_bf16 v[104:107], v[160:163], v[184:187], v[104:107]
	v_mfma_f32_16x16x32_bf16 v[100:103], v[152:155], v[192:195], v[100:103]
	v_mfma_f32_16x16x32_bf16 v[96:99], v[160:163], v[192:195], v[96:99]
	v_mfma_f32_16x16x32_bf16 v[124:127], v[156:159], v[172:175], v[124:127]
	v_mfma_f32_16x16x32_bf16 v[120:123], v[164:167], v[172:175], v[120:123]
	v_mfma_f32_16x16x32_bf16 v[116:119], v[156:159], v[180:183], v[116:119]
	v_mfma_f32_16x16x32_bf16 v[112:115], v[164:167], v[180:183], v[112:115]
	v_mfma_f32_16x16x32_bf16 v[108:111], v[156:159], v[188:191], v[108:111]
	v_mfma_f32_16x16x32_bf16 v[104:107], v[164:167], v[188:191], v[104:107]
	v_mfma_f32_16x16x32_bf16 v[100:103], v[156:159], v[200:203], v[100:103]
	v_mfma_f32_16x16x32_bf16 v[96:99], v[164:167], v[200:203], v[96:99]
	s_setprio 0
	s_barrier
	s_add_i32 s28, 0, 0x1c000
	s_add_i32 s29, s33, s30
	v_add_u32_e32 v151, s28, v146
	v_lshl_add_u64 v[196:197], v[196:197], 0, s[10:11]
	s_mov_b32 m0, s29
	ds_read_b128 v[204:207], v151
	ds_read_b128 v[208:211], v151 offset:1024
	ds_read_b128 v[216:219], v151 offset:2048
	ds_read_b128 v[220:223], v151 offset:3072
	global_load_lds_dwordx4 v[196:197], off
	v_lshl_add_u64 v[196:197], v[224:225], 0, s[10:11]
	s_add_i32 m0, s29, 0x2000
	s_nop 0
	global_load_lds_dwordx4 v[196:197], off
	s_barrier
	s_waitcnt lgkmcnt(0)
	s_setprio 1
	s_waitcnt lgkmcnt(0)
	v_mfma_f32_16x16x32_bf16 v[84:87], v[204:207], v[168:171], v[84:87]
	v_mfma_f32_16x16x32_bf16 v[76:79], v[216:219], v[168:171], v[76:79]
	v_mfma_f32_16x16x32_bf16 v[68:71], v[204:207], v[176:179], v[68:71]
	v_mfma_f32_16x16x32_bf16 v[64:67], v[216:219], v[176:179], v[64:67]
	v_mfma_f32_16x16x32_bf16 v[52:55], v[204:207], v[184:187], v[52:55]
	v_mfma_f32_16x16x32_bf16 v[48:51], v[216:219], v[184:187], v[48:51]
	v_mfma_f32_16x16x32_bf16 v[40:43], v[204:207], v[192:195], v[40:43]
	v_mfma_f32_16x16x32_bf16 v[32:35], v[216:219], v[192:195], v[32:35]
	v_mfma_f32_16x16x32_bf16 v[84:87], v[208:211], v[172:175], v[84:87]
	v_mfma_f32_16x16x32_bf16 v[76:79], v[220:223], v[172:175], v[76:79]
	v_mfma_f32_16x16x32_bf16 v[68:71], v[208:211], v[180:183], v[68:71]
	v_mfma_f32_16x16x32_bf16 v[64:67], v[220:223], v[180:183], v[64:67]
	v_mfma_f32_16x16x32_bf16 v[52:55], v[208:211], v[188:191], v[52:55]
	v_mfma_f32_16x16x32_bf16 v[48:51], v[220:223], v[188:191], v[48:51]
	v_mfma_f32_16x16x32_bf16 v[40:43], v[208:211], v[200:203], v[40:43]
	v_mfma_f32_16x16x32_bf16 v[32:35], v[220:223], v[200:203], v[32:35]
	s_setprio 0
	s_mov_b32 m0, s55
	v_lshl_add_u64 v[196:197], v[230:231], 0, s[10:11]
	s_barrier
	ds_read_b128 v[168:171], v149 offset:49152
	ds_read_b128 v[172:175], v149 offset:50176
	ds_read_b128 v[176:179], v149 offset:51200
	ds_read_b128 v[180:183], v149 offset:52224
	ds_read_b128 v[184:187], v149 offset:53248
	ds_read_b128 v[188:191], v149 offset:54272
	ds_read_b128 v[192:195], v149 offset:55296
	ds_read_b128 v[200:203], v149 offset:56320
	global_load_lds_dwordx4 v[196:197], off
	v_lshl_add_u64 v[196:197], v[232:233], 0, s[10:11]
	s_mov_b32 m0, s56
	s_nop 0
	global_load_lds_dwordx4 v[196:197], off
	s_barrier
	s_waitcnt lgkmcnt(0)
	s_setprio 1
	s_waitcnt lgkmcnt(0)
	v_mfma_f32_16x16x32_bf16 v[92:95], v[152:155], v[168:171], v[92:95]
	v_mfma_f32_16x16x32_bf16 v[88:91], v[160:163], v[168:171], v[88:91]
	v_mfma_f32_16x16x32_bf16 v[80:83], v[152:155], v[176:179], v[80:83]
	v_mfma_f32_16x16x32_bf16 v[72:75], v[160:163], v[176:179], v[72:75]
	v_mfma_f32_16x16x32_bf16 v[60:63], v[152:155], v[184:187], v[60:63]
	v_mfma_f32_16x16x32_bf16 v[56:59], v[160:163], v[184:187], v[56:59]
	v_mfma_f32_16x16x32_bf16 v[44:47], v[152:155], v[192:195], v[44:47]
	v_mfma_f32_16x16x32_bf16 v[36:39], v[160:163], v[192:195], v[36:39]
	v_mfma_f32_16x16x32_bf16 v[92:95], v[156:159], v[172:175], v[92:95]
	v_mfma_f32_16x16x32_bf16 v[88:91], v[164:167], v[172:175], v[88:91]
	v_mfma_f32_16x16x32_bf16 v[80:83], v[156:159], v[180:183], v[80:83]
	v_mfma_f32_16x16x32_bf16 v[72:75], v[164:167], v[180:183], v[72:75]
	v_mfma_f32_16x16x32_bf16 v[60:63], v[156:159], v[188:191], v[60:63]
	v_mfma_f32_16x16x32_bf16 v[56:59], v[164:167], v[188:191], v[56:59]
	v_mfma_f32_16x16x32_bf16 v[44:47], v[156:159], v[200:203], v[44:47]
	v_mfma_f32_16x16x32_bf16 v[36:39], v[164:167], v[200:203], v[36:39]
	s_setprio 0
	s_barrier
	s_add_u32 s26, s26, 0x80080
	s_addc_u32 s27, s27, 0
	s_add_i32 s28, s28, s30
	v_lshl_add_u64 v[152:153], s[26:27], 0, v[130:131]
	s_mov_b32 m0, s28
	s_nop 0
	global_load_lds_dwordx4 v[152:153], off
	v_lshl_add_u64 v[152:153], s[26:27], 0, v[128:129]
	s_add_i32 m0, s28, 0x2000
	s_nop 0
	global_load_lds_dwordx4 v[152:153], off
	s_waitcnt vmcnt(6)
	s_barrier
	s_setprio 1
	v_mfma_f32_16x16x32_bf16 v[28:31], v[204:207], v[168:171], v[28:31]
	v_mfma_f32_16x16x32_bf16 v[24:27], v[216:219], v[168:171], v[24:27]
	v_mfma_f32_16x16x32_bf16 v[20:23], v[204:207], v[176:179], v[20:23]
	v_mfma_f32_16x16x32_bf16 v[16:19], v[216:219], v[176:179], v[16:19]
	v_mfma_f32_16x16x32_bf16 v[12:15], v[204:207], v[184:187], v[12:15]
	v_mfma_f32_16x16x32_bf16 v[8:11], v[216:219], v[184:187], v[8:11]
	v_mfma_f32_16x16x32_bf16 v[4:7], v[204:207], v[192:195], v[4:7]
	v_mfma_f32_16x16x32_bf16 v[0:3], v[216:219], v[192:195], v[0:3]
	v_mfma_f32_16x16x32_bf16 v[28:31], v[208:211], v[172:175], v[28:31]
	v_mfma_f32_16x16x32_bf16 v[24:27], v[220:223], v[172:175], v[24:27]
	v_mfma_f32_16x16x32_bf16 v[20:23], v[208:211], v[180:183], v[20:23]
	v_mfma_f32_16x16x32_bf16 v[16:19], v[220:223], v[180:183], v[16:19]
	v_mfma_f32_16x16x32_bf16 v[12:15], v[208:211], v[188:191], v[12:15]
	v_mfma_f32_16x16x32_bf16 v[8:11], v[220:223], v[188:191], v[8:11]
	v_mfma_f32_16x16x32_bf16 v[4:7], v[208:211], v[200:203], v[4:7]
	v_mfma_f32_16x16x32_bf16 v[0:3], v[220:223], v[200:203], v[0:3]
	s_setprio 0
	s_add_i32 s67, s67, 2
	s_add_u32 s24, s24, 0x100
	s_addc_u32 s25, s25, 0
	s_add_u32 s65, s65, 0x100
	s_addc_u32 s66, s66, 0
	s_cmp_gt_u32 s67, 29
	s_barrier
	s_cbranch_scc0 .LBB0_820
	v_lshl_or_b32 v152, s62, 8, v147
	v_lshl_add_u32 v151, s12, 8, v145
	v_ashrrev_i32_e32 v153, 31, v152
	v_cvt_pk_bf16_f32 v124, v124, v125
	v_cvt_pk_bf16_f32 v125, v126, v127
	v_cvt_pk_bf16_f32 v126, v120, v121
	v_mov_b64_e32 v[120:121], s[8:9]
	v_cvt_pk_bf16_f32 v127, v122, v123
	v_mad_i64_i32 v[122:123], s[24:25], v151, s61, v[120:121]
	v_lshlrev_b64 v[152:153], 1, v[152:153]
	v_lshl_add_u64 v[122:123], v[122:123], 0, v[152:153]
	v_cvt_pk_bf16_f32 v60, v60, v61
	v_cvt_pk_bf16_f32 v61, v62, v63
	v_cvt_pk_bf16_f32 v63, v58, v59
	v_add_u32_e32 v58, 0xb0, v151
	global_store_dwordx4 v[122:123], v[124:127], off sc1
	v_cvt_pk_bf16_f32 v44, v44, v45
	v_cvt_pk_bf16_f32 v45, v46, v47
	v_or_b32_e32 v124, 16, v151
	v_cvt_pk_bf16_f32 v46, v36, v37
	v_mad_i64_i32 v[36:37], s[24:25], v58, s61, v[120:121]
	v_cvt_pk_bf16_f32 v116, v116, v117
	v_cvt_pk_bf16_f32 v117, v118, v119
	v_cvt_pk_bf16_f32 v118, v112, v113
	v_cvt_pk_bf16_f32 v119, v114, v115
	v_mad_i64_i32 v[112:113], s[24:25], v124, s61, v[120:121]
	v_or_b32_e32 v114, 32, v151
	v_cvt_pk_bf16_f32 v47, v38, v39
	v_lshl_add_u64 v[58:59], v[36:37], 0, v[152:153]
	v_cvt_pk_bf16_f32 v36, v84, v85
	v_cvt_pk_bf16_f32 v37, v86, v87
	v_cvt_pk_bf16_f32 v38, v76, v77
	v_cvt_pk_bf16_f32 v39, v78, v79
	v_lshl_add_u64 v[112:113], v[112:113], 0, v[152:153]
	v_cvt_pk_bf16_f32 v108, v108, v109
	v_cvt_pk_bf16_f32 v109, v110, v111
	v_cvt_pk_bf16_f32 v110, v104, v105
	v_cvt_pk_bf16_f32 v111, v106, v107
	v_mad_i64_i32 v[104:105], s[24:25], v114, s61, v[120:121]
	v_or_b32_e32 v106, 48, v151
	v_cvt_pk_bf16_f32 v100, v100, v101
	v_cvt_pk_bf16_f32 v101, v102, v103
	v_cvt_pk_bf16_f32 v103, v98, v99
	v_add_u32_e32 v98, 0x80, v151
	v_cvt_pk_bf16_f32 v92, v92, v93
	v_cvt_pk_bf16_f32 v93, v94, v95
	v_cvt_pk_bf16_f32 v95, v90, v91
	v_add_u32_e32 v90, 0x90, v151
	v_cvt_pk_bf16_f32 v80, v80, v81
	v_cvt_pk_bf16_f32 v81, v82, v83
	v_cvt_pk_bf16_f32 v83, v74, v75
	v_add_u32_e32 v74, 0xa0, v151
	global_store_dwordx4 v[122:123], v[36:39], off offset:256 sc1
	v_lshl_add_u64 v[104:105], v[104:105], 0, v[152:153]
	v_cvt_pk_bf16_f32 v102, v96, v97
	v_cvt_pk_bf16_f32 v36, v68, v69
	v_cvt_pk_bf16_f32 v37, v70, v71
	v_cvt_pk_bf16_f32 v38, v64, v65
	v_cvt_pk_bf16_f32 v39, v66, v67
	v_mad_i64_i32 v[96:97], s[24:25], v106, s61, v[120:121]
	v_cvt_pk_bf16_f32 v94, v88, v89
	v_mad_i64_i32 v[88:89], s[24:25], v98, s61, v[120:121]
	v_cvt_pk_bf16_f32 v82, v72, v73
	v_mad_i64_i32 v[72:73], s[24:25], v90, s61, v[120:121]
	v_cvt_pk_bf16_f32 v62, v56, v57
	v_mad_i64_i32 v[56:57], s[24:25], v74, s61, v[120:121]
	global_store_dwordx4 v[112:113], v[36:39], off offset:256 sc1
	v_lshl_add_u64 v[96:97], v[96:97], 0, v[152:153]
	v_lshl_add_u64 v[88:89], v[88:89], 0, v[152:153]
	v_cvt_pk_bf16_f32 v36, v52, v53
	v_cvt_pk_bf16_f32 v37, v54, v55
	v_cvt_pk_bf16_f32 v38, v48, v49
	v_cvt_pk_bf16_f32 v39, v50, v51
	v_lshl_add_u64 v[72:73], v[72:73], 0, v[152:153]
	v_lshl_add_u64 v[56:57], v[56:57], 0, v[152:153]
	global_store_dwordx4 v[104:105], v[36:39], off offset:256 sc1
	v_cvt_pk_bf16_f32 v28, v28, v29
	v_cvt_pk_bf16_f32 v29, v30, v31
	v_cvt_pk_bf16_f32 v36, v40, v41
	v_cvt_pk_bf16_f32 v37, v42, v43
	v_cvt_pk_bf16_f32 v38, v32, v33
	v_cvt_pk_bf16_f32 v39, v34, v35
	v_cvt_pk_bf16_f32 v30, v24, v25
	v_cvt_pk_bf16_f32 v31, v26, v27
	v_cvt_pk_bf16_f32 v20, v20, v21
	v_cvt_pk_bf16_f32 v21, v22, v23
	v_cvt_pk_bf16_f32 v22, v16, v17
	v_cvt_pk_bf16_f32 v23, v18, v19
	v_cvt_pk_bf16_f32 v12, v12, v13
	v_cvt_pk_bf16_f32 v13, v14, v15
	v_cvt_pk_bf16_f32 v14, v8, v9
	v_cvt_pk_bf16_f32 v15, v10, v11
	v_cvt_pk_bf16_f32 v4, v4, v5
	v_cvt_pk_bf16_f32 v5, v6, v7
	v_cvt_pk_bf16_f32 v6, v0, v1
	v_cvt_pk_bf16_f32 v7, v2, v3
	s_and_b64 vcc, exec, s[6:7]
	s_mov_b32 s12, s18
	s_mov_b32 s62, s14
	s_mov_b64 s[26:27], s[22:23]
	s_mov_b64 s[24:25], s[20:21]
	global_store_dwordx4 v[112:113], v[116:119], off sc1
	global_store_dwordx4 v[104:105], v[108:111], off sc1
	global_store_dwordx4 v[96:97], v[100:103], off sc1
	global_store_dwordx4 v[88:89], v[92:95], off sc1
	global_store_dwordx4 v[72:73], v[80:83], off sc1
	global_store_dwordx4 v[56:57], v[60:63], off sc1
	global_store_dwordx4 v[58:59], v[44:47], off sc1
	global_store_dwordx4 v[96:97], v[36:39], off offset:256 sc1
	global_store_dwordx4 v[88:89], v[28:31], off offset:256 sc1
	global_store_dwordx4 v[72:73], v[20:23], off offset:256 sc1
	global_store_dwordx4 v[56:57], v[12:15], off offset:256 sc1
	global_store_dwordx4 v[58:59], v[4:7], off offset:256 sc1
	s_cbranch_vccz .LBB0_817
	s_waitcnt vmcnt(0)
	s_cmpk_gt_u32 s3, 0xff
	s_cbranch_scc1 .LBB0_824
	s_barrier

.LBB0_878:
	s_or_b64 exec, exec, s[10:11]
	s_waitcnt vmcnt(0)
	v_mul_f32_e32 v0, v19, v0
	v_mul_f32_e32 v1, v4, v0
	v_cvt_pk_bf16_f32 v1, v1, s0
	ds_write_b16 v29, v1 offset:192
	v_mul_f32_e32 v1, v5, v0
	v_cvt_pk_bf16_f32 v1, v1, s0
	ds_write_b16 v29, v1 offset:464
	v_mul_f32_e32 v1, v6, v0
	v_mul_f32_e32 v0, v7, v0
	v_cvt_pk_bf16_f32 v1, v1, s0
	v_cvt_pk_bf16_f32 v0, v0, s0
	v_or_b32_e32 v4, s20, v226
	s_ashr_i32 s10, s20, 31
	ds_write_b16 v29, v1 offset:736
	ds_write_b16 v29, v0 offset:1008
	s_waitcnt lgkmcnt(0)
	s_barrier
	ds_read_b128 v[0:3], v26
	s_mul_i32 s18, s10, s38
	v_mad_u64_u32 v[4:5], s[10:11], v4, s38, 0
	s_ashr_i32 s15, s14, 31
	v_add_u32_e32 v5, s18, v5
	v_lshl_add_u64 v[4:5], v[4:5], 1, s[6:7]
	s_lshl_b64 s[10:11], s[14:15], 1
	v_lshl_add_u64 v[4:5], v[4:5], 0, s[10:11]
	v_mov_b32_e32 v19, v17
	v_lshl_add_u64 v[8:9], v[4:5], 0, v[18:19]
	ds_read_b128 v[4:7], v27
	s_waitcnt lgkmcnt(1)
	global_store_dwordx4 v[8:9], v[0:3], off sc1
	s_add_i32 s22, s22, s25
	s_add_i32 s39, s39, s52
	v_add_u32_e32 v0, s20, v25
	v_ashrrev_i32_e32 v3, 31, v0
	v_mad_u64_u32 v[0:1], s[14:15], v0, s38, 0
	v_mov_b32_e32 v2, v1
	v_mad_u64_u32 v[2:3], s[14:15], v3, s38, v[2:3]
	v_mov_b32_e32 v1, v2
	v_lshl_add_u64 v[0:1], v[0:1], 1, s[6:7]
	v_lshl_add_u64 v[0:1], v[0:1], 0, s[10:11]
	v_lshl_add_u64 v[0:1], v[0:1], 0, v[18:19]
	s_cmp_ge_i32 s22, s36
	s_waitcnt lgkmcnt(0)
	global_store_dwordx4 v[0:1], v[4:7], off sc1
	s_barrier
	s_cbranch_scc1 .LBB0_827

.LBB0_969:
	s_waitcnt lgkmcnt(0)
	v_mad_i64_i32 v[18:19], s[8:9], v0, s23, v[10:11]
	v_lshl_add_u64 v[18:19], v[18:19], 0, v[12:13]
	v_add_co_u32_e32 v20, vcc, 0x1000, v18
	v_ashrrev_i32_e32 v1, 31, v0
	s_nop 0
	v_addc_co_u32_e32 v21, vcc, 0, v19, vcc
	global_load_dwordx4 v[22:25], v[20:21], off offset:2048
	global_load_dwordx4 v[48:51], v[18:19], off
	v_add_u32_e32 v20, 1, v0
	v_mad_i64_i32 v[18:19], s[8:9], v20, s23, v[10:11]
	v_lshl_add_u64 v[18:19], v[18:19], 0, v[12:13]
	v_add_co_u32_e32 v26, vcc, s26, v18
	v_ashrrev_i32_e32 v21, 31, v20
	s_nop 0
	v_addc_co_u32_e32 v27, vcc, 0, v19, vcc
	global_load_dwordx4 v[52:55], v[26:27], off offset:2048
	global_load_dwordx4 v[56:59], v[18:19], off
	v_add_u32_e32 v18, v227, v0
	v_mad_i64_i32 v[26:27], s[8:9], v18, s23, v[4:5]
	v_ashrrev_i32_e32 v19, 31, v18
	v_add_co_u32_e32 v26, vcc, s26, v26
	s_waitcnt lgkmcnt(0)
	v_lshl_add_u64 v[28:29], v[18:19], 2, s[18:19]
	v_addc_co_u32_e32 v27, vcc, 0, v27, vcc
	global_load_dword v92, v[28:29], off
	global_load_ushort v17, v[26:27], off offset:3072
	global_load_ushort v47, v[26:27], off offset:3136
	v_lshlrev_b64 v[20:21], 10, v[20:21]
	s_waitcnt vmcnt(0)
	v_and_b32_e32 v63, 0xffff0000, v22
	v_and_b32_e32 v65, 0xffff0000, v48
	v_lshlrev_b32_e32 v26, 16, v25
	v_and_b32_e32 v27, 0xffff0000, v25
	v_lshlrev_b32_e32 v30, 16, v24
	v_and_b32_e32 v31, 0xffff0000, v24
	v_lshlrev_b32_e32 v60, 16, v23
	v_and_b32_e32 v61, 0xffff0000, v23
	v_lshlrev_b32_e32 v62, 16, v22
	v_lshlrev_b32_e32 v22, 16, v51
	v_and_b32_e32 v23, 0xffff0000, v51
	v_lshlrev_b32_e32 v24, 16, v50
	v_and_b32_e32 v25, 0xffff0000, v50
	v_lshlrev_b32_e32 v64, 16, v48
	v_mov_b32_e32 v76, v65
	v_mov_b32_e32 v77, v63
	v_lshlrev_b32_e32 v28, 16, v49
	v_and_b32_e32 v29, 0xffff0000, v49
	v_pk_mul_f32 v[48:49], v[26:27], v[26:27]
	v_pk_mul_f32 v[50:51], v[30:31], v[30:31]
	v_pk_mul_f32 v[66:67], v[22:23], v[22:23]
	v_pk_mul_f32 v[68:69], v[24:25], v[24:25]
	v_mov_b32_e32 v74, v64
	v_mov_b32_e32 v75, v62
	v_pk_mul_f32 v[76:77], v[76:77], v[76:77]
	v_mov_b32_e32 v70, v28
	v_mov_b32_e32 v71, v60
	v_mov_b32_e32 v84, v68
	v_mov_b32_e32 v85, v50
	v_mov_b32_e32 v50, v69
	v_mov_b32_e32 v68, v66
	v_mov_b32_e32 v69, v48
	v_mov_b32_e32 v48, v67
	v_pk_fma_f32 v[66:67], v[74:75], v[74:75], v[76:77]
	v_mov_b32_e32 v72, v29
	v_mov_b32_e32 v73, v61
	v_pk_fma_f32 v[66:67], v[70:71], v[70:71], v[66:67]
	v_and_b32_e32 v83, 0xffff0000, v52
	v_pk_fma_f32 v[66:67], v[72:73], v[72:73], v[66:67]
	v_lshlrev_b32_e32 v80, 16, v54
	v_pk_add_f32 v[66:67], v[84:85], v[66:67]
	v_and_b32_e32 v81, 0xffff0000, v54
	v_pk_add_f32 v[50:51], v[50:51], v[66:67]
	v_lshlrev_b32_e32 v82, 16, v52
	v_pk_add_f32 v[50:51], v[68:69], v[50:51]
	v_and_b32_e32 v69, 0xffff0000, v56
	v_pk_add_f32 v[48:49], v[48:49], v[50:51]
	ds_bpermute_b32 v51, v34, v49
	ds_bpermute_b32 v50, v34, v48
	v_lshlrev_b32_e32 v66, 16, v58
	v_and_b32_e32 v67, 0xffff0000, v58
	v_lshlrev_b32_e32 v68, 16, v56
	v_mov_b32_e32 v88, v69
	s_waitcnt lgkmcnt(0)
	v_pk_add_f32 v[48:49], v[48:49], v[50:51]
	ds_bpermute_b32 v51, v35, v49
	ds_bpermute_b32 v50, v35, v48
	v_mov_b32_e32 v89, v83
	v_pk_mul_f32 v[70:71], v[80:81], v[80:81]
	v_pk_mul_f32 v[74:75], v[66:67], v[66:67]
	v_mov_b32_e32 v86, v68
	s_waitcnt lgkmcnt(0)
	v_pk_add_f32 v[48:49], v[48:49], v[50:51]
	ds_bpermute_b32 v51, v36, v49
	ds_bpermute_b32 v50, v36, v48
	v_mov_b32_e32 v87, v82
	v_pk_mul_f32 v[88:89], v[88:89], v[88:89]
	v_mov_b32_e32 v90, v74
	v_mov_b32_e32 v91, v70
	s_waitcnt lgkmcnt(0)
	v_pk_add_f32 v[48:49], v[48:49], v[50:51]
	ds_bpermute_b32 v51, v37, v49
	ds_bpermute_b32 v50, v37, v48
	v_mov_b32_e32 v70, v75
	v_pk_fma_f32 v[74:75], v[86:87], v[86:87], v[88:89]
	v_lshlrev_b32_e32 v54, 16, v53
	v_lshlrev_b32_e32 v58, 16, v57
	s_waitcnt lgkmcnt(0)
	v_pk_add_f32 v[48:49], v[48:49], v[50:51]
	ds_bpermute_b32 v51, v38, v49
	ds_bpermute_b32 v50, v38, v48
	v_lshlrev_b32_e32 v78, 16, v55
	v_and_b32_e32 v79, 0xffff0000, v55
	v_and_b32_e32 v55, 0xffff0000, v53
	v_lshlrev_b32_e32 v52, 16, v59
	s_waitcnt lgkmcnt(0)
	v_pk_add_f32 v[48:49], v[48:49], v[50:51]
	ds_bpermute_b32 v51, v39, v49
	ds_bpermute_b32 v50, v39, v48
	v_and_b32_e32 v53, 0xffff0000, v59
	v_and_b32_e32 v59, 0xffff0000, v57
	v_mov_b32_e32 v76, v58
	v_mov_b32_e32 v77, v54
	s_waitcnt lgkmcnt(0)
	v_pk_add_f32 v[48:49], v[48:49], v[50:51]
	v_mov_b32_e32 v84, v59
	v_pk_fma_f32 v[86:87], v[48:49], s[22:23], v[14:15] op_sel_hi:[1,0,0]
	v_mov_b32_e32 v85, v55
	v_mul_f32_e32 v2, 0x4b800000, v87
	v_cmp_gt_f32_e32 vcc, s27, v87
	v_pk_fma_f32 v[48:49], v[76:77], v[76:77], v[74:75]
	v_pk_mul_f32 v[56:57], v[78:79], v[78:79]
	v_cndmask_b32_e32 v2, v87, v2, vcc
	v_rsq_f32_e32 v2, v2
	v_pk_fma_f32 v[48:49], v[84:85], v[84:85], v[48:49]
	v_pk_mul_f32 v[72:73], v[52:53], v[52:53]
	v_pk_add_f32 v[48:49], v[90:91], v[48:49]
	v_mul_f32_e32 v50, 0x45800000, v2
	v_cndmask_b32_e32 v2, v2, v50, vcc
	v_pk_add_f32 v[48:49], v[70:71], v[48:49]
	v_mov_b32_e32 v50, v72
	v_mov_b32_e32 v51, v56
	v_pk_add_f32 v[48:49], v[50:51], v[48:49]
	v_mov_b32_e32 v56, v73
	v_pk_add_f32 v[50:51], v[56:57], v[48:49]
	ds_bpermute_b32 v57, v34, v51
	ds_bpermute_b32 v56, v34, v50
	v_pk_mul_f32 v[48:49], v[2:3], v[62:63] op_sel_hi:[0,1]
	v_pk_mul_f32 v[60:61], v[2:3], v[60:61] op_sel_hi:[0,1]
	v_cvt_pk_bf16_f32 v48, v48, v49
	v_cvt_pk_bf16_f32 v49, v60, v61
	s_waitcnt lgkmcnt(0)
	v_pk_add_f32 v[56:57], v[50:51], v[56:57]
	ds_bpermute_b32 v61, v35, v57
	ds_bpermute_b32 v60, v35, v56
	v_pk_mul_f32 v[26:27], v[2:3], v[26:27] op_sel_hi:[0,1]
	v_pk_mul_f32 v[30:31], v[2:3], v[30:31] op_sel_hi:[0,1]
	v_cvt_pk_bf16_f32 v51, v26, v27
	v_cvt_pk_bf16_f32 v50, v30, v31
	s_waitcnt lgkmcnt(0)
	v_pk_add_f32 v[26:27], v[56:57], v[60:61]
	ds_bpermute_b32 v31, v36, v27
	ds_bpermute_b32 v30, v36, v26
	v_mul_f32_e32 v2, 0x4b800000, v86
	v_cmp_gt_f32_e32 vcc, s27, v86
	s_waitcnt lgkmcnt(0)
	v_pk_add_f32 v[30:31], v[26:27], v[30:31]
	ds_bpermute_b32 v57, v37, v31
	ds_bpermute_b32 v56, v37, v30
	v_cndmask_b32_e32 v2, v86, v2, vcc
	v_rsq_f32_e32 v2, v2
	s_waitcnt lgkmcnt(0)
	v_pk_add_f32 v[30:31], v[30:31], v[56:57]
	ds_bpermute_b32 v57, v38, v31
	ds_bpermute_b32 v56, v38, v30
	v_mul_f32_e32 v26, 0x45800000, v2
	v_cndmask_b32_e32 v2, v2, v26, vcc
	v_pk_mul_f32 v[26:27], v[2:3], v[64:65] op_sel_hi:[0,1]
	v_pk_mul_f32 v[28:29], v[2:3], v[28:29] op_sel_hi:[0,1]
	v_pk_mul_f32 v[24:25], v[2:3], v[24:25] op_sel_hi:[0,1]
	v_cvt_pk_bf16_f32 v26, v26, v27
	v_cvt_pk_bf16_f32 v27, v28, v29
	v_cvt_pk_bf16_f32 v28, v24, v25
	s_waitcnt lgkmcnt(0)
	v_pk_add_f32 v[24:25], v[30:31], v[56:57]
	ds_bpermute_b32 v31, v39, v25
	ds_bpermute_b32 v30, v39, v24
	v_pk_mul_f32 v[22:23], v[2:3], v[22:23] op_sel_hi:[0,1]
	v_cvt_pk_bf16_f32 v29, v22, v23
	v_lshlrev_b64 v[22:23], 10, v[0:1]
	v_lshl_add_u64 v[56:57], v[6:7], 0, v[22:23]
	s_waitcnt lgkmcnt(0)
	v_pk_add_f32 v[24:25], v[24:25], v[30:31]
	v_lshl_add_u64 v[22:23], v[8:9], 0, v[22:23]
	v_pk_fma_f32 v[24:25], v[24:25], s[22:23], v[14:15] op_sel_hi:[1,0,0]
	global_store_dwordx4 v[22:23], v[26:29], off sc1
	v_mul_f32_e32 v1, 0x4b800000, v25
	v_cmp_gt_f32_e32 vcc, s27, v25
	global_store_dwordx4 v[56:57], v[48:51], off sc1
	s_nop 0
	v_cndmask_b32_e32 v1, v25, v1, vcc
	v_rsq_f32_e32 v1, v1
	s_nop 0
	v_mul_f32_e32 v2, 0x45800000, v1
	v_cndmask_b32_e32 v2, v1, v2, vcc
	v_mul_f32_e32 v1, 0x4b800000, v24
	v_cmp_gt_f32_e32 vcc, s27, v24
	v_pk_mul_f32 v[22:23], v[2:3], v[82:83] op_sel_hi:[0,1]
	v_pk_mul_f32 v[26:27], v[2:3], v[54:55] op_sel_hi:[0,1]
	v_cndmask_b32_e32 v1, v24, v1, vcc
	v_rsq_f32_e32 v1, v1
	v_cvt_pk_bf16_f32 v22, v22, v23
	v_cvt_pk_bf16_f32 v23, v26, v27
	v_pk_mul_f32 v[26:27], v[2:3], v[80:81] op_sel_hi:[0,1]
	v_cvt_pk_bf16_f32 v24, v26, v27
	v_pk_mul_f32 v[26:27], v[2:3], v[78:79] op_sel_hi:[0,1]
	v_mul_f32_e32 v2, 0x45800000, v1
	v_cndmask_b32_e32 v2, v1, v2, vcc
	v_cvt_f32_i32_e32 v1, v92
	v_cvt_pk_bf16_f32 v25, v26, v27
	v_pk_mul_f32 v[26:27], v[2:3], v[68:69] op_sel_hi:[0,1]
	v_pk_mul_f32 v[28:29], v[2:3], v[58:59] op_sel_hi:[0,1]
	v_cvt_pk_bf16_f32 v26, v26, v27
	v_cvt_pk_bf16_f32 v27, v28, v29
	v_pk_mul_f32 v[28:29], v[2:3], v[66:67] op_sel_hi:[0,1]
	v_pk_mul_f32 v[30:31], v[2:3], v[52:53] op_sel_hi:[0,1]
	v_cvt_pk_bf16_f32 v28, v28, v29
	v_cvt_pk_bf16_f32 v29, v30, v31
	v_lshl_add_u64 v[30:31], v[6:7], 0, v[20:21]
	v_lshl_add_u64 v[20:21], v[8:9], 0, v[20:21]
	v_mul_f32_e32 v1, v33, v1
	global_store_dwordx4 v[20:21], v[26:29], off sc1
	v_and_b32_e32 v20, 0x7fffffff, v1
	v_cmp_nlt_f32_e64 s[8:9], |v1|, s28
	global_store_dwordx4 v[30:31], v[22:25], off sc1
	s_and_saveexec_b64 s[10:11], s[8:9]
	s_xor_b64 s[24:25], exec, s[10:11]
	s_cbranch_execz .LBB0_971
	v_lshrrev_b32_e32 v2, 23, v20
	v_add_u32_e32 v2, 0xffffff88, v2
	v_cmp_lt_u32_e32 vcc, 63, v2
	s_nop 1
	v_cndmask_b32_e32 v21, 0, v32, vcc
	v_add_u32_e32 v2, v21, v2
	v_cmp_lt_u32_e64 s[8:9], 31, v2
	s_nop 1
	v_cndmask_b32_e64 v21, 0, v45, s[8:9]
	v_add_u32_e32 v2, v21, v2
	v_cmp_lt_u32_e64 s[10:11], 31, v2
	s_nop 1
	v_cndmask_b32_e64 v21, 0, v45, s[10:11]
	v_add_u32_e32 v21, v21, v2
	v_and_b32_e32 v2, 0x7fffff, v20
	v_or_b32_e32 v50, 0x800000, v2
	v_mad_u64_u32 v[22:23], s[12:13], v50, s29, 0
	v_mov_b32_e32 v2, v23
	v_mad_u64_u32 v[24:25], s[12:13], v50, s30, v[2:3]
	v_mov_b32_e32 v2, v25
	v_mad_u64_u32 v[26:27], s[12:13], v50, s31, v[2:3]
	v_mov_b32_e32 v2, v27
	v_mad_u64_u32 v[28:29], s[12:13], v50, s34, v[2:3]
	v_mov_b32_e32 v2, v29
	v_mad_u64_u32 v[30:31], s[12:13], v50, s35, v[2:3]
	v_mov_b32_e32 v2, v31
	v_mad_u64_u32 v[48:49], s[12:13], v50, s36, v[2:3]
	v_mov_b32_e32 v2, v49
	v_mad_u64_u32 v[50:51], s[12:13], v50, s37, v[2:3]
	v_cndmask_b32_e32 v23, v48, v28, vcc
	v_cndmask_b32_e32 v2, v50, v30, vcc
	v_cndmask_b32_e32 v27, v51, v48, vcc
	v_cndmask_b32_e64 v25, v2, v23, s[8:9]
	v_cndmask_b32_e64 v2, v27, v2, s[8:9]
	v_cndmask_b32_e32 v27, v30, v26, vcc
	v_cndmask_b32_e64 v23, v23, v27, s[8:9]
	v_cndmask_b32_e64 v2, v2, v25, s[10:11]
	v_cndmask_b32_e64 v25, v25, v23, s[10:11]
	v_sub_u32_e32 v29, 32, v21
	v_alignbit_b32 v30, v2, v25, v29
	v_cmp_eq_u32_e64 s[12:13], 0, v21
	v_cndmask_b32_e32 v22, v26, v22, vcc
	s_nop 0
	v_cndmask_b32_e64 v21, v30, v2, s[12:13]
	v_cndmask_b32_e32 v2, v28, v24, vcc
	v_cndmask_b32_e64 v24, v27, v2, s[8:9]
	v_cndmask_b32_e64 v23, v23, v24, s[10:11]
	v_alignbit_b32 v27, v25, v23, v29
	v_cndmask_b32_e64 v25, v27, v25, s[12:13]
	v_bfe_u32 v30, v21, 29, 1
	v_cndmask_b32_e64 v2, v2, v22, s[8:9]
	v_alignbit_b32 v27, v21, v25, 30
	v_sub_u32_e32 v31, 0, v30
	v_cndmask_b32_e64 v2, v24, v2, s[10:11]
	v_xor_b32_e32 v27, v27, v31
	v_alignbit_b32 v22, v23, v2, v29
	v_cndmask_b32_e64 v22, v22, v23, s[12:13]
	v_ffbh_u32_e32 v24, v27
	v_alignbit_b32 v23, v25, v22, 30
	v_min_u32_e32 v24, 32, v24
	v_alignbit_b32 v2, v22, v2, 30
	v_xor_b32_e32 v23, v23, v31
	v_sub_u32_e32 v25, 31, v24
	v_xor_b32_e32 v2, v2, v31
	v_alignbit_b32 v26, v27, v23, v25
	v_alignbit_b32 v2, v23, v2, v25
	v_alignbit_b32 v22, v26, v2, 9
	v_ffbh_u32_e32 v23, v22
	v_min_u32_e32 v23, 32, v23
	v_lshrrev_b32_e32 v28, 29, v21
	v_not_b32_e32 v25, v23
	v_alignbit_b32 v2, v22, v2, v25
	v_lshlrev_b32_e32 v22, 31, v28
	v_or_b32_e32 v25, 0x33000000, v22
	v_add_lshl_u32 v23, v23, v24, 23
	v_lshrrev_b32_e32 v2, 9, v2
	v_sub_u32_e32 v23, v25, v23
	v_or_b32_e32 v22, 0.5, v22
	v_lshlrev_b32_e32 v24, 23, v24
	v_or_b32_e32 v2, v23, v2
	v_lshrrev_b32_e32 v23, 9, v26
	v_sub_u32_e32 v22, v22, v24
	v_or_b32_e32 v22, v23, v22
	v_mul_f32_e32 v23, 0x3fc90fda, v22
	v_fma_f32 v24, v22, s38, -v23
	v_fmac_f32_e32 v24, 0x33a22168, v22
	v_fmac_f32_e32 v24, 0x3fc90fda, v2
	v_lshrrev_b32_e32 v21, 30, v21
	v_add_f32_e32 v2, v23, v24
	v_add_u32_e32 v21, v30, v21
.LBB0_971:
	s_andn2_saveexec_b64 s[8:9], s[24:25]
	v_mul_f32_e64 v2, |v1|, s39
	v_rndne_f32_e32 v22, v2
	v_cvt_i32_f32_e32 v21, v22
	v_fma_f32 v2, v22, s52, |v1|
	v_fmac_f32_e32 v2, 0xb3a22168, v22
	v_fmac_f32_e32 v2, 0xa7c234c4, v22
	s_or_b64 exec, exec, s[8:9]
	v_mul_f32_e32 v23, v2, v2
	v_fmamk_f32 v24, v23, 0xb94c1982, v43
	v_fmaak_f32 v24, v23, v24, 0xbe2aaa9d
	v_mul_f32_e32 v24, v23, v24
	v_fmac_f32_e32 v2, v2, v24
	v_fmamk_f32 v24, v23, 0x37d75334, v44
	v_fmaak_f32 v24, v23, v24, 0x3d2aabf7
	v_fmaak_f32 v24, v23, v24, 0xbf000004
	v_fma_f32 v23, v23, v24, 1.0
	v_lshlrev_b32_e32 v24, 30, v21
	v_and_b32_e32 v21, 1, v21
	v_cmp_eq_u32_e32 vcc, 0, v21
	v_xor_b32_e32 v20, v20, v1
	v_and_b32_e32 v25, 0x80000000, v24
	v_cndmask_b32_e32 v21, v23, v2, vcc
	v_xor_b32_e32 v20, v20, v21
	v_xor_b32_e32 v2, 0x80000000, v2
	v_xor_b32_e32 v20, v20, v25
	v_cndmask_b32_e32 v2, v2, v23, vcc
	v_cmp_class_f32_e64 vcc, v1, s54
	v_lshlrev_b32_e32 v22, 16, v47
	v_bitop3_b32 v2, v2, v24, s53 bitop3:0x78
	v_cndmask_b32_e32 v29, v46, v20, vcc
	v_lshlrev_b32_e32 v17, 16, v17
	v_cndmask_b32_e32 v28, v46, v2, vcc
	v_mul_f32_e32 v1, v29, v22
	v_fma_f32 v2, v28, v17, -v1
	v_mul_f32_e32 v1, v29, v17
	v_fmac_f32_e32 v1, v28, v22
	v_lshlrev_b64 v[24:25], 7, v[18:19]
	ds_bpermute_b32 v17, v40, v2
	ds_bpermute_b32 v19, v41, v2
	ds_bpermute_b32 v20, v42, v2
	ds_bpermute_b32 v21, v40, v1
	ds_bpermute_b32 v22, v41, v1
	ds_bpermute_b32 v23, v42, v1
	v_lshl_or_b32 v24, v212, 2, v24
	v_lshl_add_u64 v[26:27], s[48:49], 0, v[24:25]
	v_lshl_add_u64 v[24:25], s[50:51], 0, v[24:25]
	global_store_dword v[26:27], v28, off
	global_store_dword v[24:25], v29, off
	s_and_saveexec_b64 s[8:9], s[6:7]
	s_cbranch_execz .LBB0_968
	s_waitcnt lgkmcnt(3)
	v_cvt_pk_bf16_f32 v25, v19, v20
	s_waitcnt lgkmcnt(2)
	v_cvt_pk_bf16_f32 v26, v1, v21
	v_mov_b64_e32 v[20:21], s[42:43]
	v_cvt_pk_bf16_f32 v24, v2, v17
	v_mad_i64_i32 v[18:19], s[10:11], v18, s55, v[20:21]
	v_mov_b32_e32 v17, v3
	v_lshl_add_u64 v[18:19], v[18:19], 0, v[16:17]
	v_add_co_u32_e32 v20, vcc, s56, v18
	s_waitcnt lgkmcnt(0)
	v_cvt_pk_bf16_f32 v27, v22, v23
	v_addc_co_u32_e32 v21, vcc, 0, v19, vcc
	v_add_co_u32_e32 v18, vcc, 0x19005000, v18
	global_store_dwordx4 v[20:21], v[24:27], off offset:256 sc1
	global_store_dwordx4 v[20:21], v[24:27], off offset:640 sc1
	global_store_dwordx4 v[20:21], v[24:27], off offset:1024 sc1
	global_store_dwordx4 v[20:21], v[24:27], off offset:1408 sc1
	global_store_dwordx4 v[20:21], v[24:27], off offset:1792 sc1
	global_store_dwordx4 v[20:21], v[24:27], off offset:2176 sc1
	global_store_dwordx4 v[20:21], v[24:27], off offset:2560 sc1
	global_store_dwordx4 v[20:21], v[24:27], off offset:2944 sc1
	global_store_dwordx4 v[20:21], v[24:27], off offset:3328 sc1
	global_store_dwordx4 v[20:21], v[24:27], off offset:3712 sc1
	v_addc_co_u32_e32 v19, vcc, 0, v19, vcc
	global_store_dwordx4 v[18:19], v[24:27], off sc1
	global_store_dwordx4 v[18:19], v[24:27], off offset:384 sc1
	s_branch .LBB0_968

.LBB0_1063:
	s_or_b64 exec, exec, s[6:7]
	s_bitcmp0_b32 s90, 1
	s_cselect_b64 s[8:9], -1, 0
	v_ashrrev_i32_e32 v152, 6, v154
	s_and_b32 s33, s90, 32
	v_ashrrev_i32_e32 v153, 31, v152
	v_cvt_pk_bf16_f32 v124, v124, v125
	v_cvt_pk_bf16_f32 v125, v126, v127
	v_cvt_pk_bf16_f32 v126, v120, v121
	s_bitcmp1_b32 s90, 5
	v_ashrrev_i32_e32 v120, 5, v146
	v_cvt_pk_bf16_f32 v127, v122, v123
	s_mov_b64 s[6:7], -1
	s_cselect_b64 s[68:69], -1, 0
	s_cmp_eq_u32 s33, 0
	v_lshlrev_b64 v[152:153], 12, v[152:153]
	v_ashrrev_i32_e32 v121, 31, v120
	s_cbranch_scc1 .LBB0_1065
	v_lshlrev_b64 v[122:123], 20, v[120:121]
	v_lshl_add_u64 v[122:123], s[28:29], 0, v[122:123]
	v_lshl_add_u64 v[122:123], v[122:123], 0, v[152:153]
	v_lshl_add_u64 v[122:123], v[122:123], 0, v[134:135]
	s_mov_b64 s[6:7], 0
	global_store_dwordx4 v[122:123], v[124:127], off sc1
.LBB0_1065:
	s_mul_i32 s33, s62, 0x180
	v_or_b32_e32 v122, s33, v162
	v_cndmask_b32_e64 v154, v122, v154, s[8:9]
	s_andn2_b64 vcc, exec, s[6:7]
	v_ashrrev_i32_e32 v155, 31, v154
	s_cbranch_vccnz .LBB0_1067
	v_mad_i64_i32 v[122:123], s[6:7], s71, v146, 0
	v_lshl_add_u64 v[122:123], v[122:123], 1, s[28:29]
	v_lshl_add_u64 v[122:123], v[154:155], 1, v[122:123]
	global_store_dwordx4 v[122:123], v[124:127], off sc1

.LBB0_1097:
	v_lshlrev_b64 v[112:113], 20, v[120:121]
	v_lshl_add_u64 v[112:113], s[28:29], 0, v[112:113]
	v_lshl_add_u64 v[112:113], v[112:113], 0, v[152:153]
	v_lshl_add_u64 v[112:113], v[112:113], 0, v[134:135]
	global_store_dwordx4 v[112:113], v[116:119], off offset:256 sc1
	s_cbranch_execnz .LBB0_1071
.LBB0_1098:
	v_mad_i64_i32 v[112:113], s[62:63], s71, v122, 0
	v_lshl_add_u64 v[112:113], v[112:113], 1, s[28:29]
	v_lshl_add_u64 v[112:113], v[154:155], 1, v[112:113]
	global_store_dwordx4 v[112:113], v[116:119], off sc1
	v_or_b32_e32 v112, 32, v146
	v_ashrrev_i32_e32 v113, 31, v112
	s_and_saveexec_b64 s[62:63], s[66:67]
	s_cbranch_execnz .LBB0_1072
	s_branch .LBB0_1073
.LBB0_1099:
	v_lshlrev_b64 v[104:105], 20, v[106:107]
	v_lshl_add_u64 v[104:105], s[28:29], 0, v[104:105]
	v_lshl_add_u64 v[104:105], v[104:105], 0, v[152:153]
	v_lshl_add_u64 v[104:105], v[104:105], 0, v[134:135]
	global_store_dwordx4 v[104:105], v[108:111], off sc1
	s_cbranch_execnz .LBB0_1075
.LBB0_1100:
	v_mad_i64_i32 v[104:105], s[62:63], s71, v112, 0
	v_lshl_add_u64 v[104:105], v[104:105], 1, s[28:29]
	v_lshl_add_u64 v[104:105], v[154:155], 1, v[104:105]
	global_store_dwordx4 v[104:105], v[108:111], off sc1
	v_or_b32_e32 v104, 48, v146
	v_ashrrev_i32_e32 v105, 31, v104
	s_and_saveexec_b64 s[62:63], s[66:67]
	s_cbranch_execnz .LBB0_1076
	s_branch .LBB0_1077
.LBB0_1101:
	v_lshlrev_b64 v[96:97], 20, v[98:99]
	v_lshl_add_u64 v[96:97], s[28:29], 0, v[96:97]
	v_lshl_add_u64 v[96:97], v[96:97], 0, v[152:153]
	v_lshl_add_u64 v[96:97], v[96:97], 0, v[134:135]
	global_store_dwordx4 v[96:97], v[100:103], off offset:256 sc1
	s_cbranch_execnz .LBB0_1079
.LBB0_1102:
	v_mad_i64_i32 v[96:97], s[62:63], s71, v104, 0
	v_lshl_add_u64 v[96:97], v[96:97], 1, s[28:29]
	v_lshl_add_u64 v[96:97], v[154:155], 1, v[96:97]
	global_store_dwordx4 v[96:97], v[100:103], off sc1
	v_add_u32_e32 v96, 0x80, v146
	v_ashrrev_i32_e32 v97, 31, v96
	s_and_saveexec_b64 s[62:63], s[66:67]
	s_cbranch_execnz .LBB0_1080
	s_branch .LBB0_1081
.LBB0_1103:
	v_lshlrev_b64 v[88:89], 20, v[90:91]
	v_lshl_add_u64 v[88:89], s[28:29], 0, v[88:89]
	v_lshl_add_u64 v[88:89], v[88:89], 0, v[152:153]
	v_lshl_add_u64 v[88:89], v[88:89], 0, v[134:135]
	global_store_dwordx4 v[88:89], v[92:95], off sc1
	s_cbranch_execnz .LBB0_1083
.LBB0_1104:
	v_mad_i64_i32 v[88:89], s[62:63], s71, v96, 0
	v_lshl_add_u64 v[88:89], v[88:89], 1, s[28:29]
	v_lshl_add_u64 v[88:89], v[154:155], 1, v[88:89]
	global_store_dwordx4 v[88:89], v[92:95], off sc1
	v_add_u32_e32 v88, 0x90, v146
	v_ashrrev_i32_e32 v89, 31, v88
	s_and_saveexec_b64 s[62:63], s[66:67]
	s_cbranch_execnz .LBB0_1084
	s_branch .LBB0_1085
.LBB0_1105:
	v_lshlrev_b64 v[80:81], 20, v[82:83]
	v_lshl_add_u64 v[80:81], s[28:29], 0, v[80:81]
	v_lshl_add_u64 v[80:81], v[80:81], 0, v[152:153]
	v_lshl_add_u64 v[80:81], v[80:81], 0, v[134:135]
	global_store_dwordx4 v[80:81], v[84:87], off offset:256 sc1
	s_cbranch_execnz .LBB0_1087
.LBB0_1106:
	v_mad_i64_i32 v[80:81], s[62:63], s71, v88, 0
	v_lshl_add_u64 v[80:81], v[80:81], 1, s[28:29]
	v_lshl_add_u64 v[80:81], v[154:155], 1, v[80:81]
	global_store_dwordx4 v[80:81], v[84:87], off sc1
	v_add_u32_e32 v80, 0xa0, v146
	v_ashrrev_i32_e32 v81, 31, v80
	s_and_saveexec_b64 s[62:63], s[66:67]
	s_cbranch_execnz .LBB0_1088
	s_branch .LBB0_1089
.LBB0_1107:
	v_lshlrev_b64 v[72:73], 20, v[74:75]
	v_lshl_add_u64 v[72:73], s[28:29], 0, v[72:73]
	v_lshl_add_u64 v[72:73], v[72:73], 0, v[152:153]
	v_lshl_add_u64 v[72:73], v[72:73], 0, v[134:135]
	global_store_dwordx4 v[72:73], v[76:79], off sc1
	s_cbranch_execnz .LBB0_1091
.LBB0_1108:
	v_mad_i64_i32 v[72:73], s[62:63], s71, v80, 0
	v_lshl_add_u64 v[72:73], v[72:73], 1, s[28:29]
	v_lshl_add_u64 v[72:73], v[154:155], 1, v[72:73]
	global_store_dwordx4 v[72:73], v[76:79], off sc1
	v_add_u32_e32 v72, 0xb0, v146
	v_ashrrev_i32_e32 v73, 31, v72
	s_and_saveexec_b64 s[62:63], s[66:67]
	s_cbranch_execnz .LBB0_1092
	s_branch .LBB0_1093
.LBB0_1109:
	v_lshlrev_b64 v[66:67], 20, v[64:65]
	v_lshl_add_u64 v[66:67], s[28:29], 0, v[66:67]
	v_lshl_add_u64 v[66:67], v[66:67], 0, v[152:153]
	v_lshl_add_u64 v[66:67], v[66:67], 0, v[134:135]
	global_store_dwordx4 v[66:67], v[68:71], off offset:256 sc1
	s_cbranch_execnz .LBB0_1095
.LBB0_1110:
	v_mad_i64_i32 v[66:67], s[62:63], s71, v72, 0
	v_lshl_add_u64 v[66:67], v[66:67], 1, s[28:29]
	v_lshl_add_u64 v[66:67], v[154:155], 1, v[66:67]
	global_store_dwordx4 v[66:67], v[68:71], off sc1
	s_bitset1_b32 s35, 7
	s_andn2_b64 vcc, exec, s[64:65]
	v_or_b32_e32 v70, s35, v162
	s_cbranch_vccz .LBB0_1096

.LBB0_1114:
	s_or_b64 exec, exec, s[64:65]
	v_ashrrev_i32_e32 v76, 6, v70
	v_ashrrev_i32_e32 v77, 31, v76
	v_cvt_pk_bf16_f32 v60, v60, v61
	v_cvt_pk_bf16_f32 v61, v62, v63
	v_cvt_pk_bf16_f32 v62, v56, v57
	v_cvt_pk_bf16_f32 v63, v58, v59
	s_mov_b64 s[64:65], -1
	s_and_b64 vcc, exec, s[6:7]
	v_lshlrev_b64 v[56:57], 12, v[76:77]
	s_cbranch_vccnz .LBB0_1116
	v_lshlrev_b64 v[58:59], 20, v[120:121]
	v_lshl_add_u64 v[58:59], s[28:29], 0, v[58:59]
	v_lshl_add_u64 v[58:59], v[58:59], 0, v[56:57]
	v_lshl_add_u64 v[58:59], v[58:59], 0, v[134:135]
	s_mov_b64 s[64:65], 0
	global_store_dwordx4 v[58:59], v[60:63], off sc1
.LBB0_1116:
	s_ashr_i32 s33, s35, 7
	s_mulk_i32 s33, 0xc0
	v_add_u32_e32 v58, s33, v162
	v_cndmask_b32_e64 v58, v58, v70, s[8:9]
	s_andn2_b64 vcc, exec, s[64:65]
	v_ashrrev_i32_e32 v59, 31, v58
	s_cbranch_vccnz .LBB0_1118
	v_mad_i64_i32 v[70:71], s[8:9], s71, v146, 0
	v_lshl_add_u64 v[70:71], v[70:71], 1, s[28:29]
	v_lshl_add_u64 v[70:71], v[58:59], 1, v[70:71]
	global_store_dwordx4 v[70:71], v[60:63], off sc1

.LBB0_1144:
	s_or_b64 exec, exec, s[8:9]
	v_cvt_pk_bf16_f32 v4, v4, v5
	v_cvt_pk_bf16_f32 v5, v6, v7
	v_cvt_pk_bf16_f32 v6, v0, v1
	v_cvt_pk_bf16_f32 v7, v2, v3
	s_and_b64 vcc, exec, s[6:7]
	s_mov_b64 s[6:7], -1
	s_cbranch_vccnz .LBB0_1146
	v_lshlrev_b64 v[0:1], 20, v[64:65]
	v_lshl_add_u64 v[0:1], s[28:29], 0, v[0:1]
	v_lshl_add_u64 v[0:1], v[0:1], 0, v[56:57]
	v_lshl_add_u64 v[0:1], v[0:1], 0, v[134:135]
	s_mov_b64 s[6:7], 0
	global_store_dwordx4 v[0:1], v[4:7], off offset:256 sc1
.LBB0_1146:
	s_andn2_b64 vcc, exec, s[6:7]
	s_cbranch_vccnz .LBB0_1045
	v_mad_i64_i32 v[0:1], s[6:7], s71, v72, 0
	v_lshl_add_u64 v[0:1], v[0:1], 1, s[28:29]
	v_lshl_add_u64 v[0:1], v[58:59], 1, v[0:1]
	global_store_dwordx4 v[0:1], v[4:7], off sc1
	s_branch .LBB0_1045
.LBB0_1148:
	v_lshlrev_b64 v[48:49], 20, v[120:121]
	v_lshl_add_u64 v[48:49], s[28:29], 0, v[48:49]
	v_lshl_add_u64 v[48:49], v[48:49], 0, v[56:57]
	v_lshl_add_u64 v[48:49], v[48:49], 0, v[134:135]
	global_store_dwordx4 v[48:49], v[52:55], off offset:256 sc1
	s_cbranch_execnz .LBB0_1122
.LBB0_1149:
	v_mad_i64_i32 v[48:49], s[8:9], s71, v122, 0
	v_lshl_add_u64 v[48:49], v[48:49], 1, s[28:29]
	v_lshl_add_u64 v[48:49], v[58:59], 1, v[48:49]
	global_store_dwordx4 v[48:49], v[52:55], off sc1
	s_and_saveexec_b64 s[8:9], s[62:63]
	s_cbranch_execnz .LBB0_1123
	s_branch .LBB0_1124
.LBB0_1150:
	v_lshlrev_b64 v[40:41], 20, v[106:107]
	v_lshl_add_u64 v[40:41], s[28:29], 0, v[40:41]
	v_lshl_add_u64 v[40:41], v[40:41], 0, v[56:57]
	v_lshl_add_u64 v[40:41], v[40:41], 0, v[134:135]
	global_store_dwordx4 v[40:41], v[44:47], off sc1
	s_cbranch_execnz .LBB0_1126
.LBB0_1151:
	v_mad_i64_i32 v[40:41], s[8:9], s71, v112, 0
	v_lshl_add_u64 v[40:41], v[40:41], 1, s[28:29]
	v_lshl_add_u64 v[40:41], v[58:59], 1, v[40:41]
	global_store_dwordx4 v[40:41], v[44:47], off sc1
	s_and_saveexec_b64 s[8:9], s[62:63]
	s_cbranch_execnz .LBB0_1127
	s_branch .LBB0_1128
.LBB0_1152:
	v_lshlrev_b64 v[32:33], 20, v[98:99]
	v_lshl_add_u64 v[32:33], s[28:29], 0, v[32:33]
	v_lshl_add_u64 v[32:33], v[32:33], 0, v[56:57]
	v_lshl_add_u64 v[32:33], v[32:33], 0, v[134:135]
	global_store_dwordx4 v[32:33], v[36:39], off offset:256 sc1
	s_cbranch_execnz .LBB0_1130
.LBB0_1153:
	v_mad_i64_i32 v[32:33], s[8:9], s71, v104, 0
	v_lshl_add_u64 v[32:33], v[32:33], 1, s[28:29]
	v_lshl_add_u64 v[32:33], v[58:59], 1, v[32:33]
	global_store_dwordx4 v[32:33], v[36:39], off sc1
	s_and_saveexec_b64 s[8:9], s[62:63]
	s_cbranch_execnz .LBB0_1131
	s_branch .LBB0_1132
.LBB0_1154:
	v_lshlrev_b64 v[24:25], 20, v[90:91]
	v_lshl_add_u64 v[24:25], s[28:29], 0, v[24:25]
	v_lshl_add_u64 v[24:25], v[24:25], 0, v[56:57]
	v_lshl_add_u64 v[24:25], v[24:25], 0, v[134:135]
	global_store_dwordx4 v[24:25], v[28:31], off sc1
	s_cbranch_execnz .LBB0_1134
.LBB0_1155:
	v_mad_i64_i32 v[24:25], s[8:9], s71, v96, 0
	v_lshl_add_u64 v[24:25], v[24:25], 1, s[28:29]
	v_lshl_add_u64 v[24:25], v[58:59], 1, v[24:25]
	global_store_dwordx4 v[24:25], v[28:31], off sc1
	s_and_saveexec_b64 s[8:9], s[62:63]
	s_cbranch_execnz .LBB0_1135
	s_branch .LBB0_1136
.LBB0_1156:
	v_lshlrev_b64 v[16:17], 20, v[82:83]
	v_lshl_add_u64 v[16:17], s[28:29], 0, v[16:17]
	v_lshl_add_u64 v[16:17], v[16:17], 0, v[56:57]
	v_lshl_add_u64 v[16:17], v[16:17], 0, v[134:135]
	global_store_dwordx4 v[16:17], v[20:23], off offset:256 sc1
	s_cbranch_execnz .LBB0_1138
.LBB0_1157:
	v_mad_i64_i32 v[16:17], s[8:9], s71, v88, 0
	v_lshl_add_u64 v[16:17], v[16:17], 1, s[28:29]
	v_lshl_add_u64 v[16:17], v[58:59], 1, v[16:17]
	global_store_dwordx4 v[16:17], v[20:23], off sc1
	s_and_saveexec_b64 s[8:9], s[62:63]
	s_cbranch_execnz .LBB0_1139
	s_branch .LBB0_1140
.LBB0_1158:
	v_lshlrev_b64 v[8:9], 20, v[74:75]
	v_lshl_add_u64 v[8:9], s[28:29], 0, v[8:9]
	v_lshl_add_u64 v[8:9], v[8:9], 0, v[56:57]
	v_lshl_add_u64 v[8:9], v[8:9], 0, v[134:135]
	global_store_dwordx4 v[8:9], v[12:15], off sc1
	s_cbranch_execnz .LBB0_1142
.LBB0_1159:
	v_mad_i64_i32 v[8:9], s[8:9], s71, v80, 0
	v_lshl_add_u64 v[8:9], v[8:9], 1, s[28:29]
	v_lshl_add_u64 v[8:9], v[58:59], 1, v[8:9]
	global_store_dwordx4 v[8:9], v[12:15], off sc1
	s_and_saveexec_b64 s[8:9], s[62:63]
	s_cbranch_execnz .LBB0_1143
	s_branch .LBB0_1144

.LBB0_1220:
	ds_bpermute_b32 v64, v241, v184
	s_mul_i32 s6, s50, 0x1e00
	s_add_u32 s6, s61, s6
	s_addc_u32 s7, s62, 0
	s_lshl_b32 s10, s49, 1
	s_add_u32 s6, s6, s10
	s_addc_u32 s7, s7, 0
	s_lshl_b32 s8, s50, 12
	s_waitcnt lgkmcnt(0)
	v_add_f32_e32 v72, v184, v64
	s_add_u32 s11, s63, s8
	v_div_scale_f32 v73, s[8:9], v72, v72, 1.0
	v_rcp_f32_e32 v74, v73
	s_addc_u32 s9, s64, 0
	s_add_u32 s8, s11, s10
	s_addc_u32 s9, s9, 0
	v_lshlrev_b32_e32 v144, 1, v150
	v_fma_f32 v64, -v73, v74, 1.0
	v_lshl_add_u64 v[70:71], s[6:7], 0, v[144:145]
	v_lshl_add_u64 v[68:69], s[8:9], 0, v[144:145]
	v_or_b32_e32 v144, s24, v199
	v_fmac_f32_e32 v74, v64, v74
	v_mad_u64_u32 v[64:65], s[6:7], v144, s72, v[70:71]
	s_waitcnt vmcnt(0)
	s_barrier
	global_load_dwordx4 v[64:67], v[64:65], off offset:1024
	v_div_scale_f32 v75, vcc, 1.0, v72, 1.0
	v_mul_f32_e32 v76, v75, v74
	v_fma_f32 v77, -v73, v76, v75
	v_fmac_f32_e32 v76, v77, v74
	v_fma_f32 v73, -v73, v76, v75
	v_div_fmas_f32 v73, v73, v74, v76
	v_div_fixup_f32 v72, v73, v72, 1.0
	v_pk_mul_f32 v[16:17], v[16:17], v[72:73] op_sel_hi:[1,0]
	v_pk_mul_f32 v[18:19], v[18:19], v[72:73] op_sel_hi:[1,0]
	v_cvt_pk_bf16_f32 v16, v16, v17
	v_cvt_pk_bf16_f32 v17, v18, v19
	v_pk_mul_f32 v[18:19], v[20:21], v[72:73] op_sel_hi:[1,0]
	v_pk_mul_f32 v[20:21], v[22:23], v[72:73] op_sel_hi:[1,0]
	v_pk_mul_f32 v[0:1], v[0:1], v[72:73] op_sel_hi:[1,0]
	v_pk_mul_f32 v[2:3], v[2:3], v[72:73] op_sel_hi:[1,0]
	v_mad_u64_u32 v[74:75], s[6:7], v240, s69, v[146:147]
	v_cvt_pk_bf16_f32 v18, v18, v19
	v_cvt_pk_bf16_f32 v19, v20, v21
	v_cvt_pk_bf16_f32 v0, v0, v1
	v_cvt_pk_bf16_f32 v1, v2, v3
	v_pk_mul_f32 v[2:3], v[4:5], v[72:73] op_sel_hi:[1,0]
	v_pk_mul_f32 v[4:5], v[6:7], v[72:73] op_sel_hi:[1,0]
	ds_write2_b64 v74, v[16:17], v[18:19] offset0:16 offset1:18
	v_pk_mul_f32 v[16:17], v[24:25], v[72:73] op_sel_hi:[1,0]
	v_pk_mul_f32 v[18:19], v[26:27], v[72:73] op_sel_hi:[1,0]
	v_cvt_pk_bf16_f32 v2, v2, v3
	v_cvt_pk_bf16_f32 v3, v4, v5
	v_cvt_pk_bf16_f32 v16, v16, v17
	v_cvt_pk_bf16_f32 v17, v18, v19
	v_pk_mul_f32 v[18:19], v[28:29], v[72:73] op_sel_hi:[1,0]
	v_pk_mul_f32 v[20:21], v[30:31], v[72:73] op_sel_hi:[1,0]
	ds_write2_b64 v74, v[0:1], v[2:3] offset0:24 offset1:26
	v_pk_mul_f32 v[0:1], v[8:9], v[72:73] op_sel_hi:[1,0]
	v_pk_mul_f32 v[2:3], v[10:11], v[72:73] op_sel_hi:[1,0]
	v_cvt_pk_bf16_f32 v18, v18, v19
	v_cvt_pk_bf16_f32 v19, v20, v21
	v_cvt_pk_bf16_f32 v0, v0, v1
	v_cvt_pk_bf16_f32 v1, v2, v3
	v_pk_mul_f32 v[2:3], v[12:13], v[72:73] op_sel_hi:[1,0]
	v_pk_mul_f32 v[4:5], v[14:15], v[72:73] op_sel_hi:[1,0]
	v_pk_mul_f32 v[48:49], v[48:49], v[72:73] op_sel_hi:[1,0]
	v_pk_mul_f32 v[50:51], v[50:51], v[72:73] op_sel_hi:[1,0]
	v_pk_mul_f32 v[32:33], v[32:33], v[72:73] op_sel_hi:[1,0]
	v_pk_mul_f32 v[34:35], v[34:35], v[72:73] op_sel_hi:[1,0]
	ds_write2_b64 v74, v[16:17], v[18:19] offset0:20 offset1:22
	v_cvt_pk_bf16_f32 v2, v2, v3
	v_cvt_pk_bf16_f32 v3, v4, v5
	v_cvt_pk_bf16_f32 v48, v48, v49
	v_cvt_pk_bf16_f32 v49, v50, v51
	v_pk_mul_f32 v[50:51], v[52:53], v[72:73] op_sel_hi:[1,0]
	v_pk_mul_f32 v[52:53], v[54:55], v[72:73] op_sel_hi:[1,0]
	v_cvt_pk_bf16_f32 v32, v32, v33
	v_cvt_pk_bf16_f32 v33, v34, v35
	v_pk_mul_f32 v[34:35], v[36:37], v[72:73] op_sel_hi:[1,0]
	v_pk_mul_f32 v[36:37], v[38:39], v[72:73] op_sel_hi:[1,0]
	ds_write2_b64 v74, v[0:1], v[2:3] offset0:28 offset1:30
	v_cvt_pk_bf16_f32 v50, v50, v51
	v_cvt_pk_bf16_f32 v51, v52, v53
	v_cvt_pk_bf16_f32 v34, v34, v35
	v_cvt_pk_bf16_f32 v35, v36, v37
	ds_write2_b64 v74, v[48:49], v[50:51] offset1:2
	v_pk_mul_f32 v[48:49], v[56:57], v[72:73] op_sel_hi:[1,0]
	v_pk_mul_f32 v[50:51], v[58:59], v[72:73] op_sel_hi:[1,0]
	ds_write2_b64 v74, v[32:33], v[34:35] offset0:8 offset1:10
	v_pk_mul_f32 v[32:33], v[40:41], v[72:73] op_sel_hi:[1,0]
	v_pk_mul_f32 v[34:35], v[42:43], v[72:73] op_sel_hi:[1,0]
	v_cvt_pk_bf16_f32 v48, v48, v49
	v_cvt_pk_bf16_f32 v49, v50, v51
	v_pk_mul_f32 v[50:51], v[60:61], v[72:73] op_sel_hi:[1,0]
	v_pk_mul_f32 v[52:53], v[62:63], v[72:73] op_sel_hi:[1,0]
	v_cvt_pk_bf16_f32 v32, v32, v33
	v_cvt_pk_bf16_f32 v33, v34, v35
	v_pk_mul_f32 v[34:35], v[44:45], v[72:73] op_sel_hi:[1,0]
	v_pk_mul_f32 v[36:37], v[46:47], v[72:73] op_sel_hi:[1,0]
	v_cvt_pk_bf16_f32 v50, v50, v51
	v_cvt_pk_bf16_f32 v51, v52, v53
	v_cvt_pk_bf16_f32 v34, v34, v35
	s_waitcnt vmcnt(0)
	v_lshlrev_b32_e32 v16, 16, v64
	v_and_b32_e32 v14, 0xffff0000, v64
	v_mul_f32_e32 v0, 0xbfb8aa3b, v16
	v_mul_f32_e32 v1, 0xbfb8aa3b, v14
	v_exp_f32_e32 v0, v0
	v_exp_f32_e32 v1, v1
	v_cvt_pk_bf16_f32 v35, v36, v37
	ds_write2_b64 v74, v[48:49], v[50:51] offset0:4 offset1:6
	ds_write2_b64 v74, v[32:33], v[34:35] offset0:12 offset1:14
	v_mad_u64_u32 v[12:13], s[6:7], v144, s69, v[148:149]
	v_pk_add_f32 v[8:9], v[0:1], 1.0 op_sel_hi:[1,0]
	ds_read_b128 v[4:7], v12
	ds_read_b128 v[0:3], v12 offset:1088
	v_div_scale_f32 v13, s[6:7], v9, v9, v14
	v_rcp_f32_e32 v15, v13
	s_waitcnt lgkmcnt(1)
	v_lshlrev_b32_e32 v10, 16, v4
	v_and_b32_e32 v11, 0xffff0000, v4
	v_and_b32_e32 v19, 0xffff0000, v65
	v_fma_f32 v4, -v13, v15, 1.0
	v_fmac_f32_e32 v15, v4, v15
	v_div_scale_f32 v4, vcc, v14, v9, v14
	v_mul_f32_e32 v17, v4, v15
	v_fma_f32 v18, -v13, v17, v4
	v_fmac_f32_e32 v17, v18, v15
	v_fma_f32 v4, -v13, v17, v4
	v_div_scale_f32 v13, s[6:7], v8, v8, v16
	v_rcp_f32_e32 v18, v13
	v_div_fmas_f32 v4, v4, v15, v17
	v_div_fixup_f32 v9, v4, v9, v14
	v_mul_f32_e32 v15, 0xbfb8aa3b, v19
	v_fma_f32 v4, -v13, v18, 1.0
	v_fmac_f32_e32 v18, v4, v18
	v_div_scale_f32 v4, vcc, v16, v8, v16
	v_mul_f32_e32 v17, v4, v18
	v_fma_f32 v14, -v13, v17, v4
	v_fmac_f32_e32 v17, v14, v18
	v_fma_f32 v4, -v13, v17, v4
	v_lshlrev_b32_e32 v13, 16, v65
	v_mul_f32_e32 v14, 0xbfb8aa3b, v13
	v_exp_f32_e32 v14, v14
	v_exp_f32_e32 v15, v15
	v_div_fmas_f32 v4, v4, v18, v17
	v_div_fixup_f32 v8, v4, v8, v16
	v_pk_mul_f32 v[8:9], v[8:9], v[10:11]
	v_pk_add_f32 v[10:11], v[14:15], 1.0 op_sel_hi:[1,0]
	v_cvt_pk_bf16_f32 v4, v8, v9
	v_div_scale_f32 v14, s[6:7], v11, v11, v19
	v_rcp_f32_e32 v15, v14
	v_lshlrev_b32_e32 v8, 16, v5
	v_and_b32_e32 v9, 0xffff0000, v5
	v_lshlrev_b32_e32 v18, 16, v66
	v_fma_f32 v5, -v14, v15, 1.0
	v_fmac_f32_e32 v15, v5, v15
	v_div_scale_f32 v5, vcc, v19, v11, v19
	v_mul_f32_e32 v16, v5, v15
	v_fma_f32 v17, -v14, v16, v5
	v_fmac_f32_e32 v16, v17, v15
	v_fma_f32 v5, -v14, v16, v5
	v_div_scale_f32 v14, s[6:7], v10, v10, v13
	v_rcp_f32_e32 v17, v14
	v_div_fmas_f32 v5, v5, v15, v16
	v_div_fixup_f32 v11, v5, v11, v19
	v_and_b32_e32 v19, 0xffff0000, v66
	v_fma_f32 v5, -v14, v17, 1.0
	v_fmac_f32_e32 v17, v5, v17
	v_div_scale_f32 v5, vcc, v13, v10, v13
	v_mul_f32_e32 v16, v5, v17
	v_fma_f32 v15, -v14, v16, v5
	v_fmac_f32_e32 v16, v15, v17
	v_fma_f32 v5, -v14, v16, v5
	v_mul_f32_e32 v14, 0xbfb8aa3b, v18
	v_mul_f32_e32 v15, 0xbfb8aa3b, v19
	v_exp_f32_e32 v14, v14
	v_exp_f32_e32 v15, v15
	v_div_fmas_f32 v5, v5, v17, v16
	v_div_fixup_f32 v10, v5, v10, v13
	v_pk_mul_f32 v[8:9], v[10:11], v[8:9]
	v_pk_add_f32 v[10:11], v[14:15], 1.0 op_sel_hi:[1,0]
	v_cvt_pk_bf16_f32 v5, v8, v9
	v_div_scale_f32 v13, s[6:7], v11, v11, v19
	v_rcp_f32_e32 v14, v13
	v_lshlrev_b32_e32 v8, 16, v6
	v_and_b32_e32 v9, 0xffff0000, v6
	v_fma_f32 v6, -v13, v14, 1.0
	v_fmac_f32_e32 v14, v6, v14
	v_div_scale_f32 v6, vcc, v19, v11, v19
	v_mul_f32_e32 v15, v6, v14
	v_fma_f32 v16, -v13, v15, v6
	v_fmac_f32_e32 v15, v16, v14
	v_fma_f32 v6, -v13, v15, v6
	v_div_scale_f32 v13, s[6:7], v10, v10, v18
	v_rcp_f32_e32 v16, v13
	v_div_fmas_f32 v6, v6, v14, v15
	v_div_fixup_f32 v11, v6, v11, v19
	v_and_b32_e32 v19, 0xffff0000, v67
	v_fma_f32 v6, -v13, v16, 1.0
	v_fmac_f32_e32 v16, v6, v16
	v_div_scale_f32 v6, vcc, v18, v10, v18
	v_mul_f32_e32 v17, v6, v16
	v_fma_f32 v14, -v13, v17, v6
	v_fmac_f32_e32 v17, v14, v16
	v_fma_f32 v6, -v13, v17, v6
	v_lshlrev_b32_e32 v13, 16, v67
	v_mul_f32_e32 v14, 0xbfb8aa3b, v13
	v_mul_f32_e32 v15, 0xbfb8aa3b, v19
	v_exp_f32_e32 v14, v14
	v_exp_f32_e32 v15, v15
	v_div_fmas_f32 v6, v6, v16, v17
	v_div_fixup_f32 v10, v6, v10, v18
	v_pk_mul_f32 v[8:9], v[10:11], v[8:9]
	v_pk_add_f32 v[10:11], v[14:15], 1.0 op_sel_hi:[1,0]
	v_cvt_pk_bf16_f32 v6, v8, v9
	v_div_scale_f32 v14, s[6:7], v11, v11, v19
	v_rcp_f32_e32 v15, v14
	v_lshlrev_b32_e32 v8, 16, v7
	v_and_b32_e32 v9, 0xffff0000, v7
	v_fma_f32 v7, -v14, v15, 1.0
	v_fmac_f32_e32 v15, v7, v15
	v_div_scale_f32 v7, vcc, v19, v11, v19
	v_mul_f32_e32 v16, v7, v15
	v_fma_f32 v17, -v14, v16, v7
	v_fmac_f32_e32 v16, v17, v15
	v_fma_f32 v7, -v14, v16, v7
	v_div_scale_f32 v14, s[6:7], v10, v10, v13
	v_rcp_f32_e32 v17, v14
	v_div_fmas_f32 v7, v7, v15, v16
	v_div_fixup_f32 v11, v7, v11, v19
	v_fma_f32 v7, -v14, v17, 1.0
	v_fmac_f32_e32 v17, v7, v17
	v_div_scale_f32 v7, vcc, v13, v10, v13
	v_mul_f32_e32 v15, v7, v17
	v_fma_f32 v16, -v14, v15, v7
	v_fmac_f32_e32 v15, v16, v17
	v_fma_f32 v7, -v14, v15, v7
	v_div_fmas_f32 v7, v7, v17, v15
	v_div_fixup_f32 v10, v7, v10, v13
	v_pk_mul_f32 v[8:9], v[10:11], v[8:9]
	s_waitcnt lgkmcnt(0)
	v_lshlrev_b32_e32 v14, 16, v0
	v_cvt_pk_bf16_f32 v7, v8, v9
	v_lshlrev_b64 v[8:9], 12, v[144:145]
	v_lshl_add_u64 v[8:9], v[68:69], 0, v[8:9]
	global_store_dwordx4 v[8:9], v[4:7], off sc1
	v_or_b32_e32 v8, 4, v144
	v_and_b32_e32 v15, 0xffff0000, v0
	v_mad_u64_u32 v[4:5], s[6:7], v8, s72, v[70:71]
	global_load_dwordx4 v[4:7], v[4:5], off offset:1024
	s_waitcnt vmcnt(0)
	v_lshlrev_b32_e32 v13, 16, v4
	v_and_b32_e32 v4, 0xffff0000, v4
	v_mul_f32_e32 v9, 0xbfb8aa3b, v13
	v_exp_f32_e32 v10, v9
	v_mul_f32_e32 v9, 0xbfb8aa3b, v4
	v_exp_f32_e32 v11, v9
	v_mov_b32_e32 v9, v145
	v_pk_add_f32 v[10:11], v[10:11], 1.0 op_sel_hi:[1,0]
	s_nop 0
	v_div_scale_f32 v16, s[6:7], v11, v11, v4
	v_rcp_f32_e32 v17, v16
	s_nop 0
	v_fma_f32 v0, -v16, v17, 1.0
	v_fmac_f32_e32 v17, v0, v17
	v_div_scale_f32 v0, vcc, v4, v11, v4
	v_mul_f32_e32 v18, v0, v17
	v_fma_f32 v19, -v16, v18, v0
	v_fmac_f32_e32 v18, v19, v17
	v_fma_f32 v0, -v16, v18, v0
	v_div_scale_f32 v16, s[6:7], v10, v10, v13
	v_rcp_f32_e32 v19, v16
	v_div_fmas_f32 v0, v0, v17, v18
	v_div_fixup_f32 v11, v0, v11, v4
	v_and_b32_e32 v18, 0xffff0000, v5
	v_fma_f32 v0, -v16, v19, 1.0
	v_fmac_f32_e32 v19, v0, v19
	v_div_scale_f32 v0, vcc, v13, v10, v13
	v_mul_f32_e32 v17, v0, v19
	v_fma_f32 v4, -v16, v17, v0
	v_fmac_f32_e32 v17, v4, v19
	v_fma_f32 v0, -v16, v17, v0
	v_lshlrev_b32_e32 v16, 16, v5
	v_mul_f32_e32 v4, 0xbfb8aa3b, v16
	v_mul_f32_e32 v5, 0xbfb8aa3b, v18
	v_exp_f32_e32 v4, v4
	v_exp_f32_e32 v5, v5
	v_div_fmas_f32 v0, v0, v19, v17
	v_div_fixup_f32 v10, v0, v10, v13
	v_pk_mul_f32 v[10:11], v[10:11], v[14:15]
	v_pk_add_f32 v[4:5], v[4:5], 1.0 op_sel_hi:[1,0]
	v_cvt_pk_bf16_f32 v0, v10, v11
	v_div_scale_f32 v13, s[6:7], v5, v5, v18
	v_rcp_f32_e32 v14, v13
	v_lshlrev_b32_e32 v10, 16, v1
	v_and_b32_e32 v11, 0xffff0000, v1
	v_fma_f32 v1, -v13, v14, 1.0
	v_fmac_f32_e32 v14, v1, v14
	v_div_scale_f32 v1, vcc, v18, v5, v18
	v_mul_f32_e32 v15, v1, v14
	v_fma_f32 v17, -v13, v15, v1
	v_fmac_f32_e32 v15, v17, v14
	v_fma_f32 v1, -v13, v15, v1
	v_div_scale_f32 v13, s[6:7], v4, v4, v16
	v_rcp_f32_e32 v17, v13
	v_div_fmas_f32 v1, v1, v14, v15
	v_div_fixup_f32 v5, v1, v5, v18
	v_fma_f32 v1, -v13, v17, 1.0
	v_fmac_f32_e32 v17, v1, v17
	v_div_scale_f32 v1, vcc, v16, v4, v16
	v_mul_f32_e32 v18, v1, v17
	v_fma_f32 v14, -v13, v18, v1
	v_fmac_f32_e32 v18, v14, v17
	v_fma_f32 v1, -v13, v18, v1
	v_lshlrev_b32_e32 v13, 16, v6
	v_and_b32_e32 v6, 0xffff0000, v6
	v_mul_f32_e32 v14, 0xbfb8aa3b, v13
	v_mul_f32_e32 v15, 0xbfb8aa3b, v6
	v_exp_f32_e32 v14, v14
	v_exp_f32_e32 v15, v15
	v_div_fmas_f32 v1, v1, v17, v18
	v_div_fixup_f32 v4, v1, v4, v16
	v_pk_mul_f32 v[4:5], v[4:5], v[10:11]
	v_pk_add_f32 v[10:11], v[14:15], 1.0 op_sel_hi:[1,0]
	v_cvt_pk_bf16_f32 v1, v4, v5
	v_div_scale_f32 v14, s[6:7], v11, v11, v6
	v_rcp_f32_e32 v15, v14
	v_lshlrev_b32_e32 v4, 16, v2
	v_and_b32_e32 v5, 0xffff0000, v2
	v_fma_f32 v2, -v14, v15, 1.0
	v_fmac_f32_e32 v15, v2, v15
	v_div_scale_f32 v2, vcc, v6, v11, v6
	v_mul_f32_e32 v16, v2, v15
	v_fma_f32 v17, -v14, v16, v2
	v_fmac_f32_e32 v16, v17, v15
	v_fma_f32 v2, -v14, v16, v2
	v_div_scale_f32 v14, s[6:7], v10, v10, v13
	v_rcp_f32_e32 v17, v14
	v_div_fmas_f32 v2, v2, v15, v16
	v_div_fixup_f32 v11, v2, v11, v6
	v_and_b32_e32 v16, 0xffff0000, v7
	v_fma_f32 v2, -v14, v17, 1.0
	v_fmac_f32_e32 v17, v2, v17
	v_div_scale_f32 v2, vcc, v13, v10, v13
	v_mul_f32_e32 v15, v2, v17
	v_fma_f32 v6, -v14, v15, v2
	v_fmac_f32_e32 v15, v6, v17
	v_fma_f32 v2, -v14, v15, v2
	v_lshlrev_b32_e32 v14, 16, v7
	v_mul_f32_e32 v6, 0xbfb8aa3b, v14
	v_mul_f32_e32 v7, 0xbfb8aa3b, v16
	v_exp_f32_e32 v6, v6
	v_exp_f32_e32 v7, v7
	v_div_fmas_f32 v2, v2, v17, v15
	v_div_fixup_f32 v10, v2, v10, v13
	v_pk_mul_f32 v[4:5], v[10:11], v[4:5]
	v_pk_add_f32 v[6:7], v[6:7], 1.0 op_sel_hi:[1,0]
	v_cvt_pk_bf16_f32 v2, v4, v5
	v_div_scale_f32 v10, s[6:7], v7, v7, v16
	v_rcp_f32_e32 v11, v10
	v_lshlrev_b32_e32 v4, 16, v3
	v_and_b32_e32 v5, 0xffff0000, v3
	v_fma_f32 v3, -v10, v11, 1.0
	v_fmac_f32_e32 v11, v3, v11
	v_div_scale_f32 v3, vcc, v16, v7, v16
	v_mul_f32_e32 v13, v3, v11
	v_fma_f32 v15, -v10, v13, v3
	v_fmac_f32_e32 v13, v15, v11
	v_fma_f32 v3, -v10, v13, v3
	v_div_scale_f32 v10, s[6:7], v6, v6, v14
	v_rcp_f32_e32 v15, v10
	v_div_fmas_f32 v3, v3, v11, v13
	v_div_fixup_f32 v7, v3, v7, v16
	v_fma_f32 v3, -v10, v15, 1.0
	v_fmac_f32_e32 v15, v3, v15
	v_div_scale_f32 v3, vcc, v14, v6, v14
	v_mul_f32_e32 v11, v3, v15
	v_fma_f32 v13, -v10, v11, v3
	v_fmac_f32_e32 v11, v13, v15
	v_fma_f32 v3, -v10, v11, v3
	v_div_fmas_f32 v3, v3, v15, v11
	v_div_fixup_f32 v6, v3, v6, v14
	v_pk_mul_f32 v[4:5], v[6:7], v[4:5]
	v_or_b32_e32 v14, 8, v144
	v_cvt_pk_bf16_f32 v3, v4, v5
	v_lshlrev_b64 v[4:5], 12, v[8:9]
	v_lshl_add_u64 v[4:5], v[68:69], 0, v[4:5]
	global_store_dwordx4 v[4:5], v[0:3], off sc1
	ds_read_b128 v[4:7], v12 offset:2176
	v_mov_b32_e32 v15, v145
	v_mad_u64_u32 v[0:1], s[6:7], v14, s72, v[70:71]
	global_load_dwordx4 v[8:11], v[0:1], off offset:1024
	s_waitcnt vmcnt(0)
	v_lshlrev_b32_e32 v13, 16, v8
	v_and_b32_e32 v8, 0xffff0000, v8
	v_mul_f32_e32 v0, 0xbfb8aa3b, v13
	v_mul_f32_e32 v1, 0xbfb8aa3b, v8
	v_exp_f32_e32 v0, v0
	v_exp_f32_e32 v1, v1
	s_nop 0
	v_pk_add_f32 v[16:17], v[0:1], 1.0 op_sel_hi:[1,0]
	s_nop 0
	v_div_scale_f32 v20, s[6:7], v17, v17, v8
	v_rcp_f32_e32 v21, v20
	ds_read_b128 v[0:3], v12 offset:3264
	s_waitcnt lgkmcnt(1)
	v_lshlrev_b32_e32 v18, 16, v4
	v_and_b32_e32 v19, 0xffff0000, v4
	v_fma_f32 v4, -v20, v21, 1.0
	v_fmac_f32_e32 v21, v4, v21
	v_div_scale_f32 v4, vcc, v8, v17, v8
	v_mul_f32_e32 v22, v4, v21
	v_fma_f32 v23, -v20, v22, v4
	v_fmac_f32_e32 v22, v23, v21
	v_fma_f32 v4, -v20, v22, v4
	v_div_scale_f32 v20, s[6:7], v16, v16, v13
	v_rcp_f32_e32 v23, v20
	v_div_fmas_f32 v4, v4, v21, v22
	v_div_fixup_f32 v17, v4, v17, v8
	v_and_b32_e32 v22, 0xffff0000, v9
	v_fma_f32 v4, -v20, v23, 1.0
	v_fmac_f32_e32 v23, v4, v23
	v_div_scale_f32 v4, vcc, v13, v16, v13
	v_mul_f32_e32 v21, v4, v23
	v_fma_f32 v8, -v20, v21, v4
	v_fmac_f32_e32 v21, v8, v23
	v_fma_f32 v4, -v20, v21, v4
	v_lshlrev_b32_e32 v20, 16, v9
	v_mul_f32_e32 v8, 0xbfb8aa3b, v20
	v_mul_f32_e32 v9, 0xbfb8aa3b, v22
	v_exp_f32_e32 v8, v8
	v_exp_f32_e32 v9, v9
	v_div_fmas_f32 v4, v4, v23, v21
	v_div_fixup_f32 v16, v4, v16, v13
	v_pk_mul_f32 v[16:17], v[16:17], v[18:19]
	v_pk_add_f32 v[8:9], v[8:9], 1.0 op_sel_hi:[1,0]
	v_cvt_pk_bf16_f32 v4, v16, v17
	v_div_scale_f32 v13, s[6:7], v9, v9, v22
	v_rcp_f32_e32 v18, v13
	v_lshlrev_b32_e32 v16, 16, v5
	v_and_b32_e32 v17, 0xffff0000, v5
	v_fma_f32 v5, -v13, v18, 1.0
	v_fmac_f32_e32 v18, v5, v18
	v_div_scale_f32 v5, vcc, v22, v9, v22
	v_mul_f32_e32 v19, v5, v18
	v_fma_f32 v21, -v13, v19, v5
	v_fmac_f32_e32 v19, v21, v18
	v_fma_f32 v5, -v13, v19, v5
	v_div_scale_f32 v13, s[6:7], v8, v8, v20
	v_rcp_f32_e32 v21, v13
	v_div_fmas_f32 v5, v5, v18, v19
	v_div_fixup_f32 v9, v5, v9, v22
	v_fma_f32 v5, -v13, v21, 1.0
	v_fmac_f32_e32 v21, v5, v21
	v_div_scale_f32 v5, vcc, v20, v8, v20
	v_mul_f32_e32 v22, v5, v21
	v_fma_f32 v18, -v13, v22, v5
	v_fmac_f32_e32 v22, v18, v21
	v_fma_f32 v5, -v13, v22, v5
	v_lshlrev_b32_e32 v13, 16, v10
	v_and_b32_e32 v10, 0xffff0000, v10
	v_mul_f32_e32 v18, 0xbfb8aa3b, v13
	v_mul_f32_e32 v19, 0xbfb8aa3b, v10
	v_exp_f32_e32 v18, v18
	v_exp_f32_e32 v19, v19
	v_div_fmas_f32 v5, v5, v21, v22
	v_div_fixup_f32 v8, v5, v8, v20
	v_pk_mul_f32 v[8:9], v[8:9], v[16:17]
	v_pk_add_f32 v[16:17], v[18:19], 1.0 op_sel_hi:[1,0]
	v_cvt_pk_bf16_f32 v5, v8, v9
	v_div_scale_f32 v18, s[6:7], v17, v17, v10
	v_rcp_f32_e32 v19, v18
	v_lshlrev_b32_e32 v8, 16, v6
	v_and_b32_e32 v9, 0xffff0000, v6
	v_fma_f32 v6, -v18, v19, 1.0
	v_fmac_f32_e32 v19, v6, v19
	v_div_scale_f32 v6, vcc, v10, v17, v10
	v_mul_f32_e32 v20, v6, v19
	v_fma_f32 v21, -v18, v20, v6
	v_fmac_f32_e32 v20, v21, v19
	v_fma_f32 v6, -v18, v20, v6
	v_div_scale_f32 v18, s[6:7], v16, v16, v13
	v_rcp_f32_e32 v21, v18
	v_div_fmas_f32 v6, v6, v19, v20
	v_div_fixup_f32 v17, v6, v17, v10
	v_and_b32_e32 v20, 0xffff0000, v11
	v_fma_f32 v6, -v18, v21, 1.0
	v_fmac_f32_e32 v21, v6, v21
	v_div_scale_f32 v6, vcc, v13, v16, v13
	v_mul_f32_e32 v19, v6, v21
	v_fma_f32 v10, -v18, v19, v6
	v_fmac_f32_e32 v19, v10, v21
	v_fma_f32 v6, -v18, v19, v6
	v_lshlrev_b32_e32 v18, 16, v11
	v_mul_f32_e32 v10, 0xbfb8aa3b, v18
	v_mul_f32_e32 v11, 0xbfb8aa3b, v20
	v_exp_f32_e32 v10, v10
	v_exp_f32_e32 v11, v11
	v_div_fmas_f32 v6, v6, v21, v19
	v_div_fixup_f32 v16, v6, v16, v13
	v_pk_mul_f32 v[8:9], v[16:17], v[8:9]
	v_pk_add_f32 v[10:11], v[10:11], 1.0 op_sel_hi:[1,0]
	v_cvt_pk_bf16_f32 v6, v8, v9
	v_div_scale_f32 v13, s[6:7], v11, v11, v20
	v_rcp_f32_e32 v16, v13
	v_lshlrev_b32_e32 v8, 16, v7
	v_and_b32_e32 v9, 0xffff0000, v7
	v_fma_f32 v7, -v13, v16, 1.0
	v_fmac_f32_e32 v16, v7, v16
	v_div_scale_f32 v7, vcc, v20, v11, v20
	v_mul_f32_e32 v17, v7, v16
	v_fma_f32 v19, -v13, v17, v7
	v_fmac_f32_e32 v17, v19, v16
	v_fma_f32 v7, -v13, v17, v7
	v_div_scale_f32 v13, s[6:7], v10, v10, v18
	v_rcp_f32_e32 v19, v13
	v_div_fmas_f32 v7, v7, v16, v17
	v_div_fixup_f32 v11, v7, v11, v20
	v_fma_f32 v7, -v13, v19, 1.0
	v_fmac_f32_e32 v19, v7, v19
	v_div_scale_f32 v7, vcc, v18, v10, v18
	v_mul_f32_e32 v16, v7, v19
	v_fma_f32 v17, -v13, v16, v7
	v_fmac_f32_e32 v16, v17, v19
	v_fma_f32 v7, -v13, v16, v7
	v_div_fmas_f32 v7, v7, v19, v16
	v_div_fixup_f32 v10, v7, v10, v18
	v_pk_mul_f32 v[8:9], v[10:11], v[8:9]
	s_nop 0
	v_cvt_pk_bf16_f32 v7, v8, v9
	v_lshlrev_b64 v[8:9], 12, v[14:15]
	v_lshl_add_u64 v[8:9], v[68:69], 0, v[8:9]
	global_store_dwordx4 v[8:9], v[4:7], off sc1
	v_or_b32_e32 v8, 12, v144
	s_waitcnt lgkmcnt(0)
	v_lshlrev_b32_e32 v14, 16, v0
	v_mad_u64_u32 v[4:5], s[6:7], v8, s72, v[70:71]
	global_load_dwordx4 v[4:7], v[4:5], off offset:1024
	v_and_b32_e32 v15, 0xffff0000, v0
	s_waitcnt vmcnt(0)
	v_lshlrev_b32_e32 v13, 16, v4
	v_and_b32_e32 v4, 0xffff0000, v4
	v_mul_f32_e32 v9, 0xbfb8aa3b, v13
	v_exp_f32_e32 v10, v9
	v_mul_f32_e32 v9, 0xbfb8aa3b, v4
	v_exp_f32_e32 v11, v9
	v_mov_b32_e32 v9, v145
	v_pk_add_f32 v[10:11], v[10:11], 1.0 op_sel_hi:[1,0]
	s_nop 0
	v_div_scale_f32 v16, s[6:7], v11, v11, v4
	v_rcp_f32_e32 v17, v16
	s_nop 0
	v_fma_f32 v0, -v16, v17, 1.0
	v_fmac_f32_e32 v17, v0, v17
	v_div_scale_f32 v0, vcc, v4, v11, v4
	v_mul_f32_e32 v18, v0, v17
	v_fma_f32 v19, -v16, v18, v0
	v_fmac_f32_e32 v18, v19, v17
	v_fma_f32 v0, -v16, v18, v0
	v_div_scale_f32 v16, s[6:7], v10, v10, v13
	v_rcp_f32_e32 v19, v16
	v_div_fmas_f32 v0, v0, v17, v18
	v_div_fixup_f32 v11, v0, v11, v4
	v_and_b32_e32 v18, 0xffff0000, v5
	v_fma_f32 v0, -v16, v19, 1.0
	v_fmac_f32_e32 v19, v0, v19
	v_div_scale_f32 v0, vcc, v13, v10, v13
	v_mul_f32_e32 v17, v0, v19
	v_fma_f32 v4, -v16, v17, v0
	v_fmac_f32_e32 v17, v4, v19
	v_fma_f32 v0, -v16, v17, v0
	v_lshlrev_b32_e32 v16, 16, v5
	v_mul_f32_e32 v4, 0xbfb8aa3b, v16
	v_mul_f32_e32 v5, 0xbfb8aa3b, v18
	v_exp_f32_e32 v4, v4
	v_exp_f32_e32 v5, v5
	v_div_fmas_f32 v0, v0, v19, v17
	v_div_fixup_f32 v10, v0, v10, v13
	v_pk_mul_f32 v[10:11], v[10:11], v[14:15]
	v_pk_add_f32 v[4:5], v[4:5], 1.0 op_sel_hi:[1,0]
	v_cvt_pk_bf16_f32 v0, v10, v11
	v_div_scale_f32 v13, s[6:7], v5, v5, v18
	v_rcp_f32_e32 v14, v13
	v_lshlrev_b32_e32 v10, 16, v1
	v_and_b32_e32 v11, 0xffff0000, v1
	v_fma_f32 v1, -v13, v14, 1.0
	v_fmac_f32_e32 v14, v1, v14
	v_div_scale_f32 v1, vcc, v18, v5, v18
	v_mul_f32_e32 v15, v1, v14
	v_fma_f32 v17, -v13, v15, v1
	v_fmac_f32_e32 v15, v17, v14
	v_fma_f32 v1, -v13, v15, v1
	v_div_scale_f32 v13, s[6:7], v4, v4, v16
	v_rcp_f32_e32 v17, v13
	v_div_fmas_f32 v1, v1, v14, v15
	v_div_fixup_f32 v5, v1, v5, v18
	v_fma_f32 v1, -v13, v17, 1.0
	v_fmac_f32_e32 v17, v1, v17
	v_div_scale_f32 v1, vcc, v16, v4, v16
	v_mul_f32_e32 v18, v1, v17
	v_fma_f32 v14, -v13, v18, v1
	v_fmac_f32_e32 v18, v14, v17
	v_fma_f32 v1, -v13, v18, v1
	v_lshlrev_b32_e32 v13, 16, v6
	v_and_b32_e32 v6, 0xffff0000, v6
	v_mul_f32_e32 v14, 0xbfb8aa3b, v13
	v_mul_f32_e32 v15, 0xbfb8aa3b, v6
	v_exp_f32_e32 v14, v14
	v_exp_f32_e32 v15, v15
	v_div_fmas_f32 v1, v1, v17, v18
	v_div_fixup_f32 v4, v1, v4, v16
	v_pk_mul_f32 v[4:5], v[4:5], v[10:11]
	v_pk_add_f32 v[10:11], v[14:15], 1.0 op_sel_hi:[1,0]
	v_cvt_pk_bf16_f32 v1, v4, v5
	v_div_scale_f32 v14, s[6:7], v11, v11, v6
	v_rcp_f32_e32 v15, v14
	v_lshlrev_b32_e32 v4, 16, v2
	v_and_b32_e32 v5, 0xffff0000, v2
	v_fma_f32 v2, -v14, v15, 1.0
	v_fmac_f32_e32 v15, v2, v15
	v_div_scale_f32 v2, vcc, v6, v11, v6
	v_mul_f32_e32 v16, v2, v15
	v_fma_f32 v17, -v14, v16, v2
	v_fmac_f32_e32 v16, v17, v15
	v_fma_f32 v2, -v14, v16, v2
	v_div_scale_f32 v14, s[6:7], v10, v10, v13
	v_rcp_f32_e32 v17, v14
	v_div_fmas_f32 v2, v2, v15, v16
	v_div_fixup_f32 v11, v2, v11, v6
	v_and_b32_e32 v16, 0xffff0000, v7
	v_fma_f32 v2, -v14, v17, 1.0
	v_fmac_f32_e32 v17, v2, v17
	v_div_scale_f32 v2, vcc, v13, v10, v13
	v_mul_f32_e32 v15, v2, v17
	v_fma_f32 v6, -v14, v15, v2
	v_fmac_f32_e32 v15, v6, v17
	v_fma_f32 v2, -v14, v15, v2
	v_lshlrev_b32_e32 v14, 16, v7
	v_mul_f32_e32 v6, 0xbfb8aa3b, v14
	v_mul_f32_e32 v7, 0xbfb8aa3b, v16
	v_exp_f32_e32 v6, v6
	v_exp_f32_e32 v7, v7
	v_div_fmas_f32 v2, v2, v17, v15
	v_div_fixup_f32 v10, v2, v10, v13
	v_pk_mul_f32 v[4:5], v[10:11], v[4:5]
	v_pk_add_f32 v[6:7], v[6:7], 1.0 op_sel_hi:[1,0]
	v_cvt_pk_bf16_f32 v2, v4, v5
	v_div_scale_f32 v10, s[6:7], v7, v7, v16
	v_rcp_f32_e32 v11, v10
	v_lshlrev_b32_e32 v4, 16, v3
	v_and_b32_e32 v5, 0xffff0000, v3
	v_fma_f32 v3, -v10, v11, 1.0
	v_fmac_f32_e32 v11, v3, v11
	v_div_scale_f32 v3, vcc, v16, v7, v16
	v_mul_f32_e32 v13, v3, v11
	v_fma_f32 v15, -v10, v13, v3
	v_fmac_f32_e32 v13, v15, v11
	v_fma_f32 v3, -v10, v13, v3
	v_div_scale_f32 v10, s[6:7], v6, v6, v14
	v_rcp_f32_e32 v15, v10
	v_div_fmas_f32 v3, v3, v11, v13
	v_div_fixup_f32 v7, v3, v7, v16
	v_fma_f32 v3, -v10, v15, 1.0
	v_fmac_f32_e32 v15, v3, v15
	v_div_scale_f32 v3, vcc, v14, v6, v14
	v_mul_f32_e32 v11, v3, v15
	v_fma_f32 v13, -v10, v11, v3
	v_fmac_f32_e32 v11, v13, v15
	v_fma_f32 v3, -v10, v11, v3
	v_div_fmas_f32 v3, v3, v15, v11
	v_div_fixup_f32 v6, v3, v6, v14
	v_pk_mul_f32 v[4:5], v[6:7], v[4:5]
	v_or_b32_e32 v14, 16, v144
	v_cvt_pk_bf16_f32 v3, v4, v5
	v_lshlrev_b64 v[4:5], 12, v[8:9]
	v_lshl_add_u64 v[4:5], v[68:69], 0, v[4:5]
	global_store_dwordx4 v[4:5], v[0:3], off sc1
	ds_read_b128 v[4:7], v12 offset:4352
	v_mov_b32_e32 v15, v145
	v_mad_u64_u32 v[0:1], s[6:7], v14, s72, v[70:71]
	global_load_dwordx4 v[8:11], v[0:1], off offset:1024
	s_waitcnt vmcnt(0)
	v_lshlrev_b32_e32 v13, 16, v8
	v_and_b32_e32 v8, 0xffff0000, v8
	v_mul_f32_e32 v0, 0xbfb8aa3b, v13
	v_mul_f32_e32 v1, 0xbfb8aa3b, v8
	v_exp_f32_e32 v0, v0
	v_exp_f32_e32 v1, v1
	s_nop 0
	v_pk_add_f32 v[16:17], v[0:1], 1.0 op_sel_hi:[1,0]
	s_nop 0
	v_div_scale_f32 v20, s[6:7], v17, v17, v8
	v_rcp_f32_e32 v21, v20
	ds_read_b128 v[0:3], v12 offset:5440
	s_waitcnt lgkmcnt(1)
	v_lshlrev_b32_e32 v18, 16, v4
	v_and_b32_e32 v19, 0xffff0000, v4
	v_fma_f32 v4, -v20, v21, 1.0
	v_fmac_f32_e32 v21, v4, v21
	v_div_scale_f32 v4, vcc, v8, v17, v8
	v_mul_f32_e32 v22, v4, v21
	v_fma_f32 v23, -v20, v22, v4
	v_fmac_f32_e32 v22, v23, v21
	v_fma_f32 v4, -v20, v22, v4
	v_div_scale_f32 v20, s[6:7], v16, v16, v13
	v_rcp_f32_e32 v23, v20
	v_div_fmas_f32 v4, v4, v21, v22
	v_div_fixup_f32 v17, v4, v17, v8
	v_and_b32_e32 v22, 0xffff0000, v9
	v_fma_f32 v4, -v20, v23, 1.0
	v_fmac_f32_e32 v23, v4, v23
	v_div_scale_f32 v4, vcc, v13, v16, v13
	v_mul_f32_e32 v21, v4, v23
	v_fma_f32 v8, -v20, v21, v4
	v_fmac_f32_e32 v21, v8, v23
	v_fma_f32 v4, -v20, v21, v4
	v_lshlrev_b32_e32 v20, 16, v9
	v_mul_f32_e32 v8, 0xbfb8aa3b, v20
	v_mul_f32_e32 v9, 0xbfb8aa3b, v22
	v_exp_f32_e32 v8, v8
	v_exp_f32_e32 v9, v9
	v_div_fmas_f32 v4, v4, v23, v21
	v_div_fixup_f32 v16, v4, v16, v13
	v_pk_mul_f32 v[16:17], v[16:17], v[18:19]
	v_pk_add_f32 v[8:9], v[8:9], 1.0 op_sel_hi:[1,0]
	v_cvt_pk_bf16_f32 v4, v16, v17
	v_div_scale_f32 v13, s[6:7], v9, v9, v22
	v_rcp_f32_e32 v18, v13
	v_lshlrev_b32_e32 v16, 16, v5
	v_and_b32_e32 v17, 0xffff0000, v5
	v_fma_f32 v5, -v13, v18, 1.0
	v_fmac_f32_e32 v18, v5, v18
	v_div_scale_f32 v5, vcc, v22, v9, v22
	v_mul_f32_e32 v19, v5, v18
	v_fma_f32 v21, -v13, v19, v5
	v_fmac_f32_e32 v19, v21, v18
	v_fma_f32 v5, -v13, v19, v5
	v_div_scale_f32 v13, s[6:7], v8, v8, v20
	v_rcp_f32_e32 v21, v13
	v_div_fmas_f32 v5, v5, v18, v19
	v_div_fixup_f32 v9, v5, v9, v22
	v_fma_f32 v5, -v13, v21, 1.0
	v_fmac_f32_e32 v21, v5, v21
	v_div_scale_f32 v5, vcc, v20, v8, v20
	v_mul_f32_e32 v22, v5, v21
	v_fma_f32 v18, -v13, v22, v5
	v_fmac_f32_e32 v22, v18, v21
	v_fma_f32 v5, -v13, v22, v5
	v_lshlrev_b32_e32 v13, 16, v10
	v_and_b32_e32 v10, 0xffff0000, v10
	v_mul_f32_e32 v18, 0xbfb8aa3b, v13
	v_mul_f32_e32 v19, 0xbfb8aa3b, v10
	v_exp_f32_e32 v18, v18
	v_exp_f32_e32 v19, v19
	v_div_fmas_f32 v5, v5, v21, v22
	v_div_fixup_f32 v8, v5, v8, v20
	v_pk_mul_f32 v[8:9], v[8:9], v[16:17]
	v_pk_add_f32 v[16:17], v[18:19], 1.0 op_sel_hi:[1,0]
	v_cvt_pk_bf16_f32 v5, v8, v9
	v_div_scale_f32 v18, s[6:7], v17, v17, v10
	v_rcp_f32_e32 v19, v18
	v_lshlrev_b32_e32 v8, 16, v6
	v_and_b32_e32 v9, 0xffff0000, v6
	v_fma_f32 v6, -v18, v19, 1.0
	v_fmac_f32_e32 v19, v6, v19
	v_div_scale_f32 v6, vcc, v10, v17, v10
	v_mul_f32_e32 v20, v6, v19
	v_fma_f32 v21, -v18, v20, v6
	v_fmac_f32_e32 v20, v21, v19
	v_fma_f32 v6, -v18, v20, v6
	v_div_scale_f32 v18, s[6:7], v16, v16, v13
	v_rcp_f32_e32 v21, v18
	v_div_fmas_f32 v6, v6, v19, v20
	v_div_fixup_f32 v17, v6, v17, v10
	v_and_b32_e32 v20, 0xffff0000, v11
	v_fma_f32 v6, -v18, v21, 1.0
	v_fmac_f32_e32 v21, v6, v21
	v_div_scale_f32 v6, vcc, v13, v16, v13
	v_mul_f32_e32 v19, v6, v21
	v_fma_f32 v10, -v18, v19, v6
	v_fmac_f32_e32 v19, v10, v21
	v_fma_f32 v6, -v18, v19, v6
	v_lshlrev_b32_e32 v18, 16, v11
	v_mul_f32_e32 v10, 0xbfb8aa3b, v18
	v_mul_f32_e32 v11, 0xbfb8aa3b, v20
	v_exp_f32_e32 v10, v10
	v_exp_f32_e32 v11, v11
	v_div_fmas_f32 v6, v6, v21, v19
	v_div_fixup_f32 v16, v6, v16, v13
	v_pk_mul_f32 v[8:9], v[16:17], v[8:9]
	v_pk_add_f32 v[10:11], v[10:11], 1.0 op_sel_hi:[1,0]
	v_cvt_pk_bf16_f32 v6, v8, v9
	v_div_scale_f32 v13, s[6:7], v11, v11, v20
	v_rcp_f32_e32 v16, v13
	v_lshlrev_b32_e32 v8, 16, v7
	v_and_b32_e32 v9, 0xffff0000, v7
	v_fma_f32 v7, -v13, v16, 1.0
	v_fmac_f32_e32 v16, v7, v16
	v_div_scale_f32 v7, vcc, v20, v11, v20
	v_mul_f32_e32 v17, v7, v16
	v_fma_f32 v19, -v13, v17, v7
	v_fmac_f32_e32 v17, v19, v16
	v_fma_f32 v7, -v13, v17, v7
	v_div_scale_f32 v13, s[6:7], v10, v10, v18
	v_rcp_f32_e32 v19, v13
	v_div_fmas_f32 v7, v7, v16, v17
	v_div_fixup_f32 v11, v7, v11, v20
	v_fma_f32 v7, -v13, v19, 1.0
	v_fmac_f32_e32 v19, v7, v19
	v_div_scale_f32 v7, vcc, v18, v10, v18
	v_mul_f32_e32 v16, v7, v19
	v_fma_f32 v17, -v13, v16, v7
	v_fmac_f32_e32 v16, v17, v19
	v_fma_f32 v7, -v13, v16, v7
	v_div_fmas_f32 v7, v7, v19, v16
	v_div_fixup_f32 v10, v7, v10, v18
	v_pk_mul_f32 v[8:9], v[10:11], v[8:9]
	s_nop 0
	v_cvt_pk_bf16_f32 v7, v8, v9
	v_lshlrev_b64 v[8:9], 12, v[14:15]
	v_lshl_add_u64 v[8:9], v[68:69], 0, v[8:9]
	global_store_dwordx4 v[8:9], v[4:7], off sc1
	v_or_b32_e32 v8, 20, v144
	s_waitcnt lgkmcnt(0)
	v_lshlrev_b32_e32 v14, 16, v0
	v_mad_u64_u32 v[4:5], s[6:7], v8, s72, v[70:71]
	global_load_dwordx4 v[4:7], v[4:5], off offset:1024
	v_and_b32_e32 v15, 0xffff0000, v0
	s_waitcnt vmcnt(0)
	v_lshlrev_b32_e32 v13, 16, v4
	v_and_b32_e32 v4, 0xffff0000, v4
	v_mul_f32_e32 v9, 0xbfb8aa3b, v13
	v_exp_f32_e32 v10, v9
	v_mul_f32_e32 v9, 0xbfb8aa3b, v4
	v_exp_f32_e32 v11, v9
	v_mov_b32_e32 v9, v145
	v_pk_add_f32 v[10:11], v[10:11], 1.0 op_sel_hi:[1,0]
	s_nop 0
	v_div_scale_f32 v16, s[6:7], v11, v11, v4
	v_rcp_f32_e32 v17, v16
	s_nop 0
	v_fma_f32 v0, -v16, v17, 1.0
	v_fmac_f32_e32 v17, v0, v17
	v_div_scale_f32 v0, vcc, v4, v11, v4
	v_mul_f32_e32 v18, v0, v17
	v_fma_f32 v19, -v16, v18, v0
	v_fmac_f32_e32 v18, v19, v17
	v_fma_f32 v0, -v16, v18, v0
	v_div_scale_f32 v16, s[6:7], v10, v10, v13
	v_rcp_f32_e32 v19, v16
	v_div_fmas_f32 v0, v0, v17, v18
	v_div_fixup_f32 v11, v0, v11, v4
	v_and_b32_e32 v18, 0xffff0000, v5
	v_fma_f32 v0, -v16, v19, 1.0
	v_fmac_f32_e32 v19, v0, v19
	v_div_scale_f32 v0, vcc, v13, v10, v13
	v_mul_f32_e32 v17, v0, v19
	v_fma_f32 v4, -v16, v17, v0
	v_fmac_f32_e32 v17, v4, v19
	v_fma_f32 v0, -v16, v17, v0
	v_lshlrev_b32_e32 v16, 16, v5
	v_mul_f32_e32 v4, 0xbfb8aa3b, v16
	v_mul_f32_e32 v5, 0xbfb8aa3b, v18
	v_exp_f32_e32 v4, v4
	v_exp_f32_e32 v5, v5
	v_div_fmas_f32 v0, v0, v19, v17
	v_div_fixup_f32 v10, v0, v10, v13
	v_pk_mul_f32 v[10:11], v[10:11], v[14:15]
	v_pk_add_f32 v[4:5], v[4:5], 1.0 op_sel_hi:[1,0]
	v_cvt_pk_bf16_f32 v0, v10, v11
	v_div_scale_f32 v13, s[6:7], v5, v5, v18
	v_rcp_f32_e32 v14, v13
	v_lshlrev_b32_e32 v10, 16, v1
	v_and_b32_e32 v11, 0xffff0000, v1
	v_fma_f32 v1, -v13, v14, 1.0
	v_fmac_f32_e32 v14, v1, v14
	v_div_scale_f32 v1, vcc, v18, v5, v18
	v_mul_f32_e32 v15, v1, v14
	v_fma_f32 v17, -v13, v15, v1
	v_fmac_f32_e32 v15, v17, v14
	v_fma_f32 v1, -v13, v15, v1
	v_div_scale_f32 v13, s[6:7], v4, v4, v16
	v_rcp_f32_e32 v17, v13
	v_div_fmas_f32 v1, v1, v14, v15
	v_div_fixup_f32 v5, v1, v5, v18
	v_fma_f32 v1, -v13, v17, 1.0
	v_fmac_f32_e32 v17, v1, v17
	v_div_scale_f32 v1, vcc, v16, v4, v16
	v_mul_f32_e32 v18, v1, v17
	v_fma_f32 v14, -v13, v18, v1
	v_fmac_f32_e32 v18, v14, v17
	v_fma_f32 v1, -v13, v18, v1
	v_lshlrev_b32_e32 v13, 16, v6
	v_and_b32_e32 v6, 0xffff0000, v6
	v_mul_f32_e32 v14, 0xbfb8aa3b, v13
	v_mul_f32_e32 v15, 0xbfb8aa3b, v6
	v_exp_f32_e32 v14, v14
	v_exp_f32_e32 v15, v15
	v_div_fmas_f32 v1, v1, v17, v18
	v_div_fixup_f32 v4, v1, v4, v16
	v_pk_mul_f32 v[4:5], v[4:5], v[10:11]
	v_pk_add_f32 v[10:11], v[14:15], 1.0 op_sel_hi:[1,0]
	v_cvt_pk_bf16_f32 v1, v4, v5
	v_div_scale_f32 v14, s[6:7], v11, v11, v6
	v_rcp_f32_e32 v15, v14
	v_lshlrev_b32_e32 v4, 16, v2
	v_and_b32_e32 v5, 0xffff0000, v2
	v_fma_f32 v2, -v14, v15, 1.0
	v_fmac_f32_e32 v15, v2, v15
	v_div_scale_f32 v2, vcc, v6, v11, v6
	v_mul_f32_e32 v16, v2, v15
	v_fma_f32 v17, -v14, v16, v2
	v_fmac_f32_e32 v16, v17, v15
	v_fma_f32 v2, -v14, v16, v2
	v_div_scale_f32 v14, s[6:7], v10, v10, v13
	v_rcp_f32_e32 v17, v14
	v_div_fmas_f32 v2, v2, v15, v16
	v_div_fixup_f32 v11, v2, v11, v6
	v_and_b32_e32 v16, 0xffff0000, v7
	v_fma_f32 v2, -v14, v17, 1.0
	v_fmac_f32_e32 v17, v2, v17
	v_div_scale_f32 v2, vcc, v13, v10, v13
	v_mul_f32_e32 v15, v2, v17
	v_fma_f32 v6, -v14, v15, v2
	v_fmac_f32_e32 v15, v6, v17
	v_fma_f32 v2, -v14, v15, v2
	v_lshlrev_b32_e32 v14, 16, v7
	v_mul_f32_e32 v6, 0xbfb8aa3b, v14
	v_mul_f32_e32 v7, 0xbfb8aa3b, v16
	v_exp_f32_e32 v6, v6
	v_exp_f32_e32 v7, v7
	v_div_fmas_f32 v2, v2, v17, v15
	v_div_fixup_f32 v10, v2, v10, v13
	v_pk_mul_f32 v[4:5], v[10:11], v[4:5]
	v_pk_add_f32 v[6:7], v[6:7], 1.0 op_sel_hi:[1,0]
	v_cvt_pk_bf16_f32 v2, v4, v5
	v_div_scale_f32 v10, s[6:7], v7, v7, v16
	v_rcp_f32_e32 v11, v10
	v_lshlrev_b32_e32 v4, 16, v3
	v_and_b32_e32 v5, 0xffff0000, v3
	v_fma_f32 v3, -v10, v11, 1.0
	v_fmac_f32_e32 v11, v3, v11
	v_div_scale_f32 v3, vcc, v16, v7, v16
	v_mul_f32_e32 v13, v3, v11
	v_fma_f32 v15, -v10, v13, v3
	v_fmac_f32_e32 v13, v15, v11
	v_fma_f32 v3, -v10, v13, v3
	v_div_scale_f32 v10, s[6:7], v6, v6, v14
	v_rcp_f32_e32 v15, v10
	v_div_fmas_f32 v3, v3, v11, v13
	v_div_fixup_f32 v7, v3, v7, v16
	v_fma_f32 v3, -v10, v15, 1.0
	v_fmac_f32_e32 v15, v3, v15
	v_div_scale_f32 v3, vcc, v14, v6, v14
	v_mul_f32_e32 v11, v3, v15
	v_fma_f32 v13, -v10, v11, v3
	v_fmac_f32_e32 v11, v13, v15
	v_fma_f32 v3, -v10, v11, v3
	v_div_fmas_f32 v3, v3, v15, v11
	v_div_fixup_f32 v6, v3, v6, v14
	v_pk_mul_f32 v[4:5], v[6:7], v[4:5]
	v_or_b32_e32 v14, 24, v144
	v_cvt_pk_bf16_f32 v3, v4, v5
	v_lshlrev_b64 v[4:5], 12, v[8:9]
	v_lshl_add_u64 v[4:5], v[68:69], 0, v[4:5]
	global_store_dwordx4 v[4:5], v[0:3], off sc1
	ds_read_b128 v[4:7], v12 offset:6528
	v_mov_b32_e32 v15, v145
	v_mad_u64_u32 v[0:1], s[6:7], v14, s72, v[70:71]
	global_load_dwordx4 v[8:11], v[0:1], off offset:1024
	v_or_b32_e32 v144, 28, v144
	s_waitcnt vmcnt(0)
	v_lshlrev_b32_e32 v18, 16, v8
	v_and_b32_e32 v8, 0xffff0000, v8
	v_mul_f32_e32 v0, 0xbfb8aa3b, v18
	v_mul_f32_e32 v1, 0xbfb8aa3b, v8
	v_exp_f32_e32 v0, v0
	v_exp_f32_e32 v1, v1
	s_nop 0
	v_pk_add_f32 v[16:17], v[0:1], 1.0 op_sel_hi:[1,0]
	s_nop 0
	v_div_scale_f32 v19, s[6:7], v17, v17, v8
	v_rcp_f32_e32 v20, v19
	ds_read_b128 v[0:3], v12 offset:7616
	s_waitcnt lgkmcnt(1)
	v_lshlrev_b32_e32 v12, 16, v4
	v_and_b32_e32 v13, 0xffff0000, v4
	v_fma_f32 v4, -v19, v20, 1.0
	v_fmac_f32_e32 v20, v4, v20
	v_div_scale_f32 v4, vcc, v8, v17, v8
	v_mul_f32_e32 v21, v4, v20
	v_fma_f32 v22, -v19, v21, v4
	v_fmac_f32_e32 v21, v22, v20
	v_fma_f32 v4, -v19, v21, v4
	v_div_scale_f32 v19, s[6:7], v16, v16, v18
	v_rcp_f32_e32 v22, v19
	v_div_fmas_f32 v4, v4, v20, v21
	v_div_fixup_f32 v17, v4, v17, v8
	v_and_b32_e32 v21, 0xffff0000, v9
	v_fma_f32 v4, -v19, v22, 1.0
	v_fmac_f32_e32 v22, v4, v22
	v_div_scale_f32 v4, vcc, v18, v16, v18
	v_mul_f32_e32 v20, v4, v22
	v_fma_f32 v8, -v19, v20, v4
	v_fmac_f32_e32 v20, v8, v22
	v_fma_f32 v4, -v19, v20, v4
	v_lshlrev_b32_e32 v19, 16, v9
	v_mul_f32_e32 v8, 0xbfb8aa3b, v19
	v_mul_f32_e32 v9, 0xbfb8aa3b, v21
	v_exp_f32_e32 v8, v8
	v_exp_f32_e32 v9, v9
	v_div_fmas_f32 v4, v4, v22, v20
	v_div_fixup_f32 v16, v4, v16, v18
	v_pk_mul_f32 v[12:13], v[16:17], v[12:13]
	v_pk_add_f32 v[8:9], v[8:9], 1.0 op_sel_hi:[1,0]
	v_cvt_pk_bf16_f32 v4, v12, v13
	v_div_scale_f32 v16, s[6:7], v9, v9, v21
	v_rcp_f32_e32 v17, v16
	v_lshlrev_b32_e32 v12, 16, v5
	v_and_b32_e32 v13, 0xffff0000, v5
	v_fma_f32 v5, -v16, v17, 1.0
	v_fmac_f32_e32 v17, v5, v17
	v_div_scale_f32 v5, vcc, v21, v9, v21
	v_mul_f32_e32 v18, v5, v17
	v_fma_f32 v20, -v16, v18, v5
	v_fmac_f32_e32 v18, v20, v17
	v_fma_f32 v5, -v16, v18, v5
	v_div_scale_f32 v16, s[6:7], v8, v8, v19
	v_rcp_f32_e32 v20, v16
	v_div_fmas_f32 v5, v5, v17, v18
	v_div_fixup_f32 v9, v5, v9, v21
	v_lshlrev_b32_e32 v21, 16, v10
	v_fma_f32 v5, -v16, v20, 1.0
	v_fmac_f32_e32 v20, v5, v20
	v_div_scale_f32 v5, vcc, v19, v8, v19
	v_mul_f32_e32 v18, v5, v20
	v_fma_f32 v17, -v16, v18, v5
	v_fmac_f32_e32 v18, v17, v20
	v_and_b32_e32 v10, 0xffff0000, v10
	v_fma_f32 v5, -v16, v18, v5
	v_mul_f32_e32 v16, 0xbfb8aa3b, v21
	v_mul_f32_e32 v17, 0xbfb8aa3b, v10
	v_exp_f32_e32 v16, v16
	v_exp_f32_e32 v17, v17
	v_div_fmas_f32 v5, v5, v20, v18
	v_div_fixup_f32 v8, v5, v8, v19
	v_pk_mul_f32 v[8:9], v[8:9], v[12:13]
	v_pk_add_f32 v[12:13], v[16:17], 1.0 op_sel_hi:[1,0]
	v_cvt_pk_bf16_f32 v5, v8, v9
	v_div_scale_f32 v16, s[6:7], v13, v13, v10
	v_rcp_f32_e32 v17, v16
	v_lshlrev_b32_e32 v8, 16, v6
	v_and_b32_e32 v9, 0xffff0000, v6
	v_fma_f32 v6, -v16, v17, 1.0
	v_fmac_f32_e32 v17, v6, v17
	v_div_scale_f32 v6, vcc, v10, v13, v10
	v_mul_f32_e32 v18, v6, v17
	v_fma_f32 v19, -v16, v18, v6
	v_fmac_f32_e32 v18, v19, v17
	v_fma_f32 v6, -v16, v18, v6
	v_div_scale_f32 v16, s[6:7], v12, v12, v21
	v_rcp_f32_e32 v19, v16
	v_div_fmas_f32 v6, v6, v17, v18
	v_div_fixup_f32 v13, v6, v13, v10
	v_and_b32_e32 v18, 0xffff0000, v11
	v_fma_f32 v6, -v16, v19, 1.0
	v_fmac_f32_e32 v19, v6, v19
	v_div_scale_f32 v6, vcc, v21, v12, v21
	v_mul_f32_e32 v17, v6, v19
	v_fma_f32 v10, -v16, v17, v6
	v_fmac_f32_e32 v17, v10, v19
	v_fma_f32 v6, -v16, v17, v6
	v_lshlrev_b32_e32 v16, 16, v11
	v_mul_f32_e32 v10, 0xbfb8aa3b, v16
	v_mul_f32_e32 v11, 0xbfb8aa3b, v18
	v_exp_f32_e32 v10, v10
	v_exp_f32_e32 v11, v11
	v_div_fmas_f32 v6, v6, v19, v17
	v_div_fixup_f32 v12, v6, v12, v21
	v_pk_mul_f32 v[8:9], v[12:13], v[8:9]
	v_pk_add_f32 v[10:11], v[10:11], 1.0 op_sel_hi:[1,0]
	v_cvt_pk_bf16_f32 v6, v8, v9
	v_div_scale_f32 v12, s[6:7], v11, v11, v18
	v_rcp_f32_e32 v13, v12
	v_lshlrev_b32_e32 v8, 16, v7
	v_and_b32_e32 v9, 0xffff0000, v7
	v_fma_f32 v7, -v12, v13, 1.0
	v_fmac_f32_e32 v13, v7, v13
	v_div_scale_f32 v7, vcc, v18, v11, v18
	v_mul_f32_e32 v17, v7, v13
	v_fma_f32 v19, -v12, v17, v7
	v_fmac_f32_e32 v17, v19, v13
	v_fma_f32 v7, -v12, v17, v7
	v_div_scale_f32 v12, s[6:7], v10, v10, v16
	v_rcp_f32_e32 v19, v12
	v_div_fmas_f32 v7, v7, v13, v17
	v_div_fixup_f32 v11, v7, v11, v18
	v_fma_f32 v7, -v12, v19, 1.0
	v_fmac_f32_e32 v19, v7, v19
	v_div_scale_f32 v7, vcc, v16, v10, v16
	v_mul_f32_e32 v13, v7, v19
	v_fma_f32 v17, -v12, v13, v7
	v_fmac_f32_e32 v13, v17, v19
	v_fma_f32 v7, -v12, v13, v7
	v_div_fmas_f32 v7, v7, v19, v13
	v_div_fixup_f32 v10, v7, v10, v16
	v_pk_mul_f32 v[8:9], v[10:11], v[8:9]
	s_waitcnt lgkmcnt(0)
	v_lshlrev_b32_e32 v10, 16, v0
	v_cvt_pk_bf16_f32 v7, v8, v9
	v_lshlrev_b64 v[8:9], 12, v[14:15]
	v_lshl_add_u64 v[8:9], v[68:69], 0, v[8:9]
	global_store_dwordx4 v[8:9], v[4:7], off sc1
	v_and_b32_e32 v11, 0xffff0000, v0
	s_nop 0
	v_mad_u64_u32 v[4:5], s[6:7], v144, s72, v[70:71]
	global_load_dwordx4 v[4:7], v[4:5], off offset:1024
	s_waitcnt vmcnt(0)
	v_lshlrev_b32_e32 v12, 16, v4
	v_and_b32_e32 v4, 0xffff0000, v4
	v_mul_f32_e32 v8, 0xbfb8aa3b, v12
	v_mul_f32_e32 v9, 0xbfb8aa3b, v4
	v_exp_f32_e32 v8, v8
	v_exp_f32_e32 v9, v9
	s_nop 0
	v_pk_add_f32 v[8:9], v[8:9], 1.0 op_sel_hi:[1,0]
	s_nop 0
	v_div_scale_f32 v13, s[6:7], v9, v9, v4
	v_rcp_f32_e32 v14, v13
	s_nop 0
	v_fma_f32 v0, -v13, v14, 1.0
	v_fmac_f32_e32 v14, v0, v14
	v_div_scale_f32 v0, vcc, v4, v9, v4
	v_mul_f32_e32 v15, v0, v14
	v_fma_f32 v16, -v13, v15, v0
	v_fmac_f32_e32 v15, v16, v14
	v_fma_f32 v0, -v13, v15, v0
	v_div_scale_f32 v13, s[6:7], v8, v8, v12
	v_rcp_f32_e32 v16, v13
	v_div_fmas_f32 v0, v0, v14, v15
	v_div_fixup_f32 v9, v0, v9, v4
	v_and_b32_e32 v15, 0xffff0000, v5
	v_fma_f32 v0, -v13, v16, 1.0
	v_fmac_f32_e32 v16, v0, v16
	v_div_scale_f32 v0, vcc, v12, v8, v12
	v_mul_f32_e32 v14, v0, v16
	v_fma_f32 v4, -v13, v14, v0
	v_fmac_f32_e32 v14, v4, v16
	v_fma_f32 v0, -v13, v14, v0
	v_lshlrev_b32_e32 v13, 16, v5
	v_mul_f32_e32 v4, 0xbfb8aa3b, v13
	v_mul_f32_e32 v5, 0xbfb8aa3b, v15
	v_exp_f32_e32 v4, v4
	v_exp_f32_e32 v5, v5
	v_div_fmas_f32 v0, v0, v16, v14
	v_div_fixup_f32 v8, v0, v8, v12
	v_pk_mul_f32 v[8:9], v[8:9], v[10:11]
	v_pk_add_f32 v[4:5], v[4:5], 1.0 op_sel_hi:[1,0]
	v_cvt_pk_bf16_f32 v0, v8, v9
	v_div_scale_f32 v10, s[6:7], v5, v5, v15
	v_rcp_f32_e32 v11, v10
	v_lshlrev_b32_e32 v8, 16, v1
	v_and_b32_e32 v9, 0xffff0000, v1
	v_fma_f32 v1, -v10, v11, 1.0
	v_fmac_f32_e32 v11, v1, v11
	v_div_scale_f32 v1, vcc, v15, v5, v15
	v_mul_f32_e32 v12, v1, v11
	v_fma_f32 v14, -v10, v12, v1
	v_fmac_f32_e32 v12, v14, v11
	v_fma_f32 v1, -v10, v12, v1
	v_div_scale_f32 v10, s[6:7], v4, v4, v13
	v_rcp_f32_e32 v14, v10
	v_div_fmas_f32 v1, v1, v11, v12
	v_div_fixup_f32 v5, v1, v5, v15
	v_lshlrev_b32_e32 v15, 16, v6
	v_fma_f32 v1, -v10, v14, 1.0
	v_fmac_f32_e32 v14, v1, v14
	v_div_scale_f32 v1, vcc, v13, v4, v13
	v_mul_f32_e32 v12, v1, v14
	v_fma_f32 v11, -v10, v12, v1
	v_fmac_f32_e32 v12, v11, v14
	v_and_b32_e32 v6, 0xffff0000, v6
	v_fma_f32 v1, -v10, v12, v1
	v_mul_f32_e32 v10, 0xbfb8aa3b, v15
	v_mul_f32_e32 v11, 0xbfb8aa3b, v6
	v_exp_f32_e32 v10, v10
	v_exp_f32_e32 v11, v11
	v_div_fmas_f32 v1, v1, v14, v12
	v_div_fixup_f32 v4, v1, v4, v13
	v_pk_mul_f32 v[4:5], v[4:5], v[8:9]
	v_pk_add_f32 v[8:9], v[10:11], 1.0 op_sel_hi:[1,0]
	v_cvt_pk_bf16_f32 v1, v4, v5
	v_div_scale_f32 v10, s[6:7], v9, v9, v6
	v_rcp_f32_e32 v11, v10
	v_lshlrev_b32_e32 v4, 16, v2
	v_and_b32_e32 v5, 0xffff0000, v2
	v_fma_f32 v2, -v10, v11, 1.0
	v_fmac_f32_e32 v11, v2, v11
	v_div_scale_f32 v2, vcc, v6, v9, v6
	v_mul_f32_e32 v12, v2, v11
	v_fma_f32 v13, -v10, v12, v2
	v_fmac_f32_e32 v12, v13, v11
	v_fma_f32 v2, -v10, v12, v2
	v_div_scale_f32 v10, s[6:7], v8, v8, v15
	v_rcp_f32_e32 v13, v10
	v_div_fmas_f32 v2, v2, v11, v12
	v_div_fixup_f32 v9, v2, v9, v6
	v_and_b32_e32 v12, 0xffff0000, v7
	v_fma_f32 v2, -v10, v13, 1.0
	v_fmac_f32_e32 v13, v2, v13
	v_div_scale_f32 v2, vcc, v15, v8, v15
	v_mul_f32_e32 v11, v2, v13
	v_fma_f32 v6, -v10, v11, v2
	v_fmac_f32_e32 v11, v6, v13
	v_fma_f32 v2, -v10, v11, v2
	v_lshlrev_b32_e32 v10, 16, v7
	v_mul_f32_e32 v6, 0xbfb8aa3b, v10
	v_mul_f32_e32 v7, 0xbfb8aa3b, v12
	v_exp_f32_e32 v6, v6
	v_exp_f32_e32 v7, v7
	v_div_fmas_f32 v2, v2, v13, v11
	v_div_fixup_f32 v8, v2, v8, v15
	v_pk_mul_f32 v[4:5], v[8:9], v[4:5]
	v_pk_add_f32 v[6:7], v[6:7], 1.0 op_sel_hi:[1,0]
	v_cvt_pk_bf16_f32 v2, v4, v5
	v_div_scale_f32 v8, s[6:7], v7, v7, v12
	v_rcp_f32_e32 v9, v8
	v_lshlrev_b32_e32 v4, 16, v3
	v_and_b32_e32 v5, 0xffff0000, v3
	v_fma_f32 v3, -v8, v9, 1.0
	v_fmac_f32_e32 v9, v3, v9
	v_div_scale_f32 v3, vcc, v12, v7, v12
	v_mul_f32_e32 v11, v3, v9
	v_fma_f32 v13, -v8, v11, v3
	v_fmac_f32_e32 v11, v13, v9
	v_fma_f32 v3, -v8, v11, v3
	v_div_scale_f32 v8, s[6:7], v6, v6, v10
	v_rcp_f32_e32 v13, v8
	v_div_fmas_f32 v3, v3, v9, v11
	v_div_fixup_f32 v7, v3, v7, v12
	v_fma_f32 v3, -v8, v13, 1.0
	v_fmac_f32_e32 v13, v3, v13
	v_div_scale_f32 v3, vcc, v10, v6, v10
	v_mul_f32_e32 v9, v3, v13
	v_fma_f32 v11, -v8, v9, v3
	v_fmac_f32_e32 v9, v11, v13
	v_fma_f32 v3, -v8, v9, v3
	v_div_fmas_f32 v3, v3, v13, v9
	v_div_fixup_f32 v6, v3, v6, v10
	v_pk_mul_f32 v[4:5], v[6:7], v[4:5]
	s_nop 0
	v_cvt_pk_bf16_f32 v3, v4, v5
	v_lshlrev_b64 v[4:5], 12, v[144:145]
	v_lshl_add_u64 v[4:5], v[68:69], 0, v[4:5]
	global_store_dwordx4 v[4:5], v[0:3], off sc1
	s_barrier

.LBB0_1284:
	v_pk_add_f32 v[64:65], v[80:81], 0 op_sel_hi:[1,0]
	s_lshl_b64 s[6:7], s[38:39], 12
	v_pk_add_f32 v[64:65], v[82:83], v[64:65]
	s_add_u32 s6, s63, s6
	v_pk_add_f32 v[64:65], v[84:85], v[64:65]
	s_addc_u32 s7, s64, s7
	v_pk_add_f32 v[64:65], v[86:87], v[64:65]
	s_add_u32 s6, s6, s87
	v_pk_add_f32 v[64:65], v[88:89], v[64:65]
	s_addc_u32 s7, s7, 0
	v_pk_add_f32 v[64:65], v[90:91], v[64:65]
	v_lshlrev_b32_e32 v144, 1, v150
	v_pk_add_f32 v[64:65], v[92:93], v[64:65]
	s_nop 0
	v_pk_add_f32 v[64:65], v[94:95], v[64:65]
	s_barrier
	v_pk_add_f32 v[64:65], v[96:97], v[64:65]
	s_nop 0
	v_pk_add_f32 v[64:65], v[98:99], v[64:65]
	s_nop 0
	v_pk_add_f32 v[64:65], v[100:101], v[64:65]
	s_nop 0
	v_pk_add_f32 v[64:65], v[102:103], v[64:65]
	s_nop 0
	v_pk_add_f32 v[64:65], v[104:105], v[64:65]
	s_nop 0
	v_pk_add_f32 v[64:65], v[106:107], v[64:65]
	s_nop 0
	v_pk_add_f32 v[64:65], v[108:109], v[64:65]
	s_nop 0
	v_pk_add_f32 v[64:65], v[110:111], v[64:65]
	s_nop 0
	v_add_f32_e32 v64, v64, v65
	v_add_f32_e32 v64, v128, v64
	ds_bpermute_b32 v65, v153, v64
	s_waitcnt lgkmcnt(0)
	v_add_f32_e32 v72, v64, v65
	v_div_scale_f32 v64, s[8:9], v72, v72, 1.0
	v_rcp_f32_e32 v65, v64
	s_add_u32 s8, s85, s87
	s_addc_u32 s9, s86, 0
	v_fma_f32 v66, -v64, v65, 1.0
	v_fmac_f32_e32 v65, v66, v65
	v_div_scale_f32 v66, vcc, 1.0, v72, 1.0
	v_mul_f32_e32 v67, v66, v65
	v_fma_f32 v68, -v64, v67, v66
	v_fmac_f32_e32 v67, v68, v65
	v_fma_f32 v64, -v64, v67, v66
	v_div_fmas_f32 v73, v64, v65, v67
	v_lshl_add_u64 v[64:65], s[8:9], 0, v[144:145]
	v_lshl_add_u64 v[70:71], v[64:65], 0, s[34:35]
	v_lshl_add_u64 v[68:69], s[6:7], 0, v[144:145]
	v_or_b32_e32 v144, s82, v199
	v_mad_u64_u32 v[64:65], s[6:7], v144, s72, v[70:71]
	global_load_dwordx4 v[64:67], v[64:65], off
	v_div_fixup_f32 v72, v73, v72, 1.0
	v_pk_mul_f32 v[0:1], v[0:1], v[72:73] op_sel_hi:[1,0]
	v_pk_mul_f32 v[2:3], v[2:3], v[72:73] op_sel_hi:[1,0]
	v_cvt_pk_bf16_f32 v0, v0, v1
	v_cvt_pk_bf16_f32 v1, v2, v3
	v_pk_mul_f32 v[2:3], v[4:5], v[72:73] op_sel_hi:[1,0]
	v_pk_mul_f32 v[4:5], v[6:7], v[72:73] op_sel_hi:[1,0]
	v_mad_u64_u32 v[74:75], s[6:7], v180, s69, v[146:147]
	v_pk_mul_f32 v[16:17], v[16:17], v[72:73] op_sel_hi:[1,0]
	v_pk_mul_f32 v[18:19], v[18:19], v[72:73] op_sel_hi:[1,0]
	v_cvt_pk_bf16_f32 v2, v2, v3
	v_cvt_pk_bf16_f32 v3, v4, v5
	v_cvt_pk_bf16_f32 v16, v16, v17
	v_cvt_pk_bf16_f32 v17, v18, v19
	v_pk_mul_f32 v[18:19], v[20:21], v[72:73] op_sel_hi:[1,0]
	v_pk_mul_f32 v[20:21], v[22:23], v[72:73] op_sel_hi:[1,0]
	ds_write2_b64 v74, v[0:1], v[2:3] offset0:24 offset1:26
	v_pk_mul_f32 v[0:1], v[8:9], v[72:73] op_sel_hi:[1,0]
	v_pk_mul_f32 v[2:3], v[10:11], v[72:73] op_sel_hi:[1,0]
	v_cvt_pk_bf16_f32 v18, v18, v19
	v_cvt_pk_bf16_f32 v19, v20, v21
	v_cvt_pk_bf16_f32 v0, v0, v1
	v_cvt_pk_bf16_f32 v1, v2, v3
	v_pk_mul_f32 v[2:3], v[12:13], v[72:73] op_sel_hi:[1,0]
	v_pk_mul_f32 v[4:5], v[14:15], v[72:73] op_sel_hi:[1,0]
	ds_write2_b64 v74, v[16:17], v[18:19] offset0:16 offset1:18
	v_pk_mul_f32 v[16:17], v[24:25], v[72:73] op_sel_hi:[1,0]
	v_pk_mul_f32 v[18:19], v[26:27], v[72:73] op_sel_hi:[1,0]
	v_cvt_pk_bf16_f32 v2, v2, v3
	v_cvt_pk_bf16_f32 v3, v4, v5
	v_or_b32_e32 v14, 4, v144
	v_cvt_pk_bf16_f32 v16, v16, v17
	v_cvt_pk_bf16_f32 v17, v18, v19
	v_pk_mul_f32 v[18:19], v[28:29], v[72:73] op_sel_hi:[1,0]
	v_pk_mul_f32 v[20:21], v[30:31], v[72:73] op_sel_hi:[1,0]
	ds_write2_b64 v74, v[0:1], v[2:3] offset0:28 offset1:30
	v_mad_u64_u32 v[0:1], s[6:7], v14, s72, v[70:71]
	v_pk_mul_f32 v[48:49], v[48:49], v[72:73] op_sel_hi:[1,0]
	v_pk_mul_f32 v[50:51], v[50:51], v[72:73] op_sel_hi:[1,0]
	v_pk_mul_f32 v[32:33], v[32:33], v[72:73] op_sel_hi:[1,0]
	v_pk_mul_f32 v[34:35], v[34:35], v[72:73] op_sel_hi:[1,0]
	v_cvt_pk_bf16_f32 v18, v18, v19
	v_cvt_pk_bf16_f32 v19, v20, v21
	global_load_dwordx4 v[4:7], v[0:1], off
	v_cvt_pk_bf16_f32 v48, v48, v49
	v_cvt_pk_bf16_f32 v49, v50, v51
	v_pk_mul_f32 v[50:51], v[52:53], v[72:73] op_sel_hi:[1,0]
	v_pk_mul_f32 v[52:53], v[54:55], v[72:73] op_sel_hi:[1,0]
	v_cvt_pk_bf16_f32 v32, v32, v33
	v_cvt_pk_bf16_f32 v33, v34, v35
	v_pk_mul_f32 v[34:35], v[36:37], v[72:73] op_sel_hi:[1,0]
	v_pk_mul_f32 v[36:37], v[38:39], v[72:73] op_sel_hi:[1,0]
	v_cvt_pk_bf16_f32 v50, v50, v51
	v_cvt_pk_bf16_f32 v51, v52, v53
	v_cvt_pk_bf16_f32 v34, v34, v35
	v_cvt_pk_bf16_f32 v35, v36, v37
	ds_write2_b64 v74, v[48:49], v[50:51] offset1:2
	v_pk_mul_f32 v[48:49], v[56:57], v[72:73] op_sel_hi:[1,0]
	v_pk_mul_f32 v[50:51], v[58:59], v[72:73] op_sel_hi:[1,0]
	ds_write2_b64 v74, v[32:33], v[34:35] offset0:8 offset1:10
	v_pk_mul_f32 v[32:33], v[40:41], v[72:73] op_sel_hi:[1,0]
	v_pk_mul_f32 v[34:35], v[42:43], v[72:73] op_sel_hi:[1,0]
	v_cvt_pk_bf16_f32 v48, v48, v49
	v_cvt_pk_bf16_f32 v49, v50, v51
	v_pk_mul_f32 v[50:51], v[60:61], v[72:73] op_sel_hi:[1,0]
	v_pk_mul_f32 v[52:53], v[62:63], v[72:73] op_sel_hi:[1,0]
	v_cvt_pk_bf16_f32 v32, v32, v33
	v_cvt_pk_bf16_f32 v33, v34, v35
	v_pk_mul_f32 v[34:35], v[44:45], v[72:73] op_sel_hi:[1,0]
	v_pk_mul_f32 v[36:37], v[46:47], v[72:73] op_sel_hi:[1,0]
	v_cvt_pk_bf16_f32 v50, v50, v51
	v_cvt_pk_bf16_f32 v51, v52, v53
	v_cvt_pk_bf16_f32 v34, v34, v35
	v_cvt_pk_bf16_f32 v35, v36, v37
	ds_write2_b64 v74, v[48:49], v[50:51] offset0:4 offset1:6
	ds_write2_b64 v74, v[32:33], v[34:35] offset0:12 offset1:14
	ds_write2_b64 v74, v[16:17], v[18:19] offset0:20 offset1:22
	s_waitcnt vmcnt(1)
	v_lshlrev_b32_e32 v15, 16, v64
	v_and_b32_e32 v20, 0xffff0000, v64
	v_mul_f32_e32 v0, 0xbfb8aa3b, v15
	v_mul_f32_e32 v1, 0xbfb8aa3b, v20
	v_exp_f32_e32 v0, v0
	v_exp_f32_e32 v1, v1
	v_mad_u64_u32 v[12:13], s[6:7], v144, s69, v[148:149]
	ds_read_b128 v[8:11], v12
	v_pk_add_f32 v[16:17], v[0:1], 1.0 op_sel_hi:[1,0]
	ds_read_b128 v[0:3], v12 offset:1088
	v_div_scale_f32 v13, s[6:7], v17, v17, v20
	v_rcp_f32_e32 v21, v13
	s_waitcnt lgkmcnt(1)
	v_lshlrev_b32_e32 v18, 16, v8
	v_and_b32_e32 v19, 0xffff0000, v8
	v_and_b32_e32 v24, 0xffff0000, v65
	v_fma_f32 v8, -v13, v21, 1.0
	v_fmac_f32_e32 v21, v8, v21
	v_div_scale_f32 v8, vcc, v20, v17, v20
	v_mul_f32_e32 v22, v8, v21
	v_fma_f32 v23, -v13, v22, v8
	v_fmac_f32_e32 v22, v23, v21
	v_fma_f32 v8, -v13, v22, v8
	v_div_scale_f32 v13, s[6:7], v16, v16, v15
	v_rcp_f32_e32 v23, v13
	v_div_fmas_f32 v8, v8, v21, v22
	v_div_fixup_f32 v17, v8, v17, v20
	v_mul_f32_e32 v21, 0xbfb8aa3b, v24
	v_fma_f32 v8, -v13, v23, 1.0
	v_fmac_f32_e32 v23, v8, v23
	v_div_scale_f32 v8, vcc, v15, v16, v15
	v_mul_f32_e32 v22, v8, v23
	v_fma_f32 v20, -v13, v22, v8
	v_fmac_f32_e32 v22, v20, v23
	v_fma_f32 v8, -v13, v22, v8
	v_lshlrev_b32_e32 v13, 16, v65
	v_mul_f32_e32 v20, 0xbfb8aa3b, v13
	v_exp_f32_e32 v20, v20
	v_exp_f32_e32 v21, v21
	v_div_fmas_f32 v8, v8, v23, v22
	v_div_fixup_f32 v16, v8, v16, v15
	v_pk_mul_f32 v[16:17], v[16:17], v[18:19]
	v_pk_add_f32 v[18:19], v[20:21], 1.0 op_sel_hi:[1,0]
	v_cvt_pk_bf16_f32 v8, v16, v17
	v_div_scale_f32 v15, s[6:7], v19, v19, v24
	v_rcp_f32_e32 v20, v15
	v_lshlrev_b32_e32 v16, 16, v9
	v_and_b32_e32 v17, 0xffff0000, v9
	v_fma_f32 v9, -v15, v20, 1.0
	v_fmac_f32_e32 v20, v9, v20
	v_div_scale_f32 v9, vcc, v24, v19, v24
	v_mul_f32_e32 v21, v9, v20
	v_fma_f32 v22, -v15, v21, v9
	v_fmac_f32_e32 v21, v22, v20
	v_fma_f32 v9, -v15, v21, v9
	v_div_scale_f32 v15, s[6:7], v18, v18, v13
	v_rcp_f32_e32 v22, v15
	v_div_fmas_f32 v9, v9, v20, v21
	v_div_fixup_f32 v19, v9, v19, v24
	v_and_b32_e32 v24, 0xffff0000, v66
	v_fma_f32 v9, -v15, v22, 1.0
	v_fmac_f32_e32 v22, v9, v22
	v_div_scale_f32 v9, vcc, v13, v18, v13
	v_mul_f32_e32 v23, v9, v22
	v_fma_f32 v20, -v15, v23, v9
	v_fmac_f32_e32 v23, v20, v22
	v_fma_f32 v9, -v15, v23, v9
	v_lshlrev_b32_e32 v15, 16, v66
	v_mul_f32_e32 v20, 0xbfb8aa3b, v15
	v_mul_f32_e32 v21, 0xbfb8aa3b, v24
	v_exp_f32_e32 v20, v20
	v_exp_f32_e32 v21, v21
	v_div_fmas_f32 v9, v9, v22, v23
	v_div_fixup_f32 v18, v9, v18, v13
	v_pk_mul_f32 v[16:17], v[18:19], v[16:17]
	v_pk_add_f32 v[18:19], v[20:21], 1.0 op_sel_hi:[1,0]
	v_cvt_pk_bf16_f32 v9, v16, v17
	v_div_scale_f32 v13, s[6:7], v19, v19, v24
	v_rcp_f32_e32 v20, v13
	v_lshlrev_b32_e32 v16, 16, v10
	v_and_b32_e32 v17, 0xffff0000, v10
	v_fma_f32 v10, -v13, v20, 1.0
	v_fmac_f32_e32 v20, v10, v20
	v_div_scale_f32 v10, vcc, v24, v19, v24
	v_mul_f32_e32 v21, v10, v20
	v_fma_f32 v22, -v13, v21, v10
	v_fmac_f32_e32 v21, v22, v20
	v_fma_f32 v10, -v13, v21, v10
	v_div_scale_f32 v13, s[6:7], v18, v18, v15
	v_rcp_f32_e32 v22, v13
	v_div_fmas_f32 v10, v10, v20, v21
	v_div_fixup_f32 v19, v10, v19, v24
	v_and_b32_e32 v24, 0xffff0000, v67
	v_fma_f32 v10, -v13, v22, 1.0
	v_fmac_f32_e32 v22, v10, v22
	v_div_scale_f32 v10, vcc, v15, v18, v15
	v_mul_f32_e32 v23, v10, v22
	v_fma_f32 v20, -v13, v23, v10
	v_fmac_f32_e32 v23, v20, v22
	v_fma_f32 v10, -v13, v23, v10
	v_lshlrev_b32_e32 v13, 16, v67
	v_mul_f32_e32 v20, 0xbfb8aa3b, v13
	v_mul_f32_e32 v21, 0xbfb8aa3b, v24
	v_exp_f32_e32 v20, v20
	v_exp_f32_e32 v21, v21
	v_div_fmas_f32 v10, v10, v22, v23
	v_div_fixup_f32 v18, v10, v18, v15
	v_pk_mul_f32 v[16:17], v[18:19], v[16:17]
	v_pk_add_f32 v[18:19], v[20:21], 1.0 op_sel_hi:[1,0]
	v_cvt_pk_bf16_f32 v10, v16, v17
	v_div_scale_f32 v15, s[6:7], v19, v19, v24
	v_rcp_f32_e32 v20, v15
	v_lshlrev_b32_e32 v16, 16, v11
	v_and_b32_e32 v17, 0xffff0000, v11
	v_fma_f32 v11, -v15, v20, 1.0
	v_fmac_f32_e32 v20, v11, v20
	v_div_scale_f32 v11, vcc, v24, v19, v24
	v_mul_f32_e32 v21, v11, v20
	v_fma_f32 v22, -v15, v21, v11
	v_fmac_f32_e32 v21, v22, v20
	v_fma_f32 v11, -v15, v21, v11
	v_div_scale_f32 v15, s[6:7], v18, v18, v13
	v_rcp_f32_e32 v22, v15
	v_div_fmas_f32 v11, v11, v20, v21
	v_div_fixup_f32 v19, v11, v19, v24
	v_fma_f32 v11, -v15, v22, 1.0
	v_fmac_f32_e32 v22, v11, v22
	v_div_scale_f32 v11, vcc, v13, v18, v13
	v_mul_f32_e32 v20, v11, v22
	v_fma_f32 v21, -v15, v20, v11
	v_fmac_f32_e32 v20, v21, v22
	v_fma_f32 v11, -v15, v20, v11
	v_div_fmas_f32 v11, v11, v22, v20
	v_div_fixup_f32 v18, v11, v18, v13
	s_waitcnt vmcnt(0)
	v_lshlrev_b32_e32 v13, 16, v4
	v_pk_mul_f32 v[16:17], v[18:19], v[16:17]
	v_and_b32_e32 v4, 0xffff0000, v4
	v_mul_f32_e32 v15, 0xbfb8aa3b, v13
	v_cvt_pk_bf16_f32 v11, v16, v17
	v_exp_f32_e32 v16, v15
	v_mul_f32_e32 v15, 0xbfb8aa3b, v4
	v_exp_f32_e32 v17, v15
	v_lshlrev_b64 v[18:19], 12, v[144:145]
	v_lshl_add_u64 v[18:19], v[68:69], 0, v[18:19]
	global_store_dwordx4 v[18:19], v[8:11], off offset:3072 sc1
	v_mov_b32_e32 v15, v145
	s_nop 0
	v_pk_add_f32 v[8:9], v[16:17], 1.0 op_sel_hi:[1,0]
	s_waitcnt lgkmcnt(0)
	v_lshlrev_b32_e32 v10, 16, v0
	v_div_scale_f32 v16, s[6:7], v9, v9, v4
	v_rcp_f32_e32 v17, v16
	v_and_b32_e32 v11, 0xffff0000, v0
	v_fma_f32 v0, -v16, v17, 1.0
	v_fmac_f32_e32 v17, v0, v17
	v_div_scale_f32 v0, vcc, v4, v9, v4
	v_mul_f32_e32 v18, v0, v17
	v_fma_f32 v19, -v16, v18, v0
	v_fmac_f32_e32 v18, v19, v17
	v_fma_f32 v0, -v16, v18, v0
	v_div_scale_f32 v16, s[6:7], v8, v8, v13
	v_rcp_f32_e32 v19, v16
	v_div_fmas_f32 v0, v0, v17, v18
	v_div_fixup_f32 v9, v0, v9, v4
	v_and_b32_e32 v18, 0xffff0000, v5
	v_fma_f32 v0, -v16, v19, 1.0
	v_fmac_f32_e32 v19, v0, v19
	v_div_scale_f32 v0, vcc, v13, v8, v13
	v_mul_f32_e32 v17, v0, v19
	v_fma_f32 v4, -v16, v17, v0
	v_fmac_f32_e32 v17, v4, v19
	v_fma_f32 v0, -v16, v17, v0
	v_lshlrev_b32_e32 v16, 16, v5
	v_mul_f32_e32 v4, 0xbfb8aa3b, v16
	v_mul_f32_e32 v5, 0xbfb8aa3b, v18
	v_exp_f32_e32 v4, v4
	v_exp_f32_e32 v5, v5
	v_div_fmas_f32 v0, v0, v19, v17
	v_div_fixup_f32 v8, v0, v8, v13
	v_pk_mul_f32 v[8:9], v[8:9], v[10:11]
	v_pk_add_f32 v[4:5], v[4:5], 1.0 op_sel_hi:[1,0]
	v_cvt_pk_bf16_f32 v0, v8, v9
	v_div_scale_f32 v10, s[6:7], v5, v5, v18
	v_rcp_f32_e32 v11, v10
	v_lshlrev_b32_e32 v8, 16, v1
	v_and_b32_e32 v9, 0xffff0000, v1
	v_fma_f32 v1, -v10, v11, 1.0
	v_fmac_f32_e32 v11, v1, v11
	v_div_scale_f32 v1, vcc, v18, v5, v18
	v_mul_f32_e32 v13, v1, v11
	v_fma_f32 v17, -v10, v13, v1
	v_fmac_f32_e32 v13, v17, v11
	v_fma_f32 v1, -v10, v13, v1
	v_div_scale_f32 v10, s[6:7], v4, v4, v16
	v_rcp_f32_e32 v17, v10
	v_div_fmas_f32 v1, v1, v11, v13
	v_div_fixup_f32 v5, v1, v5, v18
	v_fma_f32 v1, -v10, v17, 1.0
	v_fmac_f32_e32 v17, v1, v17
	v_div_scale_f32 v1, vcc, v16, v4, v16
	v_mul_f32_e32 v11, v1, v17
	v_fma_f32 v13, -v10, v11, v1
	v_fmac_f32_e32 v11, v13, v17
	v_fma_f32 v1, -v10, v11, v1
	v_div_fmas_f32 v1, v1, v17, v11
	v_div_fixup_f32 v4, v1, v4, v16
	v_or_b32_e32 v16, 8, v144
	v_pk_mul_f32 v[4:5], v[4:5], v[8:9]
	v_mad_u64_u32 v[8:9], s[6:7], v16, s72, v[70:71]
	global_load_dwordx4 v[8:11], v[8:9], off
	v_lshlrev_b32_e32 v13, 16, v6
	v_and_b32_e32 v6, 0xffff0000, v6
	v_mul_f32_e32 v1, 0xbfb8aa3b, v13
	v_exp_f32_e32 v18, v1
	v_mul_f32_e32 v1, 0xbfb8aa3b, v6
	v_exp_f32_e32 v19, v1
	v_cvt_pk_bf16_f32 v1, v4, v5
	v_lshlrev_b32_e32 v4, 16, v2
	v_and_b32_e32 v5, 0xffff0000, v2
	v_pk_add_f32 v[18:19], v[18:19], 1.0 op_sel_hi:[1,0]
	s_nop 0
	v_div_scale_f32 v17, s[6:7], v19, v19, v6
	v_rcp_f32_e32 v20, v17
	s_nop 0
	v_fma_f32 v2, -v17, v20, 1.0
	v_fmac_f32_e32 v20, v2, v20
	v_div_scale_f32 v2, vcc, v6, v19, v6
	v_mul_f32_e32 v21, v2, v20
	v_fma_f32 v22, -v17, v21, v2
	v_fmac_f32_e32 v21, v22, v20
	v_fma_f32 v2, -v17, v21, v2
	v_div_scale_f32 v17, s[6:7], v18, v18, v13
	v_rcp_f32_e32 v22, v17
	v_div_fmas_f32 v2, v2, v20, v21
	v_div_fixup_f32 v19, v2, v19, v6
	v_and_b32_e32 v21, 0xffff0000, v7
	v_fma_f32 v2, -v17, v22, 1.0
	v_fmac_f32_e32 v22, v2, v22
	v_div_scale_f32 v2, vcc, v13, v18, v13
	v_mul_f32_e32 v20, v2, v22
	v_fma_f32 v6, -v17, v20, v2
	v_fmac_f32_e32 v20, v6, v22
	v_fma_f32 v2, -v17, v20, v2
	v_lshlrev_b32_e32 v17, 16, v7
	v_mul_f32_e32 v6, 0xbfb8aa3b, v17
	v_mul_f32_e32 v7, 0xbfb8aa3b, v21
	v_exp_f32_e32 v6, v6
	v_exp_f32_e32 v7, v7
	v_div_fmas_f32 v2, v2, v22, v20
	v_div_fixup_f32 v18, v2, v18, v13
	v_pk_mul_f32 v[4:5], v[18:19], v[4:5]
	v_pk_add_f32 v[6:7], v[6:7], 1.0 op_sel_hi:[1,0]
	v_cvt_pk_bf16_f32 v2, v4, v5
	v_div_scale_f32 v13, s[6:7], v7, v7, v21
	v_rcp_f32_e32 v18, v13
	v_lshlrev_b32_e32 v4, 16, v3
	v_and_b32_e32 v5, 0xffff0000, v3
	v_fma_f32 v3, -v13, v18, 1.0
	v_fmac_f32_e32 v18, v3, v18
	v_div_scale_f32 v3, vcc, v21, v7, v21
	v_mul_f32_e32 v19, v3, v18
	v_fma_f32 v20, -v13, v19, v3
	v_fmac_f32_e32 v19, v20, v18
	v_fma_f32 v3, -v13, v19, v3
	v_div_scale_f32 v13, s[6:7], v6, v6, v17
	v_rcp_f32_e32 v20, v13
	v_div_fmas_f32 v3, v3, v18, v19
	v_div_fixup_f32 v7, v3, v7, v21
	v_fma_f32 v3, -v13, v20, 1.0
	v_fmac_f32_e32 v20, v3, v20
	v_div_scale_f32 v3, vcc, v17, v6, v17
	v_mul_f32_e32 v18, v3, v20
	v_fma_f32 v19, -v13, v18, v3
	v_fmac_f32_e32 v18, v19, v20
	v_fma_f32 v3, -v13, v18, v3
	v_div_fmas_f32 v3, v3, v20, v18
	v_div_fixup_f32 v6, v3, v6, v17
	v_pk_mul_f32 v[4:5], v[6:7], v[4:5]
	v_mov_b32_e32 v17, v145
	v_cvt_pk_bf16_f32 v3, v4, v5
	v_lshlrev_b64 v[4:5], 12, v[14:15]
	v_or_b32_e32 v14, 12, v144
	v_lshl_add_u64 v[18:19], v[68:69], 0, v[4:5]
	v_mad_u64_u32 v[4:5], s[6:7], v14, s72, v[70:71]
	global_load_dwordx4 v[4:7], v[4:5], off
	s_waitcnt vmcnt(1)
	v_lshlrev_b32_e32 v13, 16, v8
	v_and_b32_e32 v8, 0xffff0000, v8
	v_mul_f32_e32 v15, 0xbfb8aa3b, v13
	v_exp_f32_e32 v22, v15
	v_mul_f32_e32 v15, 0xbfb8aa3b, v8
	v_exp_f32_e32 v23, v15
	global_store_dwordx4 v[18:19], v[0:3], off offset:3072 sc1
	ds_read_b128 v[18:21], v12 offset:2176
	ds_read_b128 v[0:3], v12 offset:3264
	v_pk_add_f32 v[22:23], v[22:23], 1.0 op_sel_hi:[1,0]
	v_lshlrev_b32_e32 v29, 16, v9
	v_div_scale_f32 v15, s[6:7], v23, v23, v8
	v_rcp_f32_e32 v26, v15
	s_waitcnt lgkmcnt(1)
	v_lshlrev_b32_e32 v24, 16, v18
	v_and_b32_e32 v25, 0xffff0000, v18
	v_lshlrev_b64 v[16:17], 12, v[16:17]
	v_fma_f32 v18, -v15, v26, 1.0
	v_fmac_f32_e32 v26, v18, v26
	v_div_scale_f32 v18, vcc, v8, v23, v8
	v_mul_f32_e32 v27, v18, v26
	v_fma_f32 v28, -v15, v27, v18
	v_fmac_f32_e32 v27, v28, v26
	v_fma_f32 v15, -v15, v27, v18
	v_div_scale_f32 v18, s[6:7], v22, v22, v13
	v_rcp_f32_e32 v28, v18
	v_div_fmas_f32 v15, v15, v26, v27
	v_div_fixup_f32 v23, v15, v23, v8
	v_lshl_add_u64 v[16:17], v[68:69], 0, v[16:17]
	v_fma_f32 v8, -v18, v28, 1.0
	v_fmac_f32_e32 v28, v8, v28
	v_div_scale_f32 v8, vcc, v13, v22, v13
	v_mul_f32_e32 v15, v8, v28
	v_fma_f32 v26, -v18, v15, v8
	v_fmac_f32_e32 v15, v26, v28
	v_and_b32_e32 v26, 0xffff0000, v9
	v_fma_f32 v18, -v18, v15, v8
	v_mul_f32_e32 v8, 0xbfb8aa3b, v29
	v_mul_f32_e32 v9, 0xbfb8aa3b, v26
	v_exp_f32_e32 v8, v8
	v_exp_f32_e32 v9, v9
	v_div_fmas_f32 v15, v18, v28, v15
	v_div_fixup_f32 v22, v15, v22, v13
	v_pk_mul_f32 v[22:23], v[22:23], v[24:25]
	v_pk_add_f32 v[24:25], v[8:9], 1.0 op_sel_hi:[1,0]
	v_cvt_pk_bf16_f32 v8, v22, v23
	v_div_scale_f32 v9, s[6:7], v25, v25, v26
	v_rcp_f32_e32 v13, v9
	v_lshlrev_b32_e32 v18, 16, v19
	v_and_b32_e32 v19, 0xffff0000, v19
	v_fma_f32 v15, -v9, v13, 1.0
	v_fmac_f32_e32 v13, v15, v13
	v_div_scale_f32 v15, vcc, v26, v25, v26
	v_mul_f32_e32 v22, v15, v13
	v_fma_f32 v23, -v9, v22, v15
	v_fmac_f32_e32 v22, v23, v13
	v_fma_f32 v9, -v9, v22, v15
	v_div_scale_f32 v15, s[6:7], v24, v24, v29
	v_rcp_f32_e32 v28, v15
	v_div_fmas_f32 v9, v9, v13, v22
	v_div_fixup_f32 v23, v9, v25, v26
	v_fma_f32 v9, -v15, v28, 1.0
	v_fmac_f32_e32 v28, v9, v28
	v_div_scale_f32 v9, vcc, v29, v24, v29
	v_mul_f32_e32 v13, v9, v28
	v_fma_f32 v22, -v15, v13, v9
	v_fmac_f32_e32 v13, v22, v28
	v_fma_f32 v9, -v15, v13, v9
	v_lshlrev_b32_e32 v15, 16, v10
	v_and_b32_e32 v10, 0xffff0000, v10
	v_mul_f32_e32 v22, 0xbfb8aa3b, v15
	v_exp_f32_e32 v26, v22
	v_mul_f32_e32 v22, 0xbfb8aa3b, v10
	v_exp_f32_e32 v27, v22
	v_div_fmas_f32 v9, v9, v28, v13
	v_div_fixup_f32 v22, v9, v24, v29
	v_pk_mul_f32 v[18:19], v[22:23], v[18:19]
	v_pk_add_f32 v[22:23], v[26:27], 1.0 op_sel_hi:[1,0]
	v_cvt_pk_bf16_f32 v9, v18, v19
	v_div_scale_f32 v13, s[6:7], v23, v23, v10
	v_rcp_f32_e32 v24, v13
	v_lshlrev_b32_e32 v18, 16, v20
	v_and_b32_e32 v19, 0xffff0000, v20
	v_fma_f32 v20, -v13, v24, 1.0
	v_fmac_f32_e32 v24, v20, v24
	v_div_scale_f32 v20, vcc, v10, v23, v10
	v_mul_f32_e32 v25, v20, v24
	v_fma_f32 v26, -v13, v25, v20
	v_fmac_f32_e32 v25, v26, v24
	v_fma_f32 v13, -v13, v25, v20
	v_div_scale_f32 v20, s[6:7], v22, v22, v15
	v_rcp_f32_e32 v26, v20
	v_div_fmas_f32 v13, v13, v24, v25
	v_div_fixup_f32 v23, v13, v23, v10
	v_and_b32_e32 v25, 0xffff0000, v11
	v_fma_f32 v10, -v20, v26, 1.0
	v_fmac_f32_e32 v26, v10, v26
	v_div_scale_f32 v10, vcc, v15, v22, v15
	v_mul_f32_e32 v13, v10, v26
	v_fma_f32 v24, -v20, v13, v10
	v_fmac_f32_e32 v13, v24, v26
	v_lshlrev_b32_e32 v24, 16, v11
	v_fma_f32 v20, -v20, v13, v10
	v_mul_f32_e32 v10, 0xbfb8aa3b, v24
	v_mul_f32_e32 v11, 0xbfb8aa3b, v25
	v_exp_f32_e32 v10, v10
	v_exp_f32_e32 v11, v11
	v_div_fmas_f32 v13, v20, v26, v13
	v_div_fixup_f32 v22, v13, v22, v15
	v_pk_mul_f32 v[18:19], v[22:23], v[18:19]
	v_pk_add_f32 v[22:23], v[10:11], 1.0 op_sel_hi:[1,0]
	v_cvt_pk_bf16_f32 v10, v18, v19
	v_div_scale_f32 v11, s[6:7], v23, v23, v25
	v_rcp_f32_e32 v13, v11
	v_lshlrev_b32_e32 v18, 16, v21
	v_and_b32_e32 v19, 0xffff0000, v21
	v_fma_f32 v15, -v11, v13, 1.0
	v_fmac_f32_e32 v13, v15, v13
	v_div_scale_f32 v15, vcc, v25, v23, v25
	v_mul_f32_e32 v20, v15, v13
	v_fma_f32 v21, -v11, v20, v15
	v_fmac_f32_e32 v20, v21, v13
	v_fma_f32 v11, -v11, v20, v15
	v_div_scale_f32 v15, s[6:7], v22, v22, v24
	v_rcp_f32_e32 v26, v15
	v_div_fmas_f32 v11, v11, v13, v20
	v_div_fixup_f32 v21, v11, v23, v25
	v_fma_f32 v11, -v15, v26, 1.0
	v_fmac_f32_e32 v26, v11, v26
	v_div_scale_f32 v11, vcc, v24, v22, v24
	v_mul_f32_e32 v13, v11, v26
	v_fma_f32 v20, -v15, v13, v11
	v_fmac_f32_e32 v13, v20, v26
	v_fma_f32 v11, -v15, v13, v11
	v_div_fmas_f32 v11, v11, v26, v13
	v_div_fixup_f32 v20, v11, v22, v24
	s_waitcnt vmcnt(1)
	v_lshlrev_b32_e32 v13, 16, v4
	v_pk_mul_f32 v[18:19], v[20:21], v[18:19]
	v_and_b32_e32 v4, 0xffff0000, v4
	v_mul_f32_e32 v15, 0xbfb8aa3b, v13
	v_cvt_pk_bf16_f32 v11, v18, v19
	v_exp_f32_e32 v18, v15
	v_mul_f32_e32 v15, 0xbfb8aa3b, v4
	v_exp_f32_e32 v19, v15
	global_store_dwordx4 v[16:17], v[8:11], off offset:3072 sc1
	v_mov_b32_e32 v15, v145
	s_nop 0
	v_pk_add_f32 v[8:9], v[18:19], 1.0 op_sel_hi:[1,0]
	s_waitcnt lgkmcnt(0)
	v_lshlrev_b32_e32 v10, 16, v0
	v_div_scale_f32 v16, s[6:7], v9, v9, v4
	v_rcp_f32_e32 v17, v16
	v_and_b32_e32 v11, 0xffff0000, v0
	v_fma_f32 v0, -v16, v17, 1.0
	v_fmac_f32_e32 v17, v0, v17
	v_div_scale_f32 v0, vcc, v4, v9, v4
	v_mul_f32_e32 v18, v0, v17
	v_fma_f32 v19, -v16, v18, v0
	v_fmac_f32_e32 v18, v19, v17
	v_fma_f32 v0, -v16, v18, v0
	v_div_scale_f32 v16, s[6:7], v8, v8, v13
	v_rcp_f32_e32 v19, v16
	v_div_fmas_f32 v0, v0, v17, v18
	v_div_fixup_f32 v9, v0, v9, v4
	v_and_b32_e32 v18, 0xffff0000, v5
	v_fma_f32 v0, -v16, v19, 1.0
	v_fmac_f32_e32 v19, v0, v19
	v_div_scale_f32 v0, vcc, v13, v8, v13
	v_mul_f32_e32 v17, v0, v19
	v_fma_f32 v4, -v16, v17, v0
	v_fmac_f32_e32 v17, v4, v19
	v_fma_f32 v0, -v16, v17, v0
	v_lshlrev_b32_e32 v16, 16, v5
	v_mul_f32_e32 v4, 0xbfb8aa3b, v16
	v_mul_f32_e32 v5, 0xbfb8aa3b, v18
	v_exp_f32_e32 v4, v4
	v_exp_f32_e32 v5, v5
	v_div_fmas_f32 v0, v0, v19, v17
	v_div_fixup_f32 v8, v0, v8, v13
	v_pk_mul_f32 v[8:9], v[8:9], v[10:11]
	v_pk_add_f32 v[4:5], v[4:5], 1.0 op_sel_hi:[1,0]
	v_cvt_pk_bf16_f32 v0, v8, v9
	v_div_scale_f32 v10, s[6:7], v5, v5, v18
	v_rcp_f32_e32 v11, v10
	v_lshlrev_b32_e32 v8, 16, v1
	v_and_b32_e32 v9, 0xffff0000, v1
	v_fma_f32 v1, -v10, v11, 1.0
	v_fmac_f32_e32 v11, v1, v11
	v_div_scale_f32 v1, vcc, v18, v5, v18
	v_mul_f32_e32 v13, v1, v11
	v_fma_f32 v17, -v10, v13, v1
	v_fmac_f32_e32 v13, v17, v11
	v_fma_f32 v1, -v10, v13, v1
	v_div_scale_f32 v10, s[6:7], v4, v4, v16
	v_rcp_f32_e32 v17, v10
	v_div_fmas_f32 v1, v1, v11, v13
	v_div_fixup_f32 v5, v1, v5, v18
	v_fma_f32 v1, -v10, v17, 1.0
	v_fmac_f32_e32 v17, v1, v17
	v_div_scale_f32 v1, vcc, v16, v4, v16
	v_mul_f32_e32 v11, v1, v17
	v_fma_f32 v13, -v10, v11, v1
	v_fmac_f32_e32 v11, v13, v17
	v_fma_f32 v1, -v10, v11, v1
	v_div_fmas_f32 v1, v1, v17, v11
	v_div_fixup_f32 v4, v1, v4, v16
	v_or_b32_e32 v16, 16, v144
	v_pk_mul_f32 v[4:5], v[4:5], v[8:9]
	v_mad_u64_u32 v[8:9], s[6:7], v16, s72, v[70:71]
	global_load_dwordx4 v[8:11], v[8:9], off
	v_lshlrev_b32_e32 v13, 16, v6
	v_and_b32_e32 v6, 0xffff0000, v6
	v_mul_f32_e32 v1, 0xbfb8aa3b, v13
	v_exp_f32_e32 v18, v1
	v_mul_f32_e32 v1, 0xbfb8aa3b, v6
	v_exp_f32_e32 v19, v1
	v_cvt_pk_bf16_f32 v1, v4, v5
	v_lshlrev_b32_e32 v4, 16, v2
	v_and_b32_e32 v5, 0xffff0000, v2
	v_pk_add_f32 v[18:19], v[18:19], 1.0 op_sel_hi:[1,0]
	s_nop 0
	v_div_scale_f32 v17, s[6:7], v19, v19, v6
	v_rcp_f32_e32 v20, v17
	s_nop 0
	v_fma_f32 v2, -v17, v20, 1.0
	v_fmac_f32_e32 v20, v2, v20
	v_div_scale_f32 v2, vcc, v6, v19, v6
	v_mul_f32_e32 v21, v2, v20
	v_fma_f32 v22, -v17, v21, v2
	v_fmac_f32_e32 v21, v22, v20
	v_fma_f32 v2, -v17, v21, v2
	v_div_scale_f32 v17, s[6:7], v18, v18, v13
	v_rcp_f32_e32 v22, v17
	v_div_fmas_f32 v2, v2, v20, v21
	v_div_fixup_f32 v19, v2, v19, v6
	v_and_b32_e32 v21, 0xffff0000, v7
	v_fma_f32 v2, -v17, v22, 1.0
	v_fmac_f32_e32 v22, v2, v22
	v_div_scale_f32 v2, vcc, v13, v18, v13
	v_mul_f32_e32 v20, v2, v22
	v_fma_f32 v6, -v17, v20, v2
	v_fmac_f32_e32 v20, v6, v22
	v_fma_f32 v2, -v17, v20, v2
	v_lshlrev_b32_e32 v17, 16, v7
	v_mul_f32_e32 v6, 0xbfb8aa3b, v17
	v_mul_f32_e32 v7, 0xbfb8aa3b, v21
	v_exp_f32_e32 v6, v6
	v_exp_f32_e32 v7, v7
	v_div_fmas_f32 v2, v2, v22, v20
	v_div_fixup_f32 v18, v2, v18, v13
	v_pk_mul_f32 v[4:5], v[18:19], v[4:5]
	v_pk_add_f32 v[6:7], v[6:7], 1.0 op_sel_hi:[1,0]
	v_cvt_pk_bf16_f32 v2, v4, v5
	v_div_scale_f32 v13, s[6:7], v7, v7, v21
	v_rcp_f32_e32 v18, v13
	v_lshlrev_b32_e32 v4, 16, v3
	v_and_b32_e32 v5, 0xffff0000, v3
	v_fma_f32 v3, -v13, v18, 1.0
	v_fmac_f32_e32 v18, v3, v18
	v_div_scale_f32 v3, vcc, v21, v7, v21
	v_mul_f32_e32 v19, v3, v18
	v_fma_f32 v20, -v13, v19, v3
	v_fmac_f32_e32 v19, v20, v18
	v_fma_f32 v3, -v13, v19, v3
	v_div_scale_f32 v13, s[6:7], v6, v6, v17
	v_rcp_f32_e32 v20, v13
	v_div_fmas_f32 v3, v3, v18, v19
	v_div_fixup_f32 v7, v3, v7, v21
	v_fma_f32 v3, -v13, v20, 1.0
	v_fmac_f32_e32 v20, v3, v20
	v_div_scale_f32 v3, vcc, v17, v6, v17
	v_mul_f32_e32 v18, v3, v20
	v_fma_f32 v19, -v13, v18, v3
	v_fmac_f32_e32 v18, v19, v20
	v_fma_f32 v3, -v13, v18, v3
	v_div_fmas_f32 v3, v3, v20, v18
	v_div_fixup_f32 v6, v3, v6, v17
	v_pk_mul_f32 v[4:5], v[6:7], v[4:5]
	v_mov_b32_e32 v17, v145
	v_cvt_pk_bf16_f32 v3, v4, v5
	v_lshlrev_b64 v[4:5], 12, v[14:15]
	v_or_b32_e32 v14, 20, v144
	v_lshl_add_u64 v[18:19], v[68:69], 0, v[4:5]
	v_mad_u64_u32 v[4:5], s[6:7], v14, s72, v[70:71]
	global_load_dwordx4 v[4:7], v[4:5], off
	s_waitcnt vmcnt(1)
	v_lshlrev_b32_e32 v13, 16, v8
	v_and_b32_e32 v8, 0xffff0000, v8
	v_mul_f32_e32 v15, 0xbfb8aa3b, v13
	v_exp_f32_e32 v22, v15
	v_mul_f32_e32 v15, 0xbfb8aa3b, v8
	v_exp_f32_e32 v23, v15
	global_store_dwordx4 v[18:19], v[0:3], off offset:3072 sc1
	ds_read_b128 v[18:21], v12 offset:4352
	ds_read_b128 v[0:3], v12 offset:5440
	v_pk_add_f32 v[22:23], v[22:23], 1.0 op_sel_hi:[1,0]
	v_lshlrev_b32_e32 v29, 16, v9
	v_div_scale_f32 v15, s[6:7], v23, v23, v8
	v_rcp_f32_e32 v26, v15
	s_waitcnt lgkmcnt(1)
	v_lshlrev_b32_e32 v24, 16, v18
	v_and_b32_e32 v25, 0xffff0000, v18
	v_lshlrev_b64 v[16:17], 12, v[16:17]
	v_fma_f32 v18, -v15, v26, 1.0
	v_fmac_f32_e32 v26, v18, v26
	v_div_scale_f32 v18, vcc, v8, v23, v8
	v_mul_f32_e32 v27, v18, v26
	v_fma_f32 v28, -v15, v27, v18
	v_fmac_f32_e32 v27, v28, v26
	v_fma_f32 v15, -v15, v27, v18
	v_div_scale_f32 v18, s[6:7], v22, v22, v13
	v_rcp_f32_e32 v28, v18
	v_div_fmas_f32 v15, v15, v26, v27
	v_div_fixup_f32 v23, v15, v23, v8
	v_lshl_add_u64 v[16:17], v[68:69], 0, v[16:17]
	v_fma_f32 v8, -v18, v28, 1.0
	v_fmac_f32_e32 v28, v8, v28
	v_div_scale_f32 v8, vcc, v13, v22, v13
	v_mul_f32_e32 v15, v8, v28
	v_fma_f32 v26, -v18, v15, v8
	v_fmac_f32_e32 v15, v26, v28
	v_and_b32_e32 v26, 0xffff0000, v9
	v_fma_f32 v18, -v18, v15, v8
	v_mul_f32_e32 v8, 0xbfb8aa3b, v29
	v_mul_f32_e32 v9, 0xbfb8aa3b, v26
	v_exp_f32_e32 v8, v8
	v_exp_f32_e32 v9, v9
	v_div_fmas_f32 v15, v18, v28, v15
	v_div_fixup_f32 v22, v15, v22, v13
	v_pk_mul_f32 v[22:23], v[22:23], v[24:25]
	v_pk_add_f32 v[24:25], v[8:9], 1.0 op_sel_hi:[1,0]
	v_cvt_pk_bf16_f32 v8, v22, v23
	v_div_scale_f32 v9, s[6:7], v25, v25, v26
	v_rcp_f32_e32 v13, v9
	v_lshlrev_b32_e32 v18, 16, v19
	v_and_b32_e32 v19, 0xffff0000, v19
	v_fma_f32 v15, -v9, v13, 1.0
	v_fmac_f32_e32 v13, v15, v13
	v_div_scale_f32 v15, vcc, v26, v25, v26
	v_mul_f32_e32 v22, v15, v13
	v_fma_f32 v23, -v9, v22, v15
	v_fmac_f32_e32 v22, v23, v13
	v_fma_f32 v9, -v9, v22, v15
	v_div_scale_f32 v15, s[6:7], v24, v24, v29
	v_rcp_f32_e32 v28, v15
	v_div_fmas_f32 v9, v9, v13, v22
	v_div_fixup_f32 v23, v9, v25, v26
	v_fma_f32 v9, -v15, v28, 1.0
	v_fmac_f32_e32 v28, v9, v28
	v_div_scale_f32 v9, vcc, v29, v24, v29
	v_mul_f32_e32 v13, v9, v28
	v_fma_f32 v22, -v15, v13, v9
	v_fmac_f32_e32 v13, v22, v28
	v_fma_f32 v9, -v15, v13, v9
	v_lshlrev_b32_e32 v15, 16, v10
	v_and_b32_e32 v10, 0xffff0000, v10
	v_mul_f32_e32 v22, 0xbfb8aa3b, v15
	v_exp_f32_e32 v26, v22
	v_mul_f32_e32 v22, 0xbfb8aa3b, v10
	v_exp_f32_e32 v27, v22
	v_div_fmas_f32 v9, v9, v28, v13
	v_div_fixup_f32 v22, v9, v24, v29
	v_pk_mul_f32 v[18:19], v[22:23], v[18:19]
	v_pk_add_f32 v[22:23], v[26:27], 1.0 op_sel_hi:[1,0]
	v_cvt_pk_bf16_f32 v9, v18, v19
	v_div_scale_f32 v13, s[6:7], v23, v23, v10
	v_rcp_f32_e32 v24, v13
	v_lshlrev_b32_e32 v18, 16, v20
	v_and_b32_e32 v19, 0xffff0000, v20
	v_fma_f32 v20, -v13, v24, 1.0
	v_fmac_f32_e32 v24, v20, v24
	v_div_scale_f32 v20, vcc, v10, v23, v10
	v_mul_f32_e32 v25, v20, v24
	v_fma_f32 v26, -v13, v25, v20
	v_fmac_f32_e32 v25, v26, v24
	v_fma_f32 v13, -v13, v25, v20
	v_div_scale_f32 v20, s[6:7], v22, v22, v15
	v_rcp_f32_e32 v26, v20
	v_div_fmas_f32 v13, v13, v24, v25
	v_div_fixup_f32 v23, v13, v23, v10
	v_and_b32_e32 v25, 0xffff0000, v11
	v_fma_f32 v10, -v20, v26, 1.0
	v_fmac_f32_e32 v26, v10, v26
	v_div_scale_f32 v10, vcc, v15, v22, v15
	v_mul_f32_e32 v13, v10, v26
	v_fma_f32 v24, -v20, v13, v10
	v_fmac_f32_e32 v13, v24, v26
	v_lshlrev_b32_e32 v24, 16, v11
	v_fma_f32 v20, -v20, v13, v10
	v_mul_f32_e32 v10, 0xbfb8aa3b, v24
	v_mul_f32_e32 v11, 0xbfb8aa3b, v25
	v_exp_f32_e32 v10, v10
	v_exp_f32_e32 v11, v11
	v_div_fmas_f32 v13, v20, v26, v13
	v_div_fixup_f32 v22, v13, v22, v15
	v_pk_mul_f32 v[18:19], v[22:23], v[18:19]
	v_pk_add_f32 v[22:23], v[10:11], 1.0 op_sel_hi:[1,0]
	v_cvt_pk_bf16_f32 v10, v18, v19
	v_div_scale_f32 v11, s[6:7], v23, v23, v25
	v_rcp_f32_e32 v13, v11
	v_lshlrev_b32_e32 v18, 16, v21
	v_and_b32_e32 v19, 0xffff0000, v21
	v_fma_f32 v15, -v11, v13, 1.0
	v_fmac_f32_e32 v13, v15, v13
	v_div_scale_f32 v15, vcc, v25, v23, v25
	v_mul_f32_e32 v20, v15, v13
	v_fma_f32 v21, -v11, v20, v15
	v_fmac_f32_e32 v20, v21, v13
	v_fma_f32 v11, -v11, v20, v15
	v_div_scale_f32 v15, s[6:7], v22, v22, v24
	v_rcp_f32_e32 v26, v15
	v_div_fmas_f32 v11, v11, v13, v20
	v_div_fixup_f32 v21, v11, v23, v25
	v_fma_f32 v11, -v15, v26, 1.0
	v_fmac_f32_e32 v26, v11, v26
	v_div_scale_f32 v11, vcc, v24, v22, v24
	v_mul_f32_e32 v13, v11, v26
	v_fma_f32 v20, -v15, v13, v11
	v_fmac_f32_e32 v13, v20, v26
	v_fma_f32 v11, -v15, v13, v11
	v_div_fmas_f32 v11, v11, v26, v13
	v_div_fixup_f32 v20, v11, v22, v24
	s_waitcnt vmcnt(1)
	v_lshlrev_b32_e32 v13, 16, v4
	v_pk_mul_f32 v[18:19], v[20:21], v[18:19]
	v_and_b32_e32 v4, 0xffff0000, v4
	v_mul_f32_e32 v15, 0xbfb8aa3b, v13
	v_cvt_pk_bf16_f32 v11, v18, v19
	v_exp_f32_e32 v18, v15
	v_mul_f32_e32 v15, 0xbfb8aa3b, v4
	v_exp_f32_e32 v19, v15
	global_store_dwordx4 v[16:17], v[8:11], off offset:3072 sc1
	v_mov_b32_e32 v15, v145
	s_nop 0
	v_pk_add_f32 v[8:9], v[18:19], 1.0 op_sel_hi:[1,0]
	s_waitcnt lgkmcnt(0)
	v_lshlrev_b32_e32 v10, 16, v0
	v_div_scale_f32 v16, s[6:7], v9, v9, v4
	v_rcp_f32_e32 v17, v16
	v_and_b32_e32 v11, 0xffff0000, v0
	v_fma_f32 v0, -v16, v17, 1.0
	v_fmac_f32_e32 v17, v0, v17
	v_div_scale_f32 v0, vcc, v4, v9, v4
	v_mul_f32_e32 v18, v0, v17
	v_fma_f32 v19, -v16, v18, v0
	v_fmac_f32_e32 v18, v19, v17
	v_fma_f32 v0, -v16, v18, v0
	v_div_scale_f32 v16, s[6:7], v8, v8, v13
	v_rcp_f32_e32 v19, v16
	v_div_fmas_f32 v0, v0, v17, v18
	v_div_fixup_f32 v9, v0, v9, v4
	v_and_b32_e32 v18, 0xffff0000, v5
	v_fma_f32 v0, -v16, v19, 1.0
	v_fmac_f32_e32 v19, v0, v19
	v_div_scale_f32 v0, vcc, v13, v8, v13
	v_mul_f32_e32 v17, v0, v19
	v_fma_f32 v4, -v16, v17, v0
	v_fmac_f32_e32 v17, v4, v19
	v_fma_f32 v0, -v16, v17, v0
	v_lshlrev_b32_e32 v16, 16, v5
	v_mul_f32_e32 v4, 0xbfb8aa3b, v16
	v_mul_f32_e32 v5, 0xbfb8aa3b, v18
	v_exp_f32_e32 v4, v4
	v_exp_f32_e32 v5, v5
	v_div_fmas_f32 v0, v0, v19, v17
	v_div_fixup_f32 v8, v0, v8, v13
	v_pk_mul_f32 v[8:9], v[8:9], v[10:11]
	v_pk_add_f32 v[4:5], v[4:5], 1.0 op_sel_hi:[1,0]
	v_cvt_pk_bf16_f32 v0, v8, v9
	v_div_scale_f32 v10, s[6:7], v5, v5, v18
	v_rcp_f32_e32 v11, v10
	v_lshlrev_b32_e32 v8, 16, v1
	v_and_b32_e32 v9, 0xffff0000, v1
	v_fma_f32 v1, -v10, v11, 1.0
	v_fmac_f32_e32 v11, v1, v11
	v_div_scale_f32 v1, vcc, v18, v5, v18
	v_mul_f32_e32 v13, v1, v11
	v_fma_f32 v17, -v10, v13, v1
	v_fmac_f32_e32 v13, v17, v11
	v_fma_f32 v1, -v10, v13, v1
	v_div_scale_f32 v10, s[6:7], v4, v4, v16
	v_rcp_f32_e32 v17, v10
	v_div_fmas_f32 v1, v1, v11, v13
	v_div_fixup_f32 v5, v1, v5, v18
	v_fma_f32 v1, -v10, v17, 1.0
	v_fmac_f32_e32 v17, v1, v17
	v_div_scale_f32 v1, vcc, v16, v4, v16
	v_mul_f32_e32 v11, v1, v17
	v_fma_f32 v13, -v10, v11, v1
	v_fmac_f32_e32 v11, v13, v17
	v_fma_f32 v1, -v10, v11, v1
	v_div_fmas_f32 v1, v1, v17, v11
	v_div_fixup_f32 v4, v1, v4, v16
	v_or_b32_e32 v16, 24, v144
	v_pk_mul_f32 v[4:5], v[4:5], v[8:9]
	v_mad_u64_u32 v[8:9], s[6:7], v16, s72, v[70:71]
	global_load_dwordx4 v[8:11], v[8:9], off
	v_lshlrev_b32_e32 v13, 16, v6
	v_and_b32_e32 v6, 0xffff0000, v6
	v_mul_f32_e32 v1, 0xbfb8aa3b, v13
	v_exp_f32_e32 v18, v1
	v_mul_f32_e32 v1, 0xbfb8aa3b, v6
	v_exp_f32_e32 v19, v1
	v_cvt_pk_bf16_f32 v1, v4, v5
	v_lshlrev_b32_e32 v4, 16, v2
	v_and_b32_e32 v5, 0xffff0000, v2
	v_pk_add_f32 v[18:19], v[18:19], 1.0 op_sel_hi:[1,0]
	v_or_b32_e32 v144, 28, v144
	v_div_scale_f32 v17, s[6:7], v19, v19, v6
	v_rcp_f32_e32 v20, v17
	s_nop 0
	v_fma_f32 v2, -v17, v20, 1.0
	v_fmac_f32_e32 v20, v2, v20
	v_div_scale_f32 v2, vcc, v6, v19, v6
	v_mul_f32_e32 v21, v2, v20
	v_fma_f32 v22, -v17, v21, v2
	v_fmac_f32_e32 v21, v22, v20
	v_fma_f32 v2, -v17, v21, v2
	v_div_scale_f32 v17, s[6:7], v18, v18, v13
	v_rcp_f32_e32 v22, v17
	v_div_fmas_f32 v2, v2, v20, v21
	v_div_fixup_f32 v19, v2, v19, v6
	v_and_b32_e32 v21, 0xffff0000, v7
	v_fma_f32 v2, -v17, v22, 1.0
	v_fmac_f32_e32 v22, v2, v22
	v_div_scale_f32 v2, vcc, v13, v18, v13
	v_mul_f32_e32 v20, v2, v22
	v_fma_f32 v6, -v17, v20, v2
	v_fmac_f32_e32 v20, v6, v22
	v_fma_f32 v2, -v17, v20, v2
	v_lshlrev_b32_e32 v17, 16, v7
	v_mul_f32_e32 v6, 0xbfb8aa3b, v17
	v_mul_f32_e32 v7, 0xbfb8aa3b, v21
	v_exp_f32_e32 v6, v6
	v_exp_f32_e32 v7, v7
	v_div_fmas_f32 v2, v2, v22, v20
	v_div_fixup_f32 v18, v2, v18, v13
	v_pk_mul_f32 v[4:5], v[18:19], v[4:5]
	v_pk_add_f32 v[6:7], v[6:7], 1.0 op_sel_hi:[1,0]
	v_cvt_pk_bf16_f32 v2, v4, v5
	v_div_scale_f32 v13, s[6:7], v7, v7, v21
	v_rcp_f32_e32 v18, v13
	v_lshlrev_b32_e32 v4, 16, v3
	v_and_b32_e32 v5, 0xffff0000, v3
	v_fma_f32 v3, -v13, v18, 1.0
	v_fmac_f32_e32 v18, v3, v18
	v_div_scale_f32 v3, vcc, v21, v7, v21
	v_mul_f32_e32 v19, v3, v18
	v_fma_f32 v20, -v13, v19, v3
	v_fmac_f32_e32 v19, v20, v18
	v_fma_f32 v3, -v13, v19, v3
	v_div_scale_f32 v13, s[6:7], v6, v6, v17
	v_rcp_f32_e32 v20, v13
	v_div_fmas_f32 v3, v3, v18, v19
	v_div_fixup_f32 v7, v3, v7, v21
	v_fma_f32 v3, -v13, v20, 1.0
	v_fmac_f32_e32 v20, v3, v20
	v_div_scale_f32 v3, vcc, v17, v6, v17
	v_mul_f32_e32 v18, v3, v20
	v_fma_f32 v19, -v13, v18, v3
	v_fmac_f32_e32 v18, v19, v20
	v_fma_f32 v3, -v13, v18, v3
	v_div_fmas_f32 v3, v3, v20, v18
	v_div_fixup_f32 v6, v3, v6, v17
	v_pk_mul_f32 v[4:5], v[6:7], v[4:5]
	ds_read_b128 v[18:21], v12 offset:6528
	v_cvt_pk_bf16_f32 v3, v4, v5
	v_lshlrev_b64 v[4:5], 12, v[14:15]
	v_lshl_add_u64 v[14:15], v[68:69], 0, v[4:5]
	v_mad_u64_u32 v[4:5], s[6:7], v144, s72, v[70:71]
	global_load_dwordx4 v[4:7], v[4:5], off
	s_waitcnt vmcnt(1)
	v_lshlrev_b32_e32 v24, 16, v8
	v_and_b32_e32 v8, 0xffff0000, v8
	v_mul_f32_e32 v13, 0xbfb8aa3b, v24
	v_exp_f32_e32 v22, v13
	v_mul_f32_e32 v13, 0xbfb8aa3b, v8
	v_exp_f32_e32 v23, v13
	global_store_dwordx4 v[14:15], v[0:3], off offset:3072 sc1
	ds_read_b128 v[0:3], v12 offset:7616
	s_waitcnt lgkmcnt(1)
	v_lshlrev_b32_e32 v12, 16, v18
	v_pk_add_f32 v[14:15], v[22:23], 1.0 op_sel_hi:[1,0]
	v_and_b32_e32 v13, 0xffff0000, v18
	v_div_scale_f32 v22, s[6:7], v15, v15, v8
	v_rcp_f32_e32 v23, v22
	v_mov_b32_e32 v17, v145
	v_fma_f32 v18, -v22, v23, 1.0
	v_fmac_f32_e32 v23, v18, v23
	v_div_scale_f32 v18, vcc, v8, v15, v8
	v_mul_f32_e32 v25, v18, v23
	v_fma_f32 v26, -v22, v25, v18
	v_fmac_f32_e32 v25, v26, v23
	v_fma_f32 v18, -v22, v25, v18
	v_div_scale_f32 v22, s[6:7], v14, v14, v24
	v_rcp_f32_e32 v26, v22
	v_div_fmas_f32 v18, v18, v23, v25
	v_div_fixup_f32 v15, v18, v15, v8
	v_and_b32_e32 v25, 0xffff0000, v9
	v_fma_f32 v8, -v22, v26, 1.0
	v_fmac_f32_e32 v26, v8, v26
	v_div_scale_f32 v8, vcc, v24, v14, v24
	v_mul_f32_e32 v18, v8, v26
	v_fma_f32 v23, -v22, v18, v8
	v_fmac_f32_e32 v18, v23, v26
	v_lshlrev_b32_e32 v23, 16, v9
	v_fma_f32 v22, -v22, v18, v8
	v_mul_f32_e32 v8, 0xbfb8aa3b, v23
	v_mul_f32_e32 v9, 0xbfb8aa3b, v25
	v_exp_f32_e32 v8, v8
	v_exp_f32_e32 v9, v9
	v_div_fmas_f32 v18, v22, v26, v18
	v_div_fixup_f32 v14, v18, v14, v24
	v_pk_mul_f32 v[12:13], v[14:15], v[12:13]
	v_pk_add_f32 v[14:15], v[8:9], 1.0 op_sel_hi:[1,0]
	v_cvt_pk_bf16_f32 v8, v12, v13
	v_div_scale_f32 v9, s[6:7], v15, v15, v25
	v_rcp_f32_e32 v18, v9
	v_lshlrev_b32_e32 v12, 16, v19
	v_and_b32_e32 v13, 0xffff0000, v19
	v_fma_f32 v19, -v9, v18, 1.0
	v_fmac_f32_e32 v18, v19, v18
	v_div_scale_f32 v19, vcc, v25, v15, v25
	v_mul_f32_e32 v22, v19, v18
	v_fma_f32 v24, -v9, v22, v19
	v_fmac_f32_e32 v22, v24, v18
	v_fma_f32 v9, -v9, v22, v19
	v_div_scale_f32 v19, s[6:7], v14, v14, v23
	v_rcp_f32_e32 v24, v19
	v_div_fmas_f32 v9, v9, v18, v22
	v_div_fixup_f32 v15, v9, v15, v25
	v_lshlrev_b32_e32 v25, 16, v10
	v_fma_f32 v9, -v19, v24, 1.0
	v_fmac_f32_e32 v24, v9, v24
	v_div_scale_f32 v9, vcc, v23, v14, v23
	v_mul_f32_e32 v22, v9, v24
	v_fma_f32 v18, -v19, v22, v9
	v_fmac_f32_e32 v22, v18, v24
	v_and_b32_e32 v10, 0xffff0000, v10
	v_fma_f32 v9, -v19, v22, v9
	v_mul_f32_e32 v18, 0xbfb8aa3b, v25
	v_mul_f32_e32 v19, 0xbfb8aa3b, v10
	v_exp_f32_e32 v18, v18
	v_exp_f32_e32 v19, v19
	v_div_fmas_f32 v9, v9, v24, v22
	v_div_fixup_f32 v14, v9, v14, v23
	v_pk_mul_f32 v[12:13], v[14:15], v[12:13]
	v_pk_add_f32 v[14:15], v[18:19], 1.0 op_sel_hi:[1,0]
	v_cvt_pk_bf16_f32 v9, v12, v13
	v_div_scale_f32 v18, s[6:7], v15, v15, v10
	v_rcp_f32_e32 v19, v18
	v_lshlrev_b32_e32 v12, 16, v20
	v_and_b32_e32 v13, 0xffff0000, v20
	v_fma_f32 v20, -v18, v19, 1.0
	v_fmac_f32_e32 v19, v20, v19
	v_div_scale_f32 v20, vcc, v10, v15, v10
	v_mul_f32_e32 v22, v20, v19
	v_fma_f32 v23, -v18, v22, v20
	v_fmac_f32_e32 v22, v23, v19
	v_fma_f32 v18, -v18, v22, v20
	v_div_scale_f32 v20, s[6:7], v14, v14, v25
	v_rcp_f32_e32 v23, v20
	v_div_fmas_f32 v18, v18, v19, v22
	v_div_fixup_f32 v15, v18, v15, v10
	v_and_b32_e32 v22, 0xffff0000, v11
	v_fma_f32 v10, -v20, v23, 1.0
	v_fmac_f32_e32 v23, v10, v23
	v_div_scale_f32 v10, vcc, v25, v14, v25
	v_mul_f32_e32 v18, v10, v23
	v_fma_f32 v19, -v20, v18, v10
	v_fmac_f32_e32 v18, v19, v23
	v_fma_f32 v19, -v20, v18, v10
	v_lshlrev_b32_e32 v20, 16, v11
	v_mul_f32_e32 v10, 0xbfb8aa3b, v20
	v_mul_f32_e32 v11, 0xbfb8aa3b, v22
	v_exp_f32_e32 v10, v10
	v_exp_f32_e32 v11, v11
	v_div_fmas_f32 v18, v19, v23, v18
	v_div_fixup_f32 v14, v18, v14, v25
	v_pk_mul_f32 v[12:13], v[14:15], v[12:13]
	v_pk_add_f32 v[14:15], v[10:11], 1.0 op_sel_hi:[1,0]
	v_cvt_pk_bf16_f32 v10, v12, v13
	v_div_scale_f32 v11, s[6:7], v15, v15, v22
	v_rcp_f32_e32 v18, v11
	v_lshlrev_b32_e32 v12, 16, v21
	v_and_b32_e32 v13, 0xffff0000, v21
	v_fma_f32 v19, -v11, v18, 1.0
	v_fmac_f32_e32 v18, v19, v18
	v_div_scale_f32 v19, vcc, v22, v15, v22
	v_mul_f32_e32 v21, v19, v18
	v_fma_f32 v23, -v11, v21, v19
	v_fmac_f32_e32 v21, v23, v18
	v_fma_f32 v11, -v11, v21, v19
	v_div_scale_f32 v19, s[6:7], v14, v14, v20
	v_rcp_f32_e32 v23, v19
	v_div_fmas_f32 v11, v11, v18, v21
	v_div_fixup_f32 v15, v11, v15, v22
	v_fma_f32 v11, -v19, v23, 1.0
	v_fmac_f32_e32 v23, v11, v23
	v_div_scale_f32 v11, vcc, v20, v14, v20
	v_mul_f32_e32 v18, v11, v23
	v_fma_f32 v21, -v19, v18, v11
	v_fmac_f32_e32 v18, v21, v23
	v_fma_f32 v11, -v19, v18, v11
	v_div_fmas_f32 v11, v11, v23, v18
	s_waitcnt vmcnt(1)
	v_lshlrev_b32_e32 v18, 16, v4
	v_div_fixup_f32 v14, v11, v14, v20
	v_and_b32_e32 v4, 0xffff0000, v4
	v_mul_f32_e32 v11, 0xbfb8aa3b, v18
	v_pk_mul_f32 v[12:13], v[14:15], v[12:13]
	v_exp_f32_e32 v14, v11
	v_mul_f32_e32 v11, 0xbfb8aa3b, v4
	v_exp_f32_e32 v15, v11
	v_cvt_pk_bf16_f32 v11, v12, v13
	v_lshlrev_b64 v[12:13], 12, v[16:17]
	v_lshl_add_u64 v[12:13], v[68:69], 0, v[12:13]
	v_pk_add_f32 v[14:15], v[14:15], 1.0 op_sel_hi:[1,0]
	global_store_dwordx4 v[12:13], v[8:11], off offset:3072 sc1
	v_div_scale_f32 v16, s[6:7], v15, v15, v4
	v_rcp_f32_e32 v17, v16
	s_waitcnt lgkmcnt(0)
	v_lshlrev_b32_e32 v8, 16, v0
	v_and_b32_e32 v9, 0xffff0000, v0
	v_div_scale_f32 v12, s[6:7], v14, v14, v18
	v_fma_f32 v0, -v16, v17, 1.0
	v_fmac_f32_e32 v17, v0, v17
	v_div_scale_f32 v0, vcc, v4, v15, v4
	v_mul_f32_e32 v10, v0, v17
	v_fma_f32 v11, -v16, v10, v0
	v_rcp_f32_e32 v13, v12
	v_fmac_f32_e32 v10, v11, v17
	v_fma_f32 v0, -v16, v10, v0
	v_div_fmas_f32 v0, v0, v17, v10
	v_div_fixup_f32 v11, v0, v15, v4
	v_fma_f32 v0, -v12, v13, 1.0
	v_fmac_f32_e32 v13, v0, v13
	v_div_scale_f32 v0, vcc, v18, v14, v18
	v_mul_f32_e32 v10, v0, v13
	v_fma_f32 v4, -v12, v10, v0
	v_fmac_f32_e32 v10, v4, v13
	v_fma_f32 v0, -v12, v10, v0
	v_lshlrev_b32_e32 v12, 16, v5
	v_and_b32_e32 v15, 0xffff0000, v5
	v_mul_f32_e32 v4, 0xbfb8aa3b, v12
	v_mul_f32_e32 v5, 0xbfb8aa3b, v15
	v_exp_f32_e32 v4, v4
	v_exp_f32_e32 v5, v5
	v_div_fmas_f32 v0, v0, v13, v10
	v_div_fixup_f32 v10, v0, v14, v18
	v_pk_mul_f32 v[8:9], v[10:11], v[8:9]
	v_pk_add_f32 v[4:5], v[4:5], 1.0 op_sel_hi:[1,0]
	v_cvt_pk_bf16_f32 v0, v8, v9
	v_div_scale_f32 v10, s[6:7], v5, v5, v15
	v_rcp_f32_e32 v11, v10
	v_lshlrev_b32_e32 v8, 16, v1
	v_and_b32_e32 v9, 0xffff0000, v1
	v_fma_f32 v1, -v10, v11, 1.0
	v_fmac_f32_e32 v11, v1, v11
	v_div_scale_f32 v1, vcc, v15, v5, v15
	v_mul_f32_e32 v13, v1, v11
	v_fma_f32 v14, -v10, v13, v1
	v_fmac_f32_e32 v13, v14, v11
	v_fma_f32 v1, -v10, v13, v1
	v_div_scale_f32 v10, s[6:7], v4, v4, v12
	v_rcp_f32_e32 v14, v10
	v_div_fmas_f32 v1, v1, v11, v13
	v_div_fixup_f32 v5, v1, v5, v15
	v_lshlrev_b32_e32 v15, 16, v6
	v_fma_f32 v1, -v10, v14, 1.0
	v_fmac_f32_e32 v14, v1, v14
	v_div_scale_f32 v1, vcc, v12, v4, v12
	v_mul_f32_e32 v13, v1, v14
	v_fma_f32 v11, -v10, v13, v1
	v_fmac_f32_e32 v13, v11, v14
	v_and_b32_e32 v6, 0xffff0000, v6
	v_fma_f32 v1, -v10, v13, v1
	v_mul_f32_e32 v10, 0xbfb8aa3b, v15
	v_mul_f32_e32 v11, 0xbfb8aa3b, v6
	v_exp_f32_e32 v10, v10
	v_exp_f32_e32 v11, v11
	v_div_fmas_f32 v1, v1, v14, v13
	v_div_fixup_f32 v4, v1, v4, v12
	v_pk_mul_f32 v[4:5], v[4:5], v[8:9]
	v_pk_add_f32 v[8:9], v[10:11], 1.0 op_sel_hi:[1,0]
	v_cvt_pk_bf16_f32 v1, v4, v5
	v_div_scale_f32 v10, s[6:7], v9, v9, v6
	v_rcp_f32_e32 v11, v10
	v_lshlrev_b32_e32 v4, 16, v2
	v_and_b32_e32 v5, 0xffff0000, v2
	v_fma_f32 v2, -v10, v11, 1.0
	v_fmac_f32_e32 v11, v2, v11
	v_div_scale_f32 v2, vcc, v6, v9, v6
	v_mul_f32_e32 v12, v2, v11
	v_fma_f32 v13, -v10, v12, v2
	v_fmac_f32_e32 v12, v13, v11
	v_fma_f32 v2, -v10, v12, v2
	v_div_scale_f32 v10, s[6:7], v8, v8, v15
	v_rcp_f32_e32 v13, v10
	v_div_fmas_f32 v2, v2, v11, v12
	v_div_fixup_f32 v9, v2, v9, v6
	v_and_b32_e32 v12, 0xffff0000, v7
	v_fma_f32 v2, -v10, v13, 1.0
	v_fmac_f32_e32 v13, v2, v13
	v_div_scale_f32 v2, vcc, v15, v8, v15
	v_mul_f32_e32 v11, v2, v13
	v_fma_f32 v6, -v10, v11, v2
	v_fmac_f32_e32 v11, v6, v13
	v_fma_f32 v2, -v10, v11, v2
	v_lshlrev_b32_e32 v10, 16, v7
	v_mul_f32_e32 v6, 0xbfb8aa3b, v10
	v_mul_f32_e32 v7, 0xbfb8aa3b, v12
	v_exp_f32_e32 v6, v6
	v_exp_f32_e32 v7, v7
	v_div_fmas_f32 v2, v2, v13, v11
	v_div_fixup_f32 v8, v2, v8, v15
	v_pk_mul_f32 v[4:5], v[8:9], v[4:5]
	v_pk_add_f32 v[6:7], v[6:7], 1.0 op_sel_hi:[1,0]
	v_cvt_pk_bf16_f32 v2, v4, v5
	v_div_scale_f32 v8, s[6:7], v7, v7, v12
	v_rcp_f32_e32 v9, v8
	v_lshlrev_b32_e32 v4, 16, v3
	v_and_b32_e32 v5, 0xffff0000, v3
	v_fma_f32 v3, -v8, v9, 1.0
	v_fmac_f32_e32 v9, v3, v9
	v_div_scale_f32 v3, vcc, v12, v7, v12
	v_mul_f32_e32 v11, v3, v9
	v_fma_f32 v13, -v8, v11, v3
	v_fmac_f32_e32 v11, v13, v9
	v_fma_f32 v3, -v8, v11, v3
	v_div_scale_f32 v8, s[6:7], v6, v6, v10
	v_rcp_f32_e32 v13, v8
	v_div_fmas_f32 v3, v3, v9, v11
	v_div_fixup_f32 v7, v3, v7, v12
	s_mov_b64 s[6:7], 0
	v_fma_f32 v3, -v8, v13, 1.0
	v_fmac_f32_e32 v13, v3, v13
	v_div_scale_f32 v3, vcc, v10, v6, v10
	v_mul_f32_e32 v9, v3, v13
	v_fma_f32 v11, -v8, v9, v3
	v_fmac_f32_e32 v9, v11, v13
	v_fma_f32 v3, -v8, v9, v3
	v_div_fmas_f32 v3, v3, v13, v9
	v_div_fixup_f32 v6, v3, v6, v10
	v_pk_mul_f32 v[4:5], v[6:7], v[4:5]
	s_nop 0
	v_cvt_pk_bf16_f32 v3, v4, v5
	v_lshlrev_b64 v[4:5], 12, v[144:145]
	v_lshl_add_u64 v[4:5], v[68:69], 0, v[4:5]
	global_store_dwordx4 v[4:5], v[0:3], off offset:3072 sc1
	s_barrier

.LBB0_1429:
	ds_read_b128 v[150:153], v147
	ds_read_b128 v[154:157], v147 offset:1024
	ds_read_b128 v[158:161], v147 offset:2048
	ds_read_b128 v[162:165], v147 offset:3072
	s_add_u32 s33, s34, 0xfff80080
	s_addc_u32 s36, s35, -1
	s_cmp_eq_u32 s73, 28
	s_cselect_b32 s39, s27, s36
	s_cselect_b32 s38, s69, s33
	s_cselect_b32 s37, s25, s72
	s_cselect_b32 s36, s70, s71
	v_lshl_add_u64 v[200:201], s[34:35], 0, v[136:137]
	s_add_i32 m0, s23, 0xc000
	ds_read_b128 v[166:169], v148
	ds_read_b128 v[170:173], v148 offset:1024
	ds_read_b128 v[174:177], v148 offset:2048
	ds_read_b128 v[178:181], v148 offset:3072
	ds_read_b128 v[182:185], v148 offset:4096
	ds_read_b128 v[186:189], v148 offset:5120
	ds_read_b128 v[190:193], v148 offset:6144
	ds_read_b128 v[194:197], v148 offset:7168
	global_load_lds_dwordx4 v[200:201], off
	v_lshl_add_u64 v[200:201], s[34:35], 0, v[138:139]
	s_add_i32 m0, s23, 0xe000
	s_nop 0
	global_load_lds_dwordx4 v[200:201], off
	s_waitcnt lgkmcnt(8)
	s_barrier
	s_waitcnt lgkmcnt(0)
	s_setprio 1
	s_waitcnt lgkmcnt(0)
	v_mfma_f32_16x16x32_bf16 v[124:127], v[150:153], v[166:169], v[124:127]
	v_mfma_f32_16x16x32_bf16 v[120:123], v[158:161], v[166:169], v[120:123]
	v_mfma_f32_16x16x32_bf16 v[116:119], v[150:153], v[174:177], v[116:119]
	v_mfma_f32_16x16x32_bf16 v[112:115], v[158:161], v[174:177], v[112:115]
	v_mfma_f32_16x16x32_bf16 v[108:111], v[150:153], v[182:185], v[108:111]
	v_mfma_f32_16x16x32_bf16 v[104:107], v[158:161], v[182:185], v[104:107]
	v_mfma_f32_16x16x32_bf16 v[100:103], v[150:153], v[190:193], v[100:103]
	v_mfma_f32_16x16x32_bf16 v[96:99], v[158:161], v[190:193], v[96:99]
	v_mfma_f32_16x16x32_bf16 v[124:127], v[154:157], v[170:173], v[124:127]
	v_mfma_f32_16x16x32_bf16 v[120:123], v[162:165], v[170:173], v[120:123]
	v_mfma_f32_16x16x32_bf16 v[116:119], v[154:157], v[178:181], v[116:119]
	v_mfma_f32_16x16x32_bf16 v[112:115], v[162:165], v[178:181], v[112:115]
	v_mfma_f32_16x16x32_bf16 v[108:111], v[154:157], v[186:189], v[108:111]
	v_mfma_f32_16x16x32_bf16 v[104:107], v[162:165], v[186:189], v[104:107]
	v_mfma_f32_16x16x32_bf16 v[100:103], v[154:157], v[194:197], v[100:103]
	v_mfma_f32_16x16x32_bf16 v[96:99], v[162:165], v[194:197], v[96:99]
	s_setprio 0
	s_barrier
	s_add_i32 s33, s62, s52
	v_lshl_add_u64 v[218:219], s[36:37], 0, v[130:131]
	s_mov_b32 m0, s33
	ds_read_b128 v[200:203], v149
	ds_read_b128 v[204:207], v149 offset:1024
	ds_read_b128 v[208:211], v149 offset:2048
	ds_read_b128 v[214:217], v149 offset:3072
	global_load_lds_dwordx4 v[218:219], off
	v_lshl_add_u64 v[220:221], s[36:37], 0, v[134:135]
	s_add_i32 m0, s33, 0x2000
	s_nop 0
	global_load_lds_dwordx4 v[220:221], off
	s_barrier
	s_waitcnt lgkmcnt(0)
	s_setprio 1
	s_waitcnt lgkmcnt(0)
	v_mfma_f32_16x16x32_bf16 v[80:83], v[200:203], v[166:169], v[80:83]
	v_mfma_f32_16x16x32_bf16 v[72:75], v[208:211], v[166:169], v[72:75]
	v_mfma_f32_16x16x32_bf16 v[68:71], v[200:203], v[174:177], v[68:71]
	v_mfma_f32_16x16x32_bf16 v[60:63], v[208:211], v[174:177], v[60:63]
	v_mfma_f32_16x16x32_bf16 v[52:55], v[200:203], v[182:185], v[52:55]
	v_mfma_f32_16x16x32_bf16 v[48:51], v[208:211], v[182:185], v[48:51]
	v_mfma_f32_16x16x32_bf16 v[36:39], v[200:203], v[190:193], v[36:39]
	v_mfma_f32_16x16x32_bf16 v[32:35], v[208:211], v[190:193], v[32:35]
	v_mfma_f32_16x16x32_bf16 v[80:83], v[204:207], v[170:173], v[80:83]
	v_mfma_f32_16x16x32_bf16 v[72:75], v[214:217], v[170:173], v[72:75]
	v_mfma_f32_16x16x32_bf16 v[68:71], v[204:207], v[178:181], v[68:71]
	v_mfma_f32_16x16x32_bf16 v[60:63], v[214:217], v[178:181], v[60:63]
	v_mfma_f32_16x16x32_bf16 v[52:55], v[204:207], v[186:189], v[52:55]
	v_mfma_f32_16x16x32_bf16 v[48:51], v[214:217], v[186:189], v[48:51]
	v_mfma_f32_16x16x32_bf16 v[36:39], v[204:207], v[194:197], v[36:39]
	v_mfma_f32_16x16x32_bf16 v[32:35], v[214:217], v[194:197], v[32:35]
	s_setprio 0
	s_mov_b32 m0, s23
	v_lshl_add_u64 v[222:223], s[38:39], 0, v[128:129]
	s_barrier
	ds_read_b128 v[166:169], v148 offset:16384
	ds_read_b128 v[170:173], v148 offset:17408
	ds_read_b128 v[174:177], v148 offset:18432
	ds_read_b128 v[178:181], v148 offset:19456
	ds_read_b128 v[182:185], v148 offset:20480
	ds_read_b128 v[186:189], v148 offset:21504
	ds_read_b128 v[190:193], v148 offset:22528
	ds_read_b128 v[194:197], v148 offset:23552
	global_load_lds_dwordx4 v[222:223], off
	v_lshl_add_u64 v[224:225], s[38:39], 0, v[132:133]
	s_mov_b32 m0, s54
	s_nop 0
	global_load_lds_dwordx4 v[224:225], off
	s_barrier
	s_waitcnt lgkmcnt(0)
	s_setprio 1
	s_waitcnt lgkmcnt(0)
	v_mfma_f32_16x16x32_bf16 v[92:95], v[150:153], v[166:169], v[92:95]
	v_mfma_f32_16x16x32_bf16 v[88:91], v[158:161], v[166:169], v[88:91]
	v_mfma_f32_16x16x32_bf16 v[84:87], v[150:153], v[174:177], v[84:87]
	v_mfma_f32_16x16x32_bf16 v[76:79], v[158:161], v[174:177], v[76:79]
	v_mfma_f32_16x16x32_bf16 v[64:67], v[150:153], v[182:185], v[64:67]
	v_mfma_f32_16x16x32_bf16 v[56:59], v[158:161], v[182:185], v[56:59]
	v_mfma_f32_16x16x32_bf16 v[44:47], v[150:153], v[190:193], v[44:47]
	v_mfma_f32_16x16x32_bf16 v[40:43], v[158:161], v[190:193], v[40:43]
	v_mfma_f32_16x16x32_bf16 v[92:95], v[154:157], v[170:173], v[92:95]
	v_mfma_f32_16x16x32_bf16 v[88:91], v[162:165], v[170:173], v[88:91]
	v_mfma_f32_16x16x32_bf16 v[84:87], v[154:157], v[178:181], v[84:87]
	v_mfma_f32_16x16x32_bf16 v[76:79], v[162:165], v[178:181], v[76:79]
	v_mfma_f32_16x16x32_bf16 v[64:67], v[154:157], v[186:189], v[64:67]
	v_mfma_f32_16x16x32_bf16 v[56:59], v[162:165], v[186:189], v[56:59]
	v_mfma_f32_16x16x32_bf16 v[44:47], v[154:157], v[194:197], v[44:47]
	v_mfma_f32_16x16x32_bf16 v[40:43], v[162:165], v[194:197], v[40:43]
	s_setprio 0
	s_barrier
	s_add_u32 s74, s36, 0x80000
	s_addc_u32 s75, s37, 0
	s_add_i32 s33, s63, s52
	v_lshl_add_u64 v[150:151], s[74:75], 0, v[130:131]
	s_mov_b32 m0, s33
	s_nop 0
	global_load_lds_dwordx4 v[150:151], off
	v_lshl_add_u64 v[150:151], s[74:75], 0, v[134:135]
	s_add_i32 m0, s33, 0x2000
	s_nop 0
	global_load_lds_dwordx4 v[150:151], off
	s_waitcnt vmcnt(6)
	s_barrier
	s_setprio 1
	v_mfma_f32_16x16x32_bf16 v[28:31], v[200:203], v[166:169], v[28:31]
	v_mfma_f32_16x16x32_bf16 v[24:27], v[208:211], v[166:169], v[24:27]
	v_mfma_f32_16x16x32_bf16 v[20:23], v[200:203], v[174:177], v[20:23]
	v_mfma_f32_16x16x32_bf16 v[16:19], v[208:211], v[174:177], v[16:19]
	v_mfma_f32_16x16x32_bf16 v[12:15], v[200:203], v[182:185], v[12:15]
	v_mfma_f32_16x16x32_bf16 v[8:11], v[208:211], v[182:185], v[8:11]
	v_mfma_f32_16x16x32_bf16 v[4:7], v[200:203], v[190:193], v[4:7]
	v_mfma_f32_16x16x32_bf16 v[0:3], v[208:211], v[190:193], v[0:3]
	v_mfma_f32_16x16x32_bf16 v[28:31], v[204:207], v[170:173], v[28:31]
	v_mfma_f32_16x16x32_bf16 v[24:27], v[214:217], v[170:173], v[24:27]
	v_mfma_f32_16x16x32_bf16 v[20:23], v[204:207], v[178:181], v[20:23]
	v_mfma_f32_16x16x32_bf16 v[16:19], v[214:217], v[178:181], v[16:19]
	v_mfma_f32_16x16x32_bf16 v[12:15], v[204:207], v[186:189], v[12:15]
	v_mfma_f32_16x16x32_bf16 v[8:11], v[214:217], v[186:189], v[8:11]
	v_mfma_f32_16x16x32_bf16 v[4:7], v[204:207], v[194:197], v[4:7]
	v_mfma_f32_16x16x32_bf16 v[0:3], v[214:217], v[194:197], v[0:3]
	s_setprio 0
	s_add_i32 s33, 0, 0x18000
	v_add_u32_e32 v162, s33, v145
	s_barrier
	ds_read_b128 v[150:153], v162
	ds_read_b128 v[154:157], v162 offset:1024
	ds_read_b128 v[158:161], v162 offset:2048
	ds_read_b128 v[162:165], v162 offset:3072
	s_add_u32 s38, s38, 0x80000
	s_addc_u32 s39, s39, 0
	s_mov_b32 m0, s55
	v_lshl_add_u64 v[200:201], s[38:39], 0, v[128:129]
	ds_read_b128 v[166:169], v148 offset:32768
	ds_read_b128 v[170:173], v148 offset:33792
	ds_read_b128 v[174:177], v148 offset:34816
	ds_read_b128 v[178:181], v148 offset:35840
	ds_read_b128 v[182:185], v148 offset:36864
	ds_read_b128 v[186:189], v148 offset:37888
	ds_read_b128 v[190:193], v148 offset:38912
	ds_read_b128 v[194:197], v148 offset:39936
	global_load_lds_dwordx4 v[200:201], off
	v_lshl_add_u64 v[200:201], s[38:39], 0, v[132:133]
	s_mov_b32 m0, s56
	s_nop 0
	global_load_lds_dwordx4 v[200:201], off
	s_waitcnt lgkmcnt(8)
	s_barrier
	s_waitcnt lgkmcnt(0)
	s_setprio 1
	s_waitcnt lgkmcnt(0)
	v_mfma_f32_16x16x32_bf16 v[124:127], v[150:153], v[166:169], v[124:127]
	v_mfma_f32_16x16x32_bf16 v[120:123], v[158:161], v[166:169], v[120:123]
	v_mfma_f32_16x16x32_bf16 v[116:119], v[150:153], v[174:177], v[116:119]
	v_mfma_f32_16x16x32_bf16 v[112:115], v[158:161], v[174:177], v[112:115]
	v_mfma_f32_16x16x32_bf16 v[108:111], v[150:153], v[182:185], v[108:111]
	v_mfma_f32_16x16x32_bf16 v[104:107], v[158:161], v[182:185], v[104:107]
	v_mfma_f32_16x16x32_bf16 v[100:103], v[150:153], v[190:193], v[100:103]
	v_mfma_f32_16x16x32_bf16 v[96:99], v[158:161], v[190:193], v[96:99]
	v_mfma_f32_16x16x32_bf16 v[124:127], v[154:157], v[170:173], v[124:127]
	v_mfma_f32_16x16x32_bf16 v[120:123], v[162:165], v[170:173], v[120:123]
	v_mfma_f32_16x16x32_bf16 v[116:119], v[154:157], v[178:181], v[116:119]
	v_mfma_f32_16x16x32_bf16 v[112:115], v[162:165], v[178:181], v[112:115]
	v_mfma_f32_16x16x32_bf16 v[108:111], v[154:157], v[186:189], v[108:111]
	v_mfma_f32_16x16x32_bf16 v[104:107], v[162:165], v[186:189], v[104:107]
	v_mfma_f32_16x16x32_bf16 v[100:103], v[154:157], v[194:197], v[100:103]
	v_mfma_f32_16x16x32_bf16 v[96:99], v[162:165], v[194:197], v[96:99]
	s_setprio 0
	s_barrier
	s_add_i32 s38, 0, 0x1c000
	s_add_i32 s33, s33, s52
	v_add_u32_e32 v199, s38, v145
	v_lshl_add_u64 v[218:219], v[218:219], 0, s[14:15]
	s_mov_b32 m0, s33
	ds_read_b128 v[200:203], v199
	ds_read_b128 v[204:207], v199 offset:1024
	ds_read_b128 v[208:211], v199 offset:2048
	ds_read_b128 v[214:217], v199 offset:3072
	global_load_lds_dwordx4 v[218:219], off
	v_lshl_add_u64 v[218:219], v[220:221], 0, s[14:15]
	s_add_i32 m0, s33, 0x2000
	s_nop 0
	global_load_lds_dwordx4 v[218:219], off
	s_barrier
	s_waitcnt lgkmcnt(0)
	s_setprio 1
	s_waitcnt lgkmcnt(0)
	v_mfma_f32_16x16x32_bf16 v[80:83], v[200:203], v[166:169], v[80:83]
	v_mfma_f32_16x16x32_bf16 v[72:75], v[208:211], v[166:169], v[72:75]
	v_mfma_f32_16x16x32_bf16 v[68:71], v[200:203], v[174:177], v[68:71]
	v_mfma_f32_16x16x32_bf16 v[60:63], v[208:211], v[174:177], v[60:63]
	v_mfma_f32_16x16x32_bf16 v[52:55], v[200:203], v[182:185], v[52:55]
	v_mfma_f32_16x16x32_bf16 v[48:51], v[208:211], v[182:185], v[48:51]
	v_mfma_f32_16x16x32_bf16 v[36:39], v[200:203], v[190:193], v[36:39]
	v_mfma_f32_16x16x32_bf16 v[32:35], v[208:211], v[190:193], v[32:35]
	v_mfma_f32_16x16x32_bf16 v[80:83], v[204:207], v[170:173], v[80:83]
	v_mfma_f32_16x16x32_bf16 v[72:75], v[214:217], v[170:173], v[72:75]
	v_mfma_f32_16x16x32_bf16 v[68:71], v[204:207], v[178:181], v[68:71]
	v_mfma_f32_16x16x32_bf16 v[60:63], v[214:217], v[178:181], v[60:63]
	v_mfma_f32_16x16x32_bf16 v[52:55], v[204:207], v[186:189], v[52:55]
	v_mfma_f32_16x16x32_bf16 v[48:51], v[214:217], v[186:189], v[48:51]
	v_mfma_f32_16x16x32_bf16 v[36:39], v[204:207], v[194:197], v[36:39]
	v_mfma_f32_16x16x32_bf16 v[32:35], v[214:217], v[194:197], v[32:35]
	s_setprio 0
	s_mov_b32 m0, s59
	v_lshl_add_u64 v[218:219], v[222:223], 0, s[14:15]
	s_barrier
	ds_read_b128 v[166:169], v148 offset:49152
	ds_read_b128 v[170:173], v148 offset:50176
	ds_read_b128 v[174:177], v148 offset:51200
	ds_read_b128 v[178:181], v148 offset:52224
	ds_read_b128 v[182:185], v148 offset:53248
	ds_read_b128 v[186:189], v148 offset:54272
	ds_read_b128 v[190:193], v148 offset:55296
	ds_read_b128 v[194:197], v148 offset:56320
	global_load_lds_dwordx4 v[218:219], off
	v_lshl_add_u64 v[218:219], v[224:225], 0, s[14:15]
	s_mov_b32 m0, s60
	s_nop 0
	global_load_lds_dwordx4 v[218:219], off
	s_barrier
	s_waitcnt lgkmcnt(0)
	s_setprio 1
	s_waitcnt lgkmcnt(0)
	v_mfma_f32_16x16x32_bf16 v[92:95], v[150:153], v[166:169], v[92:95]
	v_mfma_f32_16x16x32_bf16 v[88:91], v[158:161], v[166:169], v[88:91]
	v_mfma_f32_16x16x32_bf16 v[84:87], v[150:153], v[174:177], v[84:87]
	v_mfma_f32_16x16x32_bf16 v[76:79], v[158:161], v[174:177], v[76:79]
	v_mfma_f32_16x16x32_bf16 v[64:67], v[150:153], v[182:185], v[64:67]
	v_mfma_f32_16x16x32_bf16 v[56:59], v[158:161], v[182:185], v[56:59]
	v_mfma_f32_16x16x32_bf16 v[44:47], v[150:153], v[190:193], v[44:47]
	v_mfma_f32_16x16x32_bf16 v[40:43], v[158:161], v[190:193], v[40:43]
	v_mfma_f32_16x16x32_bf16 v[92:95], v[154:157], v[170:173], v[92:95]
	v_mfma_f32_16x16x32_bf16 v[88:91], v[162:165], v[170:173], v[88:91]
	v_mfma_f32_16x16x32_bf16 v[84:87], v[154:157], v[178:181], v[84:87]
	v_mfma_f32_16x16x32_bf16 v[76:79], v[162:165], v[178:181], v[76:79]
	v_mfma_f32_16x16x32_bf16 v[64:67], v[154:157], v[186:189], v[64:67]
	v_mfma_f32_16x16x32_bf16 v[56:59], v[162:165], v[186:189], v[56:59]
	v_mfma_f32_16x16x32_bf16 v[44:47], v[154:157], v[194:197], v[44:47]
	v_mfma_f32_16x16x32_bf16 v[40:43], v[162:165], v[194:197], v[40:43]
	s_setprio 0
	s_barrier
	s_add_u32 s36, s36, 0x80080
	s_addc_u32 s37, s37, 0
	s_add_i32 s33, s38, s52
	v_lshl_add_u64 v[150:151], s[36:37], 0, v[130:131]
	s_mov_b32 m0, s33
	s_nop 0
	global_load_lds_dwordx4 v[150:151], off
	v_lshl_add_u64 v[150:151], s[36:37], 0, v[134:135]
	s_add_i32 m0, s33, 0x2000
	s_nop 0
	global_load_lds_dwordx4 v[150:151], off
	s_waitcnt vmcnt(6)
	s_barrier
	s_setprio 1
	v_mfma_f32_16x16x32_bf16 v[28:31], v[200:203], v[166:169], v[28:31]
	v_mfma_f32_16x16x32_bf16 v[24:27], v[208:211], v[166:169], v[24:27]
	v_mfma_f32_16x16x32_bf16 v[20:23], v[200:203], v[174:177], v[20:23]
	v_mfma_f32_16x16x32_bf16 v[16:19], v[208:211], v[174:177], v[16:19]
	v_mfma_f32_16x16x32_bf16 v[12:15], v[200:203], v[182:185], v[12:15]
	v_mfma_f32_16x16x32_bf16 v[8:11], v[208:211], v[182:185], v[8:11]
	v_mfma_f32_16x16x32_bf16 v[4:7], v[200:203], v[190:193], v[4:7]
	v_mfma_f32_16x16x32_bf16 v[0:3], v[208:211], v[190:193], v[0:3]
	v_mfma_f32_16x16x32_bf16 v[28:31], v[204:207], v[170:173], v[28:31]
	v_mfma_f32_16x16x32_bf16 v[24:27], v[214:217], v[170:173], v[24:27]
	v_mfma_f32_16x16x32_bf16 v[20:23], v[204:207], v[178:181], v[20:23]
	v_mfma_f32_16x16x32_bf16 v[16:19], v[214:217], v[178:181], v[16:19]
	v_mfma_f32_16x16x32_bf16 v[12:15], v[204:207], v[186:189], v[12:15]
	v_mfma_f32_16x16x32_bf16 v[8:11], v[214:217], v[186:189], v[8:11]
	v_mfma_f32_16x16x32_bf16 v[4:7], v[204:207], v[194:197], v[4:7]
	v_mfma_f32_16x16x32_bf16 v[0:3], v[214:217], v[194:197], v[0:3]
	s_setprio 0
	s_add_i32 s73, s73, 2
	s_add_u32 s34, s34, 0x100
	s_addc_u32 s35, s35, 0
	s_add_u32 s71, s71, 0x100
	s_addc_u32 s72, s72, 0
	s_cmp_gt_u32 s73, 29
	s_barrier
	s_cbranch_scc0 .LBB0_1429
	v_lshl_add_u32 v150, s22, 8, v144
	v_lshl_or_b32 v152, s68, 8, v146
	v_ashrrev_i32_e32 v151, 31, v150
	v_ashrrev_i32_e32 v153, 31, v152
	v_cvt_pk_bf16_f32 v124, v124, v125
	v_cvt_pk_bf16_f32 v125, v126, v127
	v_cvt_pk_bf16_f32 v126, v120, v121
	v_lshlrev_b64 v[120:121], 12, v[150:151]
	v_cvt_pk_bf16_f32 v127, v122, v123
	v_lshl_add_u64 v[120:121], s[12:13], 0, v[120:121]
	v_lshlrev_b64 v[122:123], 1, v[152:153]
	v_lshl_add_u64 v[120:121], v[120:121], 0, v[122:123]
	v_cvt_pk_bf16_f32 v92, v92, v93
	v_cvt_pk_bf16_f32 v93, v94, v95
	v_cvt_pk_bf16_f32 v95, v90, v91
	v_add_co_u32_e32 v90, vcc, s64, v120
	v_cvt_pk_bf16_f32 v84, v84, v85
	s_nop 0
	v_addc_co_u32_e32 v91, vcc, 0, v121, vcc
	v_cvt_pk_bf16_f32 v85, v86, v87
	v_cvt_pk_bf16_f32 v87, v78, v79
	v_add_co_u32_e32 v78, vcc, s65, v120
	v_cvt_pk_bf16_f32 v64, v64, v65
	s_nop 0
	v_addc_co_u32_e32 v79, vcc, 0, v121, vcc
	v_cvt_pk_bf16_f32 v65, v66, v67
	v_cvt_pk_bf16_f32 v67, v58, v59
	v_add_co_u32_e32 v58, vcc, s66, v120
	global_store_dwordx4 v[120:121], v[124:127], off sc1
	s_nop 0
	v_addc_co_u32_e32 v59, vcc, 0, v121, vcc
	v_or_b32_e32 v124, 16, v150
	v_cvt_pk_bf16_f32 v116, v116, v117
	v_cvt_pk_bf16_f32 v117, v118, v119
	v_cvt_pk_bf16_f32 v119, v114, v115
	v_ashrrev_i32_e32 v125, 31, v124
	v_or_b32_e32 v114, 32, v150
	v_cvt_pk_bf16_f32 v108, v108, v109
	v_cvt_pk_bf16_f32 v109, v110, v111
	v_cvt_pk_bf16_f32 v111, v106, v107
	v_or_b32_e32 v106, 48, v150
	v_cvt_pk_bf16_f32 v44, v44, v45
	v_cvt_pk_bf16_f32 v45, v46, v47
	v_cvt_pk_bf16_f32 v46, v40, v41
	v_add_co_u32_e32 v40, vcc, s67, v120
	v_cvt_pk_bf16_f32 v118, v112, v113
	v_lshlrev_b64 v[112:113], 12, v[124:125]
	v_ashrrev_i32_e32 v115, 31, v114
	v_ashrrev_i32_e32 v107, 31, v106
	v_cvt_pk_bf16_f32 v47, v42, v43
	v_addc_co_u32_e32 v41, vcc, 0, v121, vcc
	v_lshl_add_u64 v[112:113], s[12:13], 0, v[112:113]
	v_cvt_pk_bf16_f32 v110, v104, v105
	v_lshlrev_b64 v[104:105], 12, v[114:115]
	v_cvt_pk_bf16_f32 v100, v100, v101
	v_cvt_pk_bf16_f32 v101, v102, v103
	v_cvt_pk_bf16_f32 v102, v96, v97
	v_lshlrev_b64 v[96:97], 12, v[106:107]
	global_store_dwordx4 v[40:41], v[44:47], off sc1
	v_cvt_pk_bf16_f32 v40, v80, v81
	v_cvt_pk_bf16_f32 v41, v82, v83
	v_cvt_pk_bf16_f32 v42, v72, v73
	v_cvt_pk_bf16_f32 v43, v74, v75
	v_lshl_add_u64 v[112:113], v[112:113], 0, v[122:123]
	v_lshl_add_u64 v[104:105], s[12:13], 0, v[104:105]
	v_lshl_add_u64 v[96:97], s[12:13], 0, v[96:97]
	v_cvt_pk_bf16_f32 v66, v56, v57
	global_store_dwordx4 v[120:121], v[40:43], off offset:256 sc1
	v_lshl_add_u64 v[104:105], v[104:105], 0, v[122:123]
	v_cvt_pk_bf16_f32 v103, v98, v99
	v_cvt_pk_bf16_f32 v40, v68, v69
	v_cvt_pk_bf16_f32 v41, v70, v71
	v_cvt_pk_bf16_f32 v42, v60, v61
	v_cvt_pk_bf16_f32 v43, v62, v63
	v_lshl_add_u64 v[96:97], v[96:97], 0, v[122:123]
	v_cvt_pk_bf16_f32 v94, v88, v89
	v_lshl_add_u64 v[88:89], v[120:121], 0, s[10:11]
	v_cvt_pk_bf16_f32 v86, v76, v77
	v_lshl_add_u64 v[76:77], v[120:121], 0, s[16:17]
	v_lshl_add_u64 v[56:57], v[120:121], 0, s[18:19]
	global_store_dwordx4 v[58:59], v[64:67], off sc1
	v_lshl_add_u64 v[58:59], v[120:121], 0, s[20:21]
	global_store_dwordx4 v[112:113], v[40:43], off offset:256 sc1
	v_cvt_pk_bf16_f32 v36, v36, v37
	v_cvt_pk_bf16_f32 v37, v38, v39
	v_cvt_pk_bf16_f32 v40, v52, v53
	v_cvt_pk_bf16_f32 v41, v54, v55
	v_cvt_pk_bf16_f32 v42, v48, v49
	v_cvt_pk_bf16_f32 v43, v50, v51
	v_cvt_pk_bf16_f32 v38, v32, v33
	v_cvt_pk_bf16_f32 v39, v34, v35
	v_cvt_pk_bf16_f32 v28, v28, v29
	v_cvt_pk_bf16_f32 v29, v30, v31
	v_cvt_pk_bf16_f32 v30, v24, v25
	v_cvt_pk_bf16_f32 v31, v26, v27
	v_cvt_pk_bf16_f32 v20, v20, v21
	v_cvt_pk_bf16_f32 v21, v22, v23
	v_cvt_pk_bf16_f32 v22, v16, v17
	v_cvt_pk_bf16_f32 v23, v18, v19
	v_cvt_pk_bf16_f32 v12, v12, v13
	v_cvt_pk_bf16_f32 v13, v14, v15
	v_cvt_pk_bf16_f32 v14, v8, v9
	v_cvt_pk_bf16_f32 v15, v10, v11
	v_cvt_pk_bf16_f32 v4, v4, v5
	v_cvt_pk_bf16_f32 v5, v6, v7
	v_cvt_pk_bf16_f32 v6, v0, v1
	v_cvt_pk_bf16_f32 v7, v2, v3
	s_and_b64 vcc, exec, s[6:7]
	s_mov_b32 s22, s26
	s_mov_b32 s68, s24
	s_mov_b64 s[36:37], s[30:31]
	s_mov_b64 s[34:35], s[28:29]
	global_store_dwordx4 v[112:113], v[116:119], off sc1
	global_store_dwordx4 v[104:105], v[108:111], off sc1
	global_store_dwordx4 v[96:97], v[100:103], off sc1
	global_store_dwordx4 v[90:91], v[92:95], off sc1
	global_store_dwordx4 v[78:79], v[84:87], off sc1
	global_store_dwordx4 v[104:105], v[40:43], off offset:256 sc1
	global_store_dwordx4 v[96:97], v[36:39], off offset:256 sc1
	global_store_dwordx4 v[88:89], v[28:31], off offset:256 sc1
	global_store_dwordx4 v[76:77], v[20:23], off offset:256 sc1
	global_store_dwordx4 v[56:57], v[12:15], off offset:256 sc1
	global_store_dwordx4 v[58:59], v[4:7], off offset:256 sc1
	s_cbranch_vccz .LBB0_1422
	s_waitcnt vmcnt(0)
	s_cmpk_gt_u32 s3, 0xff
	s_cbranch_scc1 .LBB0_1433
	s_barrier
